# batched epilogue/prologue load chains (gate_b, residual, panel fix-up) + SGU V-tile prefetched during attention
# speedup vs baseline: 1.0066x; 1.0041x over previous
; #define LAS __attribute__((address_space(3)))
; __device__ __forceinline__ void attn_unit(LAS unsigned char* lds, bf16* Q, const bf16* Kg, const bf16* Vg, const float* snk, int unit, int tid) {
;     ...
;     for (int i = 0; i < 2; ++i) { const int idx = tid + 512 * i, j = (idx >> 3) * 2, c = idx & 7, p = n * 128 - 128 + j;
;         v4u w0 = zero4, w1 = zero4;
;         if (p >= 0) { w0 = *(const v4u*)(Vg + (size_t)(b * SEQ + p) * 128 + h * 64 + c * 8); w1 = *(const v4u*)(Vg + (size_t)(b * SEQ + p + 1) * 128 + h * 64 + c * 8); }
;         const unsigned A0[4] = {w0.x, w0.y, w0.z, w0.w}, A1[4] = {w1.x, w1.y, w1.z, w1.w};
; #pragma unroll
;         for (int e = 0; e < 8; ++e) { const unsigned lo = (e & 1) ? (A0[e >> 1] >> 16) : (A0[e >> 1] & 0xffffu), hi = (e & 1) ? (A1[e >> 1] & 0xffff0000u) : (A1[e >> 1] << 16);
;             *(LAS unsigned*)(lds + ATT_VOFF + (8 * c + e) * ATT_VP + j * 2) = lo | hi; } }
;     __syncthreads();
;     const float sink = snk[hq] * 1.4426950408889634f;
;     bool lo_ok[4];
; #pragma unroll
;     for (int i = 0; i < 4; ++i) lo_ok[i] = (4 * fq + i - fr) > 0;
; #pragma unroll
;     for (int mt = 0; mt < 8; ++mt) {
;         f32x4 st[9];
; #pragma unroll
;         for (int kb = 0; kb < 9; ++kb) { const LAS unsigned char* kp = lds + (16 * (mt + kb) + fr) * ATT_KP + 16 * fq;
;             const bf16x8_t k0 = *(const LAS bf16x8_t*)kp, k1 = *(const LAS bf16x8_t*)(kp + 64);
;             f32x4 z = {0.f, 0.f, 0.f, 0.f}; z = __builtin_amdgcn_mfma_f32_16x16x32_bf16(k0, qf[mt][0], z, 0, 0, 0); z = __builtin_amdgcn_mfma_f32_16x16x32_bf16(k1, qf[mt][1], z, 0, 0, 0); st[kb] = z; }
;         float mx = sink;
; #pragma unroll
;         for (int kb = 0; kb < 9; ++kb) {
;             const bool tile_ok = (n > 0) || (mt + kb >= 8);
; #pragma unroll
;             for (int i = 0; i < 4; ++i) { const bool ok = tile_ok && (kb == 0 ? lo_ok[i] : (kb == 8 ? !lo_ok[i] : true));
;                 st[kb][i] = ok ? st[kb][i] : -INFINITY; mx = fmaxf(mx, st[kb][i]); }
.LBB0_493:
	s_or_b64 exec, exec, s[14:15]
	s_waitcnt vmcnt(0)
	v_lshlrev_b32_e32 v74, 16, v66
	v_and_or_b32 v74, v70, s61, v74
	v_lshrrev_b32_e32 v70, 16, v70
	v_and_or_b32 v66, v66, s60, v70
	v_add_u32_e32 v70, 0x9000, v189
	ds_write2_b32 v70, v74, v66 offset1:132
	v_lshlrev_b32_e32 v66, 16, v67
	v_lshrrev_b32_e32 v70, 16, v71
	v_and_or_b32 v66, v71, s61, v66
	v_and_or_b32 v67, v67, s60, v70
	v_add_u32_e32 v70, 0x9400, v189
	ds_write2_b32 v70, v66, v67 offset0:8 offset1:140
	v_lshlrev_b32_e32 v66, 16, v68
	v_lshrrev_b32_e32 v67, 16, v72
	v_and_or_b32 v66, v72, s61, v66
	v_and_or_b32 v67, v68, s60, v67
	v_add_u32_e32 v68, 0x9800, v189
	ds_write2_b32 v68, v66, v67 offset0:16 offset1:148
	v_lshlrev_b32_e32 v66, 16, v69
	v_lshrrev_b32_e32 v67, 16, v73
	v_and_or_b32 v66, v73, s61, v66
	v_and_or_b32 v67, v69, s60, v67
	v_add_u32_e32 v68, 0x9c00, v189
	ds_write2_b32 v68, v66, v67 offset0:24 offset1:156
	s_waitcnt lgkmcnt(0)
	s_barrier
	ds_read_b128 v[66:69], v179
	ds_read_b128 v[70:73], v179 offset:64
	s_waitcnt lgkmcnt(1)
	v_mfma_f32_16x16x32_bf16 v[66:69], v[66:69], v[62:65], 0
	ds_read_b128 v[80:83], v179 offset:2304
	ds_read_b128 v[84:87], v179 offset:4608
	ds_read_b128 v[88:91], v179 offset:6912
	s_waitcnt lgkmcnt(3)
	v_mfma_f32_16x16x32_bf16 v[66:69], v[70:73], v[58:61], v[66:69]
	ds_read_b128 v[70:73], v179 offset:2368
	ds_read_b128 v[92:95], v179 offset:9216
	ds_read_b128 v[96:99], v179 offset:11520
	s_waitcnt lgkmcnt(5)
	v_mfma_f32_16x16x32_bf16 v[80:83], v[80:83], v[62:65], 0
	ds_read_b128 v[100:103], v179 offset:13824
	v_ashrrev_i32_e32 v79, 31, v78
	s_cmp_lg_u32 s64, 0
	s_waitcnt lgkmcnt(3)
	v_mfma_f32_16x16x32_bf16 v[72:75], v[70:73], v[58:61], v[80:83]
	v_lshl_add_u64 v[70:71], v[78:79], 2, s[28:29]
	s_cselect_b64 s[14:15], -1, 0
	s_and_b64 s[18:19], s[14:15], s[6:7]
	ds_read_b128 v[80:83], v179 offset:4672
	v_mfma_f32_16x16x32_bf16 v[84:87], v[84:87], v[62:65], 0
	s_and_b64 s[16:17], s[14:15], s[10:11]
	s_and_b64 s[20:21], s[14:15], s[12:13]
	v_cndmask_b32_e64 v68, v191, v68, s[16:17]
	s_waitcnt lgkmcnt(0)
	v_mfma_f32_16x16x32_bf16 v[80:83], v[80:83], v[58:61], v[84:87]
	s_nop 2
	ds_read_b128 v[84:87], v179 offset:6976
	v_cndmask_b32_e64 v69, v191, v69, s[20:21]
	s_cmp_eq_u32 s64, 0
	v_mfma_f32_16x16x32_bf16 v[88:91], v[88:91], v[62:65], 0
	s_nop 0
	v_cndmask_b32_e64 v78, v191, v80, s[14:15]
	v_cndmask_b32_e64 v79, v191, v81, s[14:15]
	v_cndmask_b32_e64 v80, v191, v82, s[14:15]
	s_waitcnt lgkmcnt(0)
	v_mfma_f32_16x16x32_bf16 v[84:87], v[84:87], v[58:61], v[88:91]
	v_cndmask_b32_e64 v81, v191, v83, s[14:15]
	s_nop 1
	ds_read_b128 v[88:91], v179 offset:9280
	v_mov_b32_e32 v157, v147
	v_mfma_f32_16x16x32_bf16 v[92:95], v[92:95], v[62:65], 0
	s_nop 1
	v_cndmask_b32_e64 v82, v191, v84, s[14:15]
	v_cndmask_b32_e64 v83, v191, v85, s[14:15]
	v_cndmask_b32_e64 v84, v191, v86, s[14:15]
	s_waitcnt lgkmcnt(0)
	v_mfma_f32_16x16x32_bf16 v[88:91], v[88:91], v[58:61], v[92:95]
	v_cndmask_b32_e64 v85, v191, v87, s[14:15]
	s_nop 1
	ds_read_b128 v[92:95], v179 offset:11584
	s_nop 3
	v_cndmask_b32_e64 v86, v191, v88, s[14:15]
	v_mfma_f32_16x16x32_bf16 v[96:99], v[96:99], v[62:65], 0
	v_cndmask_b32_e64 v87, v191, v89, s[14:15]
	v_cndmask_b32_e64 v88, v191, v90, s[14:15]
	v_cndmask_b32_e64 v89, v191, v91, s[14:15]
	s_waitcnt lgkmcnt(0)
	v_mfma_f32_16x16x32_bf16 v[92:95], v[92:95], v[58:61], v[96:99]
	s_nop 2
	ds_read_b128 v[96:99], v179 offset:16128
	ds_read_b128 v[104:107], v179 offset:13888
	ds_read_b128 v[108:111], v179 offset:18432
	ds_read_b128 v[112:115], v179 offset:16192
	ds_read_b128 v[116:119], v179 offset:18496
	v_mfma_f32_16x16x32_bf16 v[100:103], v[100:103], v[62:65], 0
	s_waitcnt lgkmcnt(4)
	v_mfma_f32_16x16x32_bf16 v[96:99], v[96:99], v[62:65], 0
	s_waitcnt lgkmcnt(2)
	v_mfma_f32_16x16x32_bf16 v[108:111], v[108:111], v[62:65], 0
	global_load_dword v64, v[70:71], off
	v_and_b32_e32 v63, 64, v190
	v_xor_b32_e32 v62, 16, v190
	v_add_u32_e32 v63, 64, v63
	v_cmp_lt_i32_e32 vcc, v62, v63
	v_cndmask_b32_e64 v70, v191, v72, s[14:15]
	v_cndmask_b32_e64 v72, v191, v73, s[14:15]
	v_cndmask_b32_e32 v62, v190, v62, vcc
	v_lshlrev_b32_e32 v65, 2, v62
	v_cndmask_b32_e64 v62, v67, v191, s[8:9]
	v_cndmask_b32_e64 v62, v191, v62, s[14:15]
	v_cndmask_b32_e64 v67, v191, v66, s[18:19]
	v_cndmask_b32_e64 v73, v191, v74, s[14:15]
	v_cndmask_b32_e64 v74, v191, v75, s[14:15]
	v_mfma_f32_16x16x32_bf16 v[100:103], v[104:107], v[58:61], v[100:103]
	v_cndmask_b32_e64 v106, v191, v92, s[14:15]
	v_cndmask_b32_e64 v107, v191, v93, s[14:15]
	s_cselect_b64 vcc, -1, 0
	s_waitcnt lgkmcnt(1)
	v_mfma_f32_16x16x32_bf16 v[96:99], v[112:115], v[58:61], v[96:99]
	s_waitcnt vmcnt(0)
; __device__ __forceinline__ unsigned cvt_pk_bf16(float lo, float hi) { unsigned r; asm volatile("v_cvt_pk_bf16_f32 %0, %1, %2" : "=v"(r) : "v"(lo), "v"(hi)); return r; }
; #define LAS __attribute__((address_space(3)))
; __device__ __forceinline__ void attn_unit(LAS unsigned char* lds, bf16* Q, const bf16* Kg, const bf16* Vg, const float* snk, int unit, int tid) {
;     ...
;         float mx = sink;
; #pragma unroll
;         for (int kb = 0; kb < 9; ++kb) {
;             const bool tile_ok = (n > 0) || (mt + kb >= 8);
; #pragma unroll
;             for (int i = 0; i < 4; ++i) { const bool ok = tile_ok && (kb == 0 ? lo_ok[i] : (kb == 8 ? !lo_ok[i] : true));
;                 st[kb][i] = ok ? st[kb][i] : -INFINITY; mx = fmaxf(mx, st[kb][i]); }
;         }
;         mx = fmaxf(mx, __shfl_xor(mx, 16)); mx = fmaxf(mx, __shfl_xor(mx, 32));
;         f32x4 ls4 = {0.f, 0.f, 0.f, 0.f};
; #pragma unroll
;         for (int kb = 0; kb < 9; ++kb) { f32x4 d = st[kb] - mx;
; #pragma unroll
;             for (int i = 0; i < 4; ++i) d[i] = __builtin_amdgcn_exp2f(d[i]);
;             st[kb] = d; ls4 = ls4 + d; }
;         float ls = (ls4[0] + ls4[1]) + (ls4[2] + ls4[3]);
;         ls += __shfl_xor(ls, 16); ls += __shfl_xor(ls, 32);
;         const float inv = 1.f / (ls + __builtin_amdgcn_exp2f(sink - mx));
;         f32x4 o[4];
; #pragma unroll
;         for (int dt = 0; dt < 4; ++dt) o[dt] = (f32x4){0.f, 0.f, 0.f, 0.f};
; #pragma unroll
;         for (int kp = 0; kp < 5; ++kp) {
;             v4u pw; pw.x = cvt_pk_bf16(st[2 * kp][0], st[2 * kp][1]); pw.y = cvt_pk_bf16(st[2 * kp][2], st[2 * kp][3]);
;             if (kp < 4) { pw.z = cvt_pk_bf16(st[(2 * kp + 1) % 9][0], st[(2 * kp + 1) % 9][1]); pw.w = cvt_pk_bf16(st[(2 * kp + 1) % 9][2], st[(2 * kp + 1) % 9][3]); } else { pw.z = 0u; pw.w = 0u; }
;             const bf16x8_t pb = __builtin_bit_cast(bf16x8_t, pw);
; #pragma unroll
;             for (int dt = 0; dt < 4; ++dt) { const LAS unsigned char* vp = lds + ATT_VOFF + (16 * dt + fr) * ATT_VP + (16 * (mt + 2 * kp) + 4 * fq) * 2;
;                 const v2u lo = *(const LAS v2u*)vp; v2u hi = {0u, 0u}; if (kp < 4) hi = *(const LAS v2u*)(vp + 32);
;                 v4u aw; aw.x = lo.x; aw.y = lo.y; aw.z = hi.x; aw.w = hi.y;
;                 o[dt] = __builtin_amdgcn_mfma_f32_16x16x32_bf16(__builtin_bit_cast(bf16x8_t, aw), pb, o[dt], 0, 0, 0); }
	s_cselect_b32 s100, 1, 0
	s_and_b32 s98, s23, 4
	v_add_u32_e32 v254, s98, v165
	v_lshlrev_b32_e32 v254, 7, v254
	v_or_b32_e32 v254, v254, v168
	v_or_b32_e32 v254, v254, v170
	s_and_b32 s98, s25, 0x3f80
	v_lshl_or_b32 v252, s98, 11, v181
	v_mov_b32_e32 v253, 0
	v_lshl_add_u64 v[252:253], s[48:49], 0, v[252:253]
	v_mov_b32_e32 v255, 0
	v_lshl_add_u64 v[252:253], v[254:255], 1, v[252:253]
	global_load_dwordx4 v[206:209], v[252:253], off
	global_load_dwordx4 v[210:213], v[252:253], off offset:2048
	s_mov_b64 s[98:99], 0x8000
	v_lshl_add_u64 v[254:255], v[252:253], 0, s[98:99]
	global_load_dwordx4 v[214:217], v[254:255], off
	global_load_dwordx4 v[218:221], v[254:255], off offset:2048
	s_mov_b64 s[98:99], 0x10000
	v_lshl_add_u64 v[254:255], v[252:253], 0, s[98:99]
	global_load_dwordx4 v[138:141], v[254:255], off
	global_load_dwordx4 v[142:145], v[254:255], off offset:2048
	s_mov_b64 s[98:99], 0x18000
	v_lshl_add_u64 v[254:255], v[252:253], 0, s[98:99]
	global_load_dwordx4 v[130:133], v[254:255], off
	global_load_dwordx4 v[134:137], v[254:255], off offset:2048
	s_mov_b64 s[98:99], 0x20000
	v_lshl_add_u64 v[254:255], v[252:253], 0, s[98:99]
	global_load_dwordx4 v[222:225], v[254:255], off
	global_load_dwordx4 v[226:229], v[254:255], off offset:2048
	s_mov_b64 s[98:99], 0x28000
	v_lshl_add_u64 v[254:255], v[252:253], 0, s[98:99]
	global_load_dwordx4 v[230:233], v[254:255], off
	global_load_dwordx4 v[234:237], v[254:255], off offset:2048
	s_mov_b64 s[98:99], 0x30000
	v_lshl_add_u64 v[254:255], v[252:253], 0, s[98:99]
	global_load_dwordx4 v[238:241], v[254:255], off
	global_load_dwordx4 v[242:245], v[254:255], off offset:2048
	s_mov_b64 s[98:99], 0x38000
	v_lshl_add_u64 v[254:255], v[252:253], 0, s[98:99]
	global_load_dwordx4 v[248:251], v[254:255], off
	global_load_dwordx4 v[252:255], v[254:255], off offset:2048
	s_cmp_lg_u32 s100, 0
	v_mul_f32_e32 v71, 0x3fb8aa3b, v64
	v_max3_f32 v66, v71, v67, v62
	v_max3_f32 v66, v66, v68, v69
	v_max3_f32 v66, v66, v70, v72
	v_max3_f32 v66, v66, v73, v74
	v_max3_f32 v66, v66, v78, v79
	v_max3_f32 v66, v66, v80, v81
	v_max3_f32 v66, v66, v82, v83
	v_max3_f32 v66, v66, v84, v85
	v_max3_f32 v66, v66, v86, v87
	v_max3_f32 v66, v66, v88, v89
	s_waitcnt lgkmcnt(0)
	v_mfma_f32_16x16x32_bf16 v[58:61], v[116:119], v[58:61], v[108:111]
	v_max3_f32 v66, v66, v106, v107
	v_cndmask_b32_e64 v100, v191, v100, s[14:15]
	v_cndmask_b32_e64 v101, v191, v101, s[14:15]
	v_cndmask_b32_e64 v108, v191, v94, s[14:15]
	v_cndmask_b32_e64 v109, v191, v95, s[14:15]
	v_max3_f32 v66, v66, v108, v109
	v_max3_f32 v66, v66, v100, v101
	v_cndmask_b32_e64 v110, v191, v102, s[14:15]
	v_cndmask_b32_e64 v111, v191, v103, s[14:15]
	v_max3_f32 v66, v66, v110, v111
	v_cndmask_b32_e32 v116, v96, v191, vcc
	v_cndmask_b32_e32 v117, v97, v191, vcc
	v_max3_f32 v66, v66, v116, v117
	v_cndmask_b32_e32 v98, v98, v191, vcc
	v_cndmask_b32_e32 v99, v99, v191, vcc
	v_max3_f32 v66, v66, v98, v99
	v_cndmask_b32_e64 v120, v58, v191, s[6:7]
	v_cndmask_b32_e64 v121, v191, v59, s[8:9]
	v_max3_f32 v58, v66, v120, v121
	v_cndmask_b32_e64 v122, v60, v191, s[10:11]
	v_cndmask_b32_e64 v123, v61, v191, s[12:13]
	v_max3_f32 v58, v58, v122, v123
	ds_bpermute_b32 v59, v65, v58
	v_xor_b32_e32 v60, 32, v190
	v_cmp_lt_i32_e32 vcc, v60, v63
	s_waitcnt lgkmcnt(0)
	v_max_f32_e32 v59, v59, v59
	v_cndmask_b32_e32 v60, v190, v60, vcc
	v_lshlrev_b32_e32 v66, 2, v60
	v_max_f32_e32 v58, v58, v59
	ds_bpermute_b32 v59, v66, v58
	s_waitcnt lgkmcnt(0)
	v_max_f32_e32 v59, v59, v59
	v_max_f32_e32 v124, v58, v59
	v_sub_f32_e32 v59, v69, v124
	v_sub_f32_e32 v62, v62, v124
	v_sub_f32_e32 v58, v67, v124
	v_exp_f32_e32 v58, v58
	v_exp_f32_e32 v61, v59
	v_exp_f32_e32 v59, v62
	v_sub_f32_e32 v67, v74, v124
	v_sub_f32_e32 v74, v73, v124
	v_sub_f32_e32 v73, v72, v124
	v_sub_f32_e32 v70, v70, v124
	v_exp_f32_e32 v72, v70
	v_exp_f32_e32 v73, v73
	v_sub_f32_e32 v79, v79, v124
	v_sub_f32_e32 v78, v78, v124
	v_exp_f32_e32 v90, v78
	v_exp_f32_e32 v91, v79
	v_sub_f32_e32 v78, v83, v124
	v_sub_f32_e32 v79, v82, v124
	v_exp_f32_e32 v94, v79
	v_exp_f32_e32 v95, v78
	v_sub_f32_e32 v78, v87, v124
	v_sub_f32_e32 v79, v86, v124
	v_sub_f32_e32 v60, v68, v124
	v_pk_add_f32 v[68:69], v[58:59], 0 op_sel_hi:[1,0]
	v_exp_f32_e32 v102, v79
	v_exp_f32_e32 v103, v78
	v_exp_f32_e32 v75, v67
	v_sub_f32_e32 v67, v81, v124
	v_sub_f32_e32 v70, v80, v124
	v_pk_add_f32 v[68:69], v[72:73], v[68:69]
	v_exp_f32_e32 v60, v60
	v_exp_f32_e32 v92, v70
	v_exp_f32_e32 v93, v67
	v_pk_add_f32 v[68:69], v[90:91], v[68:69]
	v_sub_f32_e32 v67, v85, v124
	v_sub_f32_e32 v70, v84, v124
	v_exp_f32_e32 v74, v74
	v_exp_f32_e32 v96, v70
	v_exp_f32_e32 v97, v67
	v_sub_f32_e32 v67, v89, v124
	v_sub_f32_e32 v70, v88, v124
	v_pk_add_f32 v[68:69], v[94:95], v[68:69]
	v_exp_f32_e32 v104, v70
	v_exp_f32_e32 v105, v67
	v_pk_add_f32 v[82:83], v[102:103], v[68:69]
	v_sub_f32_e32 v67, v109, v124
	v_sub_f32_e32 v69, v107, v124
	v_sub_f32_e32 v70, v106, v124
	v_sub_f32_e32 v68, v108, v124
	v_exp_f32_e32 v106, v70
	v_exp_f32_e32 v107, v69
	v_exp_f32_e32 v109, v67
	v_sub_f32_e32 v67, v101, v124
	v_sub_f32_e32 v70, v100, v124
	v_pk_add_f32 v[62:63], v[60:61], 0 op_sel_hi:[1,0]
	v_exp_f32_e32 v108, v68
	v_sub_f32_e32 v68, v111, v124
	v_sub_f32_e32 v69, v110, v124
	v_exp_f32_e32 v110, v70
	v_exp_f32_e32 v111, v67
	v_add_u32_e32 v67, 0x9000, v180
	v_pk_add_f32 v[62:63], v[74:75], v[62:63]
	v_cvt_pk_bf16_f32 v58, v58, v59
	v_cvt_pk_bf16_f32 v59, v60, v61
	v_cvt_pk_bf16_f32 v60, v72, v73
	v_cvt_pk_bf16_f32 v61, v74, v75
	ds_read2_b64 v[72:75], v67 offset1:4
	v_exp_f32_e32 v112, v69
	v_exp_f32_e32 v113, v68
	v_add_u32_e32 v68, 0xb000, v180
	v_pk_add_f32 v[82:83], v[106:107], v[82:83]
	v_add_u32_e32 v70, 0xd000, v180
	v_add_u32_e32 v69, 0xf000, v180
	v_pk_add_f32 v[62:63], v[92:93], v[62:63]
	ds_read2_b64 v[78:81], v68 offset0:32 offset1:36
	v_pk_add_f32 v[114:115], v[110:111], v[82:83]
	ds_read2_b64 v[82:85], v70 offset0:64 offset1:68
	ds_read2_b64 v[86:89], v69 offset0:96 offset1:100
	v_pk_add_f32 v[62:63], v[96:97], v[62:63]
	v_cvt_pk_bf16_f32 v90, v90, v91
	v_cvt_pk_bf16_f32 v91, v92, v93
	v_cvt_pk_bf16_f32 v92, v94, v95
	v_cvt_pk_bf16_f32 v93, v96, v97
	ds_read2_b64 v[94:97], v67 offset0:8 offset1:12
	s_waitcnt lgkmcnt(4)
; __device__ __forceinline__ unsigned cvt_pk_bf16(float lo, float hi) { unsigned r; asm volatile("v_cvt_pk_bf16_f32 %0, %1, %2" : "=v"(r) : "v"(lo), "v"(hi)); return r; }
; #define LAS __attribute__((address_space(3)))
; __device__ __forceinline__ void attn_unit(LAS unsigned char* lds, bf16* Q, const bf16* Kg, const bf16* Vg, const float* snk, int unit, int tid) {
;     ...
;     for (int mt = 0; mt < 8; ++mt) {
;         f32x4 st[9];
; #pragma unroll
;         for (int kb = 0; kb < 9; ++kb) { const LAS unsigned char* kp = lds + (16 * (mt + kb) + fr) * ATT_KP + 16 * fq;
;             const bf16x8_t k0 = *(const LAS bf16x8_t*)kp, k1 = *(const LAS bf16x8_t*)(kp + 64);
;             f32x4 z = {0.f, 0.f, 0.f, 0.f}; z = __builtin_amdgcn_mfma_f32_16x16x32_bf16(k0, qf[mt][0], z, 0, 0, 0); z = __builtin_amdgcn_mfma_f32_16x16x32_bf16(k1, qf[mt][1], z, 0, 0, 0); st[kb] = z; }
;     ...
;         f32x4 o[4];
; #pragma unroll
;         for (int dt = 0; dt < 4; ++dt) o[dt] = (f32x4){0.f, 0.f, 0.f, 0.f};
; #pragma unroll
;         for (int kp = 0; kp < 5; ++kp) {
;             v4u pw; pw.x = cvt_pk_bf16(st[2 * kp][0], st[2 * kp][1]); pw.y = cvt_pk_bf16(st[2 * kp][2], st[2 * kp][3]);
;             if (kp < 4) { pw.z = cvt_pk_bf16(st[(2 * kp + 1) % 9][0], st[(2 * kp + 1) % 9][1]); pw.w = cvt_pk_bf16(st[(2 * kp + 1) % 9][2], st[(2 * kp + 1) % 9][3]); } else { pw.z = 0u; pw.w = 0u; }
;             const bf16x8_t pb = __builtin_bit_cast(bf16x8_t, pw);
; #pragma unroll
;             for (int dt = 0; dt < 4; ++dt) { const LAS unsigned char* vp = lds + ATT_VOFF + (16 * dt + fr) * ATT_VP + (16 * (mt + 2 * kp) + 4 * fq) * 2;
;                 const v2u lo = *(const LAS v2u*)vp; v2u hi = {0u, 0u}; if (kp < 4) hi = *(const LAS v2u*)(vp + 32);
;                 v4u aw; aw.x = lo.x; aw.y = lo.y; aw.z = hi.x; aw.w = hi.y;
;                 o[dt] = __builtin_amdgcn_mfma_f32_16x16x32_bf16(__builtin_bit_cast(bf16x8_t, aw), pb, o[dt], 0, 0, 0); }
;         }
; #pragma unroll
;         for (int dt = 0; dt < 4; ++dt) { const f32x4 y = o[dt] * inv; v2u w; w.x = cvt_pk_bf16(y[0], y[1]); w.y = cvt_pk_bf16(y[2], y[3]); *(v2u*)(qbase + (size_t)mt * 16 * 1024 + 16 * dt + 4 * fq) = w; }
	v_mfma_f32_16x16x32_bf16 v[72:75], v[72:75], v[58:61], 0
	v_sub_f32_e32 v119, v99, v124
	v_sub_f32_e32 v118, v98, v124
	ds_read2_b64 v[98:101], v68 offset0:40 offset1:44
	s_waitcnt lgkmcnt(4)
	v_mfma_f32_16x16x32_bf16 v[78:81], v[78:81], v[58:61], 0
	v_add_f32_e64 v62, v104, v62
	v_add_f32_e64 v63, v105, v63
	v_sub_f32_e32 v117, v117, v124
	v_pk_add_f32 v[62:63], v[108:109], v[62:63]
	s_waitcnt lgkmcnt(3)
	v_mfma_f32_16x16x32_bf16 v[82:85], v[82:85], v[58:61], 0
	v_exp_f32_e32 v117, v117
	v_exp_f32_e32 v118, v118
	v_exp_f32_e32 v119, v119
	s_waitcnt lgkmcnt(2)
	v_mfma_f32_16x16x32_bf16 v[58:61], v[86:89], v[58:61], 0
	v_sub_f32_e32 v86, v116, v124
	v_exp_f32_e32 v116, v86
	ds_read2_b64 v[86:89], v70 offset0:72 offset1:76
	s_waitcnt lgkmcnt(2)
	v_mfma_f32_16x16x32_bf16 v[72:75], v[94:97], v[90:93], v[72:75]
	ds_read2_b64 v[94:97], v69 offset0:104 offset1:108
	v_pk_add_f32 v[62:63], v[112:113], v[62:63]
	s_waitcnt lgkmcnt(2)
	v_mfma_f32_16x16x32_bf16 v[78:81], v[98:101], v[90:93], v[78:81]
	v_cvt_pk_bf16_f32 v98, v102, v103
	v_cvt_pk_bf16_f32 v99, v104, v105
	v_cvt_pk_bf16_f32 v100, v106, v107
	v_cvt_pk_bf16_f32 v101, v108, v109
	s_waitcnt lgkmcnt(1)
	v_mfma_f32_16x16x32_bf16 v[82:85], v[86:89], v[90:93], v[82:85]
	ds_read2_b64 v[86:89], v68 offset0:48 offset1:52
	ds_read2_b64 v[102:105], v67 offset0:16 offset1:20
	v_pk_add_f32 v[106:107], v[116:117], v[114:115]
	s_waitcnt lgkmcnt(2)
	v_mfma_f32_16x16x32_bf16 v[58:61], v[94:97], v[90:93], v[58:61]
	ds_read2_b64 v[90:93], v70 offset0:80 offset1:84
	v_sub_f32_e32 v94, v120, v124
	v_exp_f32_e32 v108, v94
	s_waitcnt lgkmcnt(2)
	v_mfma_f32_16x16x32_bf16 v[78:81], v[86:89], v[98:101], v[78:81]
	ds_read2_b64 v[86:89], v69 offset0:112 offset1:116
	v_cvt_pk_bf16_f32 v94, v110, v111
	v_cvt_pk_bf16_f32 v95, v112, v113
	v_cvt_pk_bf16_f32 v96, v116, v117
	v_cvt_pk_bf16_f32 v97, v118, v119
	s_waitcnt lgkmcnt(1)
	v_mfma_f32_16x16x32_bf16 v[82:85], v[90:93], v[98:101], v[82:85]
	ds_read2_b64 v[90:93], v68 offset0:56 offset1:60
	v_sub_f32_e32 v109, v123, v124
	v_sub_f32_e32 v114, v122, v124
	s_waitcnt lgkmcnt(1)
	v_mfma_f32_16x16x32_bf16 v[58:61], v[86:89], v[98:101], v[58:61]
	ds_read2_b64 v[86:89], v70 offset0:88 offset1:92
	v_sub_f32_e32 v115, v121, v124
	v_exp_f32_e32 v110, v114
	s_waitcnt lgkmcnt(1)
	v_mfma_f32_16x16x32_bf16 v[78:81], v[90:93], v[94:97], v[78:81]
	ds_read2_b64 v[90:93], v69 offset0:120 offset1:124
	v_exp_f32_e32 v111, v109
	v_exp_f32_e32 v109, v115
	v_mfma_f32_16x16x32_bf16 v[72:75], v[102:105], v[98:101], v[72:75]
	ds_read2_b64 v[102:105], v67 offset0:24 offset1:28
	v_pk_add_f32 v[62:63], v[118:119], v[62:63]
	v_pk_add_f32 v[98:99], v[108:109], v[106:107]
	v_pk_add_f32 v[62:63], v[110:111], v[62:63]
	s_waitcnt lgkmcnt(2)
	v_mfma_f32_16x16x32_bf16 v[82:85], v[86:89], v[94:97], v[82:85]
	v_pk_mov_b32 v[100:101], v[98:99], v[62:63] op_sel:[1,0]
	v_mov_b32_e32 v99, v63
	v_pk_add_f32 v[62:63], v[100:101], v[98:99]
	s_waitcnt lgkmcnt(1)
	v_mfma_f32_16x16x32_bf16 v[58:61], v[90:93], v[94:97], v[58:61]
	v_cvt_pk_bf16_f32 v86, v108, v109
	v_cvt_pk_bf16_f32 v87, v110, v111
	ds_read_b64 v[90:91], v180 offset:37120
	v_add_f32_e32 v62, v62, v63
	ds_bpermute_b32 v63, v65, v62
	v_mov_b32_e32 v92, v147
	v_mov_b32_e32 v93, v147
	s_waitcnt lgkmcnt(2)
	v_mfma_f32_16x16x32_bf16 v[72:75], v[102:105], v[94:97], v[72:75]
	v_mov_b32_e32 v88, v147
	s_waitcnt lgkmcnt(0)
	v_add_f32_e32 v62, v62, v63
	v_mov_b32_e32 v89, v147
	ds_bpermute_b32 v63, v66, v62
	ds_read_b64 v[94:95], v180 offset:45568
	v_mfma_f32_16x16x32_bf16 v[72:75], v[90:93], v[86:89], v[72:75]
	v_fma_f32 v90, v64, s62, -v124
	v_exp_f32_e32 v90, v90
	s_waitcnt lgkmcnt(1)
	v_add_f32_e32 v62, v62, v63
	v_mov_b32_e32 v96, v147
	v_mov_b32_e32 v97, v147
	v_add_f32_e32 v90, v90, v62
	v_div_scale_f32 v91, s[64:65], v90, v90, 1.0
	v_rcp_f32_e32 v92, v91
	ds_read_b64 v[98:99], v180 offset:54016
	ds_read_b64 v[102:103], v180 offset:62464
	v_mov_b32_e32 v100, v147
	v_mov_b32_e32 v101, v147
	v_mov_b32_e32 v104, v147
	v_mov_b32_e32 v105, v147
	v_lshl_add_u64 v[62:63], v[76:77], 0, v[156:157]
	v_fma_f32 v76, -v91, v92, 1.0
	v_fmac_f32_e32 v92, v76, v92
	v_div_scale_f32 v76, vcc, 1.0, v90, 1.0
	v_mul_f32_e32 v77, v76, v92
	s_waitcnt lgkmcnt(2)
	v_mfma_f32_16x16x32_bf16 v[78:81], v[94:97], v[86:89], v[78:81]
	s_waitcnt lgkmcnt(1)
	v_mfma_f32_16x16x32_bf16 v[82:85], v[98:101], v[86:89], v[82:85]
	s_waitcnt lgkmcnt(0)
	v_mfma_f32_16x16x32_bf16 v[58:61], v[102:105], v[86:89], v[58:61]
	v_fma_f32 v86, -v91, v77, v76
	v_fmac_f32_e32 v77, v86, v92
	v_fma_f32 v76, -v91, v77, v76
	v_div_fmas_f32 v76, v76, v92, v77
	v_div_fixup_f32 v76, v76, v90, 1.0
	v_pk_mul_f32 v[74:75], v[76:77], v[74:75] op_sel_hi:[0,1]
	v_pk_mul_f32 v[72:73], v[76:77], v[72:73] op_sel_hi:[0,1]
	v_cvt_pk_bf16_f32 v72, v72, v73
	v_cvt_pk_bf16_f32 v73, v74, v75
	v_pk_mul_f32 v[74:75], v[76:77], v[78:79] op_sel_hi:[0,1]
	global_store_dwordx2 v[62:63], v[72:73], off
	v_pk_mul_f32 v[72:73], v[76:77], v[80:81] op_sel_hi:[0,1]
	v_cvt_pk_bf16_f32 v74, v74, v75
	v_cvt_pk_bf16_f32 v75, v72, v73
	global_store_dwordx2 v[62:63], v[74:75], off offset:32
	v_pk_mul_f32 v[74:75], v[76:77], v[82:83] op_sel_hi:[0,1]
	v_pk_mul_f32 v[72:73], v[76:77], v[84:85] op_sel_hi:[0,1]
	v_cvt_pk_bf16_f32 v74, v74, v75
	v_cvt_pk_bf16_f32 v75, v72, v73
	v_pk_mul_f32 v[60:61], v[76:77], v[60:61] op_sel_hi:[0,1]
	v_pk_mul_f32 v[58:59], v[76:77], v[58:59] op_sel_hi:[0,1]
	global_store_dwordx2 v[62:63], v[74:75], off offset:64
	v_cvt_pk_bf16_f32 v108, v58, v59
	v_cvt_pk_bf16_f32 v109, v60, v61
	ds_read_b128 v[58:61], v179 offset:2304
	ds_read_b128 v[72:75], v179 offset:2368
	s_waitcnt lgkmcnt(1)
; #define LAS __attribute__((address_space(3)))
; __device__ __forceinline__ void attn_unit(LAS unsigned char* lds, bf16* Q, const bf16* Kg, const bf16* Vg, const float* snk, int unit, int tid) {
;     ...
;         for (int kb = 0; kb < 9; ++kb) { const LAS unsigned char* kp = lds + (16 * (mt + kb) + fr) * ATT_KP + 16 * fq;
;             const bf16x8_t k0 = *(const LAS bf16x8_t*)kp, k1 = *(const LAS bf16x8_t*)(kp + 64);
;             f32x4 z = {0.f, 0.f, 0.f, 0.f}; z = __builtin_amdgcn_mfma_f32_16x16x32_bf16(k0, qf[mt][0], z, 0, 0, 0); z = __builtin_amdgcn_mfma_f32_16x16x32_bf16(k1, qf[mt][1], z, 0, 0, 0); st[kb] = z; }
;         float mx = sink;
; #pragma unroll
;         for (int kb = 0; kb < 9; ++kb) {
;             const bool tile_ok = (n > 0) || (mt + kb >= 8);
; #pragma unroll
;             for (int i = 0; i < 4; ++i) { const bool ok = tile_ok && (kb == 0 ? lo_ok[i] : (kb == 8 ? !lo_ok[i] : true));
;                 st[kb][i] = ok ? st[kb][i] : -INFINITY; mx = fmaxf(mx, st[kb][i]); }
;         }
;         mx = fmaxf(mx, __shfl_xor(mx, 16)); mx = fmaxf(mx, __shfl_xor(mx, 32));
	v_mfma_f32_16x16x32_bf16 v[58:61], v[58:61], v[50:53], 0
	ds_read_b128 v[76:79], v179 offset:4608
	ds_read_b128 v[80:83], v179 offset:6912
	ds_read_b128 v[84:87], v179 offset:9216
	s_waitcnt lgkmcnt(3)
	v_mfma_f32_16x16x32_bf16 v[72:75], v[72:75], v[54:57], v[58:61]
	ds_read_b128 v[88:91], v179 offset:11520
	ds_read_b128 v[92:95], v179 offset:13824
	ds_read_b128 v[96:99], v179 offset:16128
	ds_read_b128 v[58:61], v179 offset:4672
	s_waitcnt lgkmcnt(6)
	v_mfma_f32_16x16x32_bf16 v[76:79], v[76:79], v[50:53], 0
	ds_read_b128 v[100:103], v179 offset:18432
	ds_read_b128 v[104:107], v179 offset:20736
	global_store_dwordx2 v[62:63], v[108:109], off offset:96
	s_waitcnt lgkmcnt(2)
	v_mfma_f32_16x16x32_bf16 v[76:79], v[58:61], v[54:57], v[76:79]
	ds_read_b128 v[58:61], v179 offset:6976
	v_mfma_f32_16x16x32_bf16 v[80:83], v[80:83], v[50:53], 0
	s_waitcnt lgkmcnt(0)
	v_mfma_f32_16x16x32_bf16 v[80:83], v[58:61], v[54:57], v[80:83]
	ds_read_b128 v[58:61], v179 offset:9280
	v_mfma_f32_16x16x32_bf16 v[84:87], v[84:87], v[50:53], 0
	s_waitcnt lgkmcnt(0)
	v_mfma_f32_16x16x32_bf16 v[84:87], v[58:61], v[54:57], v[84:87]
	ds_read_b128 v[58:61], v179 offset:11584
	v_mfma_f32_16x16x32_bf16 v[88:91], v[88:91], v[50:53], 0
	s_waitcnt lgkmcnt(0)
	v_mfma_f32_16x16x32_bf16 v[88:91], v[58:61], v[54:57], v[88:91]
	ds_read_b128 v[58:61], v179 offset:13888
	v_mfma_f32_16x16x32_bf16 v[92:95], v[92:95], v[50:53], 0
	s_waitcnt lgkmcnt(0)
	v_mfma_f32_16x16x32_bf16 v[92:95], v[58:61], v[54:57], v[92:95]
	ds_read_b128 v[58:61], v179 offset:16192
	v_mfma_f32_16x16x32_bf16 v[96:99], v[96:99], v[50:53], 0
	s_nop 5
	v_cndmask_b32_e64 v92, v191, v92, s[14:15]
	v_cndmask_b32_e64 v93, v191, v93, s[14:15]
	v_cndmask_b32_e64 v94, v191, v94, s[14:15]
	s_waitcnt lgkmcnt(0)
	v_mfma_f32_16x16x32_bf16 v[96:99], v[58:61], v[54:57], v[96:99]
	ds_read_b128 v[58:61], v179 offset:18496
	v_cndmask_b32_e64 v95, v191, v95, s[14:15]
	v_mfma_f32_16x16x32_bf16 v[100:103], v[100:103], v[50:53], 0
	s_nop 4
	v_cndmask_b32_e64 v110, v191, v99, s[14:15]
	s_waitcnt lgkmcnt(0)
	v_mfma_f32_16x16x32_bf16 v[58:61], v[58:61], v[54:57], v[100:103]
	s_nop 2
	ds_read_b128 v[100:103], v179 offset:20800
	v_mfma_f32_16x16x32_bf16 v[50:53], v[104:107], v[50:53], 0
	v_cndmask_b32_e64 v104, v191, v91, s[14:15]
	v_cndmask_b32_e64 v105, v191, v96, s[14:15]
	v_cndmask_b32_e64 v106, v191, v97, s[14:15]
	s_waitcnt lgkmcnt(0)
	v_mfma_f32_16x16x32_bf16 v[50:53], v[100:103], v[54:57], v[50:53]
	v_cndmask_b32_e64 v55, v73, v191, s[8:9]
	v_cndmask_b32_e64 v54, v191, v72, s[18:19]
	v_cndmask_b32_e64 v55, v191, v55, s[14:15]
	v_max3_f32 v56, v71, v54, v55
	v_cndmask_b32_e64 v57, v191, v74, s[16:17]
	v_cndmask_b32_e64 v72, v191, v75, s[20:21]
	v_max3_f32 v56, v56, v57, v72
	v_cndmask_b32_e64 v73, v191, v76, s[14:15]
	v_cndmask_b32_e64 v74, v191, v77, s[14:15]
	v_max3_f32 v56, v56, v73, v74
	v_cndmask_b32_e64 v75, v191, v78, s[14:15]
	v_cndmask_b32_e64 v76, v191, v79, s[14:15]
	v_max3_f32 v56, v56, v75, v76
	v_cndmask_b32_e64 v77, v191, v80, s[14:15]
	v_cndmask_b32_e64 v78, v191, v81, s[14:15]
	v_max3_f32 v56, v56, v77, v78
	v_cndmask_b32_e64 v79, v191, v82, s[14:15]
	v_cndmask_b32_e64 v80, v191, v83, s[14:15]
	v_max3_f32 v56, v56, v79, v80
	v_cndmask_b32_e64 v81, v191, v84, s[14:15]
	v_cndmask_b32_e64 v82, v191, v85, s[14:15]
	v_max3_f32 v56, v56, v81, v82
	v_cndmask_b32_e64 v83, v191, v86, s[14:15]
	v_cndmask_b32_e64 v100, v191, v87, s[14:15]
	v_max3_f32 v56, v56, v83, v100
	v_cndmask_b32_e64 v101, v191, v88, s[14:15]
	v_cndmask_b32_e64 v102, v191, v89, s[14:15]
	v_max3_f32 v56, v56, v101, v102
	v_cndmask_b32_e64 v103, v191, v90, s[14:15]
	v_max3_f32 v56, v56, v103, v104
	v_max3_f32 v56, v56, v92, v93
	v_max3_f32 v56, v56, v94, v95
	v_max3_f32 v56, v56, v105, v106
	v_cndmask_b32_e64 v107, v191, v98, s[14:15]
	v_max3_f32 v56, v56, v107, v110
	v_max3_f32 v56, v56, v58, v59
	v_max3_f32 v56, v56, v60, v61
	v_cndmask_b32_e64 v116, v50, v191, s[6:7]
	v_cndmask_b32_e64 v117, v191, v51, s[8:9]
	v_max3_f32 v50, v56, v116, v117
	v_cndmask_b32_e64 v118, v52, v191, s[10:11]
	v_cndmask_b32_e64 v119, v53, v191, s[12:13]
	v_max3_f32 v50, v50, v118, v119
	ds_bpermute_b32 v51, v65, v50
	s_waitcnt lgkmcnt(0)
	v_max_f32_e32 v51, v51, v51
	v_max_f32_e32 v50, v50, v51
	ds_bpermute_b32 v51, v66, v50
	s_waitcnt lgkmcnt(0)
; __device__ __forceinline__ unsigned cvt_pk_bf16(float lo, float hi) { unsigned r; asm volatile("v_cvt_pk_bf16_f32 %0, %1, %2" : "=v"(r) : "v"(lo), "v"(hi)); return r; }
; #define LAS __attribute__((address_space(3)))
; __device__ __forceinline__ void attn_unit(LAS unsigned char* lds, bf16* Q, const bf16* Kg, const bf16* Vg, const float* snk, int unit, int tid) {
;     ...
;         mx = fmaxf(mx, __shfl_xor(mx, 16)); mx = fmaxf(mx, __shfl_xor(mx, 32));
;         f32x4 ls4 = {0.f, 0.f, 0.f, 0.f};
; #pragma unroll
;         for (int kb = 0; kb < 9; ++kb) { f32x4 d = st[kb] - mx;
; #pragma unroll
;             for (int i = 0; i < 4; ++i) d[i] = __builtin_amdgcn_exp2f(d[i]);
;             st[kb] = d; ls4 = ls4 + d; }
;         float ls = (ls4[0] + ls4[1]) + (ls4[2] + ls4[3]);
;         ls += __shfl_xor(ls, 16); ls += __shfl_xor(ls, 32);
;         const float inv = 1.f / (ls + __builtin_amdgcn_exp2f(sink - mx));
;         f32x4 o[4];
; #pragma unroll
;         for (int dt = 0; dt < 4; ++dt) o[dt] = (f32x4){0.f, 0.f, 0.f, 0.f};
; #pragma unroll
;         for (int kp = 0; kp < 5; ++kp) {
;             v4u pw; pw.x = cvt_pk_bf16(st[2 * kp][0], st[2 * kp][1]); pw.y = cvt_pk_bf16(st[2 * kp][2], st[2 * kp][3]);
;             if (kp < 4) { pw.z = cvt_pk_bf16(st[(2 * kp + 1) % 9][0], st[(2 * kp + 1) % 9][1]); pw.w = cvt_pk_bf16(st[(2 * kp + 1) % 9][2], st[(2 * kp + 1) % 9][3]); } else { pw.z = 0u; pw.w = 0u; }
;             const bf16x8_t pb = __builtin_bit_cast(bf16x8_t, pw);
; #pragma unroll
;             for (int dt = 0; dt < 4; ++dt) { const LAS unsigned char* vp = lds + ATT_VOFF + (16 * dt + fr) * ATT_VP + (16 * (mt + 2 * kp) + 4 * fq) * 2;
;                 const v2u lo = *(const LAS v2u*)vp; v2u hi = {0u, 0u}; if (kp < 4) hi = *(const LAS v2u*)(vp + 32);
;                 v4u aw; aw.x = lo.x; aw.y = lo.y; aw.z = hi.x; aw.w = hi.y;
;                 o[dt] = __builtin_amdgcn_mfma_f32_16x16x32_bf16(__builtin_bit_cast(bf16x8_t, aw), pb, o[dt], 0, 0, 0); }
	v_max_f32_e32 v51, v51, v51
	v_max_f32_e32 v120, v50, v51
	v_sub_f32_e32 v51, v72, v120
	v_sub_f32_e32 v52, v57, v120
	v_sub_f32_e32 v55, v55, v120
	v_sub_f32_e32 v50, v54, v120
	v_exp_f32_e32 v50, v50
	v_exp_f32_e32 v52, v52
	v_exp_f32_e32 v53, v51
	v_exp_f32_e32 v51, v55
	v_sub_f32_e32 v76, v76, v120
	v_sub_f32_e32 v75, v75, v120
	v_sub_f32_e32 v74, v74, v120
	v_sub_f32_e32 v72, v73, v120
	v_exp_f32_e32 v72, v72
	v_exp_f32_e32 v73, v74
	v_exp_f32_e32 v74, v75
	v_exp_f32_e32 v75, v76
	v_sub_f32_e32 v76, v80, v120
	v_sub_f32_e32 v79, v79, v120
	v_sub_f32_e32 v78, v78, v120
	v_sub_f32_e32 v77, v77, v120
	v_exp_f32_e32 v84, v77
	v_exp_f32_e32 v86, v79
	v_exp_f32_e32 v87, v76
	v_exp_f32_e32 v85, v78
	v_sub_f32_e32 v76, v100, v120
	v_sub_f32_e32 v77, v83, v120
	v_sub_f32_e32 v78, v82, v120
	v_sub_f32_e32 v79, v81, v120
	v_exp_f32_e32 v88, v79
	v_exp_f32_e32 v89, v78
	v_exp_f32_e32 v90, v77
	v_exp_f32_e32 v91, v76
	v_sub_f32_e32 v76, v104, v120
	v_sub_f32_e32 v77, v103, v120
	v_sub_f32_e32 v78, v102, v120
	v_sub_f32_e32 v79, v101, v120
	v_pk_add_f32 v[54:55], v[52:53], 0 op_sel_hi:[1,0]
	v_pk_add_f32 v[56:57], v[50:51], 0 op_sel_hi:[1,0]
	v_exp_f32_e32 v96, v79
	v_exp_f32_e32 v98, v77
	v_exp_f32_e32 v99, v76
	v_exp_f32_e32 v97, v78
	v_pk_add_f32 v[56:57], v[72:73], v[56:57]
	v_pk_add_f32 v[54:55], v[74:75], v[54:55]
	v_pk_add_f32 v[56:57], v[84:85], v[56:57]
	v_pk_add_f32 v[54:55], v[86:87], v[54:55]
	v_pk_add_f32 v[56:57], v[88:89], v[56:57]
	v_pk_add_f32 v[54:55], v[90:91], v[54:55]
	v_sub_f32_e32 v78, v92, v120
	v_pk_add_f32 v[76:77], v[98:99], v[54:55]
	v_pk_add_f32 v[54:55], v[96:97], v[56:57]
	v_sub_f32_e32 v57, v93, v120
	v_sub_f32_e32 v56, v95, v120
	v_exp_f32_e32 v101, v57
	v_sub_f32_e32 v57, v94, v120
	v_exp_f32_e32 v100, v78
	v_exp_f32_e32 v102, v57
	v_exp_f32_e32 v103, v56
	v_sub_f32_e32 v80, v110, v120
	v_sub_f32_e32 v81, v107, v120
	v_sub_f32_e32 v82, v106, v120
	v_sub_f32_e32 v83, v105, v120
	v_exp_f32_e32 v104, v81
	v_exp_f32_e32 v105, v80
	v_exp_f32_e32 v106, v83
	v_exp_f32_e32 v107, v82
	v_pk_add_f32 v[78:79], v[100:101], v[54:55]
	v_pk_add_f32 v[76:77], v[102:103], v[76:77]
	v_cvt_pk_bf16_f32 v50, v50, v51
	v_cvt_pk_bf16_f32 v51, v52, v53
	v_cvt_pk_bf16_f32 v52, v72, v73
	v_cvt_pk_bf16_f32 v53, v74, v75
	ds_read2_b64 v[54:57], v67 offset0:4 offset1:8
	ds_read2_b64 v[72:75], v68 offset0:36 offset1:40
	v_pk_add_f32 v[108:109], v[104:105], v[76:77]
	v_pk_add_f32 v[110:111], v[106:107], v[78:79]
	ds_read2_b64 v[76:79], v70 offset0:68 offset1:72
	ds_read2_b64 v[80:83], v69 offset0:100 offset1:104
	v_sub_f32_e32 v60, v60, v120
	v_sub_f32_e32 v59, v59, v120
	v_sub_f32_e32 v58, v58, v120
	v_sub_f32_e32 v115, v61, v120
	v_cvt_pk_bf16_f32 v84, v84, v85
	v_cvt_pk_bf16_f32 v85, v86, v87
	v_cvt_pk_bf16_f32 v86, v88, v89
	v_cvt_pk_bf16_f32 v87, v90, v91
	ds_read2_b64 v[88:91], v67 offset0:12 offset1:16
	v_exp_f32_e32 v112, v58
	v_exp_f32_e32 v113, v59
	v_exp_f32_e32 v114, v60
	ds_read2_b64 v[58:61], v70 offset0:76 offset1:80
	s_waitcnt lgkmcnt(5)
	v_mfma_f32_16x16x32_bf16 v[54:57], v[54:57], v[50:53], 0
	ds_read2_b64 v[92:95], v68 offset0:44 offset1:48
	v_exp_f32_e32 v115, v115
	s_waitcnt lgkmcnt(5)
	v_mfma_f32_16x16x32_bf16 v[72:75], v[72:75], v[50:53], 0
	s_waitcnt lgkmcnt(4)
	v_mfma_f32_16x16x32_bf16 v[76:79], v[76:79], v[50:53], 0
	s_waitcnt lgkmcnt(3)
	v_mfma_f32_16x16x32_bf16 v[50:53], v[80:83], v[50:53], 0
	ds_read2_b64 v[80:83], v69 offset0:108 offset1:112
	s_waitcnt lgkmcnt(3)
	v_mfma_f32_16x16x32_bf16 v[54:57], v[88:91], v[84:87], v[54:57]
	v_cvt_pk_bf16_f32 v88, v96, v97
	v_cvt_pk_bf16_f32 v89, v98, v99
	v_cvt_pk_bf16_f32 v90, v100, v101
	v_cvt_pk_bf16_f32 v91, v102, v103
	s_waitcnt lgkmcnt(2)
	v_mfma_f32_16x16x32_bf16 v[58:61], v[58:61], v[84:87], v[76:79]
	v_add_f32_e64 v98, v114, v108
	v_add_f32_e64 v99, v115, v109
	v_sub_f32_e32 v101, v119, v120
	v_sub_f32_e32 v102, v118, v120
	ds_read2_b64 v[76:79], v68 offset0:52 offset1:56
	s_waitcnt lgkmcnt(2)
	v_mfma_f32_16x16x32_bf16 v[72:75], v[92:95], v[84:87], v[72:75]
	ds_read2_b64 v[92:95], v67 offset0:20 offset1:24
	v_sub_f32_e32 v108, v117, v120
	v_exp_f32_e32 v102, v102
	s_waitcnt lgkmcnt(2)
	v_mfma_f32_16x16x32_bf16 v[50:53], v[80:83], v[84:87], v[50:53]
	ds_read2_b64 v[80:83], v70 offset0:84 offset1:88
	v_sub_f32_e32 v84, v116, v120
	v_exp_f32_e32 v100, v84
	s_waitcnt lgkmcnt(2)
	v_mfma_f32_16x16x32_bf16 v[72:75], v[76:79], v[88:91], v[72:75]
	ds_read2_b64 v[76:79], v69 offset0:116 offset1:120
	v_cvt_pk_bf16_f32 v84, v106, v107
	v_cvt_pk_bf16_f32 v85, v104, v105
	v_cvt_pk_bf16_f32 v86, v112, v113
	v_cvt_pk_bf16_f32 v87, v114, v115
	s_waitcnt lgkmcnt(1)
	v_mfma_f32_16x16x32_bf16 v[58:61], v[80:83], v[88:91], v[58:61]
	ds_read2_b64 v[80:83], v68 offset0:60 offset1:64
	v_exp_f32_e32 v103, v101
	v_exp_f32_e32 v101, v108
	v_mfma_f32_16x16x32_bf16 v[54:57], v[92:95], v[88:91], v[54:57]
	ds_read2_b64 v[92:95], v67 offset0:28 offset1:32
	v_pk_add_f32 v[96:97], v[112:113], v[110:111]
	s_waitcnt lgkmcnt(2)
	v_mfma_f32_16x16x32_bf16 v[50:53], v[76:79], v[88:91], v[50:53]
	ds_read2_b64 v[76:79], v70 offset0:92 offset1:96
	v_pk_add_f32 v[88:89], v[102:103], v[98:99]
	v_pk_add_f32 v[90:91], v[100:101], v[96:97]
	s_waitcnt lgkmcnt(2)
	v_mfma_f32_16x16x32_bf16 v[72:75], v[80:83], v[84:87], v[72:75]
	ds_read2_b64 v[80:83], v69 offset0:124 offset1:128
	s_waitcnt lgkmcnt(2)
	v_mfma_f32_16x16x32_bf16 v[54:57], v[92:95], v[84:87], v[54:57]
	v_pk_mov_b32 v[92:93], v[90:91], v[88:89] op_sel:[1,0]
	v_mov_b32_e32 v91, v89
	v_pk_add_f32 v[88:89], v[92:93], v[90:91]
	s_waitcnt lgkmcnt(1)
	v_mfma_f32_16x16x32_bf16 v[58:61], v[76:79], v[84:87], v[58:61]
	v_add_f32_e32 v88, v88, v89
	ds_bpermute_b32 v76, v65, v88
	v_mov_b32_e32 v78, v147
	s_waitcnt lgkmcnt(1)
; __device__ __forceinline__ unsigned cvt_pk_bf16(float lo, float hi) { unsigned r; asm volatile("v_cvt_pk_bf16_f32 %0, %1, %2" : "=v"(r) : "v"(lo), "v"(hi)); return r; }
; #define LAS __attribute__((address_space(3)))
; __device__ __forceinline__ void attn_unit(LAS unsigned char* lds, bf16* Q, const bf16* Kg, const bf16* Vg, const float* snk, int unit, int tid) {
;     ...
;         for (int kb = 0; kb < 9; ++kb) { const LAS unsigned char* kp = lds + (16 * (mt + kb) + fr) * ATT_KP + 16 * fq;
;             const bf16x8_t k0 = *(const LAS bf16x8_t*)kp, k1 = *(const LAS bf16x8_t*)(kp + 64);
;             f32x4 z = {0.f, 0.f, 0.f, 0.f}; z = __builtin_amdgcn_mfma_f32_16x16x32_bf16(k0, qf[mt][0], z, 0, 0, 0); z = __builtin_amdgcn_mfma_f32_16x16x32_bf16(k1, qf[mt][1], z, 0, 0, 0); st[kb] = z; }
;     ...
; #pragma unroll
;         for (int kp = 0; kp < 5; ++kp) {
;             v4u pw; pw.x = cvt_pk_bf16(st[2 * kp][0], st[2 * kp][1]); pw.y = cvt_pk_bf16(st[2 * kp][2], st[2 * kp][3]);
;             if (kp < 4) { pw.z = cvt_pk_bf16(st[(2 * kp + 1) % 9][0], st[(2 * kp + 1) % 9][1]); pw.w = cvt_pk_bf16(st[(2 * kp + 1) % 9][2], st[(2 * kp + 1) % 9][3]); } else { pw.z = 0u; pw.w = 0u; }
;             const bf16x8_t pb = __builtin_bit_cast(bf16x8_t, pw);
; #pragma unroll
;             for (int dt = 0; dt < 4; ++dt) { const LAS unsigned char* vp = lds + ATT_VOFF + (16 * dt + fr) * ATT_VP + (16 * (mt + 2 * kp) + 4 * fq) * 2;
;                 const v2u lo = *(const LAS v2u*)vp; v2u hi = {0u, 0u}; if (kp < 4) hi = *(const LAS v2u*)(vp + 32);
;                 v4u aw; aw.x = lo.x; aw.y = lo.y; aw.z = hi.x; aw.w = hi.y;
;                 o[dt] = __builtin_amdgcn_mfma_f32_16x16x32_bf16(__builtin_bit_cast(bf16x8_t, aw), pb, o[dt], 0, 0, 0); }
;         }
; #pragma unroll
;         for (int dt = 0; dt < 4; ++dt) { const f32x4 y = o[dt] * inv; v2u w; w.x = cvt_pk_bf16(y[0], y[1]); w.y = cvt_pk_bf16(y[2], y[3]); *(v2u*)(qbase + (size_t)mt * 16 * 1024 + 16 * dt + 4 * fq) = w; }
	v_mfma_f32_16x16x32_bf16 v[50:53], v[80:83], v[84:87], v[50:53]
	v_mov_b32_e32 v82, v147
	v_mov_b32_e32 v83, v147
	s_waitcnt lgkmcnt(0)
	v_add_f32_e32 v94, v88, v76
	v_cvt_pk_bf16_f32 v76, v100, v101
	v_cvt_pk_bf16_f32 v77, v102, v103
	ds_read_b64 v[80:81], v180 offset:37152
	ds_read_b64 v[84:85], v180 offset:45600
	v_mov_b32_e32 v79, v147
	v_mov_b32_e32 v86, v147
	v_mov_b32_e32 v87, v147
	s_waitcnt lgkmcnt(1)
	v_mfma_f32_16x16x32_bf16 v[54:57], v[80:83], v[76:79], v[54:57]
	ds_bpermute_b32 v80, v66, v94
	v_fma_f32 v81, v64, s62, -v120
	v_exp_f32_e32 v81, v81
	ds_read_b64 v[88:89], v180 offset:54048
	ds_read_b64 v[92:93], v180 offset:62496
	v_mov_b32_e32 v90, v147
	s_waitcnt lgkmcnt(2)
	v_add_f32_e32 v80, v94, v80
	v_add_f32_e32 v80, v81, v80
	v_mov_b32_e32 v91, v147
	v_mov_b32_e32 v94, v147
	v_mov_b32_e32 v95, v147
	v_div_scale_f32 v81, s[64:65], v80, v80, 1.0
	v_rcp_f32_e32 v82, v81
	v_mfma_f32_16x16x32_bf16 v[72:75], v[84:87], v[76:79], v[72:75]
	s_waitcnt lgkmcnt(1)
	v_mfma_f32_16x16x32_bf16 v[58:61], v[88:91], v[76:79], v[58:61]
	s_waitcnt lgkmcnt(0)
	v_mfma_f32_16x16x32_bf16 v[50:53], v[92:95], v[76:79], v[50:53]
	v_fma_f32 v76, -v81, v82, 1.0
	v_fmac_f32_e32 v82, v76, v82
	v_div_scale_f32 v76, vcc, 1.0, v80, 1.0
	v_mul_f32_e32 v77, v76, v82
	v_fma_f32 v78, -v81, v77, v76
	v_fmac_f32_e32 v77, v78, v82
	v_fma_f32 v76, -v81, v77, v76
	v_div_fmas_f32 v76, v76, v82, v77
	v_div_fixup_f32 v76, v76, v80, 1.0
	v_pk_mul_f32 v[56:57], v[76:77], v[56:57] op_sel_hi:[0,1]
	v_pk_mul_f32 v[54:55], v[76:77], v[54:55] op_sel_hi:[0,1]
	v_add_co_u32_e32 v100, vcc, s40, v62
	v_cvt_pk_bf16_f32 v54, v54, v55
	v_cvt_pk_bf16_f32 v55, v56, v57
	v_pk_mul_f32 v[56:57], v[76:77], v[72:73] op_sel_hi:[0,1]
	s_nop 0
	v_addc_co_u32_e32 v101, vcc, 0, v63, vcc
	global_store_dwordx2 v[100:101], v[54:55], off
	v_pk_mul_f32 v[54:55], v[76:77], v[74:75] op_sel_hi:[0,1]
	v_cvt_pk_bf16_f32 v56, v56, v57
	v_cvt_pk_bf16_f32 v57, v54, v55
	global_store_dwordx2 v[100:101], v[56:57], off offset:32
	v_pk_mul_f32 v[56:57], v[76:77], v[58:59] op_sel_hi:[0,1]
	v_pk_mul_f32 v[54:55], v[76:77], v[60:61] op_sel_hi:[0,1]
	v_cvt_pk_bf16_f32 v56, v56, v57
	v_cvt_pk_bf16_f32 v57, v54, v55
	v_pk_mul_f32 v[52:53], v[76:77], v[52:53] op_sel_hi:[0,1]
	v_pk_mul_f32 v[50:51], v[76:77], v[50:51] op_sel_hi:[0,1]
	global_store_dwordx2 v[100:101], v[56:57], off offset:64
	v_cvt_pk_bf16_f32 v102, v50, v51
	v_cvt_pk_bf16_f32 v103, v52, v53
	ds_read_b128 v[50:53], v179 offset:4608
	ds_read_b128 v[54:57], v179 offset:4672
	s_waitcnt lgkmcnt(1)
	v_mfma_f32_16x16x32_bf16 v[50:53], v[50:53], v[42:45], 0
	ds_read_b128 v[58:61], v179 offset:6912
	ds_read_b128 v[96:99], v179 offset:23040
	global_store_dwordx2 v[100:101], v[102:103], off offset:96
	s_waitcnt lgkmcnt(2)
	v_mfma_f32_16x16x32_bf16 v[72:75], v[54:57], v[46:49], v[50:53]
	s_nop 2
	ds_read_b128 v[50:53], v179 offset:6976
	s_waitcnt lgkmcnt(2)
	v_mfma_f32_16x16x32_bf16 v[54:57], v[58:61], v[42:45], 0
	ds_read_b128 v[58:61], v179 offset:9216
	s_waitcnt lgkmcnt(1)
	v_mfma_f32_16x16x32_bf16 v[76:79], v[50:53], v[46:49], v[54:57]
	ds_read_b128 v[50:53], v179 offset:9280
	s_waitcnt lgkmcnt(1)
	v_mfma_f32_16x16x32_bf16 v[54:57], v[58:61], v[42:45], 0
	ds_read_b128 v[58:61], v179 offset:11520
	s_waitcnt lgkmcnt(1)
	v_mfma_f32_16x16x32_bf16 v[80:83], v[50:53], v[46:49], v[54:57]
	ds_read_b128 v[50:53], v179 offset:11584
	s_waitcnt lgkmcnt(1)
	v_mfma_f32_16x16x32_bf16 v[54:57], v[58:61], v[42:45], 0
	ds_read_b128 v[58:61], v179 offset:13824
	s_waitcnt lgkmcnt(1)
	v_mfma_f32_16x16x32_bf16 v[84:87], v[50:53], v[46:49], v[54:57]
	ds_read_b128 v[50:53], v179 offset:13888
	s_waitcnt lgkmcnt(1)
	v_mfma_f32_16x16x32_bf16 v[54:57], v[58:61], v[42:45], 0
	ds_read_b128 v[58:61], v179 offset:16128
	s_waitcnt lgkmcnt(1)
	v_mfma_f32_16x16x32_bf16 v[88:91], v[50:53], v[46:49], v[54:57]
	ds_read_b128 v[50:53], v179 offset:16192
	s_waitcnt lgkmcnt(1)
	v_mfma_f32_16x16x32_bf16 v[54:57], v[58:61], v[42:45], 0
	ds_read_b128 v[58:61], v179 offset:18432
	s_waitcnt lgkmcnt(1)
	v_mfma_f32_16x16x32_bf16 v[92:95], v[50:53], v[46:49], v[54:57]
	ds_read_b128 v[50:53], v179 offset:18496
	s_waitcnt lgkmcnt(1)
	v_mfma_f32_16x16x32_bf16 v[54:57], v[58:61], v[42:45], 0
	ds_read_b128 v[58:61], v179 offset:20736
	s_nop 3
	v_cndmask_b32_e64 v92, v191, v92, s[14:15]
	v_cndmask_b32_e64 v93, v191, v93, s[14:15]
	s_waitcnt lgkmcnt(1)
	v_mfma_f32_16x16x32_bf16 v[54:57], v[50:53], v[46:49], v[54:57]
	ds_read_b128 v[50:53], v179 offset:20800
	v_cndmask_b32_e64 v94, v191, v94, s[14:15]
	v_cndmask_b32_e64 v95, v191, v95, s[14:15]
	s_waitcnt lgkmcnt(1)
	v_mfma_f32_16x16x32_bf16 v[58:61], v[58:61], v[42:45], 0
	s_waitcnt lgkmcnt(0)
	v_mfma_f32_16x16x32_bf16 v[50:53], v[50:53], v[46:49], v[58:61]
	s_nop 5
	ds_read_b128 v[58:61], v179 offset:23104
	v_mfma_f32_16x16x32_bf16 v[42:45], v[96:99], v[42:45], 0
	s_waitcnt lgkmcnt(0)
; #define LAS __attribute__((address_space(3)))
; __device__ __forceinline__ void attn_unit(LAS unsigned char* lds, bf16* Q, const bf16* Kg, const bf16* Vg, const float* snk, int unit, int tid) {
;     ...
;             f32x4 z = {0.f, 0.f, 0.f, 0.f}; z = __builtin_amdgcn_mfma_f32_16x16x32_bf16(k0, qf[mt][0], z, 0, 0, 0); z = __builtin_amdgcn_mfma_f32_16x16x32_bf16(k1, qf[mt][1], z, 0, 0, 0); st[kb] = z; }
;         float mx = sink;
; #pragma unroll
;         for (int kb = 0; kb < 9; ++kb) {
;             const bool tile_ok = (n > 0) || (mt + kb >= 8);
; #pragma unroll
;             for (int i = 0; i < 4; ++i) { const bool ok = tile_ok && (kb == 0 ? lo_ok[i] : (kb == 8 ? !lo_ok[i] : true));
;                 st[kb][i] = ok ? st[kb][i] : -INFINITY; mx = fmaxf(mx, st[kb][i]); }
;         }
;         mx = fmaxf(mx, __shfl_xor(mx, 16)); mx = fmaxf(mx, __shfl_xor(mx, 32));
;         f32x4 ls4 = {0.f, 0.f, 0.f, 0.f};
; #pragma unroll
;         for (int kb = 0; kb < 9; ++kb) { f32x4 d = st[kb] - mx;
; #pragma unroll
;             for (int i = 0; i < 4; ++i) d[i] = __builtin_amdgcn_exp2f(d[i]);
;             st[kb] = d; ls4 = ls4 + d; }
;         float ls = (ls4[0] + ls4[1]) + (ls4[2] + ls4[3]);
;         ls += __shfl_xor(ls, 16); ls += __shfl_xor(ls, 32);
;         const float inv = 1.f / (ls + __builtin_amdgcn_exp2f(sink - mx));
;         f32x4 o[4];
; #pragma unroll
;         for (int dt = 0; dt < 4; ++dt) o[dt] = (f32x4){0.f, 0.f, 0.f, 0.f};
; #pragma unroll
;         for (int kp = 0; kp < 5; ++kp) {
;             v4u pw; pw.x = cvt_pk_bf16(st[2 * kp][0], st[2 * kp][1]); pw.y = cvt_pk_bf16(st[2 * kp][2], st[2 * kp][3]);
;             if (kp < 4) { pw.z = cvt_pk_bf16(st[(2 * kp + 1) % 9][0], st[(2 * kp + 1) % 9][1]); pw.w = cvt_pk_bf16(st[(2 * kp + 1) % 9][2], st[(2 * kp + 1) % 9][3]); } else { pw.z = 0u; pw.w = 0u; }
;             const bf16x8_t pb = __builtin_bit_cast(bf16x8_t, pw);
; #pragma unroll
;             for (int dt = 0; dt < 4; ++dt) { const LAS unsigned char* vp = lds + ATT_VOFF + (16 * dt + fr) * ATT_VP + (16 * (mt + 2 * kp) + 4 * fq) * 2;
;                 const v2u lo = *(const LAS v2u*)vp; v2u hi = {0u, 0u}; if (kp < 4) hi = *(const LAS v2u*)(vp + 32);
;                 v4u aw; aw.x = lo.x; aw.y = lo.y; aw.z = hi.x; aw.w = hi.y;
;                 o[dt] = __builtin_amdgcn_mfma_f32_16x16x32_bf16(__builtin_bit_cast(bf16x8_t, aw), pb, o[dt], 0, 0, 0); }
	v_mfma_f32_16x16x32_bf16 v[42:45], v[58:61], v[46:49], v[42:45]
	v_cndmask_b32_e64 v47, v73, v191, s[8:9]
	v_cndmask_b32_e64 v46, v191, v72, s[18:19]
	v_cndmask_b32_e64 v47, v191, v47, s[14:15]
	v_max3_f32 v48, v71, v46, v47
	v_cndmask_b32_e64 v49, v191, v74, s[16:17]
	v_cndmask_b32_e64 v58, v191, v75, s[20:21]
	v_max3_f32 v48, v48, v49, v58
	v_cndmask_b32_e64 v59, v191, v76, s[14:15]
	v_cndmask_b32_e64 v60, v191, v77, s[14:15]
	v_max3_f32 v48, v48, v59, v60
	v_cndmask_b32_e64 v61, v191, v78, s[14:15]
	v_cndmask_b32_e64 v72, v191, v79, s[14:15]
	v_max3_f32 v48, v48, v61, v72
	v_cndmask_b32_e64 v73, v191, v80, s[14:15]
	v_cndmask_b32_e64 v74, v191, v81, s[14:15]
	v_max3_f32 v48, v48, v73, v74
	v_cndmask_b32_e64 v75, v191, v82, s[14:15]
	v_cndmask_b32_e64 v76, v191, v83, s[14:15]
	v_max3_f32 v48, v48, v75, v76
	v_cndmask_b32_e64 v80, v191, v84, s[14:15]
	v_cndmask_b32_e64 v81, v191, v85, s[14:15]
	v_max3_f32 v48, v48, v80, v81
	v_cndmask_b32_e64 v82, v191, v86, s[14:15]
	v_cndmask_b32_e64 v83, v191, v87, s[14:15]
	v_max3_f32 v48, v48, v82, v83
	v_cndmask_b32_e64 v84, v191, v88, s[14:15]
	v_cndmask_b32_e64 v85, v191, v89, s[14:15]
	v_max3_f32 v48, v48, v84, v85
	v_cndmask_b32_e64 v86, v191, v90, s[14:15]
	v_cndmask_b32_e64 v87, v191, v91, s[14:15]
	v_max3_f32 v48, v48, v86, v87
	v_max3_f32 v48, v48, v92, v93
	v_max3_f32 v48, v48, v94, v95
	v_max3_f32 v48, v48, v54, v55
	v_max3_f32 v48, v48, v56, v57
	v_max3_f32 v48, v48, v50, v51
	v_max3_f32 v48, v48, v52, v53
	v_cndmask_b32_e64 v108, v42, v191, s[6:7]
	v_cndmask_b32_e64 v109, v191, v43, s[8:9]
	v_max3_f32 v42, v48, v108, v109
	v_cndmask_b32_e64 v110, v44, v191, s[10:11]
	v_cndmask_b32_e64 v111, v45, v191, s[12:13]
	v_max3_f32 v42, v42, v110, v111
	ds_bpermute_b32 v43, v65, v42
	s_waitcnt lgkmcnt(0)
	v_max_f32_e32 v43, v43, v43
	v_max_f32_e32 v42, v42, v43
	ds_bpermute_b32 v43, v66, v42
	s_waitcnt lgkmcnt(0)
	v_max_f32_e32 v43, v43, v43
	v_max_f32_e32 v112, v42, v43
	v_sub_f32_e32 v43, v58, v112
	v_sub_f32_e32 v44, v49, v112
	v_sub_f32_e32 v47, v47, v112
	v_sub_f32_e32 v42, v46, v112
	v_exp_f32_e32 v42, v42
	v_exp_f32_e32 v44, v44
	v_exp_f32_e32 v45, v43
	v_exp_f32_e32 v43, v47
	v_sub_f32_e32 v72, v72, v112
	v_sub_f32_e32 v61, v61, v112
	v_sub_f32_e32 v60, v60, v112
	v_sub_f32_e32 v58, v59, v112
	v_exp_f32_e32 v58, v58
	v_exp_f32_e32 v59, v60
	v_exp_f32_e32 v60, v61
	v_exp_f32_e32 v61, v72
	v_sub_f32_e32 v72, v76, v112
	v_sub_f32_e32 v75, v75, v112
	v_sub_f32_e32 v74, v74, v112
	v_sub_f32_e32 v73, v73, v112
	v_exp_f32_e32 v76, v73
	v_exp_f32_e32 v78, v75
	v_exp_f32_e32 v79, v72
	v_exp_f32_e32 v77, v74
	v_sub_f32_e32 v72, v83, v112
	v_sub_f32_e32 v73, v82, v112
	v_sub_f32_e32 v74, v81, v112
	v_sub_f32_e32 v75, v80, v112
	v_exp_f32_e32 v80, v75
	v_exp_f32_e32 v81, v74
	v_exp_f32_e32 v82, v73
	v_exp_f32_e32 v83, v72
	v_sub_f32_e32 v72, v87, v112
	v_sub_f32_e32 v73, v86, v112
	v_sub_f32_e32 v74, v85, v112
	v_sub_f32_e32 v75, v84, v112
	v_pk_add_f32 v[46:47], v[44:45], 0 op_sel_hi:[1,0]
	v_pk_add_f32 v[48:49], v[42:43], 0 op_sel_hi:[1,0]
	v_exp_f32_e32 v88, v75
	v_exp_f32_e32 v90, v73
	v_exp_f32_e32 v91, v72
	v_exp_f32_e32 v89, v74
	v_pk_add_f32 v[48:49], v[58:59], v[48:49]
	v_pk_add_f32 v[46:47], v[60:61], v[46:47]
	v_pk_add_f32 v[48:49], v[76:77], v[48:49]
	v_pk_add_f32 v[46:47], v[78:79], v[46:47]
	v_pk_add_f32 v[48:49], v[80:81], v[48:49]
	v_pk_add_f32 v[46:47], v[82:83], v[46:47]
	v_sub_f32_e32 v74, v92, v112
	v_pk_add_f32 v[72:73], v[90:91], v[46:47]
	v_pk_add_f32 v[46:47], v[88:89], v[48:49]
	v_sub_f32_e32 v49, v93, v112
	v_sub_f32_e32 v48, v95, v112
	v_exp_f32_e32 v93, v49
	v_sub_f32_e32 v49, v94, v112
	v_exp_f32_e32 v92, v74
	v_exp_f32_e32 v94, v49
	v_exp_f32_e32 v95, v48
	v_sub_f32_e32 v57, v57, v112
	v_sub_f32_e32 v56, v56, v112
	v_sub_f32_e32 v84, v55, v112
	v_cvt_pk_bf16_f32 v42, v42, v43
	v_cvt_pk_bf16_f32 v43, v44, v45
	v_cvt_pk_bf16_f32 v44, v58, v59
	v_sub_f32_e32 v58, v54, v112
	v_exp_f32_e32 v96, v56
	v_exp_f32_e32 v97, v57
	v_exp_f32_e32 v98, v58
	v_exp_f32_e32 v99, v84
	v_pk_add_f32 v[74:75], v[92:93], v[46:47]
	v_pk_add_f32 v[58:59], v[94:95], v[72:73]
	v_cvt_pk_bf16_f32 v45, v60, v61
	ds_read2_b64 v[46:49], v67 offset0:8 offset1:12
	ds_read2_b64 v[54:57], v68 offset0:40 offset1:44
	v_pk_add_f32 v[100:101], v[96:97], v[58:59]
	v_pk_add_f32 v[102:103], v[98:99], v[74:75]
	ds_read2_b64 v[58:61], v70 offset0:72 offset1:76
	ds_read2_b64 v[72:75], v69 offset0:104 offset1:108
	v_sub_f32_e32 v52, v52, v112
	v_sub_f32_e32 v51, v51, v112
	v_sub_f32_e32 v50, v50, v112
	v_sub_f32_e32 v107, v53, v112
	v_cvt_pk_bf16_f32 v76, v76, v77
	v_cvt_pk_bf16_f32 v77, v78, v79
	v_cvt_pk_bf16_f32 v78, v80, v81
	v_cvt_pk_bf16_f32 v79, v82, v83
	ds_read2_b64 v[80:83], v67 offset0:16 offset1:20
	v_exp_f32_e32 v104, v50
	v_exp_f32_e32 v105, v51
	v_exp_f32_e32 v106, v52
	ds_read2_b64 v[50:53], v70 offset0:80 offset1:84
	s_waitcnt lgkmcnt(5)
	v_mfma_f32_16x16x32_bf16 v[46:49], v[46:49], v[42:45], 0
	ds_read2_b64 v[84:87], v68 offset0:48 offset1:52
	v_exp_f32_e32 v107, v107
	s_waitcnt lgkmcnt(5)
	v_mfma_f32_16x16x32_bf16 v[54:57], v[54:57], v[42:45], 0
	s_waitcnt lgkmcnt(4)
	v_mfma_f32_16x16x32_bf16 v[58:61], v[58:61], v[42:45], 0
	s_waitcnt lgkmcnt(3)
	v_mfma_f32_16x16x32_bf16 v[42:45], v[72:75], v[42:45], 0
	ds_read2_b64 v[72:75], v69 offset0:112 offset1:116
	s_waitcnt lgkmcnt(3)
	v_mfma_f32_16x16x32_bf16 v[46:49], v[80:83], v[76:79], v[46:49]
	v_cvt_pk_bf16_f32 v80, v88, v89
	v_cvt_pk_bf16_f32 v81, v90, v91
	v_cvt_pk_bf16_f32 v82, v92, v93
	v_cvt_pk_bf16_f32 v83, v94, v95
	s_waitcnt lgkmcnt(2)
; __device__ __forceinline__ unsigned cvt_pk_bf16(float lo, float hi) { unsigned r; asm volatile("v_cvt_pk_bf16_f32 %0, %1, %2" : "=v"(r) : "v"(lo), "v"(hi)); return r; }
; #define LAS __attribute__((address_space(3)))
; __device__ __forceinline__ void attn_unit(LAS unsigned char* lds, bf16* Q, const bf16* Kg, const bf16* Vg, const float* snk, int unit, int tid) {
;     ...
;         for (int kb = 0; kb < 9; ++kb) { const LAS unsigned char* kp = lds + (16 * (mt + kb) + fr) * ATT_KP + 16 * fq;
;             const bf16x8_t k0 = *(const LAS bf16x8_t*)kp, k1 = *(const LAS bf16x8_t*)(kp + 64);
;             f32x4 z = {0.f, 0.f, 0.f, 0.f}; z = __builtin_amdgcn_mfma_f32_16x16x32_bf16(k0, qf[mt][0], z, 0, 0, 0); z = __builtin_amdgcn_mfma_f32_16x16x32_bf16(k1, qf[mt][1], z, 0, 0, 0); st[kb] = z; }
;     ...
; #pragma unroll
;         for (int kp = 0; kp < 5; ++kp) {
;             v4u pw; pw.x = cvt_pk_bf16(st[2 * kp][0], st[2 * kp][1]); pw.y = cvt_pk_bf16(st[2 * kp][2], st[2 * kp][3]);
;             if (kp < 4) { pw.z = cvt_pk_bf16(st[(2 * kp + 1) % 9][0], st[(2 * kp + 1) % 9][1]); pw.w = cvt_pk_bf16(st[(2 * kp + 1) % 9][2], st[(2 * kp + 1) % 9][3]); } else { pw.z = 0u; pw.w = 0u; }
;             const bf16x8_t pb = __builtin_bit_cast(bf16x8_t, pw);
; #pragma unroll
;             for (int dt = 0; dt < 4; ++dt) { const LAS unsigned char* vp = lds + ATT_VOFF + (16 * dt + fr) * ATT_VP + (16 * (mt + 2 * kp) + 4 * fq) * 2;
;                 const v2u lo = *(const LAS v2u*)vp; v2u hi = {0u, 0u}; if (kp < 4) hi = *(const LAS v2u*)(vp + 32);
;                 v4u aw; aw.x = lo.x; aw.y = lo.y; aw.z = hi.x; aw.w = hi.y;
;                 o[dt] = __builtin_amdgcn_mfma_f32_16x16x32_bf16(__builtin_bit_cast(bf16x8_t, aw), pb, o[dt], 0, 0, 0); }
;         }
; #pragma unroll
;         for (int dt = 0; dt < 4; ++dt) { const f32x4 y = o[dt] * inv; v2u w; w.x = cvt_pk_bf16(y[0], y[1]); w.y = cvt_pk_bf16(y[2], y[3]); *(v2u*)(qbase + (size_t)mt * 16 * 1024 + 16 * dt + 4 * fq) = w; }
	v_mfma_f32_16x16x32_bf16 v[50:53], v[50:53], v[76:79], v[58:61]
	v_add_f32_e64 v90, v106, v100
	v_add_f32_e64 v91, v107, v101
	v_sub_f32_e32 v93, v111, v112
	v_sub_f32_e32 v94, v110, v112
	ds_read2_b64 v[58:61], v68 offset0:56 offset1:60
	s_waitcnt lgkmcnt(2)
	v_mfma_f32_16x16x32_bf16 v[54:57], v[84:87], v[76:79], v[54:57]
	ds_read2_b64 v[84:87], v67 offset0:24 offset1:28
	v_sub_f32_e32 v100, v109, v112
	v_exp_f32_e32 v94, v94
	s_waitcnt lgkmcnt(2)
	v_mfma_f32_16x16x32_bf16 v[42:45], v[72:75], v[76:79], v[42:45]
	ds_read2_b64 v[72:75], v70 offset0:88 offset1:92
	v_sub_f32_e32 v76, v108, v112
	v_exp_f32_e32 v92, v76
	s_waitcnt lgkmcnt(2)
	v_mfma_f32_16x16x32_bf16 v[54:57], v[58:61], v[80:83], v[54:57]
	ds_read2_b64 v[58:61], v69 offset0:120 offset1:124
	v_cvt_pk_bf16_f32 v76, v98, v99
	v_cvt_pk_bf16_f32 v77, v96, v97
	v_cvt_pk_bf16_f32 v78, v104, v105
	v_cvt_pk_bf16_f32 v79, v106, v107
	s_waitcnt lgkmcnt(1)
	v_mfma_f32_16x16x32_bf16 v[50:53], v[72:75], v[80:83], v[50:53]
	ds_read2_b64 v[72:75], v68 offset0:64 offset1:68
	v_exp_f32_e32 v95, v93
	v_exp_f32_e32 v93, v100
	v_mfma_f32_16x16x32_bf16 v[46:49], v[84:87], v[80:83], v[46:49]
	ds_read2_b64 v[84:87], v67 offset0:32 offset1:36
	v_pk_add_f32 v[88:89], v[104:105], v[102:103]
	s_waitcnt lgkmcnt(2)
	v_mfma_f32_16x16x32_bf16 v[42:45], v[58:61], v[80:83], v[42:45]
	ds_read2_b64 v[58:61], v70 offset0:96 offset1:100
	v_pk_add_f32 v[80:81], v[94:95], v[90:91]
	v_pk_add_f32 v[82:83], v[92:93], v[88:89]
	s_waitcnt lgkmcnt(2)
	v_mfma_f32_16x16x32_bf16 v[54:57], v[72:75], v[76:79], v[54:57]
	ds_read2_b64 v[72:75], v69 offset0:128 offset1:132
	s_waitcnt lgkmcnt(2)
	v_mfma_f32_16x16x32_bf16 v[46:49], v[84:87], v[76:79], v[46:49]
	v_pk_mov_b32 v[84:85], v[82:83], v[80:81] op_sel:[1,0]
	v_mov_b32_e32 v83, v81
	v_pk_add_f32 v[80:81], v[84:85], v[82:83]
	s_waitcnt lgkmcnt(1)
	v_mfma_f32_16x16x32_bf16 v[50:53], v[58:61], v[76:79], v[50:53]
	v_add_f32_e32 v80, v80, v81
	ds_bpermute_b32 v58, v65, v80
	v_mov_b32_e32 v60, v147
	s_waitcnt lgkmcnt(1)
	v_mfma_f32_16x16x32_bf16 v[42:45], v[72:75], v[76:79], v[42:45]
	v_mov_b32_e32 v74, v147
	v_mov_b32_e32 v75, v147
	s_waitcnt lgkmcnt(0)
	v_add_f32_e32 v86, v80, v58
	v_cvt_pk_bf16_f32 v58, v92, v93
	v_cvt_pk_bf16_f32 v59, v94, v95
	ds_read_b64 v[72:73], v180 offset:37184
	ds_read_b64 v[76:77], v180 offset:45632
	v_mov_b32_e32 v61, v147
	v_mov_b32_e32 v78, v147
	v_mov_b32_e32 v79, v147
	s_waitcnt lgkmcnt(1)
	v_mfma_f32_16x16x32_bf16 v[46:49], v[72:75], v[58:61], v[46:49]
	ds_bpermute_b32 v72, v66, v86
	v_fma_f32 v73, v64, s62, -v112
	v_exp_f32_e32 v73, v73
	ds_read_b64 v[80:81], v180 offset:54080
	ds_read_b64 v[84:85], v180 offset:62528
	v_mov_b32_e32 v82, v147
	s_waitcnt lgkmcnt(2)
	v_add_f32_e32 v72, v86, v72
	v_add_f32_e32 v72, v73, v72
	v_mov_b32_e32 v83, v147
	v_mov_b32_e32 v86, v147
	v_mov_b32_e32 v87, v147
	v_div_scale_f32 v73, s[64:65], v72, v72, 1.0
	v_rcp_f32_e32 v74, v73
	v_mfma_f32_16x16x32_bf16 v[54:57], v[76:79], v[58:61], v[54:57]
	s_waitcnt lgkmcnt(1)
	v_mfma_f32_16x16x32_bf16 v[50:53], v[80:83], v[58:61], v[50:53]
	s_waitcnt lgkmcnt(0)
	v_mfma_f32_16x16x32_bf16 v[42:45], v[84:87], v[58:61], v[42:45]
	v_fma_f32 v58, -v73, v74, 1.0
	v_fmac_f32_e32 v74, v58, v74
	v_div_scale_f32 v58, vcc, 1.0, v72, 1.0
	v_mul_f32_e32 v59, v58, v74
	v_fma_f32 v60, -v73, v59, v58
	v_fmac_f32_e32 v59, v60, v74
	v_fma_f32 v58, -v73, v59, v58
	v_div_fmas_f32 v58, v58, v74, v59
	v_div_fixup_f32 v58, v58, v72, 1.0
	v_pk_mul_f32 v[48:49], v[58:59], v[48:49] op_sel_hi:[0,1]
	v_pk_mul_f32 v[46:47], v[58:59], v[46:47] op_sel_hi:[0,1]
	v_add_co_u32_e32 v92, vcc, s41, v62
	v_cvt_pk_bf16_f32 v46, v46, v47
	v_cvt_pk_bf16_f32 v47, v48, v49
	v_pk_mul_f32 v[48:49], v[58:59], v[54:55] op_sel_hi:[0,1]
	s_nop 0
	v_addc_co_u32_e32 v93, vcc, 0, v63, vcc
	global_store_dwordx2 v[92:93], v[46:47], off
	v_pk_mul_f32 v[46:47], v[58:59], v[56:57] op_sel_hi:[0,1]
	v_cvt_pk_bf16_f32 v48, v48, v49
	v_cvt_pk_bf16_f32 v49, v46, v47
	global_store_dwordx2 v[92:93], v[48:49], off offset:32
	v_pk_mul_f32 v[48:49], v[58:59], v[50:51] op_sel_hi:[0,1]
	v_pk_mul_f32 v[46:47], v[58:59], v[52:53] op_sel_hi:[0,1]
	v_cvt_pk_bf16_f32 v48, v48, v49
	v_cvt_pk_bf16_f32 v49, v46, v47
	v_pk_mul_f32 v[44:45], v[58:59], v[44:45] op_sel_hi:[0,1]
	v_pk_mul_f32 v[42:43], v[58:59], v[42:43] op_sel_hi:[0,1]
	global_store_dwordx2 v[92:93], v[48:49], off offset:64
	v_cvt_pk_bf16_f32 v94, v42, v43
	v_cvt_pk_bf16_f32 v95, v44, v45
	ds_read_b128 v[42:45], v179 offset:6912
	ds_read_b128 v[46:49], v179 offset:6976
	s_waitcnt lgkmcnt(1)
	v_mfma_f32_16x16x32_bf16 v[42:45], v[42:45], v[34:37], 0
	ds_read_b128 v[50:53], v179 offset:9216
	ds_read_b128 v[54:57], v179 offset:11520
	ds_read_b128 v[58:61], v179 offset:13824
	s_waitcnt lgkmcnt(3)
	v_mfma_f32_16x16x32_bf16 v[46:49], v[46:49], v[38:41], v[42:45]
	ds_read_b128 v[72:75], v179 offset:16128
	ds_read_b128 v[76:79], v179 offset:18432
	ds_read_b128 v[80:83], v179 offset:20736
	ds_read_b128 v[42:45], v179 offset:9280
	s_waitcnt lgkmcnt(6)
	v_mfma_f32_16x16x32_bf16 v[50:53], v[50:53], v[34:37], 0
	ds_read_b128 v[84:87], v179 offset:23040
	ds_read_b128 v[88:91], v179 offset:25344
	global_store_dwordx2 v[92:93], v[94:95], off offset:96
	s_waitcnt lgkmcnt(2)
	v_mfma_f32_16x16x32_bf16 v[50:53], v[42:45], v[38:41], v[50:53]
	ds_read_b128 v[42:45], v179 offset:11584
	v_mfma_f32_16x16x32_bf16 v[54:57], v[54:57], v[34:37], 0
	s_waitcnt lgkmcnt(0)
	v_mfma_f32_16x16x32_bf16 v[54:57], v[42:45], v[38:41], v[54:57]
	ds_read_b128 v[42:45], v179 offset:13888
	v_mfma_f32_16x16x32_bf16 v[58:61], v[58:61], v[34:37], 0
	s_waitcnt lgkmcnt(0)
; __device__ __forceinline__ void attn_unit(LAS unsigned char* lds, bf16* Q, const bf16* Kg, const bf16* Vg, const float* snk, int unit, int tid) {
;     ...
;         for (int kb = 0; kb < 9; ++kb) { const LAS unsigned char* kp = lds + (16 * (mt + kb) + fr) * ATT_KP + 16 * fq;
;             const bf16x8_t k0 = *(const LAS bf16x8_t*)kp, k1 = *(const LAS bf16x8_t*)(kp + 64);
;             f32x4 z = {0.f, 0.f, 0.f, 0.f}; z = __builtin_amdgcn_mfma_f32_16x16x32_bf16(k0, qf[mt][0], z, 0, 0, 0); z = __builtin_amdgcn_mfma_f32_16x16x32_bf16(k1, qf[mt][1], z, 0, 0, 0); st[kb] = z; }
;         float mx = sink;
; #pragma unroll
;         for (int kb = 0; kb < 9; ++kb) {
;             const bool tile_ok = (n > 0) || (mt + kb >= 8);
; #pragma unroll
;             for (int i = 0; i < 4; ++i) { const bool ok = tile_ok && (kb == 0 ? lo_ok[i] : (kb == 8 ? !lo_ok[i] : true));
;                 st[kb][i] = ok ? st[kb][i] : -INFINITY; mx = fmaxf(mx, st[kb][i]); }
;         }
;         mx = fmaxf(mx, __shfl_xor(mx, 16)); mx = fmaxf(mx, __shfl_xor(mx, 32));
;         f32x4 ls4 = {0.f, 0.f, 0.f, 0.f};
; #pragma unroll
;         for (int kb = 0; kb < 9; ++kb) { f32x4 d = st[kb] - mx;
; #pragma unroll
;             for (int i = 0; i < 4; ++i) d[i] = __builtin_amdgcn_exp2f(d[i]);
;             st[kb] = d; ls4 = ls4 + d; }
;         float ls = (ls4[0] + ls4[1]) + (ls4[2] + ls4[3]);
;         ls += __shfl_xor(ls, 16); ls += __shfl_xor(ls, 32);
;         const float inv = 1.f / (ls + __builtin_amdgcn_exp2f(sink - mx));
;         f32x4 o[4];
; #pragma unroll
;         for (int dt = 0; dt < 4; ++dt) o[dt] = (f32x4){0.f, 0.f, 0.f, 0.f};
; #pragma unroll
;         for (int kp = 0; kp < 5; ++kp) {
;             v4u pw; pw.x = cvt_pk_bf16(st[2 * kp][0], st[2 * kp][1]); pw.y = cvt_pk_bf16(st[2 * kp][2], st[2 * kp][3]);
;             if (kp < 4) { pw.z = cvt_pk_bf16(st[(2 * kp + 1) % 9][0], st[(2 * kp + 1) % 9][1]); pw.w = cvt_pk_bf16(st[(2 * kp + 1) % 9][2], st[(2 * kp + 1) % 9][3]); } else { pw.z = 0u; pw.w = 0u; }
;             const bf16x8_t pb = __builtin_bit_cast(bf16x8_t, pw);
; #pragma unroll
;             for (int dt = 0; dt < 4; ++dt) { const LAS unsigned char* vp = lds + ATT_VOFF + (16 * dt + fr) * ATT_VP + (16 * (mt + 2 * kp) + 4 * fq) * 2;
;                 const v2u lo = *(const LAS v2u*)vp; v2u hi = {0u, 0u}; if (kp < 4) hi = *(const LAS v2u*)(vp + 32);
	v_mfma_f32_16x16x32_bf16 v[58:61], v[42:45], v[38:41], v[58:61]
	ds_read_b128 v[42:45], v179 offset:16192
	v_mfma_f32_16x16x32_bf16 v[72:75], v[72:75], v[34:37], 0
	s_waitcnt lgkmcnt(0)
	v_mfma_f32_16x16x32_bf16 v[72:75], v[42:45], v[38:41], v[72:75]
	ds_read_b128 v[42:45], v179 offset:18496
	v_mfma_f32_16x16x32_bf16 v[76:79], v[76:79], v[34:37], 0
	s_waitcnt lgkmcnt(0)
	v_mfma_f32_16x16x32_bf16 v[76:79], v[42:45], v[38:41], v[76:79]
	ds_read_b128 v[42:45], v179 offset:20800
	v_mfma_f32_16x16x32_bf16 v[80:83], v[80:83], v[34:37], 0
	s_waitcnt lgkmcnt(0)
	v_mfma_f32_16x16x32_bf16 v[80:83], v[42:45], v[38:41], v[80:83]
	ds_read_b128 v[42:45], v179 offset:23104
	v_mfma_f32_16x16x32_bf16 v[84:87], v[84:87], v[34:37], 0
	s_waitcnt lgkmcnt(0)
	v_mfma_f32_16x16x32_bf16 v[42:45], v[42:45], v[38:41], v[84:87]
	s_nop 5
	ds_read_b128 v[84:87], v179 offset:25408
	v_mfma_f32_16x16x32_bf16 v[34:37], v[88:91], v[34:37], 0
	v_cndmask_b32_e64 v88, v191, v75, s[14:15]
	s_waitcnt lgkmcnt(0)
	v_mfma_f32_16x16x32_bf16 v[34:37], v[84:87], v[38:41], v[34:37]
	v_cndmask_b32_e64 v39, v47, v191, s[8:9]
	v_cndmask_b32_e64 v38, v191, v46, s[18:19]
	v_cndmask_b32_e64 v39, v191, v39, s[14:15]
	v_max3_f32 v40, v71, v38, v39
	v_cndmask_b32_e64 v41, v191, v48, s[16:17]
	v_cndmask_b32_e64 v46, v191, v49, s[20:21]
	v_max3_f32 v40, v40, v41, v46
	v_cndmask_b32_e64 v47, v191, v50, s[14:15]
	v_cndmask_b32_e64 v48, v191, v51, s[14:15]
	v_max3_f32 v40, v40, v47, v48
	v_cndmask_b32_e64 v49, v191, v52, s[14:15]
	v_cndmask_b32_e64 v50, v191, v53, s[14:15]
	v_max3_f32 v40, v40, v49, v50
	v_cndmask_b32_e64 v51, v191, v54, s[14:15]
	v_cndmask_b32_e64 v52, v191, v55, s[14:15]
	v_max3_f32 v40, v40, v51, v52
	v_cndmask_b32_e64 v53, v191, v56, s[14:15]
	v_cndmask_b32_e64 v54, v191, v57, s[14:15]
	v_max3_f32 v40, v40, v53, v54
	v_cndmask_b32_e64 v55, v191, v58, s[14:15]
	v_cndmask_b32_e64 v56, v191, v59, s[14:15]
	v_max3_f32 v40, v40, v55, v56
	v_cndmask_b32_e64 v57, v191, v60, s[14:15]
	v_cndmask_b32_e64 v84, v191, v61, s[14:15]
	v_max3_f32 v40, v40, v57, v84
	v_cndmask_b32_e64 v85, v191, v72, s[14:15]
	v_cndmask_b32_e64 v86, v191, v73, s[14:15]
	v_max3_f32 v40, v40, v85, v86
	v_cndmask_b32_e64 v87, v191, v74, s[14:15]
	v_max3_f32 v40, v40, v87, v88
	v_max3_f32 v40, v40, v76, v77
	v_max3_f32 v40, v40, v78, v79
	v_max3_f32 v40, v40, v80, v81
	v_max3_f32 v40, v40, v82, v83
	v_max3_f32 v40, v40, v42, v43
	v_max3_f32 v40, v40, v44, v45
	v_cndmask_b32_e64 v100, v34, v191, s[6:7]
	v_cndmask_b32_e64 v101, v191, v35, s[8:9]
	v_max3_f32 v34, v40, v100, v101
	v_cndmask_b32_e64 v102, v36, v191, s[10:11]
	v_cndmask_b32_e64 v103, v37, v191, s[12:13]
	v_max3_f32 v34, v34, v102, v103
	ds_bpermute_b32 v35, v65, v34
	s_waitcnt lgkmcnt(0)
	v_max_f32_e32 v35, v35, v35
	v_max_f32_e32 v34, v34, v35
	ds_bpermute_b32 v35, v66, v34
	s_waitcnt lgkmcnt(0)
	v_max_f32_e32 v35, v35, v35
	v_max_f32_e32 v104, v34, v35
	v_sub_f32_e32 v35, v46, v104
	v_sub_f32_e32 v36, v41, v104
	v_sub_f32_e32 v39, v39, v104
	v_sub_f32_e32 v34, v38, v104
	v_exp_f32_e32 v34, v34
	v_exp_f32_e32 v36, v36
	v_exp_f32_e32 v37, v35
	v_exp_f32_e32 v35, v39
	v_sub_f32_e32 v50, v50, v104
	v_sub_f32_e32 v49, v49, v104
	v_sub_f32_e32 v48, v48, v104
	v_sub_f32_e32 v46, v47, v104
	v_exp_f32_e32 v46, v46
	v_exp_f32_e32 v47, v48
	v_exp_f32_e32 v48, v49
	v_exp_f32_e32 v49, v50
	v_sub_f32_e32 v50, v54, v104
	v_sub_f32_e32 v53, v53, v104
	v_sub_f32_e32 v52, v52, v104
	v_sub_f32_e32 v51, v51, v104
	v_exp_f32_e32 v58, v51
	v_exp_f32_e32 v60, v53
	v_exp_f32_e32 v61, v50
	v_exp_f32_e32 v59, v52
	v_sub_f32_e32 v50, v84, v104
	v_sub_f32_e32 v51, v57, v104
	v_sub_f32_e32 v52, v56, v104
	v_sub_f32_e32 v53, v55, v104
	v_exp_f32_e32 v72, v53
	v_exp_f32_e32 v73, v52
	v_exp_f32_e32 v74, v51
	v_exp_f32_e32 v75, v50
	v_sub_f32_e32 v50, v88, v104
	v_sub_f32_e32 v51, v87, v104
	v_sub_f32_e32 v52, v86, v104
	v_sub_f32_e32 v53, v85, v104
	v_pk_add_f32 v[38:39], v[36:37], 0 op_sel_hi:[1,0]
	v_pk_add_f32 v[40:41], v[34:35], 0 op_sel_hi:[1,0]
	v_exp_f32_e32 v84, v53
	v_exp_f32_e32 v86, v51
	v_exp_f32_e32 v87, v50
	v_exp_f32_e32 v85, v52
	v_pk_add_f32 v[40:41], v[46:47], v[40:41]
	v_pk_add_f32 v[38:39], v[48:49], v[38:39]
	v_pk_add_f32 v[40:41], v[58:59], v[40:41]
	v_pk_add_f32 v[38:39], v[60:61], v[38:39]
	v_pk_add_f32 v[40:41], v[72:73], v[40:41]
	v_pk_add_f32 v[38:39], v[74:75], v[38:39]
	v_sub_f32_e32 v52, v76, v104
	v_pk_add_f32 v[50:51], v[86:87], v[38:39]
	v_pk_add_f32 v[38:39], v[84:85], v[40:41]
	v_sub_f32_e32 v41, v77, v104
	v_sub_f32_e32 v40, v79, v104
	v_exp_f32_e32 v89, v41
	v_sub_f32_e32 v41, v78, v104
	v_exp_f32_e32 v88, v52
	v_exp_f32_e32 v90, v41
	v_exp_f32_e32 v91, v40
	v_sub_f32_e32 v54, v83, v104
	v_sub_f32_e32 v55, v82, v104
	v_sub_f32_e32 v56, v81, v104
	v_sub_f32_e32 v57, v80, v104
	v_exp_f32_e32 v80, v55
	v_exp_f32_e32 v81, v54
	v_exp_f32_e32 v82, v57
	v_exp_f32_e32 v83, v56
	v_pk_add_f32 v[52:53], v[88:89], v[38:39]
	v_pk_add_f32 v[50:51], v[90:91], v[50:51]
	v_cvt_pk_bf16_f32 v34, v34, v35
	v_cvt_pk_bf16_f32 v35, v36, v37
	v_cvt_pk_bf16_f32 v36, v46, v47
	v_cvt_pk_bf16_f32 v37, v48, v49
	ds_read2_b64 v[38:41], v67 offset0:12 offset1:16
	ds_read2_b64 v[46:49], v68 offset0:44 offset1:48
	v_pk_add_f32 v[92:93], v[80:81], v[50:51]
	v_pk_add_f32 v[94:95], v[82:83], v[52:53]
	ds_read2_b64 v[50:53], v70 offset0:76 offset1:80
	ds_read2_b64 v[54:57], v69 offset0:108 offset1:112
	v_sub_f32_e32 v44, v44, v104
	v_sub_f32_e32 v43, v43, v104
	v_sub_f32_e32 v42, v42, v104
	v_sub_f32_e32 v99, v45, v104
	v_cvt_pk_bf16_f32 v58, v58, v59
	v_cvt_pk_bf16_f32 v59, v60, v61
	v_cvt_pk_bf16_f32 v60, v72, v73
	v_cvt_pk_bf16_f32 v61, v74, v75
	ds_read2_b64 v[72:75], v67 offset0:20 offset1:24
	v_exp_f32_e32 v96, v42
	v_exp_f32_e32 v97, v43
	v_exp_f32_e32 v98, v44
	ds_read2_b64 v[42:45], v70 offset0:84 offset1:88
	s_waitcnt lgkmcnt(5)
; __device__ __forceinline__ unsigned cvt_pk_bf16(float lo, float hi) { unsigned r; asm volatile("v_cvt_pk_bf16_f32 %0, %1, %2" : "=v"(r) : "v"(lo), "v"(hi)); return r; }
; #define LAS __attribute__((address_space(3)))
; __device__ __forceinline__ void attn_unit(LAS unsigned char* lds, bf16* Q, const bf16* Kg, const bf16* Vg, const float* snk, int unit, int tid) {
;     ...
;         for (int kb = 0; kb < 9; ++kb) { const LAS unsigned char* kp = lds + (16 * (mt + kb) + fr) * ATT_KP + 16 * fq;
;             const bf16x8_t k0 = *(const LAS bf16x8_t*)kp, k1 = *(const LAS bf16x8_t*)(kp + 64);
;             f32x4 z = {0.f, 0.f, 0.f, 0.f}; z = __builtin_amdgcn_mfma_f32_16x16x32_bf16(k0, qf[mt][0], z, 0, 0, 0); z = __builtin_amdgcn_mfma_f32_16x16x32_bf16(k1, qf[mt][1], z, 0, 0, 0); st[kb] = z; }
;     ...
; #pragma unroll
;         for (int kp = 0; kp < 5; ++kp) {
;             v4u pw; pw.x = cvt_pk_bf16(st[2 * kp][0], st[2 * kp][1]); pw.y = cvt_pk_bf16(st[2 * kp][2], st[2 * kp][3]);
;             if (kp < 4) { pw.z = cvt_pk_bf16(st[(2 * kp + 1) % 9][0], st[(2 * kp + 1) % 9][1]); pw.w = cvt_pk_bf16(st[(2 * kp + 1) % 9][2], st[(2 * kp + 1) % 9][3]); } else { pw.z = 0u; pw.w = 0u; }
;             const bf16x8_t pb = __builtin_bit_cast(bf16x8_t, pw);
; #pragma unroll
;             for (int dt = 0; dt < 4; ++dt) { const LAS unsigned char* vp = lds + ATT_VOFF + (16 * dt + fr) * ATT_VP + (16 * (mt + 2 * kp) + 4 * fq) * 2;
;                 const v2u lo = *(const LAS v2u*)vp; v2u hi = {0u, 0u}; if (kp < 4) hi = *(const LAS v2u*)(vp + 32);
;                 v4u aw; aw.x = lo.x; aw.y = lo.y; aw.z = hi.x; aw.w = hi.y;
;                 o[dt] = __builtin_amdgcn_mfma_f32_16x16x32_bf16(__builtin_bit_cast(bf16x8_t, aw), pb, o[dt], 0, 0, 0); }
;         }
; #pragma unroll
;         for (int dt = 0; dt < 4; ++dt) { const f32x4 y = o[dt] * inv; v2u w; w.x = cvt_pk_bf16(y[0], y[1]); w.y = cvt_pk_bf16(y[2], y[3]); *(v2u*)(qbase + (size_t)mt * 16 * 1024 + 16 * dt + 4 * fq) = w; }
	v_mfma_f32_16x16x32_bf16 v[38:41], v[38:41], v[34:37], 0
	ds_read2_b64 v[76:79], v68 offset0:52 offset1:56
	v_exp_f32_e32 v99, v99
	s_waitcnt lgkmcnt(5)
	v_mfma_f32_16x16x32_bf16 v[46:49], v[46:49], v[34:37], 0
	s_waitcnt lgkmcnt(4)
	v_mfma_f32_16x16x32_bf16 v[50:53], v[50:53], v[34:37], 0
	s_waitcnt lgkmcnt(3)
	v_mfma_f32_16x16x32_bf16 v[34:37], v[54:57], v[34:37], 0
	ds_read2_b64 v[54:57], v69 offset0:116 offset1:120
	s_waitcnt lgkmcnt(3)
	v_mfma_f32_16x16x32_bf16 v[38:41], v[72:75], v[58:61], v[38:41]
	v_cvt_pk_bf16_f32 v72, v84, v85
	v_cvt_pk_bf16_f32 v73, v86, v87
	v_cvt_pk_bf16_f32 v74, v88, v89
	v_cvt_pk_bf16_f32 v75, v90, v91
	s_waitcnt lgkmcnt(2)
	v_mfma_f32_16x16x32_bf16 v[42:45], v[42:45], v[58:61], v[50:53]
	v_sub_f32_e32 v89, v103, v104
	v_sub_f32_e32 v90, v102, v104
	v_sub_f32_e32 v91, v101, v104
	ds_read2_b64 v[50:53], v68 offset0:60 offset1:64
	s_waitcnt lgkmcnt(2)
	v_mfma_f32_16x16x32_bf16 v[46:49], v[76:79], v[58:61], v[46:49]
	ds_read2_b64 v[76:79], v67 offset0:28 offset1:32
	v_pk_add_f32 v[84:85], v[96:97], v[94:95]
	v_pk_add_f32 v[86:87], v[98:99], v[92:93]
	s_waitcnt lgkmcnt(2)
	v_mfma_f32_16x16x32_bf16 v[34:37], v[54:57], v[58:61], v[34:37]
	ds_read2_b64 v[54:57], v70 offset0:92 offset1:96
	v_sub_f32_e32 v58, v100, v104
	v_exp_f32_e32 v88, v58
	s_waitcnt lgkmcnt(2)
	v_mfma_f32_16x16x32_bf16 v[46:49], v[50:53], v[72:75], v[46:49]
	ds_read2_b64 v[50:53], v69 offset0:124 offset1:128
	v_cvt_pk_bf16_f32 v58, v82, v83
	v_cvt_pk_bf16_f32 v59, v80, v81
	v_cvt_pk_bf16_f32 v60, v96, v97
	v_cvt_pk_bf16_f32 v61, v98, v99
	s_waitcnt lgkmcnt(1)
	v_mfma_f32_16x16x32_bf16 v[42:45], v[54:57], v[72:75], v[42:45]
	ds_read2_b64 v[54:57], v68 offset0:68 offset1:72
	v_exp_f32_e32 v80, v90
	v_exp_f32_e32 v81, v89
	v_mfma_f32_16x16x32_bf16 v[38:41], v[76:79], v[72:75], v[38:41]
	ds_read2_b64 v[76:79], v67 offset0:36 offset1:40
	v_exp_f32_e32 v89, v91
	s_waitcnt lgkmcnt(2)
	v_mfma_f32_16x16x32_bf16 v[34:37], v[50:53], v[72:75], v[34:37]
	ds_read2_b64 v[50:53], v70 offset0:100 offset1:104
	v_pk_add_f32 v[72:73], v[80:81], v[86:87]
	v_pk_add_f32 v[74:75], v[88:89], v[84:85]
	s_waitcnt lgkmcnt(2)
	v_mfma_f32_16x16x32_bf16 v[46:49], v[54:57], v[58:61], v[46:49]
	ds_read2_b64 v[54:57], v69 offset0:132 offset1:136
	s_waitcnt lgkmcnt(2)
	v_mfma_f32_16x16x32_bf16 v[38:41], v[76:79], v[58:61], v[38:41]
	v_pk_mov_b32 v[76:77], v[74:75], v[72:73] op_sel:[1,0]
	v_mov_b32_e32 v75, v73
	v_pk_add_f32 v[72:73], v[76:77], v[74:75]
	s_waitcnt lgkmcnt(1)
	v_mfma_f32_16x16x32_bf16 v[42:45], v[50:53], v[58:61], v[42:45]
	v_add_f32_e32 v72, v72, v73
	ds_bpermute_b32 v50, v65, v72
	v_mov_b32_e32 v52, v147
	s_waitcnt lgkmcnt(1)
	v_mfma_f32_16x16x32_bf16 v[34:37], v[54:57], v[58:61], v[34:37]
	v_mov_b32_e32 v56, v147
	v_mov_b32_e32 v57, v147
	s_waitcnt lgkmcnt(0)
	v_add_f32_e32 v78, v72, v50
	v_cvt_pk_bf16_f32 v50, v88, v89
	v_cvt_pk_bf16_f32 v51, v80, v81
	ds_read_b64 v[54:55], v180 offset:37216
	ds_read_b64 v[58:59], v180 offset:45664
	v_mov_b32_e32 v53, v147
	v_mov_b32_e32 v60, v147
	v_mov_b32_e32 v61, v147
	s_waitcnt lgkmcnt(1)
	v_mfma_f32_16x16x32_bf16 v[38:41], v[54:57], v[50:53], v[38:41]
	ds_bpermute_b32 v54, v66, v78
	v_fma_f32 v55, v64, s62, -v104
	v_exp_f32_e32 v55, v55
	ds_read_b64 v[72:73], v180 offset:54112
	ds_read_b64 v[76:77], v180 offset:62560
	v_mov_b32_e32 v74, v147
	s_waitcnt lgkmcnt(2)
	v_add_f32_e32 v54, v78, v54
	v_add_f32_e32 v54, v55, v54
	v_mov_b32_e32 v75, v147
	v_mov_b32_e32 v78, v147
	v_mov_b32_e32 v79, v147
	v_div_scale_f32 v55, s[64:65], v54, v54, 1.0
	v_rcp_f32_e32 v56, v55
	v_mfma_f32_16x16x32_bf16 v[46:49], v[58:61], v[50:53], v[46:49]
	s_waitcnt lgkmcnt(1)
	v_mfma_f32_16x16x32_bf16 v[42:45], v[72:75], v[50:53], v[42:45]
	s_waitcnt lgkmcnt(0)
	v_mfma_f32_16x16x32_bf16 v[34:37], v[76:79], v[50:53], v[34:37]
	v_fma_f32 v50, -v55, v56, 1.0
	v_fmac_f32_e32 v56, v50, v56
	v_div_scale_f32 v50, vcc, 1.0, v54, 1.0
	v_mul_f32_e32 v51, v50, v56
	v_fma_f32 v52, -v55, v51, v50
	v_fmac_f32_e32 v51, v52, v56
	v_fma_f32 v50, -v55, v51, v50
	v_div_fmas_f32 v50, v50, v56, v51
	v_div_fixup_f32 v50, v50, v54, 1.0
	v_pk_mul_f32 v[40:41], v[50:51], v[40:41] op_sel_hi:[0,1]
	v_pk_mul_f32 v[38:39], v[50:51], v[38:39] op_sel_hi:[0,1]
	v_add_co_u32_e32 v84, vcc, s44, v62
	v_cvt_pk_bf16_f32 v38, v38, v39
	v_cvt_pk_bf16_f32 v39, v40, v41
	v_pk_mul_f32 v[40:41], v[50:51], v[46:47] op_sel_hi:[0,1]
	s_nop 0
	v_addc_co_u32_e32 v85, vcc, 0, v63, vcc
	global_store_dwordx2 v[84:85], v[38:39], off
	v_pk_mul_f32 v[38:39], v[50:51], v[48:49] op_sel_hi:[0,1]
	v_cvt_pk_bf16_f32 v40, v40, v41
	v_cvt_pk_bf16_f32 v41, v38, v39
	global_store_dwordx2 v[84:85], v[40:41], off offset:32
	v_pk_mul_f32 v[40:41], v[50:51], v[42:43] op_sel_hi:[0,1]
	v_pk_mul_f32 v[38:39], v[50:51], v[44:45] op_sel_hi:[0,1]
	v_cvt_pk_bf16_f32 v40, v40, v41
	v_cvt_pk_bf16_f32 v41, v38, v39
	v_pk_mul_f32 v[36:37], v[50:51], v[36:37] op_sel_hi:[0,1]
	v_pk_mul_f32 v[34:35], v[50:51], v[34:35] op_sel_hi:[0,1]
	global_store_dwordx2 v[84:85], v[40:41], off offset:64
	v_cvt_pk_bf16_f32 v86, v34, v35
	v_cvt_pk_bf16_f32 v87, v36, v37
	ds_read_b128 v[34:37], v179 offset:9216
	ds_read_b128 v[38:41], v179 offset:9280
	s_waitcnt lgkmcnt(1)
	v_mfma_f32_16x16x32_bf16 v[34:37], v[34:37], v[26:29], 0
	ds_read_b128 v[42:45], v179 offset:11520
	ds_read_b128 v[46:49], v179 offset:13824
	ds_read_b128 v[50:53], v179 offset:16128
	s_waitcnt lgkmcnt(3)
	v_mfma_f32_16x16x32_bf16 v[38:41], v[38:41], v[30:33], v[34:37]
	ds_read_b128 v[54:57], v179 offset:18432
	ds_read_b128 v[58:61], v179 offset:20736
	ds_read_b128 v[72:75], v179 offset:23040
	ds_read_b128 v[34:37], v179 offset:11584
	s_waitcnt lgkmcnt(6)
; __device__ __forceinline__ void attn_unit(LAS unsigned char* lds, bf16* Q, const bf16* Kg, const bf16* Vg, const float* snk, int unit, int tid) {
;     ...
;         for (int kb = 0; kb < 9; ++kb) { const LAS unsigned char* kp = lds + (16 * (mt + kb) + fr) * ATT_KP + 16 * fq;
;             const bf16x8_t k0 = *(const LAS bf16x8_t*)kp, k1 = *(const LAS bf16x8_t*)(kp + 64);
;             f32x4 z = {0.f, 0.f, 0.f, 0.f}; z = __builtin_amdgcn_mfma_f32_16x16x32_bf16(k0, qf[mt][0], z, 0, 0, 0); z = __builtin_amdgcn_mfma_f32_16x16x32_bf16(k1, qf[mt][1], z, 0, 0, 0); st[kb] = z; }
;         float mx = sink;
; #pragma unroll
;         for (int kb = 0; kb < 9; ++kb) {
;             const bool tile_ok = (n > 0) || (mt + kb >= 8);
; #pragma unroll
;             for (int i = 0; i < 4; ++i) { const bool ok = tile_ok && (kb == 0 ? lo_ok[i] : (kb == 8 ? !lo_ok[i] : true));
;                 st[kb][i] = ok ? st[kb][i] : -INFINITY; mx = fmaxf(mx, st[kb][i]); }
;         }
;         mx = fmaxf(mx, __shfl_xor(mx, 16)); mx = fmaxf(mx, __shfl_xor(mx, 32));
;         f32x4 ls4 = {0.f, 0.f, 0.f, 0.f};
; #pragma unroll
;         for (int kb = 0; kb < 9; ++kb) { f32x4 d = st[kb] - mx;
; #pragma unroll
;             for (int i = 0; i < 4; ++i) d[i] = __builtin_amdgcn_exp2f(d[i]);
;             st[kb] = d; ls4 = ls4 + d; }
;         float ls = (ls4[0] + ls4[1]) + (ls4[2] + ls4[3]);
;         ls += __shfl_xor(ls, 16); ls += __shfl_xor(ls, 32);
;         const float inv = 1.f / (ls + __builtin_amdgcn_exp2f(sink - mx));
;         f32x4 o[4];
; #pragma unroll
;         for (int dt = 0; dt < 4; ++dt) o[dt] = (f32x4){0.f, 0.f, 0.f, 0.f};
; #pragma unroll
;         for (int kp = 0; kp < 5; ++kp) {
;             v4u pw; pw.x = cvt_pk_bf16(st[2 * kp][0], st[2 * kp][1]); pw.y = cvt_pk_bf16(st[2 * kp][2], st[2 * kp][3]);
;             if (kp < 4) { pw.z = cvt_pk_bf16(st[(2 * kp + 1) % 9][0], st[(2 * kp + 1) % 9][1]); pw.w = cvt_pk_bf16(st[(2 * kp + 1) % 9][2], st[(2 * kp + 1) % 9][3]); } else { pw.z = 0u; pw.w = 0u; }
;             const bf16x8_t pb = __builtin_bit_cast(bf16x8_t, pw);
; #pragma unroll
;             for (int dt = 0; dt < 4; ++dt) { const LAS unsigned char* vp = lds + ATT_VOFF + (16 * dt + fr) * ATT_VP + (16 * (mt + 2 * kp) + 4 * fq) * 2;
;                 const v2u lo = *(const LAS v2u*)vp; v2u hi = {0u, 0u}; if (kp < 4) hi = *(const LAS v2u*)(vp + 32);
	v_mfma_f32_16x16x32_bf16 v[42:45], v[42:45], v[26:29], 0
	ds_read_b128 v[76:79], v179 offset:25344
	ds_read_b128 v[80:83], v179 offset:27648
	global_store_dwordx2 v[84:85], v[86:87], off offset:96
	s_waitcnt lgkmcnt(2)
	v_mfma_f32_16x16x32_bf16 v[42:45], v[34:37], v[30:33], v[42:45]
	ds_read_b128 v[34:37], v179 offset:13888
	v_mfma_f32_16x16x32_bf16 v[46:49], v[46:49], v[26:29], 0
	s_waitcnt lgkmcnt(0)
	v_mfma_f32_16x16x32_bf16 v[46:49], v[34:37], v[30:33], v[46:49]
	ds_read_b128 v[34:37], v179 offset:16192
	v_mfma_f32_16x16x32_bf16 v[50:53], v[50:53], v[26:29], 0
	s_waitcnt lgkmcnt(0)
	v_mfma_f32_16x16x32_bf16 v[50:53], v[34:37], v[30:33], v[50:53]
	ds_read_b128 v[34:37], v179 offset:18496
	v_mfma_f32_16x16x32_bf16 v[54:57], v[54:57], v[26:29], 0
	s_waitcnt lgkmcnt(0)
	v_mfma_f32_16x16x32_bf16 v[54:57], v[34:37], v[30:33], v[54:57]
	ds_read_b128 v[34:37], v179 offset:20800
	v_mfma_f32_16x16x32_bf16 v[58:61], v[58:61], v[26:29], 0
	s_waitcnt lgkmcnt(0)
	v_mfma_f32_16x16x32_bf16 v[58:61], v[34:37], v[30:33], v[58:61]
	ds_read_b128 v[34:37], v179 offset:23104
	v_mfma_f32_16x16x32_bf16 v[72:75], v[72:75], v[26:29], 0
	s_waitcnt lgkmcnt(0)
	v_mfma_f32_16x16x32_bf16 v[72:75], v[34:37], v[30:33], v[72:75]
	ds_read_b128 v[34:37], v179 offset:25408
	v_mfma_f32_16x16x32_bf16 v[76:79], v[76:79], v[26:29], 0
	s_waitcnt lgkmcnt(0)
	v_mfma_f32_16x16x32_bf16 v[34:37], v[34:37], v[30:33], v[76:79]
	s_nop 5
	ds_read_b128 v[76:79], v179 offset:27712
	v_mfma_f32_16x16x32_bf16 v[26:29], v[80:83], v[26:29], 0
	s_waitcnt lgkmcnt(0)
	v_mfma_f32_16x16x32_bf16 v[26:29], v[76:79], v[30:33], v[26:29]
	v_cndmask_b32_e64 v31, v39, v191, s[8:9]
	v_cndmask_b32_e64 v30, v191, v38, s[18:19]
	v_cndmask_b32_e64 v31, v191, v31, s[14:15]
	v_max3_f32 v32, v71, v30, v31
	v_cndmask_b32_e64 v33, v191, v40, s[16:17]
	v_cndmask_b32_e64 v38, v191, v41, s[20:21]
	v_max3_f32 v32, v32, v33, v38
	v_cndmask_b32_e64 v39, v191, v42, s[14:15]
	v_cndmask_b32_e64 v40, v191, v43, s[14:15]
	v_max3_f32 v32, v32, v39, v40
	v_cndmask_b32_e64 v41, v191, v44, s[14:15]
	v_cndmask_b32_e64 v42, v191, v45, s[14:15]
	v_max3_f32 v32, v32, v41, v42
	v_cndmask_b32_e64 v43, v191, v46, s[14:15]
	v_cndmask_b32_e64 v44, v191, v47, s[14:15]
	v_max3_f32 v32, v32, v43, v44
	v_cndmask_b32_e64 v45, v191, v48, s[14:15]
	v_cndmask_b32_e64 v46, v191, v49, s[14:15]
	v_max3_f32 v32, v32, v45, v46
	v_cndmask_b32_e64 v47, v191, v50, s[14:15]
	v_cndmask_b32_e64 v48, v191, v51, s[14:15]
	v_max3_f32 v32, v32, v47, v48
	v_cndmask_b32_e64 v49, v191, v52, s[14:15]
	v_cndmask_b32_e64 v76, v191, v53, s[14:15]
	v_max3_f32 v32, v32, v49, v76
	v_max3_f32 v32, v32, v54, v55
	v_max3_f32 v32, v32, v56, v57
	v_max3_f32 v32, v32, v58, v59
	v_max3_f32 v32, v32, v60, v61
	v_max3_f32 v32, v32, v72, v73
	v_max3_f32 v32, v32, v74, v75
	v_max3_f32 v32, v32, v34, v35
	v_max3_f32 v32, v32, v36, v37
	v_cndmask_b32_e64 v92, v26, v191, s[6:7]
	v_cndmask_b32_e64 v93, v191, v27, s[8:9]
	v_max3_f32 v26, v32, v92, v93
	v_cndmask_b32_e64 v94, v28, v191, s[10:11]
	v_cndmask_b32_e64 v95, v29, v191, s[12:13]
	v_max3_f32 v26, v26, v94, v95
	ds_bpermute_b32 v27, v65, v26
	s_waitcnt lgkmcnt(0)
	v_max_f32_e32 v27, v27, v27
	v_max_f32_e32 v26, v26, v27
	ds_bpermute_b32 v27, v66, v26
	s_waitcnt lgkmcnt(0)
	v_max_f32_e32 v27, v27, v27
	v_max_f32_e32 v96, v26, v27
	v_sub_f32_e32 v27, v38, v96
	v_sub_f32_e32 v28, v33, v96
	v_sub_f32_e32 v31, v31, v96
	v_sub_f32_e32 v26, v30, v96
	v_exp_f32_e32 v26, v26
	v_exp_f32_e32 v28, v28
	v_exp_f32_e32 v29, v27
	v_exp_f32_e32 v27, v31
	v_sub_f32_e32 v42, v42, v96
	v_sub_f32_e32 v41, v41, v96
	v_sub_f32_e32 v40, v40, v96
	v_sub_f32_e32 v38, v39, v96
	v_exp_f32_e32 v38, v38
	v_exp_f32_e32 v39, v40
	v_exp_f32_e32 v40, v41
	v_exp_f32_e32 v41, v42
	v_sub_f32_e32 v42, v46, v96
	v_sub_f32_e32 v45, v45, v96
	v_sub_f32_e32 v44, v44, v96
	v_sub_f32_e32 v43, v43, v96
	v_exp_f32_e32 v50, v43
	v_exp_f32_e32 v52, v45
	v_exp_f32_e32 v53, v42
	v_exp_f32_e32 v51, v44
	v_sub_f32_e32 v42, v76, v96
	v_sub_f32_e32 v43, v49, v96
	v_sub_f32_e32 v44, v48, v96
	v_sub_f32_e32 v45, v47, v96
	v_exp_f32_e32 v76, v45
	v_exp_f32_e32 v77, v44
	v_exp_f32_e32 v78, v43
	v_exp_f32_e32 v79, v42
	v_sub_f32_e32 v42, v57, v96
	v_sub_f32_e32 v43, v56, v96
	v_sub_f32_e32 v44, v55, v96
	v_sub_f32_e32 v45, v54, v96
	v_pk_add_f32 v[30:31], v[28:29], 0 op_sel_hi:[1,0]
	v_pk_add_f32 v[32:33], v[26:27], 0 op_sel_hi:[1,0]
	v_exp_f32_e32 v80, v45
	v_exp_f32_e32 v82, v43
	v_exp_f32_e32 v83, v42
	v_exp_f32_e32 v81, v44
	v_pk_add_f32 v[32:33], v[38:39], v[32:33]
	v_pk_add_f32 v[30:31], v[40:41], v[30:31]
	v_pk_add_f32 v[32:33], v[50:51], v[32:33]
	v_pk_add_f32 v[30:31], v[52:53], v[30:31]
	v_pk_add_f32 v[32:33], v[76:77], v[32:33]
	v_pk_add_f32 v[30:31], v[78:79], v[30:31]
	v_sub_f32_e32 v44, v58, v96
	v_pk_add_f32 v[42:43], v[82:83], v[30:31]
	v_pk_add_f32 v[30:31], v[80:81], v[32:33]
	v_sub_f32_e32 v33, v59, v96
	v_sub_f32_e32 v32, v61, v96
	v_exp_f32_e32 v85, v33
	v_sub_f32_e32 v33, v60, v96
	v_exp_f32_e32 v84, v44
	v_exp_f32_e32 v86, v33
	v_exp_f32_e32 v87, v32
	v_sub_f32_e32 v46, v75, v96
	v_sub_f32_e32 v47, v74, v96
	v_sub_f32_e32 v48, v73, v96
	v_sub_f32_e32 v49, v72, v96
	v_exp_f32_e32 v72, v47
	v_exp_f32_e32 v73, v46
	v_exp_f32_e32 v74, v49
	v_exp_f32_e32 v75, v48
	v_pk_add_f32 v[44:45], v[84:85], v[30:31]
	v_pk_add_f32 v[42:43], v[86:87], v[42:43]
	v_cvt_pk_bf16_f32 v26, v26, v27
	v_cvt_pk_bf16_f32 v27, v28, v29
	v_cvt_pk_bf16_f32 v28, v38, v39
	v_cvt_pk_bf16_f32 v29, v40, v41
	ds_read2_b64 v[30:33], v67 offset0:16 offset1:20
	ds_read2_b64 v[38:41], v68 offset0:48 offset1:52
	v_pk_add_f32 v[88:89], v[72:73], v[42:43]
	v_pk_add_f32 v[90:91], v[74:75], v[44:45]
	ds_read2_b64 v[42:45], v70 offset0:80 offset1:84
	ds_read2_b64 v[46:49], v69 offset0:112 offset1:116
	v_sub_f32_e32 v36, v36, v96
	v_sub_f32_e32 v35, v35, v96
	v_sub_f32_e32 v34, v34, v96
	v_sub_f32_e32 v97, v37, v96
	v_cvt_pk_bf16_f32 v50, v50, v51
	v_cvt_pk_bf16_f32 v51, v52, v53
	v_cvt_pk_bf16_f32 v52, v76, v77
	v_cvt_pk_bf16_f32 v53, v78, v79
	ds_read2_b64 v[54:57], v67 offset0:24 offset1:28
	v_exp_f32_e32 v76, v34
	v_exp_f32_e32 v77, v35
	v_exp_f32_e32 v78, v36
	ds_read2_b64 v[34:37], v70 offset0:88 offset1:92
	s_waitcnt lgkmcnt(5)
; __device__ __forceinline__ unsigned cvt_pk_bf16(float lo, float hi) { unsigned r; asm volatile("v_cvt_pk_bf16_f32 %0, %1, %2" : "=v"(r) : "v"(lo), "v"(hi)); return r; }
; #define LAS __attribute__((address_space(3)))
; __device__ __forceinline__ void attn_unit(LAS unsigned char* lds, bf16* Q, const bf16* Kg, const bf16* Vg, const float* snk, int unit, int tid) {
;     ...
;         for (int kb = 0; kb < 9; ++kb) { const LAS unsigned char* kp = lds + (16 * (mt + kb) + fr) * ATT_KP + 16 * fq;
;             const bf16x8_t k0 = *(const LAS bf16x8_t*)kp, k1 = *(const LAS bf16x8_t*)(kp + 64);
;             f32x4 z = {0.f, 0.f, 0.f, 0.f}; z = __builtin_amdgcn_mfma_f32_16x16x32_bf16(k0, qf[mt][0], z, 0, 0, 0); z = __builtin_amdgcn_mfma_f32_16x16x32_bf16(k1, qf[mt][1], z, 0, 0, 0); st[kb] = z; }
;     ...
; #pragma unroll
;         for (int kp = 0; kp < 5; ++kp) {
;             v4u pw; pw.x = cvt_pk_bf16(st[2 * kp][0], st[2 * kp][1]); pw.y = cvt_pk_bf16(st[2 * kp][2], st[2 * kp][3]);
;             if (kp < 4) { pw.z = cvt_pk_bf16(st[(2 * kp + 1) % 9][0], st[(2 * kp + 1) % 9][1]); pw.w = cvt_pk_bf16(st[(2 * kp + 1) % 9][2], st[(2 * kp + 1) % 9][3]); } else { pw.z = 0u; pw.w = 0u; }
;             const bf16x8_t pb = __builtin_bit_cast(bf16x8_t, pw);
; #pragma unroll
;             for (int dt = 0; dt < 4; ++dt) { const LAS unsigned char* vp = lds + ATT_VOFF + (16 * dt + fr) * ATT_VP + (16 * (mt + 2 * kp) + 4 * fq) * 2;
;                 const v2u lo = *(const LAS v2u*)vp; v2u hi = {0u, 0u}; if (kp < 4) hi = *(const LAS v2u*)(vp + 32);
;                 v4u aw; aw.x = lo.x; aw.y = lo.y; aw.z = hi.x; aw.w = hi.y;
;                 o[dt] = __builtin_amdgcn_mfma_f32_16x16x32_bf16(__builtin_bit_cast(bf16x8_t, aw), pb, o[dt], 0, 0, 0); }
;         }
; #pragma unroll
;         for (int dt = 0; dt < 4; ++dt) { const f32x4 y = o[dt] * inv; v2u w; w.x = cvt_pk_bf16(y[0], y[1]); w.y = cvt_pk_bf16(y[2], y[3]); *(v2u*)(qbase + (size_t)mt * 16 * 1024 + 16 * dt + 4 * fq) = w; }
	v_mfma_f32_16x16x32_bf16 v[30:33], v[30:33], v[26:29], 0
	ds_read2_b64 v[58:61], v68 offset0:56 offset1:60
	v_exp_f32_e32 v79, v97
	s_waitcnt lgkmcnt(5)
	v_mfma_f32_16x16x32_bf16 v[38:41], v[38:41], v[26:29], 0
	s_waitcnt lgkmcnt(4)
	v_mfma_f32_16x16x32_bf16 v[42:45], v[42:45], v[26:29], 0
	s_waitcnt lgkmcnt(3)
	v_mfma_f32_16x16x32_bf16 v[26:29], v[46:49], v[26:29], 0
	ds_read2_b64 v[46:49], v69 offset0:120 offset1:124
	s_waitcnt lgkmcnt(3)
	v_mfma_f32_16x16x32_bf16 v[30:33], v[54:57], v[50:53], v[30:33]
	v_cvt_pk_bf16_f32 v54, v80, v81
	v_cvt_pk_bf16_f32 v55, v82, v83
	v_cvt_pk_bf16_f32 v56, v84, v85
	v_cvt_pk_bf16_f32 v57, v86, v87
	s_waitcnt lgkmcnt(2)
	v_mfma_f32_16x16x32_bf16 v[34:37], v[34:37], v[50:53], v[42:45]
	v_sub_f32_e32 v85, v95, v96
	v_sub_f32_e32 v86, v94, v96
	v_sub_f32_e32 v87, v93, v96
	ds_read2_b64 v[42:45], v68 offset0:64 offset1:68
	s_waitcnt lgkmcnt(2)
	v_mfma_f32_16x16x32_bf16 v[38:41], v[58:61], v[50:53], v[38:41]
	ds_read2_b64 v[58:61], v67 offset0:32 offset1:36
	v_pk_add_f32 v[80:81], v[76:77], v[90:91]
	v_pk_add_f32 v[82:83], v[78:79], v[88:89]
	s_waitcnt lgkmcnt(2)
	v_mfma_f32_16x16x32_bf16 v[26:29], v[46:49], v[50:53], v[26:29]
	ds_read2_b64 v[46:49], v70 offset0:96 offset1:100
	v_sub_f32_e32 v50, v92, v96
	v_exp_f32_e32 v84, v50
	s_waitcnt lgkmcnt(2)
	v_mfma_f32_16x16x32_bf16 v[38:41], v[42:45], v[54:57], v[38:41]
	ds_read2_b64 v[42:45], v69 offset0:128 offset1:132
	v_cvt_pk_bf16_f32 v50, v74, v75
	v_cvt_pk_bf16_f32 v51, v72, v73
	v_cvt_pk_bf16_f32 v52, v76, v77
	v_cvt_pk_bf16_f32 v53, v78, v79
	s_waitcnt lgkmcnt(1)
	v_mfma_f32_16x16x32_bf16 v[34:37], v[46:49], v[54:57], v[34:37]
	ds_read2_b64 v[46:49], v68 offset0:72 offset1:76
	v_exp_f32_e32 v72, v86
	v_exp_f32_e32 v73, v85
	v_mfma_f32_16x16x32_bf16 v[30:33], v[58:61], v[54:57], v[30:33]
	ds_read2_b64 v[58:61], v67 offset0:40 offset1:44
	v_exp_f32_e32 v85, v87
	s_waitcnt lgkmcnt(2)
	v_mfma_f32_16x16x32_bf16 v[26:29], v[42:45], v[54:57], v[26:29]
	ds_read2_b64 v[42:45], v70 offset0:104 offset1:108
	v_pk_add_f32 v[54:55], v[72:73], v[82:83]
	v_pk_add_f32 v[56:57], v[84:85], v[80:81]
	s_waitcnt lgkmcnt(2)
	v_mfma_f32_16x16x32_bf16 v[38:41], v[46:49], v[50:53], v[38:41]
	ds_read2_b64 v[46:49], v69 offset0:136 offset1:140
	s_waitcnt lgkmcnt(2)
	v_mfma_f32_16x16x32_bf16 v[30:33], v[58:61], v[50:53], v[30:33]
	v_pk_mov_b32 v[58:59], v[56:57], v[54:55] op_sel:[1,0]
	v_mov_b32_e32 v57, v55
	v_pk_add_f32 v[54:55], v[58:59], v[56:57]
	s_waitcnt lgkmcnt(1)
	v_mfma_f32_16x16x32_bf16 v[34:37], v[42:45], v[50:53], v[34:37]
	v_add_f32_e32 v54, v54, v55
	ds_bpermute_b32 v42, v65, v54
	v_mov_b32_e32 v44, v147
	s_waitcnt lgkmcnt(1)
	v_mfma_f32_16x16x32_bf16 v[26:29], v[46:49], v[50:53], v[26:29]
	v_mov_b32_e32 v48, v147
	v_mov_b32_e32 v49, v147
	s_waitcnt lgkmcnt(0)
	v_add_f32_e32 v60, v54, v42
	v_cvt_pk_bf16_f32 v42, v84, v85
	v_cvt_pk_bf16_f32 v43, v72, v73
	ds_read_b64 v[46:47], v180 offset:37248
	ds_read_b64 v[50:51], v180 offset:45696
	v_mov_b32_e32 v45, v147
	v_mov_b32_e32 v52, v147
	v_mov_b32_e32 v53, v147
	s_waitcnt lgkmcnt(1)
	v_mfma_f32_16x16x32_bf16 v[30:33], v[46:49], v[42:45], v[30:33]
	ds_bpermute_b32 v46, v66, v60
	v_fma_f32 v47, v64, s62, -v96
	v_exp_f32_e32 v47, v47
	ds_read_b64 v[54:55], v180 offset:54144
	ds_read_b64 v[58:59], v180 offset:62592
	v_mov_b32_e32 v56, v147
	s_waitcnt lgkmcnt(2)
	v_add_f32_e32 v46, v60, v46
	v_add_f32_e32 v46, v47, v46
	v_mov_b32_e32 v57, v147
	v_mov_b32_e32 v60, v147
	v_mov_b32_e32 v61, v147
	v_div_scale_f32 v47, s[64:65], v46, v46, 1.0
	v_rcp_f32_e32 v48, v47
	v_mfma_f32_16x16x32_bf16 v[38:41], v[50:53], v[42:45], v[38:41]
	s_waitcnt lgkmcnt(1)
	v_mfma_f32_16x16x32_bf16 v[34:37], v[54:57], v[42:45], v[34:37]
	s_waitcnt lgkmcnt(0)
	v_mfma_f32_16x16x32_bf16 v[26:29], v[58:61], v[42:45], v[26:29]
	v_fma_f32 v42, -v47, v48, 1.0
	v_fmac_f32_e32 v48, v42, v48
	v_div_scale_f32 v42, vcc, 1.0, v46, 1.0
	v_mul_f32_e32 v43, v42, v48
	v_fma_f32 v44, -v47, v43, v42
	v_fmac_f32_e32 v43, v44, v48
	v_fma_f32 v42, -v47, v43, v42
	v_div_fmas_f32 v42, v42, v48, v43
	v_div_fixup_f32 v42, v42, v46, 1.0
	v_pk_mul_f32 v[32:33], v[42:43], v[32:33] op_sel_hi:[0,1]
	v_pk_mul_f32 v[30:31], v[42:43], v[30:31] op_sel_hi:[0,1]
	v_add_co_u32_e32 v76, vcc, s45, v62
	v_cvt_pk_bf16_f32 v30, v30, v31
	v_cvt_pk_bf16_f32 v31, v32, v33
	v_pk_mul_f32 v[32:33], v[42:43], v[38:39] op_sel_hi:[0,1]
	s_nop 0
	v_addc_co_u32_e32 v77, vcc, 0, v63, vcc
	global_store_dwordx2 v[76:77], v[30:31], off
	v_pk_mul_f32 v[30:31], v[42:43], v[40:41] op_sel_hi:[0,1]
	v_cvt_pk_bf16_f32 v32, v32, v33
	v_cvt_pk_bf16_f32 v33, v30, v31
	global_store_dwordx2 v[76:77], v[32:33], off offset:32
	v_pk_mul_f32 v[32:33], v[42:43], v[34:35] op_sel_hi:[0,1]
	v_pk_mul_f32 v[30:31], v[42:43], v[36:37] op_sel_hi:[0,1]
	v_cvt_pk_bf16_f32 v32, v32, v33
	v_cvt_pk_bf16_f32 v33, v30, v31
	v_pk_mul_f32 v[28:29], v[42:43], v[28:29] op_sel_hi:[0,1]
	v_pk_mul_f32 v[26:27], v[42:43], v[26:27] op_sel_hi:[0,1]
	global_store_dwordx2 v[76:77], v[32:33], off offset:64
	v_cvt_pk_bf16_f32 v78, v26, v27
	v_cvt_pk_bf16_f32 v79, v28, v29
	ds_read_b128 v[26:29], v179 offset:11520
	ds_read_b128 v[30:33], v179 offset:11584
	s_waitcnt lgkmcnt(1)
	v_mfma_f32_16x16x32_bf16 v[26:29], v[26:29], v[18:21], 0
	ds_read_b128 v[34:37], v179 offset:13824
	ds_read_b128 v[38:41], v179 offset:16128
	ds_read_b128 v[42:45], v179 offset:18432
	s_waitcnt lgkmcnt(3)
	v_mfma_f32_16x16x32_bf16 v[30:33], v[30:33], v[22:25], v[26:29]
	ds_read_b128 v[46:49], v179 offset:20736
	ds_read_b128 v[50:53], v179 offset:23040
	ds_read_b128 v[54:57], v179 offset:25344
	ds_read_b128 v[26:29], v179 offset:13888
	s_waitcnt lgkmcnt(6)
; __device__ __forceinline__ void attn_unit(LAS unsigned char* lds, bf16* Q, const bf16* Kg, const bf16* Vg, const float* snk, int unit, int tid) {
;     ...
;         for (int kb = 0; kb < 9; ++kb) { const LAS unsigned char* kp = lds + (16 * (mt + kb) + fr) * ATT_KP + 16 * fq;
;             const bf16x8_t k0 = *(const LAS bf16x8_t*)kp, k1 = *(const LAS bf16x8_t*)(kp + 64);
;             f32x4 z = {0.f, 0.f, 0.f, 0.f}; z = __builtin_amdgcn_mfma_f32_16x16x32_bf16(k0, qf[mt][0], z, 0, 0, 0); z = __builtin_amdgcn_mfma_f32_16x16x32_bf16(k1, qf[mt][1], z, 0, 0, 0); st[kb] = z; }
;         float mx = sink;
; #pragma unroll
;         for (int kb = 0; kb < 9; ++kb) {
;             const bool tile_ok = (n > 0) || (mt + kb >= 8);
; #pragma unroll
;             for (int i = 0; i < 4; ++i) { const bool ok = tile_ok && (kb == 0 ? lo_ok[i] : (kb == 8 ? !lo_ok[i] : true));
;                 st[kb][i] = ok ? st[kb][i] : -INFINITY; mx = fmaxf(mx, st[kb][i]); }
;         }
;         mx = fmaxf(mx, __shfl_xor(mx, 16)); mx = fmaxf(mx, __shfl_xor(mx, 32));
;         f32x4 ls4 = {0.f, 0.f, 0.f, 0.f};
; #pragma unroll
;         for (int kb = 0; kb < 9; ++kb) { f32x4 d = st[kb] - mx;
; #pragma unroll
;             for (int i = 0; i < 4; ++i) d[i] = __builtin_amdgcn_exp2f(d[i]);
;             st[kb] = d; ls4 = ls4 + d; }
;         float ls = (ls4[0] + ls4[1]) + (ls4[2] + ls4[3]);
;         ls += __shfl_xor(ls, 16); ls += __shfl_xor(ls, 32);
;         const float inv = 1.f / (ls + __builtin_amdgcn_exp2f(sink - mx));
;         f32x4 o[4];
; #pragma unroll
;         for (int dt = 0; dt < 4; ++dt) o[dt] = (f32x4){0.f, 0.f, 0.f, 0.f};
; #pragma unroll
;         for (int kp = 0; kp < 5; ++kp) {
;             v4u pw; pw.x = cvt_pk_bf16(st[2 * kp][0], st[2 * kp][1]); pw.y = cvt_pk_bf16(st[2 * kp][2], st[2 * kp][3]);
;             if (kp < 4) { pw.z = cvt_pk_bf16(st[(2 * kp + 1) % 9][0], st[(2 * kp + 1) % 9][1]); pw.w = cvt_pk_bf16(st[(2 * kp + 1) % 9][2], st[(2 * kp + 1) % 9][3]); } else { pw.z = 0u; pw.w = 0u; }
;             const bf16x8_t pb = __builtin_bit_cast(bf16x8_t, pw);
; #pragma unroll
;             for (int dt = 0; dt < 4; ++dt) { const LAS unsigned char* vp = lds + ATT_VOFF + (16 * dt + fr) * ATT_VP + (16 * (mt + 2 * kp) + 4 * fq) * 2;
;                 const v2u lo = *(const LAS v2u*)vp; v2u hi = {0u, 0u}; if (kp < 4) hi = *(const LAS v2u*)(vp + 32);
	v_mfma_f32_16x16x32_bf16 v[34:37], v[34:37], v[18:21], 0
	ds_read_b128 v[58:61], v179 offset:27648
	ds_read_b128 v[72:75], v179 offset:29952
	global_store_dwordx2 v[76:77], v[78:79], off offset:96
	s_waitcnt lgkmcnt(2)
	v_mfma_f32_16x16x32_bf16 v[34:37], v[26:29], v[22:25], v[34:37]
	ds_read_b128 v[26:29], v179 offset:16192
	v_mfma_f32_16x16x32_bf16 v[38:41], v[38:41], v[18:21], 0
	s_waitcnt lgkmcnt(0)
	v_mfma_f32_16x16x32_bf16 v[38:41], v[26:29], v[22:25], v[38:41]
	ds_read_b128 v[26:29], v179 offset:18496
	v_mfma_f32_16x16x32_bf16 v[42:45], v[42:45], v[18:21], 0
	s_waitcnt lgkmcnt(0)
	v_mfma_f32_16x16x32_bf16 v[42:45], v[26:29], v[22:25], v[42:45]
	ds_read_b128 v[26:29], v179 offset:20800
	v_mfma_f32_16x16x32_bf16 v[46:49], v[46:49], v[18:21], 0
	s_waitcnt lgkmcnt(0)
	v_mfma_f32_16x16x32_bf16 v[46:49], v[26:29], v[22:25], v[46:49]
	ds_read_b128 v[26:29], v179 offset:23104
	v_mfma_f32_16x16x32_bf16 v[50:53], v[50:53], v[18:21], 0
	s_waitcnt lgkmcnt(0)
	v_mfma_f32_16x16x32_bf16 v[50:53], v[26:29], v[22:25], v[50:53]
	ds_read_b128 v[26:29], v179 offset:25408
	v_mfma_f32_16x16x32_bf16 v[54:57], v[54:57], v[18:21], 0
	s_waitcnt lgkmcnt(0)
	v_mfma_f32_16x16x32_bf16 v[54:57], v[26:29], v[22:25], v[54:57]
	ds_read_b128 v[26:29], v179 offset:27712
	v_mfma_f32_16x16x32_bf16 v[58:61], v[58:61], v[18:21], 0
	s_waitcnt lgkmcnt(0)
	v_mfma_f32_16x16x32_bf16 v[26:29], v[26:29], v[22:25], v[58:61]
	s_nop 5
	ds_read_b128 v[58:61], v179 offset:30016
	v_mfma_f32_16x16x32_bf16 v[18:21], v[72:75], v[18:21], 0
	s_waitcnt lgkmcnt(0)
	v_mfma_f32_16x16x32_bf16 v[18:21], v[58:61], v[22:25], v[18:21]
	v_cndmask_b32_e64 v23, v31, v191, s[8:9]
	v_cndmask_b32_e64 v22, v191, v30, s[18:19]
	v_cndmask_b32_e64 v23, v191, v23, s[14:15]
	v_max3_f32 v24, v71, v22, v23
	v_cndmask_b32_e64 v25, v191, v32, s[16:17]
	v_cndmask_b32_e64 v30, v191, v33, s[20:21]
	v_max3_f32 v24, v24, v25, v30
	v_cndmask_b32_e64 v31, v191, v34, s[14:15]
	v_cndmask_b32_e64 v32, v191, v35, s[14:15]
	v_max3_f32 v24, v24, v31, v32
	v_cndmask_b32_e64 v33, v191, v36, s[14:15]
	v_cndmask_b32_e64 v34, v191, v37, s[14:15]
	v_max3_f32 v24, v24, v33, v34
	v_cndmask_b32_e64 v35, v191, v38, s[14:15]
	v_cndmask_b32_e64 v36, v191, v39, s[14:15]
	v_max3_f32 v24, v24, v35, v36
	v_cndmask_b32_e64 v37, v191, v40, s[14:15]
	v_cndmask_b32_e64 v38, v191, v41, s[14:15]
	v_max3_f32 v24, v24, v37, v38
	v_max3_f32 v24, v24, v42, v43
	v_max3_f32 v24, v24, v44, v45
	v_max3_f32 v24, v24, v46, v47
	v_max3_f32 v24, v24, v48, v49
	v_max3_f32 v24, v24, v50, v51
	v_max3_f32 v24, v24, v52, v53
	v_max3_f32 v24, v24, v54, v55
	v_max3_f32 v24, v24, v56, v57
	v_max3_f32 v24, v24, v26, v27
	v_max3_f32 v24, v24, v28, v29
	v_cndmask_b32_e64 v86, v18, v191, s[6:7]
	v_cndmask_b32_e64 v87, v191, v19, s[8:9]
	v_max3_f32 v18, v24, v86, v87
	v_cndmask_b32_e64 v88, v20, v191, s[10:11]
	v_cndmask_b32_e64 v89, v21, v191, s[12:13]
	v_max3_f32 v18, v18, v88, v89
	ds_bpermute_b32 v19, v65, v18
	s_waitcnt lgkmcnt(0)
	v_max_f32_e32 v19, v19, v19
	v_max_f32_e32 v18, v18, v19
	ds_bpermute_b32 v19, v66, v18
	s_waitcnt lgkmcnt(0)
	v_max_f32_e32 v19, v19, v19
	v_max_f32_e32 v90, v18, v19
	v_sub_f32_e32 v19, v30, v90
	v_sub_f32_e32 v20, v25, v90
	v_sub_f32_e32 v23, v23, v90
	v_sub_f32_e32 v18, v22, v90
	v_exp_f32_e32 v18, v18
	v_exp_f32_e32 v20, v20
	v_exp_f32_e32 v21, v19
	v_exp_f32_e32 v19, v23
	v_sub_f32_e32 v34, v34, v90
	v_sub_f32_e32 v33, v33, v90
	v_sub_f32_e32 v32, v32, v90
	v_sub_f32_e32 v30, v31, v90
	v_exp_f32_e32 v30, v30
	v_exp_f32_e32 v31, v32
	v_exp_f32_e32 v32, v33
	v_exp_f32_e32 v33, v34
	v_sub_f32_e32 v34, v38, v90
	v_sub_f32_e32 v37, v37, v90
	v_sub_f32_e32 v36, v36, v90
	v_sub_f32_e32 v35, v35, v90
	v_exp_f32_e32 v58, v35
	v_exp_f32_e32 v60, v37
	v_exp_f32_e32 v61, v34
	v_exp_f32_e32 v59, v36
	v_sub_f32_e32 v34, v45, v90
	v_sub_f32_e32 v35, v44, v90
	v_sub_f32_e32 v36, v43, v90
	v_sub_f32_e32 v37, v42, v90
	v_exp_f32_e32 v44, v37
	v_exp_f32_e32 v45, v36
	v_exp_f32_e32 v72, v35
	v_exp_f32_e32 v73, v34
	v_sub_f32_e32 v34, v49, v90
	v_sub_f32_e32 v35, v48, v90
	v_sub_f32_e32 v36, v47, v90
	v_sub_f32_e32 v37, v46, v90
	v_pk_add_f32 v[22:23], v[20:21], 0 op_sel_hi:[1,0]
	v_pk_add_f32 v[24:25], v[18:19], 0 op_sel_hi:[1,0]
	v_exp_f32_e32 v74, v37
	v_exp_f32_e32 v76, v35
	v_exp_f32_e32 v77, v34
	v_exp_f32_e32 v75, v36
	v_pk_add_f32 v[24:25], v[30:31], v[24:25]
	v_pk_add_f32 v[22:23], v[32:33], v[22:23]
	v_pk_add_f32 v[24:25], v[58:59], v[24:25]
	v_pk_add_f32 v[22:23], v[60:61], v[22:23]
	v_pk_add_f32 v[24:25], v[44:45], v[24:25]
	v_pk_add_f32 v[22:23], v[72:73], v[22:23]
	v_sub_f32_e32 v36, v50, v90
	v_pk_add_f32 v[34:35], v[76:77], v[22:23]
	v_pk_add_f32 v[22:23], v[74:75], v[24:25]
	v_sub_f32_e32 v25, v51, v90
	v_sub_f32_e32 v24, v53, v90
	v_exp_f32_e32 v79, v25
	v_sub_f32_e32 v25, v52, v90
	v_exp_f32_e32 v78, v36
	v_exp_f32_e32 v80, v25
	v_exp_f32_e32 v81, v24
	v_sub_f32_e32 v38, v57, v90
	v_sub_f32_e32 v39, v56, v90
	v_sub_f32_e32 v40, v55, v90
	v_sub_f32_e32 v41, v54, v90
	v_exp_f32_e32 v54, v39
	v_exp_f32_e32 v55, v38
	v_exp_f32_e32 v56, v41
	v_exp_f32_e32 v57, v40
	v_pk_add_f32 v[36:37], v[78:79], v[22:23]
	v_pk_add_f32 v[34:35], v[80:81], v[34:35]
	v_cvt_pk_bf16_f32 v18, v18, v19
	v_cvt_pk_bf16_f32 v19, v20, v21
	v_cvt_pk_bf16_f32 v20, v30, v31
	v_cvt_pk_bf16_f32 v21, v32, v33
	ds_read2_b64 v[22:25], v67 offset0:20 offset1:24
	ds_read2_b64 v[30:33], v68 offset0:52 offset1:56
	v_pk_add_f32 v[82:83], v[54:55], v[34:35]
	v_pk_add_f32 v[84:85], v[56:57], v[36:37]
	ds_read2_b64 v[34:37], v70 offset0:84 offset1:88
	ds_read2_b64 v[38:41], v69 offset0:116 offset1:120
	v_sub_f32_e32 v28, v28, v90
	v_sub_f32_e32 v27, v27, v90
	v_sub_f32_e32 v26, v26, v90
	v_sub_f32_e32 v91, v29, v90
	v_cvt_pk_bf16_f32 v42, v58, v59
	v_cvt_pk_bf16_f32 v43, v60, v61
	v_cvt_pk_bf16_f32 v44, v44, v45
	v_cvt_pk_bf16_f32 v45, v72, v73
	ds_read2_b64 v[46:49], v67 offset0:28 offset1:32
	v_exp_f32_e32 v58, v26
	v_exp_f32_e32 v59, v27
	v_exp_f32_e32 v60, v28
	ds_read2_b64 v[26:29], v70 offset0:92 offset1:96
	s_waitcnt lgkmcnt(5)
; __device__ __forceinline__ unsigned cvt_pk_bf16(float lo, float hi) { unsigned r; asm volatile("v_cvt_pk_bf16_f32 %0, %1, %2" : "=v"(r) : "v"(lo), "v"(hi)); return r; }
; #define LAS __attribute__((address_space(3)))
; __device__ __forceinline__ void attn_unit(LAS unsigned char* lds, bf16* Q, const bf16* Kg, const bf16* Vg, const float* snk, int unit, int tid) {
;     ...
;         for (int kb = 0; kb < 9; ++kb) { const LAS unsigned char* kp = lds + (16 * (mt + kb) + fr) * ATT_KP + 16 * fq;
;             const bf16x8_t k0 = *(const LAS bf16x8_t*)kp, k1 = *(const LAS bf16x8_t*)(kp + 64);
;             f32x4 z = {0.f, 0.f, 0.f, 0.f}; z = __builtin_amdgcn_mfma_f32_16x16x32_bf16(k0, qf[mt][0], z, 0, 0, 0); z = __builtin_amdgcn_mfma_f32_16x16x32_bf16(k1, qf[mt][1], z, 0, 0, 0); st[kb] = z; }
;     ...
; #pragma unroll
;         for (int kp = 0; kp < 5; ++kp) {
;             v4u pw; pw.x = cvt_pk_bf16(st[2 * kp][0], st[2 * kp][1]); pw.y = cvt_pk_bf16(st[2 * kp][2], st[2 * kp][3]);
;             if (kp < 4) { pw.z = cvt_pk_bf16(st[(2 * kp + 1) % 9][0], st[(2 * kp + 1) % 9][1]); pw.w = cvt_pk_bf16(st[(2 * kp + 1) % 9][2], st[(2 * kp + 1) % 9][3]); } else { pw.z = 0u; pw.w = 0u; }
;             const bf16x8_t pb = __builtin_bit_cast(bf16x8_t, pw);
; #pragma unroll
;             for (int dt = 0; dt < 4; ++dt) { const LAS unsigned char* vp = lds + ATT_VOFF + (16 * dt + fr) * ATT_VP + (16 * (mt + 2 * kp) + 4 * fq) * 2;
;                 const v2u lo = *(const LAS v2u*)vp; v2u hi = {0u, 0u}; if (kp < 4) hi = *(const LAS v2u*)(vp + 32);
;                 v4u aw; aw.x = lo.x; aw.y = lo.y; aw.z = hi.x; aw.w = hi.y;
;                 o[dt] = __builtin_amdgcn_mfma_f32_16x16x32_bf16(__builtin_bit_cast(bf16x8_t, aw), pb, o[dt], 0, 0, 0); }
;         }
; #pragma unroll
;         for (int dt = 0; dt < 4; ++dt) { const f32x4 y = o[dt] * inv; v2u w; w.x = cvt_pk_bf16(y[0], y[1]); w.y = cvt_pk_bf16(y[2], y[3]); *(v2u*)(qbase + (size_t)mt * 16 * 1024 + 16 * dt + 4 * fq) = w; }
	v_mfma_f32_16x16x32_bf16 v[22:25], v[22:25], v[18:21], 0
	ds_read2_b64 v[50:53], v68 offset0:60 offset1:64
	v_exp_f32_e32 v61, v91
	v_pk_add_f32 v[72:73], v[58:59], v[84:85]
	s_waitcnt lgkmcnt(5)
	v_mfma_f32_16x16x32_bf16 v[30:33], v[30:33], v[18:21], 0
	s_waitcnt lgkmcnt(4)
	v_mfma_f32_16x16x32_bf16 v[34:37], v[34:37], v[18:21], 0
	s_waitcnt lgkmcnt(3)
	v_mfma_f32_16x16x32_bf16 v[18:21], v[38:41], v[18:21], 0
	ds_read2_b64 v[38:41], v69 offset0:124 offset1:128
	s_waitcnt lgkmcnt(3)
	v_mfma_f32_16x16x32_bf16 v[22:25], v[46:49], v[42:45], v[22:25]
	v_cvt_pk_bf16_f32 v46, v74, v75
	v_cvt_pk_bf16_f32 v47, v76, v77
	v_cvt_pk_bf16_f32 v48, v78, v79
	v_cvt_pk_bf16_f32 v49, v80, v81
	s_waitcnt lgkmcnt(2)
	v_mfma_f32_16x16x32_bf16 v[26:29], v[26:29], v[42:45], v[34:37]
	v_sub_f32_e32 v77, v89, v90
	v_sub_f32_e32 v78, v88, v90
	v_sub_f32_e32 v79, v87, v90
	ds_read2_b64 v[34:37], v68 offset0:68 offset1:72
	s_waitcnt lgkmcnt(2)
	v_mfma_f32_16x16x32_bf16 v[30:33], v[50:53], v[42:45], v[30:33]
	ds_read2_b64 v[50:53], v67 offset0:36 offset1:40
	v_pk_add_f32 v[74:75], v[60:61], v[82:83]
	s_waitcnt lgkmcnt(2)
	v_mfma_f32_16x16x32_bf16 v[18:21], v[38:41], v[42:45], v[18:21]
	ds_read2_b64 v[38:41], v70 offset0:100 offset1:104
	v_sub_f32_e32 v42, v86, v90
	v_exp_f32_e32 v76, v42
	s_waitcnt lgkmcnt(2)
	v_mfma_f32_16x16x32_bf16 v[30:33], v[34:37], v[46:49], v[30:33]
	ds_read2_b64 v[34:37], v69 offset0:132 offset1:136
	v_cvt_pk_bf16_f32 v42, v56, v57
	v_cvt_pk_bf16_f32 v43, v54, v55
	v_cvt_pk_bf16_f32 v44, v58, v59
	v_cvt_pk_bf16_f32 v45, v60, v61
	s_waitcnt lgkmcnt(1)
	v_mfma_f32_16x16x32_bf16 v[26:29], v[38:41], v[46:49], v[26:29]
	ds_read2_b64 v[38:41], v68 offset0:76 offset1:80
	v_exp_f32_e32 v54, v78
	v_exp_f32_e32 v55, v77
	v_mfma_f32_16x16x32_bf16 v[22:25], v[50:53], v[46:49], v[22:25]
	ds_read2_b64 v[50:53], v67 offset0:44 offset1:48
	v_exp_f32_e32 v77, v79
	s_waitcnt lgkmcnt(2)
	v_mfma_f32_16x16x32_bf16 v[18:21], v[34:37], v[46:49], v[18:21]
	ds_read2_b64 v[34:37], v70 offset0:108 offset1:112
	v_pk_add_f32 v[46:47], v[54:55], v[74:75]
	v_pk_add_f32 v[48:49], v[76:77], v[72:73]
	s_waitcnt lgkmcnt(2)
	v_mfma_f32_16x16x32_bf16 v[30:33], v[38:41], v[42:45], v[30:33]
	ds_read2_b64 v[38:41], v69 offset0:140 offset1:144
	s_waitcnt lgkmcnt(2)
	v_mfma_f32_16x16x32_bf16 v[22:25], v[50:53], v[42:45], v[22:25]
	v_pk_mov_b32 v[50:51], v[48:49], v[46:47] op_sel:[1,0]
	v_mov_b32_e32 v49, v47
	v_pk_add_f32 v[46:47], v[50:51], v[48:49]
	s_waitcnt lgkmcnt(1)
	v_mfma_f32_16x16x32_bf16 v[26:29], v[34:37], v[42:45], v[26:29]
	v_add_f32_e32 v46, v46, v47
	ds_bpermute_b32 v34, v65, v46
	v_mov_b32_e32 v36, v147
	s_waitcnt lgkmcnt(1)
	v_mfma_f32_16x16x32_bf16 v[18:21], v[38:41], v[42:45], v[18:21]
	v_mov_b32_e32 v40, v147
	v_mov_b32_e32 v41, v147
	s_waitcnt lgkmcnt(0)
	v_add_f32_e32 v52, v46, v34
	v_cvt_pk_bf16_f32 v34, v76, v77
	v_cvt_pk_bf16_f32 v35, v54, v55
	ds_read_b64 v[38:39], v180 offset:37280
	ds_read_b64 v[42:43], v180 offset:45728
	v_mov_b32_e32 v37, v147
	v_mov_b32_e32 v44, v147
	v_mov_b32_e32 v45, v147
	s_waitcnt lgkmcnt(1)
	v_mfma_f32_16x16x32_bf16 v[22:25], v[38:41], v[34:37], v[22:25]
	ds_bpermute_b32 v38, v66, v52
	v_fma_f32 v39, v64, s62, -v90
	v_exp_f32_e32 v39, v39
	ds_read_b64 v[46:47], v180 offset:54176
	ds_read_b64 v[50:51], v180 offset:62624
	v_mov_b32_e32 v48, v147
	s_waitcnt lgkmcnt(2)
	v_add_f32_e32 v38, v52, v38
	v_add_f32_e32 v38, v39, v38
	v_mov_b32_e32 v49, v147
	v_mov_b32_e32 v52, v147
	v_mov_b32_e32 v53, v147
	v_div_scale_f32 v39, s[64:65], v38, v38, 1.0
	v_rcp_f32_e32 v40, v39
	v_mfma_f32_16x16x32_bf16 v[30:33], v[42:45], v[34:37], v[30:33]
	s_waitcnt lgkmcnt(1)
	v_mfma_f32_16x16x32_bf16 v[26:29], v[46:49], v[34:37], v[26:29]
	s_waitcnt lgkmcnt(0)
	v_mfma_f32_16x16x32_bf16 v[18:21], v[50:53], v[34:37], v[18:21]
	v_fma_f32 v34, -v39, v40, 1.0
	v_fmac_f32_e32 v40, v34, v40
	v_div_scale_f32 v34, vcc, 1.0, v38, 1.0
	v_mul_f32_e32 v35, v34, v40
	v_fma_f32 v36, -v39, v35, v34
	v_fmac_f32_e32 v35, v36, v40
	v_fma_f32 v34, -v39, v35, v34
	v_div_fmas_f32 v34, v34, v40, v35
	v_div_fixup_f32 v34, v34, v38, 1.0
	v_pk_mul_f32 v[24:25], v[34:35], v[24:25] op_sel_hi:[0,1]
	v_pk_mul_f32 v[22:23], v[34:35], v[22:23] op_sel_hi:[0,1]
	v_add_co_u32_e32 v58, vcc, s46, v62
	v_cvt_pk_bf16_f32 v22, v22, v23
	v_cvt_pk_bf16_f32 v23, v24, v25
	v_pk_mul_f32 v[24:25], v[34:35], v[30:31] op_sel_hi:[0,1]
	s_nop 0
	v_addc_co_u32_e32 v59, vcc, 0, v63, vcc
	global_store_dwordx2 v[58:59], v[22:23], off
	v_pk_mul_f32 v[22:23], v[34:35], v[32:33] op_sel_hi:[0,1]
	v_cvt_pk_bf16_f32 v24, v24, v25
	v_cvt_pk_bf16_f32 v25, v22, v23
	global_store_dwordx2 v[58:59], v[24:25], off offset:32
	v_pk_mul_f32 v[24:25], v[34:35], v[26:27] op_sel_hi:[0,1]
	v_pk_mul_f32 v[22:23], v[34:35], v[28:29] op_sel_hi:[0,1]
	v_cvt_pk_bf16_f32 v24, v24, v25
	v_cvt_pk_bf16_f32 v25, v22, v23
	v_pk_mul_f32 v[20:21], v[34:35], v[20:21] op_sel_hi:[0,1]
	v_pk_mul_f32 v[18:19], v[34:35], v[18:19] op_sel_hi:[0,1]
	global_store_dwordx2 v[58:59], v[24:25], off offset:64
	v_cvt_pk_bf16_f32 v60, v18, v19
	v_cvt_pk_bf16_f32 v61, v20, v21
	ds_read_b128 v[18:21], v179 offset:13824
	ds_read_b128 v[22:25], v179 offset:13888
	s_waitcnt lgkmcnt(1)
	v_mfma_f32_16x16x32_bf16 v[18:21], v[18:21], v[10:13], 0
	ds_read_b128 v[26:29], v179 offset:16128
	ds_read_b128 v[30:33], v179 offset:18432
	ds_read_b128 v[34:37], v179 offset:20736
	s_waitcnt lgkmcnt(3)
	v_mfma_f32_16x16x32_bf16 v[22:25], v[22:25], v[14:17], v[18:21]
	ds_read_b128 v[38:41], v179 offset:23040
	ds_read_b128 v[42:45], v179 offset:25344
	ds_read_b128 v[46:49], v179 offset:27648
	ds_read_b128 v[18:21], v179 offset:16192
	s_waitcnt lgkmcnt(6)
; __device__ __forceinline__ void attn_unit(LAS unsigned char* lds, bf16* Q, const bf16* Kg, const bf16* Vg, const float* snk, int unit, int tid) {
;     ...
;         for (int kb = 0; kb < 9; ++kb) { const LAS unsigned char* kp = lds + (16 * (mt + kb) + fr) * ATT_KP + 16 * fq;
;             const bf16x8_t k0 = *(const LAS bf16x8_t*)kp, k1 = *(const LAS bf16x8_t*)(kp + 64);
;             f32x4 z = {0.f, 0.f, 0.f, 0.f}; z = __builtin_amdgcn_mfma_f32_16x16x32_bf16(k0, qf[mt][0], z, 0, 0, 0); z = __builtin_amdgcn_mfma_f32_16x16x32_bf16(k1, qf[mt][1], z, 0, 0, 0); st[kb] = z; }
;         float mx = sink;
; #pragma unroll
;         for (int kb = 0; kb < 9; ++kb) {
;             const bool tile_ok = (n > 0) || (mt + kb >= 8);
; #pragma unroll
;             for (int i = 0; i < 4; ++i) { const bool ok = tile_ok && (kb == 0 ? lo_ok[i] : (kb == 8 ? !lo_ok[i] : true));
;                 st[kb][i] = ok ? st[kb][i] : -INFINITY; mx = fmaxf(mx, st[kb][i]); }
;         }
;         mx = fmaxf(mx, __shfl_xor(mx, 16)); mx = fmaxf(mx, __shfl_xor(mx, 32));
;         f32x4 ls4 = {0.f, 0.f, 0.f, 0.f};
; #pragma unroll
;         for (int kb = 0; kb < 9; ++kb) { f32x4 d = st[kb] - mx;
; #pragma unroll
;             for (int i = 0; i < 4; ++i) d[i] = __builtin_amdgcn_exp2f(d[i]);
;             st[kb] = d; ls4 = ls4 + d; }
;         float ls = (ls4[0] + ls4[1]) + (ls4[2] + ls4[3]);
;         ls += __shfl_xor(ls, 16); ls += __shfl_xor(ls, 32);
;         const float inv = 1.f / (ls + __builtin_amdgcn_exp2f(sink - mx));
;         f32x4 o[4];
; #pragma unroll
;         for (int dt = 0; dt < 4; ++dt) o[dt] = (f32x4){0.f, 0.f, 0.f, 0.f};
; #pragma unroll
;         for (int kp = 0; kp < 5; ++kp) {
;             v4u pw; pw.x = cvt_pk_bf16(st[2 * kp][0], st[2 * kp][1]); pw.y = cvt_pk_bf16(st[2 * kp][2], st[2 * kp][3]);
;             if (kp < 4) { pw.z = cvt_pk_bf16(st[(2 * kp + 1) % 9][0], st[(2 * kp + 1) % 9][1]); pw.w = cvt_pk_bf16(st[(2 * kp + 1) % 9][2], st[(2 * kp + 1) % 9][3]); } else { pw.z = 0u; pw.w = 0u; }
;             const bf16x8_t pb = __builtin_bit_cast(bf16x8_t, pw);
; #pragma unroll
;             for (int dt = 0; dt < 4; ++dt) { const LAS unsigned char* vp = lds + ATT_VOFF + (16 * dt + fr) * ATT_VP + (16 * (mt + 2 * kp) + 4 * fq) * 2;
;                 const v2u lo = *(const LAS v2u*)vp; v2u hi = {0u, 0u}; if (kp < 4) hi = *(const LAS v2u*)(vp + 32);
	v_mfma_f32_16x16x32_bf16 v[26:29], v[26:29], v[10:13], 0
	ds_read_b128 v[50:53], v179 offset:29952
	ds_read_b128 v[54:57], v179 offset:32256
	global_store_dwordx2 v[58:59], v[60:61], off offset:96
	s_waitcnt lgkmcnt(2)
	v_mfma_f32_16x16x32_bf16 v[26:29], v[18:21], v[14:17], v[26:29]
	ds_read_b128 v[18:21], v179 offset:18496
	v_mfma_f32_16x16x32_bf16 v[30:33], v[30:33], v[10:13], 0
	s_waitcnt lgkmcnt(0)
	v_mfma_f32_16x16x32_bf16 v[30:33], v[18:21], v[14:17], v[30:33]
	ds_read_b128 v[18:21], v179 offset:20800
	v_mfma_f32_16x16x32_bf16 v[34:37], v[34:37], v[10:13], 0
	s_waitcnt lgkmcnt(0)
	v_mfma_f32_16x16x32_bf16 v[34:37], v[18:21], v[14:17], v[34:37]
	ds_read_b128 v[18:21], v179 offset:23104
	v_mfma_f32_16x16x32_bf16 v[38:41], v[38:41], v[10:13], 0
	s_waitcnt lgkmcnt(0)
	v_mfma_f32_16x16x32_bf16 v[38:41], v[18:21], v[14:17], v[38:41]
	ds_read_b128 v[18:21], v179 offset:25408
	v_mfma_f32_16x16x32_bf16 v[42:45], v[42:45], v[10:13], 0
	s_waitcnt lgkmcnt(0)
	v_mfma_f32_16x16x32_bf16 v[42:45], v[18:21], v[14:17], v[42:45]
	ds_read_b128 v[18:21], v179 offset:27712
	v_mfma_f32_16x16x32_bf16 v[46:49], v[46:49], v[10:13], 0
	s_waitcnt lgkmcnt(0)
	v_mfma_f32_16x16x32_bf16 v[46:49], v[18:21], v[14:17], v[46:49]
	ds_read_b128 v[18:21], v179 offset:30016
	v_mfma_f32_16x16x32_bf16 v[50:53], v[50:53], v[10:13], 0
	s_waitcnt lgkmcnt(0)
	v_mfma_f32_16x16x32_bf16 v[18:21], v[18:21], v[14:17], v[50:53]
	s_nop 5
	ds_read_b128 v[50:53], v179 offset:32320
	v_mfma_f32_16x16x32_bf16 v[10:13], v[54:57], v[10:13], 0
	s_waitcnt lgkmcnt(0)
	v_mfma_f32_16x16x32_bf16 v[10:13], v[50:53], v[14:17], v[10:13]
	v_cndmask_b32_e64 v15, v23, v191, s[8:9]
	v_cndmask_b32_e64 v14, v191, v22, s[18:19]
	v_cndmask_b32_e64 v15, v191, v15, s[14:15]
	v_max3_f32 v16, v71, v14, v15
	v_cndmask_b32_e64 v17, v191, v24, s[16:17]
	v_cndmask_b32_e64 v22, v191, v25, s[20:21]
	v_max3_f32 v16, v16, v17, v22
	v_cndmask_b32_e64 v23, v191, v26, s[14:15]
	v_cndmask_b32_e64 v24, v191, v27, s[14:15]
	v_max3_f32 v16, v16, v23, v24
	v_cndmask_b32_e64 v25, v191, v28, s[14:15]
	v_cndmask_b32_e64 v26, v191, v29, s[14:15]
	v_max3_f32 v16, v16, v25, v26
	v_max3_f32 v16, v16, v30, v31
	v_max3_f32 v16, v16, v32, v33
	v_max3_f32 v16, v16, v34, v35
	v_max3_f32 v16, v16, v36, v37
	v_max3_f32 v16, v16, v38, v39
	v_max3_f32 v16, v16, v40, v41
	v_max3_f32 v16, v16, v42, v43
	v_max3_f32 v16, v16, v44, v45
	v_max3_f32 v16, v16, v46, v47
	v_max3_f32 v16, v16, v48, v49
	v_max3_f32 v16, v16, v18, v19
	v_max3_f32 v16, v16, v20, v21
	v_cndmask_b32_e64 v78, v10, v191, s[6:7]
	v_cndmask_b32_e64 v79, v191, v11, s[8:9]
	v_max3_f32 v10, v16, v78, v79
	v_cndmask_b32_e64 v80, v12, v191, s[10:11]
	v_cndmask_b32_e64 v81, v13, v191, s[12:13]
	v_max3_f32 v10, v10, v80, v81
	ds_bpermute_b32 v11, v65, v10
	s_waitcnt lgkmcnt(0)
	v_max_f32_e32 v11, v11, v11
	v_max_f32_e32 v10, v10, v11
	ds_bpermute_b32 v11, v66, v10
	s_waitcnt lgkmcnt(0)
	v_max_f32_e32 v11, v11, v11
	v_max_f32_e32 v82, v10, v11
	v_sub_f32_e32 v11, v22, v82
	v_sub_f32_e32 v12, v17, v82
	v_sub_f32_e32 v15, v15, v82
	v_sub_f32_e32 v10, v14, v82
	v_exp_f32_e32 v10, v10
	v_exp_f32_e32 v12, v12
	v_exp_f32_e32 v13, v11
	v_exp_f32_e32 v11, v15
	v_sub_f32_e32 v26, v26, v82
	v_sub_f32_e32 v25, v25, v82
	v_sub_f32_e32 v24, v24, v82
	v_sub_f32_e32 v22, v23, v82
	v_exp_f32_e32 v22, v22
	v_exp_f32_e32 v23, v24
	v_exp_f32_e32 v24, v25
	v_exp_f32_e32 v25, v26
	v_sub_f32_e32 v26, v33, v82
	v_sub_f32_e32 v27, v32, v82
	v_sub_f32_e32 v28, v31, v82
	v_sub_f32_e32 v29, v30, v82
	v_exp_f32_e32 v50, v29
	v_exp_f32_e32 v52, v27
	v_exp_f32_e32 v53, v26
	v_exp_f32_e32 v51, v28
	v_sub_f32_e32 v26, v37, v82
	v_sub_f32_e32 v27, v36, v82
	v_sub_f32_e32 v28, v35, v82
	v_sub_f32_e32 v29, v34, v82
	v_exp_f32_e32 v36, v29
	v_exp_f32_e32 v37, v28
	v_exp_f32_e32 v54, v27
	v_exp_f32_e32 v55, v26
	v_sub_f32_e32 v26, v41, v82
	v_sub_f32_e32 v27, v40, v82
	v_sub_f32_e32 v28, v39, v82
	v_sub_f32_e32 v29, v38, v82
	v_pk_add_f32 v[14:15], v[12:13], 0 op_sel_hi:[1,0]
	v_pk_add_f32 v[16:17], v[10:11], 0 op_sel_hi:[1,0]
	v_exp_f32_e32 v56, v29
	v_exp_f32_e32 v58, v27
	v_exp_f32_e32 v59, v26
	v_exp_f32_e32 v57, v28
	v_pk_add_f32 v[16:17], v[22:23], v[16:17]
	v_pk_add_f32 v[14:15], v[24:25], v[14:15]
	v_pk_add_f32 v[16:17], v[50:51], v[16:17]
	v_pk_add_f32 v[14:15], v[52:53], v[14:15]
	v_pk_add_f32 v[16:17], v[36:37], v[16:17]
	v_pk_add_f32 v[14:15], v[54:55], v[14:15]
	v_sub_f32_e32 v28, v42, v82
	v_pk_add_f32 v[26:27], v[58:59], v[14:15]
	v_pk_add_f32 v[14:15], v[56:57], v[16:17]
	v_sub_f32_e32 v17, v43, v82
	v_sub_f32_e32 v16, v45, v82
	v_exp_f32_e32 v61, v17
	v_sub_f32_e32 v17, v44, v82
	v_exp_f32_e32 v60, v28
	v_exp_f32_e32 v72, v17
	v_exp_f32_e32 v73, v16
	v_sub_f32_e32 v30, v49, v82
	v_sub_f32_e32 v31, v48, v82
	v_sub_f32_e32 v32, v47, v82
	v_sub_f32_e32 v33, v46, v82
	v_exp_f32_e32 v46, v31
	v_exp_f32_e32 v47, v30
	v_exp_f32_e32 v48, v33
	v_exp_f32_e32 v49, v32
	v_pk_add_f32 v[28:29], v[60:61], v[14:15]
	v_pk_add_f32 v[26:27], v[72:73], v[26:27]
	v_cvt_pk_bf16_f32 v10, v10, v11
	v_cvt_pk_bf16_f32 v11, v12, v13
	v_cvt_pk_bf16_f32 v12, v22, v23
	v_cvt_pk_bf16_f32 v13, v24, v25
	ds_read2_b64 v[14:17], v67 offset0:24 offset1:28
	ds_read2_b64 v[22:25], v68 offset0:56 offset1:60
	v_pk_add_f32 v[74:75], v[46:47], v[26:27]
	v_pk_add_f32 v[76:77], v[48:49], v[28:29]
	ds_read2_b64 v[26:29], v70 offset0:88 offset1:92
	ds_read2_b64 v[30:33], v69 offset0:120 offset1:124
	v_sub_f32_e32 v20, v20, v82
	v_sub_f32_e32 v19, v19, v82
	v_sub_f32_e32 v18, v18, v82
	v_sub_f32_e32 v83, v21, v82
	v_cvt_pk_bf16_f32 v34, v50, v51
	v_cvt_pk_bf16_f32 v35, v52, v53
	v_cvt_pk_bf16_f32 v36, v36, v37
	v_cvt_pk_bf16_f32 v37, v54, v55
	ds_read2_b64 v[38:41], v67 offset0:32 offset1:36
	v_exp_f32_e32 v50, v18
	v_exp_f32_e32 v51, v19
	v_exp_f32_e32 v52, v20
	ds_read2_b64 v[18:21], v70 offset0:96 offset1:100
	s_waitcnt lgkmcnt(5)
; __device__ __forceinline__ unsigned cvt_pk_bf16(float lo, float hi) { unsigned r; asm volatile("v_cvt_pk_bf16_f32 %0, %1, %2" : "=v"(r) : "v"(lo), "v"(hi)); return r; }
; #define LAS __attribute__((address_space(3)))
; __device__ __forceinline__ void attn_unit(LAS unsigned char* lds, bf16* Q, const bf16* Kg, const bf16* Vg, const float* snk, int unit, int tid) {
;     ...
;         for (int kb = 0; kb < 9; ++kb) { const LAS unsigned char* kp = lds + (16 * (mt + kb) + fr) * ATT_KP + 16 * fq;
;             const bf16x8_t k0 = *(const LAS bf16x8_t*)kp, k1 = *(const LAS bf16x8_t*)(kp + 64);
;             f32x4 z = {0.f, 0.f, 0.f, 0.f}; z = __builtin_amdgcn_mfma_f32_16x16x32_bf16(k0, qf[mt][0], z, 0, 0, 0); z = __builtin_amdgcn_mfma_f32_16x16x32_bf16(k1, qf[mt][1], z, 0, 0, 0); st[kb] = z; }
;     ...
; #pragma unroll
;         for (int kp = 0; kp < 5; ++kp) {
;             v4u pw; pw.x = cvt_pk_bf16(st[2 * kp][0], st[2 * kp][1]); pw.y = cvt_pk_bf16(st[2 * kp][2], st[2 * kp][3]);
;             if (kp < 4) { pw.z = cvt_pk_bf16(st[(2 * kp + 1) % 9][0], st[(2 * kp + 1) % 9][1]); pw.w = cvt_pk_bf16(st[(2 * kp + 1) % 9][2], st[(2 * kp + 1) % 9][3]); } else { pw.z = 0u; pw.w = 0u; }
;             const bf16x8_t pb = __builtin_bit_cast(bf16x8_t, pw);
; #pragma unroll
;             for (int dt = 0; dt < 4; ++dt) { const LAS unsigned char* vp = lds + ATT_VOFF + (16 * dt + fr) * ATT_VP + (16 * (mt + 2 * kp) + 4 * fq) * 2;
;                 const v2u lo = *(const LAS v2u*)vp; v2u hi = {0u, 0u}; if (kp < 4) hi = *(const LAS v2u*)(vp + 32);
;                 v4u aw; aw.x = lo.x; aw.y = lo.y; aw.z = hi.x; aw.w = hi.y;
;                 o[dt] = __builtin_amdgcn_mfma_f32_16x16x32_bf16(__builtin_bit_cast(bf16x8_t, aw), pb, o[dt], 0, 0, 0); }
;         }
; #pragma unroll
;         for (int dt = 0; dt < 4; ++dt) { const f32x4 y = o[dt] * inv; v2u w; w.x = cvt_pk_bf16(y[0], y[1]); w.y = cvt_pk_bf16(y[2], y[3]); *(v2u*)(qbase + (size_t)mt * 16 * 1024 + 16 * dt + 4 * fq) = w; }
	v_mfma_f32_16x16x32_bf16 v[14:17], v[14:17], v[10:13], 0
	ds_read2_b64 v[42:45], v68 offset0:64 offset1:68
	v_exp_f32_e32 v53, v83
	v_pk_add_f32 v[54:55], v[50:51], v[76:77]
	s_waitcnt lgkmcnt(5)
	v_mfma_f32_16x16x32_bf16 v[22:25], v[22:25], v[10:13], 0
	s_waitcnt lgkmcnt(4)
	v_mfma_f32_16x16x32_bf16 v[26:29], v[26:29], v[10:13], 0
	s_waitcnt lgkmcnt(3)
	v_mfma_f32_16x16x32_bf16 v[10:13], v[30:33], v[10:13], 0
	ds_read2_b64 v[30:33], v69 offset0:128 offset1:132
	s_waitcnt lgkmcnt(3)
	v_mfma_f32_16x16x32_bf16 v[14:17], v[38:41], v[34:37], v[14:17]
	v_cvt_pk_bf16_f32 v38, v56, v57
	v_cvt_pk_bf16_f32 v39, v58, v59
	v_cvt_pk_bf16_f32 v40, v60, v61
	v_cvt_pk_bf16_f32 v41, v72, v73
	s_waitcnt lgkmcnt(2)
	v_mfma_f32_16x16x32_bf16 v[18:21], v[18:21], v[34:37], v[26:29]
	v_sub_f32_e32 v59, v81, v82
	v_sub_f32_e32 v60, v80, v82
	v_sub_f32_e32 v61, v79, v82
	ds_read2_b64 v[26:29], v68 offset0:72 offset1:76
	s_waitcnt lgkmcnt(2)
	v_mfma_f32_16x16x32_bf16 v[22:25], v[42:45], v[34:37], v[22:25]
	ds_read2_b64 v[42:45], v67 offset0:40 offset1:44
	v_pk_add_f32 v[56:57], v[52:53], v[74:75]
	s_waitcnt lgkmcnt(2)
	v_mfma_f32_16x16x32_bf16 v[10:13], v[30:33], v[34:37], v[10:13]
	ds_read2_b64 v[30:33], v70 offset0:104 offset1:108
	v_sub_f32_e32 v34, v78, v82
	v_exp_f32_e32 v58, v34
	s_waitcnt lgkmcnt(2)
	v_mfma_f32_16x16x32_bf16 v[22:25], v[26:29], v[38:41], v[22:25]
	ds_read2_b64 v[26:29], v69 offset0:136 offset1:140
	v_cvt_pk_bf16_f32 v34, v48, v49
	v_cvt_pk_bf16_f32 v35, v46, v47
	v_cvt_pk_bf16_f32 v36, v50, v51
	v_cvt_pk_bf16_f32 v37, v52, v53
	s_waitcnt lgkmcnt(1)
	v_mfma_f32_16x16x32_bf16 v[18:21], v[30:33], v[38:41], v[18:21]
	ds_read2_b64 v[30:33], v68 offset0:80 offset1:84
	v_exp_f32_e32 v46, v60
	v_exp_f32_e32 v47, v59
	v_mfma_f32_16x16x32_bf16 v[14:17], v[42:45], v[38:41], v[14:17]
	ds_read2_b64 v[42:45], v67 offset0:48 offset1:52
	v_exp_f32_e32 v59, v61
	s_waitcnt lgkmcnt(2)
	v_mfma_f32_16x16x32_bf16 v[10:13], v[26:29], v[38:41], v[10:13]
	ds_read2_b64 v[26:29], v70 offset0:112 offset1:116
	v_pk_add_f32 v[38:39], v[46:47], v[56:57]
	v_pk_add_f32 v[40:41], v[58:59], v[54:55]
	s_waitcnt lgkmcnt(2)
	v_mfma_f32_16x16x32_bf16 v[22:25], v[30:33], v[34:37], v[22:25]
	ds_read2_b64 v[30:33], v69 offset0:144 offset1:148
	s_waitcnt lgkmcnt(2)
	v_mfma_f32_16x16x32_bf16 v[14:17], v[42:45], v[34:37], v[14:17]
	v_pk_mov_b32 v[42:43], v[40:41], v[38:39] op_sel:[1,0]
	v_mov_b32_e32 v41, v39
	v_pk_add_f32 v[38:39], v[42:43], v[40:41]
	s_waitcnt lgkmcnt(1)
	v_mfma_f32_16x16x32_bf16 v[18:21], v[26:29], v[34:37], v[18:21]
	v_add_f32_e32 v38, v38, v39
	ds_bpermute_b32 v26, v65, v38
	v_mov_b32_e32 v28, v147
	s_waitcnt lgkmcnt(1)
	v_mfma_f32_16x16x32_bf16 v[10:13], v[30:33], v[34:37], v[10:13]
	v_mov_b32_e32 v32, v147
	v_mov_b32_e32 v33, v147
	s_waitcnt lgkmcnt(0)
	v_add_f32_e32 v44, v38, v26
	v_cvt_pk_bf16_f32 v26, v58, v59
	v_cvt_pk_bf16_f32 v27, v46, v47
	ds_read_b64 v[30:31], v180 offset:37312
	ds_read_b64 v[34:35], v180 offset:45760
	v_mov_b32_e32 v29, v147
	v_mov_b32_e32 v36, v147
	v_mov_b32_e32 v37, v147
	s_waitcnt lgkmcnt(1)
	v_mfma_f32_16x16x32_bf16 v[14:17], v[30:33], v[26:29], v[14:17]
	ds_bpermute_b32 v30, v66, v44
	v_fma_f32 v31, v64, s62, -v82
	v_exp_f32_e32 v31, v31
	ds_read_b64 v[38:39], v180 offset:54208
	ds_read_b64 v[42:43], v180 offset:62656
	v_mov_b32_e32 v40, v147
	s_waitcnt lgkmcnt(2)
	v_add_f32_e32 v30, v44, v30
	v_add_f32_e32 v30, v31, v30
	v_mov_b32_e32 v41, v147
	v_mov_b32_e32 v44, v147
	v_mov_b32_e32 v45, v147
	v_div_scale_f32 v31, s[64:65], v30, v30, 1.0
	v_rcp_f32_e32 v32, v31
	v_mfma_f32_16x16x32_bf16 v[22:25], v[34:37], v[26:29], v[22:25]
	s_waitcnt lgkmcnt(1)
	v_mfma_f32_16x16x32_bf16 v[18:21], v[38:41], v[26:29], v[18:21]
	s_waitcnt lgkmcnt(0)
	v_mfma_f32_16x16x32_bf16 v[10:13], v[42:45], v[26:29], v[10:13]
	v_fma_f32 v26, -v31, v32, 1.0
	v_fmac_f32_e32 v32, v26, v32
	v_div_scale_f32 v26, vcc, 1.0, v30, 1.0
	v_mul_f32_e32 v27, v26, v32
	v_fma_f32 v28, -v31, v27, v26
	v_fmac_f32_e32 v27, v28, v32
	v_fma_f32 v26, -v31, v27, v26
	v_div_fmas_f32 v26, v26, v32, v27
	v_div_fixup_f32 v26, v26, v30, 1.0
	v_pk_mul_f32 v[16:17], v[26:27], v[16:17] op_sel_hi:[0,1]
	v_pk_mul_f32 v[14:15], v[26:27], v[14:15] op_sel_hi:[0,1]
	v_add_co_u32_e32 v50, vcc, s47, v62
	v_cvt_pk_bf16_f32 v14, v14, v15
	v_cvt_pk_bf16_f32 v15, v16, v17
	v_pk_mul_f32 v[16:17], v[26:27], v[22:23] op_sel_hi:[0,1]
	s_nop 0
	v_addc_co_u32_e32 v51, vcc, 0, v63, vcc
	global_store_dwordx2 v[50:51], v[14:15], off
	v_pk_mul_f32 v[14:15], v[26:27], v[24:25] op_sel_hi:[0,1]
	v_cvt_pk_bf16_f32 v16, v16, v17
	v_cvt_pk_bf16_f32 v17, v14, v15
	global_store_dwordx2 v[50:51], v[16:17], off offset:32
	v_pk_mul_f32 v[16:17], v[26:27], v[18:19] op_sel_hi:[0,1]
	v_pk_mul_f32 v[14:15], v[26:27], v[20:21] op_sel_hi:[0,1]
	v_cvt_pk_bf16_f32 v16, v16, v17
	v_cvt_pk_bf16_f32 v17, v14, v15
	v_pk_mul_f32 v[12:13], v[26:27], v[12:13] op_sel_hi:[0,1]
	v_pk_mul_f32 v[10:11], v[26:27], v[10:11] op_sel_hi:[0,1]
	global_store_dwordx2 v[50:51], v[16:17], off offset:64
	v_cvt_pk_bf16_f32 v52, v10, v11
	v_cvt_pk_bf16_f32 v53, v12, v13
	ds_read_b128 v[10:13], v179 offset:16128
	ds_read_b128 v[14:17], v179 offset:16192
	s_waitcnt lgkmcnt(1)
	v_mfma_f32_16x16x32_bf16 v[10:13], v[10:13], v[2:5], 0
	ds_read_b128 v[18:21], v179 offset:18432
	ds_read_b128 v[22:25], v179 offset:20736
	ds_read_b128 v[26:29], v179 offset:23040
	s_waitcnt lgkmcnt(3)
	v_mfma_f32_16x16x32_bf16 v[14:17], v[14:17], v[6:9], v[10:13]
	ds_read_b128 v[30:33], v179 offset:25344
	ds_read_b128 v[34:37], v179 offset:27648
	ds_read_b128 v[38:41], v179 offset:29952
	ds_read_b128 v[10:13], v179 offset:18496
	s_waitcnt lgkmcnt(6)
; __device__ __forceinline__ void attn_unit(LAS unsigned char* lds, bf16* Q, const bf16* Kg, const bf16* Vg, const float* snk, int unit, int tid) {
;     ...
;         for (int kb = 0; kb < 9; ++kb) { const LAS unsigned char* kp = lds + (16 * (mt + kb) + fr) * ATT_KP + 16 * fq;
;             const bf16x8_t k0 = *(const LAS bf16x8_t*)kp, k1 = *(const LAS bf16x8_t*)(kp + 64);
;             f32x4 z = {0.f, 0.f, 0.f, 0.f}; z = __builtin_amdgcn_mfma_f32_16x16x32_bf16(k0, qf[mt][0], z, 0, 0, 0); z = __builtin_amdgcn_mfma_f32_16x16x32_bf16(k1, qf[mt][1], z, 0, 0, 0); st[kb] = z; }
;         float mx = sink;
; #pragma unroll
;         for (int kb = 0; kb < 9; ++kb) {
;             const bool tile_ok = (n > 0) || (mt + kb >= 8);
; #pragma unroll
;             for (int i = 0; i < 4; ++i) { const bool ok = tile_ok && (kb == 0 ? lo_ok[i] : (kb == 8 ? !lo_ok[i] : true));
;                 st[kb][i] = ok ? st[kb][i] : -INFINITY; mx = fmaxf(mx, st[kb][i]); }
;         }
;         mx = fmaxf(mx, __shfl_xor(mx, 16)); mx = fmaxf(mx, __shfl_xor(mx, 32));
;         f32x4 ls4 = {0.f, 0.f, 0.f, 0.f};
; #pragma unroll
;         for (int kb = 0; kb < 9; ++kb) { f32x4 d = st[kb] - mx;
; #pragma unroll
;             for (int i = 0; i < 4; ++i) d[i] = __builtin_amdgcn_exp2f(d[i]);
;             st[kb] = d; ls4 = ls4 + d; }
;         float ls = (ls4[0] + ls4[1]) + (ls4[2] + ls4[3]);
;         ls += __shfl_xor(ls, 16); ls += __shfl_xor(ls, 32);
;         const float inv = 1.f / (ls + __builtin_amdgcn_exp2f(sink - mx));
;         f32x4 o[4];
; #pragma unroll
;         for (int dt = 0; dt < 4; ++dt) o[dt] = (f32x4){0.f, 0.f, 0.f, 0.f};
; #pragma unroll
;         for (int kp = 0; kp < 5; ++kp) {
;             v4u pw; pw.x = cvt_pk_bf16(st[2 * kp][0], st[2 * kp][1]); pw.y = cvt_pk_bf16(st[2 * kp][2], st[2 * kp][3]);
;             if (kp < 4) { pw.z = cvt_pk_bf16(st[(2 * kp + 1) % 9][0], st[(2 * kp + 1) % 9][1]); pw.w = cvt_pk_bf16(st[(2 * kp + 1) % 9][2], st[(2 * kp + 1) % 9][3]); } else { pw.z = 0u; pw.w = 0u; }
;             const bf16x8_t pb = __builtin_bit_cast(bf16x8_t, pw);
; #pragma unroll
;             for (int dt = 0; dt < 4; ++dt) { const LAS unsigned char* vp = lds + ATT_VOFF + (16 * dt + fr) * ATT_VP + (16 * (mt + 2 * kp) + 4 * fq) * 2;
;                 const v2u lo = *(const LAS v2u*)vp; v2u hi = {0u, 0u}; if (kp < 4) hi = *(const LAS v2u*)(vp + 32);
	v_mfma_f32_16x16x32_bf16 v[18:21], v[18:21], v[2:5], 0
	ds_read_b128 v[42:45], v179 offset:32256
	ds_read_b128 v[46:49], v179 offset:34560
	global_store_dwordx2 v[50:51], v[52:53], off offset:96
	s_waitcnt lgkmcnt(2)
	v_mfma_f32_16x16x32_bf16 v[18:21], v[10:13], v[6:9], v[18:21]
	ds_read_b128 v[10:13], v179 offset:20800
	v_mfma_f32_16x16x32_bf16 v[22:25], v[22:25], v[2:5], 0
	s_waitcnt lgkmcnt(0)
	v_mfma_f32_16x16x32_bf16 v[22:25], v[10:13], v[6:9], v[22:25]
	ds_read_b128 v[10:13], v179 offset:23104
	v_mfma_f32_16x16x32_bf16 v[26:29], v[26:29], v[2:5], 0
	s_waitcnt lgkmcnt(0)
	v_mfma_f32_16x16x32_bf16 v[26:29], v[10:13], v[6:9], v[26:29]
	ds_read_b128 v[10:13], v179 offset:25408
	v_mfma_f32_16x16x32_bf16 v[30:33], v[30:33], v[2:5], 0
	s_waitcnt lgkmcnt(0)
	v_mfma_f32_16x16x32_bf16 v[30:33], v[10:13], v[6:9], v[30:33]
	ds_read_b128 v[10:13], v179 offset:27712
	v_mfma_f32_16x16x32_bf16 v[34:37], v[34:37], v[2:5], 0
	s_waitcnt lgkmcnt(0)
	v_mfma_f32_16x16x32_bf16 v[34:37], v[10:13], v[6:9], v[34:37]
	ds_read_b128 v[10:13], v179 offset:30016
	v_mfma_f32_16x16x32_bf16 v[38:41], v[38:41], v[2:5], 0
	s_waitcnt lgkmcnt(0)
	v_mfma_f32_16x16x32_bf16 v[38:41], v[10:13], v[6:9], v[38:41]
	ds_read_b128 v[10:13], v179 offset:32320
	v_mfma_f32_16x16x32_bf16 v[42:45], v[42:45], v[2:5], 0
	s_waitcnt lgkmcnt(0)
	v_mfma_f32_16x16x32_bf16 v[10:13], v[10:13], v[6:9], v[42:45]
	s_nop 5
	ds_read_b128 v[42:45], v179 offset:34624
	v_mfma_f32_16x16x32_bf16 v[2:5], v[46:49], v[2:5], 0
	s_waitcnt lgkmcnt(0)
	v_mfma_f32_16x16x32_bf16 v[2:5], v[42:45], v[6:9], v[2:5]
	v_cndmask_b32_e64 v7, v15, v191, s[8:9]
	v_cndmask_b32_e64 v6, v191, v14, s[18:19]
	v_cndmask_b32_e64 v7, v191, v7, s[14:15]
	v_max3_f32 v8, v71, v6, v7
	v_cndmask_b32_e64 v9, v191, v16, s[16:17]
	v_cndmask_b32_e64 v14, v191, v17, s[20:21]
	v_max3_f32 v8, v8, v9, v14
	v_max3_f32 v8, v8, v18, v19
	v_max3_f32 v8, v8, v20, v21
	v_max3_f32 v8, v8, v22, v23
	v_max3_f32 v8, v8, v24, v25
	v_max3_f32 v8, v8, v26, v27
	v_max3_f32 v8, v8, v28, v29
	v_max3_f32 v8, v8, v30, v31
	v_max3_f32 v8, v8, v32, v33
	v_max3_f32 v8, v8, v34, v35
	v_max3_f32 v8, v8, v36, v37
	v_max3_f32 v8, v8, v38, v39
	v_max3_f32 v8, v8, v40, v41
	v_max3_f32 v8, v8, v10, v11
	v_max3_f32 v8, v8, v12, v13
	v_cndmask_b32_e64 v60, v2, v191, s[6:7]
	v_cndmask_b32_e64 v61, v191, v3, s[8:9]
	v_max3_f32 v2, v8, v60, v61
	v_cndmask_b32_e64 v71, v4, v191, s[10:11]
	v_cndmask_b32_e64 v72, v5, v191, s[12:13]
	v_max3_f32 v2, v2, v71, v72
	ds_bpermute_b32 v3, v65, v2
	s_waitcnt lgkmcnt(0)
	v_max_f32_e32 v3, v3, v3
	v_max_f32_e32 v2, v2, v3
	ds_bpermute_b32 v3, v66, v2
	s_waitcnt lgkmcnt(0)
	v_max_f32_e32 v3, v3, v3
	v_max_f32_e32 v73, v2, v3
	v_sub_f32_e32 v3, v14, v73
	v_sub_f32_e32 v4, v9, v73
	v_sub_f32_e32 v7, v7, v73
	v_sub_f32_e32 v2, v6, v73
	v_exp_f32_e32 v2, v2
	v_exp_f32_e32 v4, v4
	v_exp_f32_e32 v5, v3
	v_exp_f32_e32 v3, v7
	v_sub_f32_e32 v17, v21, v73
	v_sub_f32_e32 v16, v20, v73
	v_sub_f32_e32 v15, v19, v73
	v_sub_f32_e32 v14, v18, v73
	v_exp_f32_e32 v14, v14
	v_exp_f32_e32 v15, v15
	v_exp_f32_e32 v16, v16
	v_exp_f32_e32 v17, v17
	v_sub_f32_e32 v18, v25, v73
	v_sub_f32_e32 v19, v24, v73
	v_sub_f32_e32 v20, v23, v73
	v_sub_f32_e32 v21, v22, v73
	v_exp_f32_e32 v42, v21
	v_exp_f32_e32 v44, v19
	v_exp_f32_e32 v45, v18
	v_exp_f32_e32 v43, v20
	v_sub_f32_e32 v18, v29, v73
	v_sub_f32_e32 v19, v28, v73
	v_sub_f32_e32 v20, v27, v73
	v_sub_f32_e32 v21, v26, v73
	v_exp_f32_e32 v28, v21
	v_exp_f32_e32 v29, v20
	v_exp_f32_e32 v46, v19
	v_exp_f32_e32 v47, v18
	v_sub_f32_e32 v18, v33, v73
	v_sub_f32_e32 v19, v32, v73
	v_sub_f32_e32 v20, v31, v73
	v_sub_f32_e32 v21, v30, v73
	v_pk_add_f32 v[6:7], v[4:5], 0 op_sel_hi:[1,0]
	v_pk_add_f32 v[8:9], v[2:3], 0 op_sel_hi:[1,0]
	v_exp_f32_e32 v48, v21
	v_exp_f32_e32 v50, v19
	v_exp_f32_e32 v51, v18
	v_exp_f32_e32 v49, v20
	v_pk_add_f32 v[8:9], v[14:15], v[8:9]
	v_pk_add_f32 v[6:7], v[16:17], v[6:7]
	v_pk_add_f32 v[8:9], v[42:43], v[8:9]
	v_pk_add_f32 v[6:7], v[44:45], v[6:7]
	v_pk_add_f32 v[8:9], v[28:29], v[8:9]
	v_pk_add_f32 v[6:7], v[46:47], v[6:7]
	v_sub_f32_e32 v20, v34, v73
	v_pk_add_f32 v[18:19], v[50:51], v[6:7]
	v_pk_add_f32 v[6:7], v[48:49], v[8:9]
	v_sub_f32_e32 v9, v35, v73
	v_sub_f32_e32 v8, v37, v73
	v_exp_f32_e32 v53, v9
	v_sub_f32_e32 v9, v36, v73
	v_exp_f32_e32 v52, v20
	v_exp_f32_e32 v54, v9
	v_exp_f32_e32 v55, v8
	v_sub_f32_e32 v22, v41, v73
	v_sub_f32_e32 v23, v40, v73
	v_sub_f32_e32 v24, v39, v73
	v_sub_f32_e32 v25, v38, v73
	v_exp_f32_e32 v38, v23
	v_exp_f32_e32 v39, v22
	v_exp_f32_e32 v40, v25
	v_exp_f32_e32 v41, v24
	v_pk_add_f32 v[20:21], v[52:53], v[6:7]
	v_pk_add_f32 v[18:19], v[54:55], v[18:19]
	v_cvt_pk_bf16_f32 v2, v2, v3
	v_cvt_pk_bf16_f32 v3, v4, v5
	v_cvt_pk_bf16_f32 v4, v14, v15
	v_cvt_pk_bf16_f32 v5, v16, v17
	ds_read2_b64 v[6:9], v67 offset0:28 offset1:32
	ds_read2_b64 v[14:17], v68 offset0:60 offset1:64
	v_pk_add_f32 v[56:57], v[38:39], v[18:19]
	v_pk_add_f32 v[58:59], v[40:41], v[20:21]
	ds_read2_b64 v[18:21], v70 offset0:92 offset1:96
	ds_read2_b64 v[22:25], v69 offset0:124 offset1:128
	v_sub_f32_e32 v12, v12, v73
	v_sub_f32_e32 v11, v11, v73
	v_sub_f32_e32 v10, v10, v73
	v_sub_f32_e32 v74, v13, v73
	v_cvt_pk_bf16_f32 v26, v42, v43
	v_cvt_pk_bf16_f32 v27, v44, v45
	v_cvt_pk_bf16_f32 v28, v28, v29
	v_cvt_pk_bf16_f32 v29, v46, v47
	ds_read2_b64 v[30:33], v67 offset0:36 offset1:40
	v_exp_f32_e32 v42, v10
	v_exp_f32_e32 v43, v11
	v_exp_f32_e32 v44, v12
	ds_read2_b64 v[10:13], v70 offset0:100 offset1:104
	s_waitcnt lgkmcnt(5)
; __device__ __forceinline__ unsigned cvt_pk_bf16(float lo, float hi) { unsigned r; asm volatile("v_cvt_pk_bf16_f32 %0, %1, %2" : "=v"(r) : "v"(lo), "v"(hi)); return r; }
; #define LAS __attribute__((address_space(3)))
; __device__ __forceinline__ void attn_unit(LAS unsigned char* lds, bf16* Q, const bf16* Kg, const bf16* Vg, const float* snk, int unit, int tid) {
;     ...
; #pragma unroll
;         for (int kp = 0; kp < 5; ++kp) {
;             v4u pw; pw.x = cvt_pk_bf16(st[2 * kp][0], st[2 * kp][1]); pw.y = cvt_pk_bf16(st[2 * kp][2], st[2 * kp][3]);
;             if (kp < 4) { pw.z = cvt_pk_bf16(st[(2 * kp + 1) % 9][0], st[(2 * kp + 1) % 9][1]); pw.w = cvt_pk_bf16(st[(2 * kp + 1) % 9][2], st[(2 * kp + 1) % 9][3]); } else { pw.z = 0u; pw.w = 0u; }
;             const bf16x8_t pb = __builtin_bit_cast(bf16x8_t, pw);
; #pragma unroll
;             for (int dt = 0; dt < 4; ++dt) { const LAS unsigned char* vp = lds + ATT_VOFF + (16 * dt + fr) * ATT_VP + (16 * (mt + 2 * kp) + 4 * fq) * 2;
;                 const v2u lo = *(const LAS v2u*)vp; v2u hi = {0u, 0u}; if (kp < 4) hi = *(const LAS v2u*)(vp + 32);
;                 v4u aw; aw.x = lo.x; aw.y = lo.y; aw.z = hi.x; aw.w = hi.y;
;                 o[dt] = __builtin_amdgcn_mfma_f32_16x16x32_bf16(__builtin_bit_cast(bf16x8_t, aw), pb, o[dt], 0, 0, 0); }
;         }
; #pragma unroll
;         for (int dt = 0; dt < 4; ++dt) { const f32x4 y = o[dt] * inv; v2u w; w.x = cvt_pk_bf16(y[0], y[1]); w.y = cvt_pk_bf16(y[2], y[3]); *(v2u*)(qbase + (size_t)mt * 16 * 1024 + 16 * dt + 4 * fq) = w; }
;     }
;     __syncthreads();
	v_mfma_f32_16x16x32_bf16 v[6:9], v[6:9], v[2:5], 0
	ds_read2_b64 v[34:37], v68 offset0:68 offset1:72
	v_exp_f32_e32 v45, v74
	v_pk_add_f32 v[46:47], v[42:43], v[58:59]
	s_waitcnt lgkmcnt(5)
	v_mfma_f32_16x16x32_bf16 v[14:17], v[14:17], v[2:5], 0
	s_waitcnt lgkmcnt(4)
	v_mfma_f32_16x16x32_bf16 v[18:21], v[18:21], v[2:5], 0
	s_waitcnt lgkmcnt(3)
	v_mfma_f32_16x16x32_bf16 v[2:5], v[22:25], v[2:5], 0
	ds_read2_b64 v[22:25], v69 offset0:132 offset1:136
	s_waitcnt lgkmcnt(3)
	v_mfma_f32_16x16x32_bf16 v[6:9], v[30:33], v[26:29], v[6:9]
	v_cvt_pk_bf16_f32 v30, v48, v49
	v_cvt_pk_bf16_f32 v31, v50, v51
	v_cvt_pk_bf16_f32 v32, v52, v53
	v_cvt_pk_bf16_f32 v33, v54, v55
	s_waitcnt lgkmcnt(2)
	v_mfma_f32_16x16x32_bf16 v[10:13], v[10:13], v[26:29], v[18:21]
	v_sub_f32_e32 v51, v72, v73
	v_sub_f32_e32 v52, v71, v73
	v_sub_f32_e32 v53, v61, v73
	ds_read2_b64 v[18:21], v68 offset0:76 offset1:80
	s_waitcnt lgkmcnt(2)
	v_mfma_f32_16x16x32_bf16 v[14:17], v[34:37], v[26:29], v[14:17]
	ds_read2_b64 v[34:37], v67 offset0:44 offset1:48
	v_pk_add_f32 v[48:49], v[44:45], v[56:57]
	s_waitcnt lgkmcnt(2)
	v_mfma_f32_16x16x32_bf16 v[2:5], v[22:25], v[26:29], v[2:5]
	ds_read2_b64 v[22:25], v70 offset0:108 offset1:112
	v_sub_f32_e32 v26, v60, v73
	v_exp_f32_e32 v50, v26
	s_waitcnt lgkmcnt(2)
	v_mfma_f32_16x16x32_bf16 v[14:17], v[18:21], v[30:33], v[14:17]
	ds_read2_b64 v[18:21], v69 offset0:140 offset1:144
	v_cvt_pk_bf16_f32 v26, v40, v41
	v_cvt_pk_bf16_f32 v27, v38, v39
	v_cvt_pk_bf16_f32 v28, v42, v43
	v_cvt_pk_bf16_f32 v29, v44, v45
	s_waitcnt lgkmcnt(1)
	v_mfma_f32_16x16x32_bf16 v[10:13], v[22:25], v[30:33], v[10:13]
	ds_read2_b64 v[22:25], v68 offset0:84 offset1:88
	v_exp_f32_e32 v38, v52
	v_exp_f32_e32 v39, v51
	v_mfma_f32_16x16x32_bf16 v[6:9], v[34:37], v[30:33], v[6:9]
	ds_read2_b64 v[34:37], v67 offset0:52 offset1:56
	v_exp_f32_e32 v51, v53
	s_waitcnt lgkmcnt(2)
	v_mfma_f32_16x16x32_bf16 v[2:5], v[18:21], v[30:33], v[2:5]
	ds_read2_b64 v[18:21], v70 offset0:116 offset1:120
	v_pk_add_f32 v[30:31], v[38:39], v[48:49]
	v_pk_add_f32 v[32:33], v[50:51], v[46:47]
	s_waitcnt lgkmcnt(2)
	v_mfma_f32_16x16x32_bf16 v[14:17], v[22:25], v[26:29], v[14:17]
	ds_read2_b64 v[22:25], v69 offset0:148 offset1:152
	s_waitcnt lgkmcnt(2)
	v_mfma_f32_16x16x32_bf16 v[6:9], v[34:37], v[26:29], v[6:9]
	v_pk_mov_b32 v[34:35], v[32:33], v[30:31] op_sel:[1,0]
	v_mov_b32_e32 v33, v31
	v_pk_add_f32 v[30:31], v[34:35], v[32:33]
	s_waitcnt lgkmcnt(1)
	v_mfma_f32_16x16x32_bf16 v[10:13], v[18:21], v[26:29], v[10:13]
	v_add_f32_e32 v30, v30, v31
	ds_bpermute_b32 v18, v65, v30
	v_mov_b32_e32 v20, v147
	s_waitcnt lgkmcnt(1)
	v_mfma_f32_16x16x32_bf16 v[2:5], v[22:25], v[26:29], v[2:5]
	v_mov_b32_e32 v24, v147
	v_mov_b32_e32 v25, v147
	s_waitcnt lgkmcnt(0)
	v_add_f32_e32 v36, v30, v18
	v_cvt_pk_bf16_f32 v18, v50, v51
	v_cvt_pk_bf16_f32 v19, v38, v39
	ds_read_b64 v[22:23], v180 offset:37344
	ds_read_b64 v[26:27], v180 offset:45792
	v_mov_b32_e32 v21, v147
	v_mov_b32_e32 v28, v147
	v_mov_b32_e32 v29, v147
	s_waitcnt lgkmcnt(1)
	v_mfma_f32_16x16x32_bf16 v[6:9], v[22:25], v[18:21], v[6:9]
	ds_bpermute_b32 v22, v66, v36
	v_fma_f32 v23, v64, s62, -v73
	v_exp_f32_e32 v23, v23
	ds_read_b64 v[30:31], v180 offset:54240
	ds_read_b64 v[34:35], v180 offset:62688
	v_mov_b32_e32 v32, v147
	s_waitcnt lgkmcnt(2)
	v_add_f32_e32 v22, v36, v22
	v_add_f32_e32 v22, v23, v22
	v_mov_b32_e32 v33, v147
	v_mov_b32_e32 v36, v147
	v_mov_b32_e32 v37, v147
	v_div_scale_f32 v23, s[14:15], v22, v22, 1.0
	v_rcp_f32_e32 v24, v23
	v_mfma_f32_16x16x32_bf16 v[14:17], v[26:29], v[18:21], v[14:17]
	s_waitcnt lgkmcnt(1)
	v_mfma_f32_16x16x32_bf16 v[10:13], v[30:33], v[18:21], v[10:13]
	s_waitcnt lgkmcnt(0)
	v_mfma_f32_16x16x32_bf16 v[2:5], v[34:37], v[18:21], v[2:5]
	v_fma_f32 v18, -v23, v24, 1.0
	v_fmac_f32_e32 v24, v18, v24
	v_div_scale_f32 v18, vcc, 1.0, v22, 1.0
	v_mul_f32_e32 v19, v18, v24
	v_fma_f32 v20, -v23, v19, v18
	v_fmac_f32_e32 v19, v20, v24
	v_fma_f32 v18, -v23, v19, v18
	v_div_fmas_f32 v18, v18, v24, v19
	v_div_fixup_f32 v18, v18, v22, 1.0
	v_pk_mul_f32 v[8:9], v[18:19], v[8:9] op_sel_hi:[0,1]
	v_pk_mul_f32 v[6:7], v[18:19], v[6:7] op_sel_hi:[0,1]
	v_cvt_pk_bf16_f32 v6, v6, v7
	v_cvt_pk_bf16_f32 v7, v8, v9
	v_add_co_u32_e32 v8, vcc, s59, v62
	v_pk_mul_f32 v[14:15], v[18:19], v[14:15] op_sel_hi:[0,1]
	s_nop 0
	v_addc_co_u32_e32 v9, vcc, 0, v63, vcc
	global_store_dwordx2 v[8:9], v[6:7], off
	v_pk_mul_f32 v[6:7], v[18:19], v[16:17] op_sel_hi:[0,1]
	v_pk_mul_f32 v[10:11], v[18:19], v[10:11] op_sel_hi:[0,1]
	v_pk_mul_f32 v[2:3], v[18:19], v[2:3] op_sel_hi:[0,1]
	v_cvt_pk_bf16_f32 v14, v14, v15
	v_cvt_pk_bf16_f32 v15, v6, v7
	global_store_dwordx2 v[8:9], v[14:15], off offset:32
	v_pk_mul_f32 v[6:7], v[18:19], v[12:13] op_sel_hi:[0,1]
	v_cvt_pk_bf16_f32 v10, v10, v11
	v_cvt_pk_bf16_f32 v11, v6, v7
	global_store_dwordx2 v[8:9], v[10:11], off offset:64
	v_pk_mul_f32 v[4:5], v[18:19], v[4:5] op_sel_hi:[0,1]
	v_cvt_pk_bf16_f32 v2, v2, v3
	v_cvt_pk_bf16_f32 v3, v4, v5
	global_store_dwordx2 v[8:9], v[2:3], off offset:96
	s_barrier

; __device__ __forceinline__ void sgu_unit(LAS unsigned char* lds, bf16* U, const bf16* VS, const float* SGS, const float* lnw, const float* lnb, const v4u* WF, const float* bsl, int unit, int tid) {
;     ...
;     v4u wfr[20]; float bbv[8];
; #pragma unroll
;     for (int q = 0; q < 20; ++q) wfr[q] = WF[(size_t)(g * 20 + q) * 64 + lane];
; #pragma unroll
;     for (int mt = 0; mt < 8; ++mt) bbv[mt] = bsl[g * 128 + 16 * mt + fr];
;     if (tid < 128) {
;         const f32x4* p = (const f32x4*)(SGS + (size_t)(r0 + tid) * 32);
;         float s = 0.f, ss = 0.f;
; #pragma unroll
;         for (int k = 0; k < 8; ++k) { const f32x4 v = p[k]; s += v.x + v.z; ss += v.y + v.w; }
;         const float mean = s * (1.f / 1024.f), var = fmaxf(ss * (1.f / 1024.f) - mean * mean, 0.f);
;         stat[2 * tid] = mean; stat[2 * tid + 1] = rsqrtf(var + 1e-6f);
;     }
.LBB0_495:
	s_cmpk_gt_i32 s63, 0xff
	s_mov_b64 s[14:15], -1
	s_cbranch_scc0 .LBB0_499
	s_waitcnt vmcnt(0)
	s_and_b32 s14, s23, 4
	v_add_u32_e32 v82, s14, v165
	v_mul_lo_u32 v2, v82, 20
	v_or_b32_e32 v6, 1, v2
	v_ashrrev_i32_e32 v3, 31, v2
	v_ashrrev_i32_e32 v7, 31, v6
	v_lshlrev_b64 v[4:5], 10, v[2:3]
	v_lshlrev_b64 v[6:7], 10, v[6:7]
	v_lshl_add_u64 v[4:5], v[148:149], 0, v[4:5]
	v_lshl_add_u64 v[6:7], v[148:149], 0, v[6:7]
	global_load_dwordx4 v[78:81], v[4:5], off
	global_load_dwordx4 v[74:77], v[6:7], off
	v_or_b32_e32 v6, 2, v2
	v_or_b32_e32 v2, 3, v2
	v_ashrrev_i32_e32 v7, 31, v6
	v_ashrrev_i32_e32 v3, 31, v2
	v_lshlrev_b64 v[6:7], 10, v[6:7]
	v_lshlrev_b64 v[2:3], 10, v[2:3]
	v_lshl_add_u64 v[6:7], v[148:149], 0, v[6:7]
	v_lshl_add_u64 v[2:3], v[148:149], 0, v[2:3]
	global_load_dwordx4 v[70:73], v[6:7], off
	global_load_dwordx4 v[66:69], v[2:3], off
	v_add_co_u32_e32 v2, vcc, s35, v4
	v_lshlrev_b32_e32 v82, 7, v82
	s_nop 0
	v_addc_co_u32_e32 v3, vcc, 0, v5, vcc
	v_add_co_u32_e32 v6, vcc, s36, v4
	v_or_b32_e32 v84, v82, v163
	s_nop 0
	v_addc_co_u32_e32 v7, vcc, 0, v5, vcc
	v_add_co_u32_e32 v8, vcc, s37, v4
	global_load_dwordx4 v[58:61], v[2:3], off offset:1024
	global_load_dwordx4 v[50:53], v[2:3], off offset:2048
	global_load_dwordx4 v[62:65], v[6:7], off offset:-4096
	global_load_dwordx4 v[46:49], v[6:7], off
	global_load_dwordx4 v[42:45], v[6:7], off offset:1024
	global_load_dwordx4 v[34:37], v[6:7], off offset:2048
	v_addc_co_u32_e32 v9, vcc, 0, v5, vcc
	v_add_co_u32_e32 v4, vcc, s38, v4
	v_ashrrev_i32_e32 v85, 31, v84
	s_nop 0
	v_addc_co_u32_e32 v5, vcc, 0, v5, vcc
	global_load_dwordx4 v[38:41], v[6:7], off offset:3072
	global_load_dwordx4 v[30:33], v[4:5], off offset:-4096
	global_load_dwordx4 v[54:57], v[2:3], off offset:3072
	global_load_dwordx4 v[26:29], v[8:9], off offset:1024
	global_load_dwordx4 v[22:25], v[8:9], off offset:2048
	global_load_dwordx4 v[18:21], v[8:9], off offset:3072
	global_load_dwordx4 v[14:17], v[4:5], off
	global_load_dwordx4 v[10:13], v[4:5], off offset:1024
	s_nop 0
	global_load_dwordx4 v[6:9], v[4:5], off offset:2048
	s_nop 0
	global_load_dwordx4 v[2:5], v[4:5], off offset:3072
	v_lshl_add_u64 v[84:85], v[84:85], 2, s[42:43]
	global_load_dword v198, v[84:85], off
	global_load_dword v197, v[84:85], off offset:64
	global_load_dword v196, v[84:85], off offset:128
	global_load_dword v195, v[84:85], off offset:192
	global_load_dword v194, v[84:85], off offset:256
	global_load_dword v193, v[84:85], off offset:320
	global_load_dword v192, v[84:85], off offset:384
	global_load_dword v157, v[84:85], off offset:448
	s_add_i32 s14, s25, 0xffffc000
	s_and_b32 s16, s14, 0x3f80
	s_and_saveexec_b64 s[14:15], s[4:5]
	s_cbranch_execz .LBB0_498
	v_add_u32_e32 v84, s16, v161
	v_ashrrev_i32_e32 v85, 31, v84
	v_lshlrev_b64 v[84:85], 7, v[84:85]
	v_lshl_add_u64 v[112:113], s[52:53], 0, v[84:85]
	global_load_dwordx4 v[84:87], v[112:113], off
	global_load_dwordx4 v[88:91], v[112:113], off offset:16
	global_load_dwordx4 v[92:95], v[112:113], off offset:32
	global_load_dwordx4 v[96:99], v[112:113], off offset:48
	global_load_dwordx4 v[100:103], v[112:113], off offset:64
	global_load_dwordx4 v[104:107], v[112:113], off offset:80
	global_load_dwordx4 v[108:111], v[112:113], off offset:96
	s_nop 0
	global_load_dwordx4 v[112:115], v[112:113], off offset:112
	s_waitcnt vmcnt(7)
	v_pk_add_f32 v[84:85], v[84:85], v[86:87]
	s_waitcnt vmcnt(6)
	v_pk_add_f32 v[86:87], v[88:89], v[90:91]
	v_pk_add_f32 v[84:85], v[84:85], 0 op_sel_hi:[1,0]
	s_waitcnt vmcnt(5)
	v_pk_add_f32 v[88:89], v[92:93], v[94:95]
	v_pk_add_f32 v[84:85], v[84:85], v[86:87]
	s_waitcnt vmcnt(4)
	v_pk_add_f32 v[90:91], v[96:97], v[98:99]
	v_pk_add_f32 v[84:85], v[84:85], v[88:89]
	s_waitcnt vmcnt(3)
	v_pk_add_f32 v[92:93], v[100:101], v[102:103]
	v_pk_add_f32 v[84:85], v[84:85], v[90:91]
	s_waitcnt vmcnt(2)
	v_pk_add_f32 v[94:95], v[104:105], v[106:107]
	v_pk_add_f32 v[84:85], v[84:85], v[92:93]
	s_waitcnt vmcnt(1)
	v_pk_add_f32 v[96:97], v[108:109], v[110:111]
	v_pk_add_f32 v[84:85], v[84:85], v[94:95]
	s_waitcnt vmcnt(0)
	v_pk_add_f32 v[98:99], v[112:113], v[114:115]
	v_pk_add_f32 v[84:85], v[84:85], v[96:97]
	v_add_u32_e32 v86, 0, v167
	v_pk_add_f32 v[84:85], v[84:85], v[98:99]
	s_nop 0
	v_pk_mul_f32 v[84:85], v[84:85], s[58:59] op_sel_hi:[1,0]
	s_nop 0
	v_fma_f32 v83, -v84, v84, v85
	v_max_f32_e32 v83, 0, v83
	v_add_f32_e32 v83, 0x358637bd, v83
	v_mul_f32_e32 v85, 0x4b800000, v83
	v_cmp_gt_f32_e32 vcc, s39, v83
	s_nop 1
	v_cndmask_b32_e32 v83, v83, v85, vcc
	v_rsq_f32_e32 v83, v83
	s_nop 0
	v_mul_f32_e32 v85, 0x45800000, v83
	v_cndmask_b32_e32 v85, v83, v85, vcc
	ds_write_b64 v86, v[84:85]
; __device__ __forceinline__ unsigned cvt_pk_bf16(float lo, float hi) { unsigned r; asm volatile("v_cvt_pk_bf16_f32 %0, %1, %2" : "=v"(r) : "v"(lo), "v"(hi)); return r; }
; __device__ __forceinline__ float bf_lo(unsigned w) { return __uint_as_float(w << 16); }
; __device__ __forceinline__ float bf_hi(unsigned w) { return __uint_as_float(w & 0xffff0000u); }
; #define LAS __attribute__((address_space(3)))
; __device__ __forceinline__ void sgu_unit(LAS unsigned char* lds, bf16* U, const bf16* VS, const float* SGS, const float* lnw, const float* lnb, const v4u* WF, const float* bsl, int unit, int tid) {
;     ...
;     LAS unsigned char* vt = lds + SGU_VT + wave * SGU_WREG;
;     {
;         const int c8 = lane & 7, rp = lane >> 3, col = colbase + 8 * c8;
;         v4u sl[8][2];
; #pragma unroll
;         for (int i = 0; i < 8; ++i) { const int s0 = 2 * (rp + 8 * i); sl[i][0] = *(const v4u*)(VS + (size_t)(r0 + s0) * 1024 + col); sl[i][1] = *(const v4u*)(VS + (size_t)(r0 + s0 + 1) * 1024 + col); }
;         const f32x4 lw0 = *(const f32x4*)(lnw + col), lw1 = *(const f32x4*)(lnw + col + 4), lb0 = *(const f32x4*)(lnb + col), lb1 = *(const f32x4*)(lnb + col + 4);
;         const float lw[8] = {lw0.x, lw0.y, lw0.z, lw0.w, lw1.x, lw1.y, lw1.z, lw1.w}, lb[8] = {lb0.x, lb0.y, lb0.z, lb0.w, lb1.x, lb1.y, lb1.z, lb1.w};
;         __syncthreads();
;         LAS unsigned char* wbase = vt + c8 * SGU_VP + rp * 4;
; #pragma unroll
;         for (int i = 0; i < 8; ++i) {
;             const f32x4 st4 = *(const LAS f32x4*)(stat + 4 * (rp + 8 * i));
;             const v4u w0 = sl[i][0], w1 = sl[i][1];
;             const unsigned A0[4] = {w0.x, w0.y, w0.z, w0.w}, A1[4] = {w1.x, w1.y, w1.z, w1.w};
; #pragma unroll
;             for (int e = 0; e < 8; ++e) { typedef float f32x2p __attribute__((ext_vector_type(2)));
;                 f32x2p v; v.x = (e & 1) ? bf_hi(A0[e >> 1]) : bf_lo(A0[e >> 1]); v.y = (e & 1) ? bf_hi(A1[e >> 1]) : bf_lo(A1[e >> 1]);
;                 const f32x2p mn = {st4.x, st4.z}, rs = {st4.y, st4.w};
;                 const f32x2p o = ((v - mn) * rs) * lw[e] + lb[e];
;                 *(LAS unsigned*)(wbase + e * 8 * SGU_VP + i * 32) = cvt_pk_bf16(o.x, o.y); }
;         }
.LBB0_498:
	s_or_b64 exec, exec, s[14:15]
	v_mov_b32_e32 v122, v222
	v_mov_b32_e32 v123, v223
	v_mov_b32_e32 v124, v224
	v_mov_b32_e32 v125, v225
	v_mov_b32_e32 v126, v226
	v_mov_b32_e32 v127, v227
	v_mov_b32_e32 v128, v228
	v_mov_b32_e32 v129, v229
	v_mov_b32_e32 v114, v230
	v_mov_b32_e32 v115, v231
	v_mov_b32_e32 v116, v232
	v_mov_b32_e32 v117, v233
	v_mov_b32_e32 v118, v234
	v_mov_b32_e32 v119, v235
	v_mov_b32_e32 v120, v236
	v_mov_b32_e32 v121, v237
	v_mov_b32_e32 v106, v238
	v_mov_b32_e32 v107, v239
	v_mov_b32_e32 v108, v240
	v_mov_b32_e32 v109, v241
	v_mov_b32_e32 v110, v242
	v_mov_b32_e32 v111, v243
	v_mov_b32_e32 v112, v244
	v_mov_b32_e32 v113, v245
	v_or_b32_e32 v158, v82, v168
	v_or_b32_e32 v82, v158, v170
	v_lshl_or_b32 v84, s16, 11, v181
	v_mov_b32_e32 v85, v147
	v_ashrrev_i32_e32 v83, 31, v82
	v_lshl_add_u64 v[84:85], s[48:49], 0, v[84:85]
	v_lshl_add_u64 v[90:91], v[82:83], 1, v[84:85]
	v_lshlrev_b64 v[82:83], 2, v[82:83]
	s_waitcnt lgkmcnt(0)
	v_lshl_add_u64 v[84:85], s[30:31], 0, v[82:83]
	v_lshl_add_u64 v[86:87], s[50:51], 0, v[82:83]
	global_load_dwordx4 v[98:101], v[86:87], off
	global_load_dwordx4 v[102:105], v[84:85], off
	s_nop 0
	global_load_dwordx4 v[82:85], v[84:85], off offset:16
	s_nop 0
	global_load_dwordx4 v[86:89], v[86:87], off offset:16
	v_add_co_u32_e32 v92, vcc, 0x8000, v90
	s_mov_b64 s[14:15], 0
	s_nop 0
	v_addc_co_u32_e32 v93, vcc, 0, v91, vcc
	v_add_co_u32_e32 v94, vcc, 0x10000, v90
	s_waitcnt vmcnt(7)
	v_and_b32_e32 v228, 0xffff0000, v206
	v_addc_co_u32_e32 v95, vcc, 0, v91, vcc
	v_add_co_u32_e32 v92, vcc, 0x18000, v90
	s_waitcnt vmcnt(8)
	v_and_b32_e32 v229, 0xffff0000, v210
	v_addc_co_u32_e32 v93, vcc, 0, v91, vcc
	v_add_co_u32_e32 v94, vcc, 0x20000, v90
	v_addc_co_u32_e32 v95, vcc, 0, v91, vcc
	v_add_co_u32_e32 v92, vcc, 0x28000, v90
	v_addc_co_u32_e32 v93, vcc, 0, v91, vcc
	v_add_co_u32_e32 v94, vcc, 0x30000, v90
	v_addc_co_u32_e32 v95, vcc, 0, v91, vcc
	v_add_co_u32_e32 v96, vcc, 0x38000, v90
	v_addc_co_u32_e32 v97, vcc, 0, v91, vcc
	v_mov_b32_e32 v90, v248
	v_mov_b32_e32 v91, v249
	v_mov_b32_e32 v92, v250
	v_mov_b32_e32 v93, v251
	s_nop 0
	v_mov_b32_e32 v94, v252
	v_mov_b32_e32 v95, v253
	v_mov_b32_e32 v96, v254
	v_mov_b32_e32 v97, v255
	s_barrier
	ds_read_b128 v[222:225], v182
	v_lshlrev_b32_e32 v230, 16, v207
	v_lshlrev_b32_e32 v231, 16, v211
	s_waitcnt vmcnt(2)
	v_mov_b32_e32 v160, v105
	v_mov_b32_e32 v162, v101
	s_waitcnt lgkmcnt(0)
	v_mov_b32_e32 v226, v222
	v_mov_b32_e32 v227, v224
	v_mov_b32_e32 v224, v223
	v_lshlrev_b32_e32 v222, 16, v206
	v_lshlrev_b32_e32 v223, 16, v210
	v_pk_add_f32 v[222:223], v[222:223], v[226:227] neg_lo:[0,1] neg_hi:[0,1]
	v_and_b32_e32 v206, 0xffff0000, v207
	v_and_b32_e32 v207, 0xffff0000, v211
	v_pk_add_f32 v[228:229], v[228:229], v[226:227] neg_lo:[0,1] neg_hi:[0,1]
	v_pk_mul_f32 v[222:223], v[224:225], v[222:223]
	v_pk_add_f32 v[206:207], v[206:207], v[226:227] neg_lo:[0,1] neg_hi:[0,1]
	v_pk_add_f32 v[230:231], v[230:231], v[226:227] neg_lo:[0,1] neg_hi:[0,1]
	v_pk_mul_f32 v[228:229], v[224:225], v[228:229]
	v_pk_fma_f32 v[222:223], v[102:103], v[222:223], v[98:99] op_sel_hi:[0,1,0]
	v_cvt_pk_bf16_f32 v159, v222, v223
	v_pk_mul_f32 v[206:207], v[224:225], v[206:207]
	v_pk_mul_f32 v[230:231], v[224:225], v[230:231]
	v_pk_fma_f32 v[228:229], v[102:103], v[228:229], v[98:99] op_sel:[1,0,1]
	ds_write_b32 v178, v159 offset:1024
	v_cvt_pk_bf16_f32 v159, v228, v229
	v_pk_fma_f32 v[206:207], v[160:161], v[206:207], v[162:163] op_sel_hi:[0,1,0]
	v_pk_fma_f32 v[230:231], v[104:105], v[230:231], v[100:101] op_sel_hi:[0,1,0]
	ds_write_b32 v178, v159 offset:3200
	v_cvt_pk_bf16_f32 v159, v230, v231
	ds_write_b32 v178, v159 offset:5376
	v_cvt_pk_bf16_f32 v101, v206, v207
	v_lshlrev_b32_e32 v206, 16, v208
	v_lshlrev_b32_e32 v207, 16, v212
	v_pk_add_f32 v[206:207], v[206:207], v[226:227] neg_lo:[0,1] neg_hi:[0,1]
	ds_write_b32 v178, v101 offset:7552
	v_pk_mul_f32 v[206:207], v[224:225], v[206:207]
	s_waitcnt vmcnt(1)
	v_mov_b32_e32 v164, v85
	s_waitcnt vmcnt(0)
	v_pk_fma_f32 v[206:207], v[82:83], v[206:207], v[86:87] op_sel_hi:[0,1,0]
	v_cvt_pk_bf16_f32 v101, v206, v207
	v_and_b32_e32 v206, 0xffff0000, v208
	v_and_b32_e32 v207, 0xffff0000, v212
	v_pk_add_f32 v[206:207], v[206:207], v[226:227] neg_lo:[0,1] neg_hi:[0,1]
	ds_write_b32 v178, v101 offset:9728
	v_pk_mul_f32 v[206:207], v[224:225], v[206:207]
	v_mov_b32_e32 v166, v89
	v_pk_fma_f32 v[206:207], v[82:83], v[206:207], v[86:87] op_sel:[1,0,1]
	v_ashrrev_i32_e32 v159, 31, v158
	v_cvt_pk_bf16_f32 v101, v206, v207
	v_lshlrev_b32_e32 v206, 16, v209
	v_lshlrev_b32_e32 v207, 16, v213
	v_pk_add_f32 v[206:207], v[206:207], v[226:227] neg_lo:[0,1] neg_hi:[0,1]
	ds_write_b32 v178, v101 offset:11904
	v_pk_mul_f32 v[206:207], v[224:225], v[206:207]
	s_nop 0
	v_pk_fma_f32 v[206:207], v[84:85], v[206:207], v[88:89] op_sel_hi:[0,1,0]
	v_cvt_pk_bf16_f32 v101, v206, v207
	v_and_b32_e32 v206, 0xffff0000, v209
	v_and_b32_e32 v207, 0xffff0000, v213
	v_pk_add_f32 v[206:207], v[206:207], v[226:227] neg_lo:[0,1] neg_hi:[0,1]
	ds_write_b32 v178, v101 offset:14080
	v_pk_mul_f32 v[206:207], v[224:225], v[206:207]
	s_nop 0
	v_pk_fma_f32 v[206:207], v[164:165], v[206:207], v[166:167] op_sel_hi:[0,1,0]
	v_cvt_pk_bf16_f32 v85, v206, v207
	ds_write_b32 v178, v85 offset:16256
	ds_read_b128 v[206:209], v182 offset:128
	s_waitcnt lgkmcnt(0)
	v_mov_b32_e32 v210, v206
	v_mov_b32_e32 v211, v208
	v_mov_b32_e32 v208, v207
	s_waitcnt vmcnt(13)
	v_lshlrev_b32_e32 v206, 16, v214
	s_waitcnt vmcnt(12)
; __device__ __forceinline__ unsigned cvt_pk_bf16(float lo, float hi) { unsigned r; asm volatile("v_cvt_pk_bf16_f32 %0, %1, %2" : "=v"(r) : "v"(lo), "v"(hi)); return r; }
; __device__ __forceinline__ float bf_lo(unsigned w) { return __uint_as_float(w << 16); }
; __device__ __forceinline__ float bf_hi(unsigned w) { return __uint_as_float(w & 0xffff0000u); }
; #define LAS __attribute__((address_space(3)))
; __device__ __forceinline__ void sgu_unit(LAS unsigned char* lds, bf16* U, const bf16* VS, const float* SGS, const float* lnw, const float* lnb, const v4u* WF, const float* bsl, int unit, int tid) {
;     ...
;         LAS unsigned char* wbase = vt + c8 * SGU_VP + rp * 4;
; #pragma unroll
;         for (int i = 0; i < 8; ++i) {
;             const f32x4 st4 = *(const LAS f32x4*)(stat + 4 * (rp + 8 * i));
;             const v4u w0 = sl[i][0], w1 = sl[i][1];
;             const unsigned A0[4] = {w0.x, w0.y, w0.z, w0.w}, A1[4] = {w1.x, w1.y, w1.z, w1.w};
; #pragma unroll
;             for (int e = 0; e < 8; ++e) { typedef float f32x2p __attribute__((ext_vector_type(2)));
;                 f32x2p v; v.x = (e & 1) ? bf_hi(A0[e >> 1]) : bf_lo(A0[e >> 1]); v.y = (e & 1) ? bf_hi(A1[e >> 1]) : bf_lo(A1[e >> 1]);
;                 const f32x2p mn = {st4.x, st4.z}, rs = {st4.y, st4.w};
;                 const f32x2p o = ((v - mn) * rs) * lw[e] + lb[e];
;                 *(LAS unsigned*)(wbase + e * 8 * SGU_VP + i * 32) = cvt_pk_bf16(o.x, o.y); }
;         }
	v_lshlrev_b32_e32 v207, 16, v218
	v_pk_add_f32 v[206:207], v[206:207], v[210:211] neg_lo:[0,1] neg_hi:[0,1]
	s_nop 0
	v_pk_mul_f32 v[206:207], v[208:209], v[206:207]
	s_nop 0
	v_pk_fma_f32 v[206:207], v[102:103], v[206:207], v[98:99] op_sel_hi:[0,1,0]
	v_cvt_pk_bf16_f32 v85, v206, v207
	v_and_b32_e32 v206, 0xffff0000, v214
	v_and_b32_e32 v207, 0xffff0000, v218
	v_pk_add_f32 v[206:207], v[206:207], v[210:211] neg_lo:[0,1] neg_hi:[0,1]
	ds_write_b32 v178, v85 offset:1056
	v_pk_mul_f32 v[206:207], v[208:209], v[206:207]
	s_nop 0
	v_pk_fma_f32 v[206:207], v[102:103], v[206:207], v[98:99] op_sel:[1,0,1]
	s_nop 0
	v_cvt_pk_bf16_f32 v85, v206, v207
	v_lshlrev_b32_e32 v206, 16, v215
	v_lshlrev_b32_e32 v207, 16, v219
	v_pk_add_f32 v[206:207], v[206:207], v[210:211] neg_lo:[0,1] neg_hi:[0,1]
	ds_write_b32 v178, v85 offset:3232
	v_pk_mul_f32 v[206:207], v[208:209], v[206:207]
	s_nop 0
	v_pk_fma_f32 v[206:207], v[104:105], v[206:207], v[100:101] op_sel_hi:[0,1,0]
	v_cvt_pk_bf16_f32 v85, v206, v207
	v_and_b32_e32 v206, 0xffff0000, v215
	v_and_b32_e32 v207, 0xffff0000, v219
	v_pk_add_f32 v[206:207], v[206:207], v[210:211] neg_lo:[0,1] neg_hi:[0,1]
	ds_write_b32 v178, v85 offset:5408
	v_pk_mul_f32 v[206:207], v[208:209], v[206:207]
	s_nop 0
	v_pk_fma_f32 v[206:207], v[160:161], v[206:207], v[162:163] op_sel_hi:[0,1,0]
	v_cvt_pk_bf16_f32 v85, v206, v207
	v_lshlrev_b32_e32 v206, 16, v216
	v_lshlrev_b32_e32 v207, 16, v220
	v_pk_add_f32 v[206:207], v[206:207], v[210:211] neg_lo:[0,1] neg_hi:[0,1]
	ds_write_b32 v178, v85 offset:7584
	v_pk_mul_f32 v[206:207], v[208:209], v[206:207]
	s_nop 0
	v_pk_fma_f32 v[206:207], v[82:83], v[206:207], v[86:87] op_sel_hi:[0,1,0]
	v_cvt_pk_bf16_f32 v85, v206, v207
	v_and_b32_e32 v206, 0xffff0000, v216
	v_and_b32_e32 v207, 0xffff0000, v220
	v_pk_add_f32 v[206:207], v[206:207], v[210:211] neg_lo:[0,1] neg_hi:[0,1]
	ds_write_b32 v178, v85 offset:9760
	v_pk_mul_f32 v[206:207], v[208:209], v[206:207]
	s_nop 0
	v_pk_fma_f32 v[206:207], v[82:83], v[206:207], v[86:87] op_sel:[1,0,1]
	s_nop 0
	v_cvt_pk_bf16_f32 v85, v206, v207
	v_lshlrev_b32_e32 v206, 16, v217
	v_lshlrev_b32_e32 v207, 16, v221
	v_pk_add_f32 v[206:207], v[206:207], v[210:211] neg_lo:[0,1] neg_hi:[0,1]
	ds_write_b32 v178, v85 offset:11936
	v_pk_mul_f32 v[206:207], v[208:209], v[206:207]
	s_nop 0
	v_pk_fma_f32 v[206:207], v[84:85], v[206:207], v[88:89] op_sel_hi:[0,1,0]
	v_cvt_pk_bf16_f32 v85, v206, v207
	v_and_b32_e32 v206, 0xffff0000, v217
	v_and_b32_e32 v207, 0xffff0000, v221
	v_pk_add_f32 v[206:207], v[206:207], v[210:211] neg_lo:[0,1] neg_hi:[0,1]
	ds_write_b32 v178, v85 offset:14112
	v_pk_mul_f32 v[206:207], v[208:209], v[206:207]
	s_nop 0
	v_pk_fma_f32 v[206:207], v[164:165], v[206:207], v[166:167] op_sel_hi:[0,1,0]
	v_cvt_pk_bf16_f32 v85, v206, v207
	ds_write_b32 v178, v85 offset:16288
	ds_read_b128 v[206:209], v182 offset:256
	s_waitcnt lgkmcnt(0)
	v_mov_b32_e32 v210, v206
	v_mov_b32_e32 v211, v208
	v_mov_b32_e32 v208, v207
	s_waitcnt vmcnt(11)
	v_lshlrev_b32_e32 v206, 16, v138
	s_waitcnt vmcnt(10)
	v_lshlrev_b32_e32 v207, 16, v142
	v_pk_add_f32 v[206:207], v[206:207], v[210:211] neg_lo:[0,1] neg_hi:[0,1]
	s_nop 0
	v_pk_mul_f32 v[206:207], v[208:209], v[206:207]
	s_nop 0
	v_pk_fma_f32 v[206:207], v[102:103], v[206:207], v[98:99] op_sel_hi:[0,1,0]
	v_cvt_pk_bf16_f32 v85, v206, v207
	v_and_b32_e32 v206, 0xffff0000, v138
	v_and_b32_e32 v207, 0xffff0000, v142
	v_pk_add_f32 v[206:207], v[206:207], v[210:211] neg_lo:[0,1] neg_hi:[0,1]
	ds_write_b32 v178, v85 offset:1088
	v_pk_mul_f32 v[206:207], v[208:209], v[206:207]
	v_and_b32_e32 v138, 0xffff0000, v139
	v_pk_fma_f32 v[206:207], v[102:103], v[206:207], v[98:99] op_sel:[1,0,1]
	s_nop 0
	v_cvt_pk_bf16_f32 v85, v206, v207
	v_lshlrev_b32_e32 v206, 16, v139
	v_lshlrev_b32_e32 v207, 16, v143
	v_and_b32_e32 v139, 0xffff0000, v143
	v_pk_add_f32 v[206:207], v[206:207], v[210:211] neg_lo:[0,1] neg_hi:[0,1]
	v_pk_add_f32 v[138:139], v[138:139], v[210:211] neg_lo:[0,1] neg_hi:[0,1]
	v_pk_mul_f32 v[206:207], v[208:209], v[206:207]
	v_pk_mul_f32 v[138:139], v[208:209], v[138:139]
	ds_write_b32 v178, v85 offset:3264
	v_pk_fma_f32 v[206:207], v[104:105], v[206:207], v[100:101] op_sel_hi:[0,1,0]
	v_cvt_pk_bf16_f32 v85, v206, v207
	v_pk_fma_f32 v[138:139], v[160:161], v[138:139], v[162:163] op_sel_hi:[0,1,0]
	ds_write_b32 v178, v85 offset:5440
	v_cvt_pk_bf16_f32 v85, v138, v139
	v_lshlrev_b32_e32 v138, 16, v140
	v_lshlrev_b32_e32 v139, 16, v144
	v_pk_add_f32 v[138:139], v[138:139], v[210:211] neg_lo:[0,1] neg_hi:[0,1]
	ds_write_b32 v178, v85 offset:7616
	v_pk_mul_f32 v[138:139], v[208:209], v[138:139]
	s_nop 0
	v_pk_fma_f32 v[138:139], v[82:83], v[138:139], v[86:87] op_sel_hi:[0,1,0]
	v_cvt_pk_bf16_f32 v85, v138, v139
	v_and_b32_e32 v138, 0xffff0000, v140
	v_and_b32_e32 v139, 0xffff0000, v144
	v_pk_add_f32 v[138:139], v[138:139], v[210:211] neg_lo:[0,1] neg_hi:[0,1]
	ds_write_b32 v178, v85 offset:9792
	v_pk_mul_f32 v[138:139], v[208:209], v[138:139]
	s_nop 0
	v_pk_fma_f32 v[138:139], v[82:83], v[138:139], v[86:87] op_sel:[1,0,1]
	s_nop 0
	v_cvt_pk_bf16_f32 v85, v138, v139
	v_lshlrev_b32_e32 v138, 16, v141
	v_lshlrev_b32_e32 v139, 16, v145
	v_pk_add_f32 v[138:139], v[138:139], v[210:211] neg_lo:[0,1] neg_hi:[0,1]
	ds_write_b32 v178, v85 offset:11968
	v_pk_mul_f32 v[138:139], v[208:209], v[138:139]
	s_nop 0
	v_pk_fma_f32 v[138:139], v[84:85], v[138:139], v[88:89] op_sel_hi:[0,1,0]
	v_cvt_pk_bf16_f32 v85, v138, v139
	v_and_b32_e32 v138, 0xffff0000, v141
	v_and_b32_e32 v139, 0xffff0000, v145
	v_pk_add_f32 v[138:139], v[138:139], v[210:211] neg_lo:[0,1] neg_hi:[0,1]
	ds_write_b32 v178, v85 offset:14144
	v_pk_mul_f32 v[138:139], v[208:209], v[138:139]
	s_nop 0
	v_pk_fma_f32 v[138:139], v[164:165], v[138:139], v[166:167] op_sel_hi:[0,1,0]
	v_cvt_pk_bf16_f32 v85, v138, v139
	ds_write_b32 v178, v85 offset:16320
	ds_read_b128 v[138:141], v182 offset:384
	s_waitcnt lgkmcnt(0)
; __device__ __forceinline__ unsigned cvt_pk_bf16(float lo, float hi) { unsigned r; asm volatile("v_cvt_pk_bf16_f32 %0, %1, %2" : "=v"(r) : "v"(lo), "v"(hi)); return r; }
; __device__ __forceinline__ float bf_lo(unsigned w) { return __uint_as_float(w << 16); }
; __device__ __forceinline__ float bf_hi(unsigned w) { return __uint_as_float(w & 0xffff0000u); }
; #define LAS __attribute__((address_space(3)))
; __device__ __forceinline__ void sgu_unit(LAS unsigned char* lds, bf16* U, const bf16* VS, const float* SGS, const float* lnw, const float* lnb, const v4u* WF, const float* bsl, int unit, int tid) {
;     ...
;         LAS unsigned char* wbase = vt + c8 * SGU_VP + rp * 4;
; #pragma unroll
;         for (int i = 0; i < 8; ++i) {
;             const f32x4 st4 = *(const LAS f32x4*)(stat + 4 * (rp + 8 * i));
;             const v4u w0 = sl[i][0], w1 = sl[i][1];
;             const unsigned A0[4] = {w0.x, w0.y, w0.z, w0.w}, A1[4] = {w1.x, w1.y, w1.z, w1.w};
; #pragma unroll
;             for (int e = 0; e < 8; ++e) { typedef float f32x2p __attribute__((ext_vector_type(2)));
;                 f32x2p v; v.x = (e & 1) ? bf_hi(A0[e >> 1]) : bf_lo(A0[e >> 1]); v.y = (e & 1) ? bf_hi(A1[e >> 1]) : bf_lo(A1[e >> 1]);
;                 const f32x2p mn = {st4.x, st4.z}, rs = {st4.y, st4.w};
;                 const f32x2p o = ((v - mn) * rs) * lw[e] + lb[e];
;                 *(LAS unsigned*)(wbase + e * 8 * SGU_VP + i * 32) = cvt_pk_bf16(o.x, o.y); }
;         }
	v_mov_b32_e32 v142, v138
	v_mov_b32_e32 v143, v140
	v_mov_b32_e32 v140, v139
	s_waitcnt vmcnt(9)
	v_lshlrev_b32_e32 v138, 16, v130
	s_waitcnt vmcnt(8)
	v_lshlrev_b32_e32 v139, 16, v134
	v_pk_add_f32 v[138:139], v[138:139], v[142:143] neg_lo:[0,1] neg_hi:[0,1]
	s_nop 0
	v_pk_mul_f32 v[138:139], v[140:141], v[138:139]
	s_nop 0
	v_pk_fma_f32 v[138:139], v[102:103], v[138:139], v[98:99] op_sel_hi:[0,1,0]
	v_cvt_pk_bf16_f32 v85, v138, v139
	v_and_b32_e32 v138, 0xffff0000, v130
	v_and_b32_e32 v139, 0xffff0000, v134
	v_pk_add_f32 v[138:139], v[138:139], v[142:143] neg_lo:[0,1] neg_hi:[0,1]
	ds_write_b32 v178, v85 offset:1120
	v_pk_mul_f32 v[138:139], v[140:141], v[138:139]
	v_and_b32_e32 v130, 0xffff0000, v131
	v_pk_fma_f32 v[138:139], v[102:103], v[138:139], v[98:99] op_sel:[1,0,1]
	s_nop 0
	v_cvt_pk_bf16_f32 v85, v138, v139
	v_lshlrev_b32_e32 v138, 16, v131
	v_lshlrev_b32_e32 v139, 16, v135
	v_and_b32_e32 v131, 0xffff0000, v135
	v_pk_add_f32 v[138:139], v[138:139], v[142:143] neg_lo:[0,1] neg_hi:[0,1]
	v_pk_add_f32 v[130:131], v[130:131], v[142:143] neg_lo:[0,1] neg_hi:[0,1]
	v_pk_mul_f32 v[138:139], v[140:141], v[138:139]
	v_pk_mul_f32 v[130:131], v[140:141], v[130:131]
	ds_write_b32 v178, v85 offset:3296
	v_pk_fma_f32 v[138:139], v[104:105], v[138:139], v[100:101] op_sel_hi:[0,1,0]
	v_cvt_pk_bf16_f32 v85, v138, v139
	v_pk_fma_f32 v[130:131], v[160:161], v[130:131], v[162:163] op_sel_hi:[0,1,0]
	ds_write_b32 v178, v85 offset:5472
	v_cvt_pk_bf16_f32 v85, v130, v131
	v_lshlrev_b32_e32 v130, 16, v132
	v_lshlrev_b32_e32 v131, 16, v136
	v_pk_add_f32 v[130:131], v[130:131], v[142:143] neg_lo:[0,1] neg_hi:[0,1]
	ds_write_b32 v178, v85 offset:7648
	v_pk_mul_f32 v[130:131], v[140:141], v[130:131]
	s_nop 0
	v_pk_fma_f32 v[130:131], v[82:83], v[130:131], v[86:87] op_sel_hi:[0,1,0]
	v_cvt_pk_bf16_f32 v85, v130, v131
	v_and_b32_e32 v130, 0xffff0000, v132
	v_and_b32_e32 v131, 0xffff0000, v136
	v_pk_add_f32 v[130:131], v[130:131], v[142:143] neg_lo:[0,1] neg_hi:[0,1]
	ds_write_b32 v178, v85 offset:9824
	v_pk_mul_f32 v[130:131], v[140:141], v[130:131]
	s_nop 0
	v_pk_fma_f32 v[130:131], v[82:83], v[130:131], v[86:87] op_sel:[1,0,1]
	s_nop 0
	v_cvt_pk_bf16_f32 v85, v130, v131
	v_lshlrev_b32_e32 v130, 16, v133
	v_lshlrev_b32_e32 v131, 16, v137
	v_pk_add_f32 v[130:131], v[130:131], v[142:143] neg_lo:[0,1] neg_hi:[0,1]
	ds_write_b32 v178, v85 offset:12000
	v_pk_mul_f32 v[130:131], v[140:141], v[130:131]
	s_nop 0
	v_pk_fma_f32 v[130:131], v[84:85], v[130:131], v[88:89] op_sel_hi:[0,1,0]
	v_cvt_pk_bf16_f32 v85, v130, v131
	v_and_b32_e32 v130, 0xffff0000, v133
	v_and_b32_e32 v131, 0xffff0000, v137
	v_pk_add_f32 v[130:131], v[130:131], v[142:143] neg_lo:[0,1] neg_hi:[0,1]
	ds_write_b32 v178, v85 offset:14176
	v_pk_mul_f32 v[130:131], v[140:141], v[130:131]
	s_nop 0
	v_pk_fma_f32 v[130:131], v[164:165], v[130:131], v[166:167] op_sel_hi:[0,1,0]
	v_cvt_pk_bf16_f32 v85, v130, v131
	ds_write_b32 v178, v85 offset:16352
	ds_read_b128 v[130:133], v182 offset:512
	s_waitcnt lgkmcnt(0)
	v_mov_b32_e32 v134, v130
	v_mov_b32_e32 v135, v132
	v_mov_b32_e32 v132, v131
	s_waitcnt vmcnt(7)
	v_lshlrev_b32_e32 v130, 16, v122
	s_waitcnt vmcnt(6)
	v_lshlrev_b32_e32 v131, 16, v126
	v_pk_add_f32 v[130:131], v[130:131], v[134:135] neg_lo:[0,1] neg_hi:[0,1]
	s_nop 0
	v_pk_mul_f32 v[130:131], v[132:133], v[130:131]
	s_nop 0
	v_pk_fma_f32 v[130:131], v[102:103], v[130:131], v[98:99] op_sel_hi:[0,1,0]
	v_cvt_pk_bf16_f32 v85, v130, v131
	v_and_b32_e32 v130, 0xffff0000, v122
	v_and_b32_e32 v131, 0xffff0000, v126
	v_pk_add_f32 v[130:131], v[130:131], v[134:135] neg_lo:[0,1] neg_hi:[0,1]
	ds_write_b32 v178, v85 offset:1152
	v_pk_mul_f32 v[130:131], v[132:133], v[130:131]
	v_and_b32_e32 v122, 0xffff0000, v123
	v_pk_fma_f32 v[130:131], v[102:103], v[130:131], v[98:99] op_sel:[1,0,1]
	s_nop 0
	v_cvt_pk_bf16_f32 v85, v130, v131
	v_lshlrev_b32_e32 v130, 16, v123
	v_lshlrev_b32_e32 v131, 16, v127
	v_and_b32_e32 v123, 0xffff0000, v127
	v_pk_add_f32 v[130:131], v[130:131], v[134:135] neg_lo:[0,1] neg_hi:[0,1]
	v_pk_add_f32 v[122:123], v[122:123], v[134:135] neg_lo:[0,1] neg_hi:[0,1]
	v_pk_mul_f32 v[130:131], v[132:133], v[130:131]
	v_pk_mul_f32 v[122:123], v[132:133], v[122:123]
	ds_write_b32 v178, v85 offset:3328
	v_pk_fma_f32 v[130:131], v[104:105], v[130:131], v[100:101] op_sel_hi:[0,1,0]
	v_cvt_pk_bf16_f32 v85, v130, v131
	v_pk_fma_f32 v[122:123], v[160:161], v[122:123], v[162:163] op_sel_hi:[0,1,0]
	ds_write_b32 v178, v85 offset:5504
	v_cvt_pk_bf16_f32 v85, v122, v123
	v_lshlrev_b32_e32 v122, 16, v124
	v_lshlrev_b32_e32 v123, 16, v128
	v_pk_add_f32 v[122:123], v[122:123], v[134:135] neg_lo:[0,1] neg_hi:[0,1]
	ds_write_b32 v178, v85 offset:7680
	v_pk_mul_f32 v[122:123], v[132:133], v[122:123]
	s_nop 0
	v_pk_fma_f32 v[122:123], v[82:83], v[122:123], v[86:87] op_sel_hi:[0,1,0]
	v_cvt_pk_bf16_f32 v85, v122, v123
	v_and_b32_e32 v122, 0xffff0000, v124
	v_and_b32_e32 v123, 0xffff0000, v128
	v_pk_add_f32 v[122:123], v[122:123], v[134:135] neg_lo:[0,1] neg_hi:[0,1]
	ds_write_b32 v178, v85 offset:9856
	v_pk_mul_f32 v[122:123], v[132:133], v[122:123]
	s_nop 0
	v_pk_fma_f32 v[122:123], v[82:83], v[122:123], v[86:87] op_sel:[1,0,1]
	s_nop 0
	v_cvt_pk_bf16_f32 v85, v122, v123
	v_lshlrev_b32_e32 v122, 16, v125
	v_lshlrev_b32_e32 v123, 16, v129
	v_pk_add_f32 v[122:123], v[122:123], v[134:135] neg_lo:[0,1] neg_hi:[0,1]
	ds_write_b32 v178, v85 offset:12032
	v_pk_mul_f32 v[122:123], v[132:133], v[122:123]
	s_nop 0
	v_pk_fma_f32 v[122:123], v[84:85], v[122:123], v[88:89] op_sel_hi:[0,1,0]
	v_cvt_pk_bf16_f32 v85, v122, v123
	v_and_b32_e32 v122, 0xffff0000, v125
	v_and_b32_e32 v123, 0xffff0000, v129
	v_pk_add_f32 v[122:123], v[122:123], v[134:135] neg_lo:[0,1] neg_hi:[0,1]
	ds_write_b32 v178, v85 offset:14208
	v_pk_mul_f32 v[122:123], v[132:133], v[122:123]
	s_nop 0
	v_pk_fma_f32 v[122:123], v[164:165], v[122:123], v[166:167] op_sel_hi:[0,1,0]
	v_cvt_pk_bf16_f32 v85, v122, v123
	ds_write_b32 v178, v85 offset:16384
	ds_read_b128 v[122:125], v182 offset:640
	s_waitcnt lgkmcnt(0)
; __device__ __forceinline__ unsigned cvt_pk_bf16(float lo, float hi) { unsigned r; asm volatile("v_cvt_pk_bf16_f32 %0, %1, %2" : "=v"(r) : "v"(lo), "v"(hi)); return r; }
; __device__ __forceinline__ float bf_lo(unsigned w) { return __uint_as_float(w << 16); }
; __device__ __forceinline__ float bf_hi(unsigned w) { return __uint_as_float(w & 0xffff0000u); }
; #define LAS __attribute__((address_space(3)))
; __device__ __forceinline__ void sgu_unit(LAS unsigned char* lds, bf16* U, const bf16* VS, const float* SGS, const float* lnw, const float* lnb, const v4u* WF, const float* bsl, int unit, int tid) {
;     ...
;         LAS unsigned char* wbase = vt + c8 * SGU_VP + rp * 4;
; #pragma unroll
;         for (int i = 0; i < 8; ++i) {
;             const f32x4 st4 = *(const LAS f32x4*)(stat + 4 * (rp + 8 * i));
;             const v4u w0 = sl[i][0], w1 = sl[i][1];
;             const unsigned A0[4] = {w0.x, w0.y, w0.z, w0.w}, A1[4] = {w1.x, w1.y, w1.z, w1.w};
; #pragma unroll
;             for (int e = 0; e < 8; ++e) { typedef float f32x2p __attribute__((ext_vector_type(2)));
;                 f32x2p v; v.x = (e & 1) ? bf_hi(A0[e >> 1]) : bf_lo(A0[e >> 1]); v.y = (e & 1) ? bf_hi(A1[e >> 1]) : bf_lo(A1[e >> 1]);
;                 const f32x2p mn = {st4.x, st4.z}, rs = {st4.y, st4.w};
;                 const f32x2p o = ((v - mn) * rs) * lw[e] + lb[e];
;                 *(LAS unsigned*)(wbase + e * 8 * SGU_VP + i * 32) = cvt_pk_bf16(o.x, o.y); }
;         }
	v_mov_b32_e32 v126, v122
	v_mov_b32_e32 v127, v124
	v_mov_b32_e32 v124, v123
	s_waitcnt vmcnt(5)
	v_lshlrev_b32_e32 v122, 16, v114
	s_waitcnt vmcnt(4)
	v_lshlrev_b32_e32 v123, 16, v118
	v_pk_add_f32 v[122:123], v[122:123], v[126:127] neg_lo:[0,1] neg_hi:[0,1]
	s_nop 0
	v_pk_mul_f32 v[122:123], v[124:125], v[122:123]
	s_nop 0
	v_pk_fma_f32 v[122:123], v[102:103], v[122:123], v[98:99] op_sel_hi:[0,1,0]
	v_cvt_pk_bf16_f32 v85, v122, v123
	v_and_b32_e32 v122, 0xffff0000, v114
	v_and_b32_e32 v123, 0xffff0000, v118
	v_pk_add_f32 v[122:123], v[122:123], v[126:127] neg_lo:[0,1] neg_hi:[0,1]
	ds_write_b32 v178, v85 offset:1184
	v_pk_mul_f32 v[122:123], v[124:125], v[122:123]
	v_and_b32_e32 v114, 0xffff0000, v115
	v_pk_fma_f32 v[122:123], v[102:103], v[122:123], v[98:99] op_sel:[1,0,1]
	s_nop 0
	v_cvt_pk_bf16_f32 v85, v122, v123
	v_lshlrev_b32_e32 v122, 16, v115
	v_lshlrev_b32_e32 v123, 16, v119
	v_and_b32_e32 v115, 0xffff0000, v119
	v_pk_add_f32 v[122:123], v[122:123], v[126:127] neg_lo:[0,1] neg_hi:[0,1]
	v_pk_add_f32 v[114:115], v[114:115], v[126:127] neg_lo:[0,1] neg_hi:[0,1]
	v_pk_mul_f32 v[122:123], v[124:125], v[122:123]
	v_pk_mul_f32 v[114:115], v[124:125], v[114:115]
	ds_write_b32 v178, v85 offset:3360
	v_pk_fma_f32 v[122:123], v[104:105], v[122:123], v[100:101] op_sel_hi:[0,1,0]
	v_cvt_pk_bf16_f32 v85, v122, v123
	v_pk_fma_f32 v[114:115], v[160:161], v[114:115], v[162:163] op_sel_hi:[0,1,0]
	ds_write_b32 v178, v85 offset:5536
	v_cvt_pk_bf16_f32 v85, v114, v115
	v_lshlrev_b32_e32 v114, 16, v116
	v_lshlrev_b32_e32 v115, 16, v120
	v_pk_add_f32 v[114:115], v[114:115], v[126:127] neg_lo:[0,1] neg_hi:[0,1]
	ds_write_b32 v178, v85 offset:7712
	v_pk_mul_f32 v[114:115], v[124:125], v[114:115]
	s_nop 0
	v_pk_fma_f32 v[114:115], v[82:83], v[114:115], v[86:87] op_sel_hi:[0,1,0]
	v_cvt_pk_bf16_f32 v85, v114, v115
	v_and_b32_e32 v114, 0xffff0000, v116
	v_and_b32_e32 v115, 0xffff0000, v120
	v_pk_add_f32 v[114:115], v[114:115], v[126:127] neg_lo:[0,1] neg_hi:[0,1]
	ds_write_b32 v178, v85 offset:9888
	v_pk_mul_f32 v[114:115], v[124:125], v[114:115]
	s_nop 0
	v_pk_fma_f32 v[114:115], v[82:83], v[114:115], v[86:87] op_sel:[1,0,1]
	s_nop 0
	v_cvt_pk_bf16_f32 v85, v114, v115
	v_lshlrev_b32_e32 v114, 16, v117
	v_lshlrev_b32_e32 v115, 16, v121
	v_pk_add_f32 v[114:115], v[114:115], v[126:127] neg_lo:[0,1] neg_hi:[0,1]
	ds_write_b32 v178, v85 offset:12064
	v_pk_mul_f32 v[114:115], v[124:125], v[114:115]
	s_nop 0
	v_pk_fma_f32 v[114:115], v[84:85], v[114:115], v[88:89] op_sel_hi:[0,1,0]
	v_cvt_pk_bf16_f32 v85, v114, v115
	v_and_b32_e32 v114, 0xffff0000, v117
	v_and_b32_e32 v115, 0xffff0000, v121
	v_pk_add_f32 v[114:115], v[114:115], v[126:127] neg_lo:[0,1] neg_hi:[0,1]
	ds_write_b32 v178, v85 offset:14240
	v_pk_mul_f32 v[114:115], v[124:125], v[114:115]
	s_nop 0
	v_pk_fma_f32 v[114:115], v[164:165], v[114:115], v[166:167] op_sel_hi:[0,1,0]
	v_cvt_pk_bf16_f32 v85, v114, v115
	ds_write_b32 v178, v85 offset:16416
	ds_read_b128 v[114:117], v182 offset:768
	s_waitcnt lgkmcnt(0)
	v_mov_b32_e32 v118, v114
	v_mov_b32_e32 v119, v116
	v_mov_b32_e32 v116, v115
	s_waitcnt vmcnt(3)
	v_lshlrev_b32_e32 v114, 16, v106
	s_waitcnt vmcnt(2)
	v_lshlrev_b32_e32 v115, 16, v110
	v_pk_add_f32 v[114:115], v[114:115], v[118:119] neg_lo:[0,1] neg_hi:[0,1]
	s_nop 0
	v_pk_mul_f32 v[114:115], v[116:117], v[114:115]
	s_nop 0
	v_pk_fma_f32 v[114:115], v[102:103], v[114:115], v[98:99] op_sel_hi:[0,1,0]
	v_cvt_pk_bf16_f32 v85, v114, v115
	v_and_b32_e32 v114, 0xffff0000, v106
	v_and_b32_e32 v115, 0xffff0000, v110
	v_pk_add_f32 v[114:115], v[114:115], v[118:119] neg_lo:[0,1] neg_hi:[0,1]
	ds_write_b32 v178, v85 offset:1216
	v_pk_mul_f32 v[114:115], v[116:117], v[114:115]
	v_and_b32_e32 v106, 0xffff0000, v107
	v_pk_fma_f32 v[114:115], v[102:103], v[114:115], v[98:99] op_sel:[1,0,1]
	s_nop 0
	v_cvt_pk_bf16_f32 v85, v114, v115
	v_lshlrev_b32_e32 v114, 16, v107
	v_lshlrev_b32_e32 v115, 16, v111
	v_and_b32_e32 v107, 0xffff0000, v111
	v_pk_add_f32 v[114:115], v[114:115], v[118:119] neg_lo:[0,1] neg_hi:[0,1]
	v_pk_add_f32 v[106:107], v[106:107], v[118:119] neg_lo:[0,1] neg_hi:[0,1]
	v_pk_mul_f32 v[114:115], v[116:117], v[114:115]
	v_pk_mul_f32 v[106:107], v[116:117], v[106:107]
	ds_write_b32 v178, v85 offset:3392
	v_pk_fma_f32 v[114:115], v[104:105], v[114:115], v[100:101] op_sel_hi:[0,1,0]
	v_cvt_pk_bf16_f32 v85, v114, v115
	v_pk_fma_f32 v[106:107], v[160:161], v[106:107], v[162:163] op_sel_hi:[0,1,0]
	ds_write_b32 v178, v85 offset:5568
	v_cvt_pk_bf16_f32 v85, v106, v107
	v_lshlrev_b32_e32 v106, 16, v108
	v_lshlrev_b32_e32 v107, 16, v112
	v_pk_add_f32 v[106:107], v[106:107], v[118:119] neg_lo:[0,1] neg_hi:[0,1]
	ds_write_b32 v178, v85 offset:7744
	v_pk_mul_f32 v[106:107], v[116:117], v[106:107]
	s_nop 0
	v_pk_fma_f32 v[106:107], v[82:83], v[106:107], v[86:87] op_sel_hi:[0,1,0]
	v_cvt_pk_bf16_f32 v85, v106, v107
	v_and_b32_e32 v106, 0xffff0000, v108
	v_and_b32_e32 v107, 0xffff0000, v112
	v_pk_add_f32 v[106:107], v[106:107], v[118:119] neg_lo:[0,1] neg_hi:[0,1]
	ds_write_b32 v178, v85 offset:9920
	v_pk_mul_f32 v[106:107], v[116:117], v[106:107]
	s_nop 0
	v_pk_fma_f32 v[106:107], v[82:83], v[106:107], v[86:87] op_sel:[1,0,1]
	s_nop 0
	v_cvt_pk_bf16_f32 v85, v106, v107
	v_lshlrev_b32_e32 v106, 16, v109
	v_lshlrev_b32_e32 v107, 16, v113
	v_pk_add_f32 v[106:107], v[106:107], v[118:119] neg_lo:[0,1] neg_hi:[0,1]
	ds_write_b32 v178, v85 offset:12096
	v_pk_mul_f32 v[106:107], v[116:117], v[106:107]
	s_nop 0
	v_pk_fma_f32 v[106:107], v[84:85], v[106:107], v[88:89] op_sel_hi:[0,1,0]
	v_cvt_pk_bf16_f32 v85, v106, v107
	v_and_b32_e32 v106, 0xffff0000, v109
	v_and_b32_e32 v107, 0xffff0000, v113
	v_pk_add_f32 v[106:107], v[106:107], v[118:119] neg_lo:[0,1] neg_hi:[0,1]
	ds_write_b32 v178, v85 offset:14272
	v_pk_mul_f32 v[106:107], v[116:117], v[106:107]
	s_nop 0
	v_pk_fma_f32 v[106:107], v[164:165], v[106:107], v[166:167] op_sel_hi:[0,1,0]
	v_cvt_pk_bf16_f32 v85, v106, v107
	ds_write_b32 v178, v85 offset:16448
	ds_read_b128 v[106:109], v182 offset:896
	s_waitcnt lgkmcnt(0)
; __device__ __forceinline__ unsigned cvt_pk_bf16(float lo, float hi) { unsigned r; asm volatile("v_cvt_pk_bf16_f32 %0, %1, %2" : "=v"(r) : "v"(lo), "v"(hi)); return r; }
; __device__ __forceinline__ float bf_lo(unsigned w) { return __uint_as_float(w << 16); }
; __device__ __forceinline__ float bf_hi(unsigned w) { return __uint_as_float(w & 0xffff0000u); }
; #define LAS __attribute__((address_space(3)))
; __device__ __forceinline__ void sgu_unit(LAS unsigned char* lds, bf16* U, const bf16* VS, const float* SGS, const float* lnw, const float* lnb, const v4u* WF, const float* bsl, int unit, int tid) {
;     ...
;         for (int i = 0; i < 8; ++i) {
;             const f32x4 st4 = *(const LAS f32x4*)(stat + 4 * (rp + 8 * i));
;             const v4u w0 = sl[i][0], w1 = sl[i][1];
;             const unsigned A0[4] = {w0.x, w0.y, w0.z, w0.w}, A1[4] = {w1.x, w1.y, w1.z, w1.w};
; #pragma unroll
;             for (int e = 0; e < 8; ++e) { typedef float f32x2p __attribute__((ext_vector_type(2)));
;                 f32x2p v; v.x = (e & 1) ? bf_hi(A0[e >> 1]) : bf_lo(A0[e >> 1]); v.y = (e & 1) ? bf_hi(A1[e >> 1]) : bf_lo(A1[e >> 1]);
;                 const f32x2p mn = {st4.x, st4.z}, rs = {st4.y, st4.w};
;                 const f32x2p o = ((v - mn) * rs) * lw[e] + lb[e];
;                 *(LAS unsigned*)(wbase + e * 8 * SGU_VP + i * 32) = cvt_pk_bf16(o.x, o.y); }
;         }
;     }
;     v2u uu[8][4];
; #pragma unroll
;     for (int mt = 0; mt < 8; ++mt)
; #pragma unroll
;         for (int nt = 0; nt < 4; ++nt) uu[mt][nt] = *(const v2u*)(U + (size_t)(r0 + 16 * mt + fr) * 1024 + colbase + 16 * nt + 4 * fq);
	v_mov_b32_e32 v110, v106
	v_mov_b32_e32 v111, v108
	v_mov_b32_e32 v108, v107
	s_waitcnt vmcnt(1)
	v_lshlrev_b32_e32 v106, 16, v90
	s_waitcnt vmcnt(0)
	v_lshlrev_b32_e32 v107, 16, v94
	v_pk_add_f32 v[106:107], v[106:107], v[110:111] neg_lo:[0,1] neg_hi:[0,1]
	s_nop 0
	v_pk_mul_f32 v[106:107], v[108:109], v[106:107]
	s_nop 0
	v_pk_fma_f32 v[106:107], v[102:103], v[106:107], v[98:99] op_sel_hi:[0,1,0]
	v_cvt_pk_bf16_f32 v85, v106, v107
	v_and_b32_e32 v106, 0xffff0000, v90
	v_and_b32_e32 v107, 0xffff0000, v94
	v_pk_add_f32 v[106:107], v[106:107], v[110:111] neg_lo:[0,1] neg_hi:[0,1]
	ds_write_b32 v178, v85 offset:1248
	v_pk_mul_f32 v[106:107], v[108:109], v[106:107]
	v_and_b32_e32 v90, 0xffff0000, v91
	v_pk_fma_f32 v[98:99], v[102:103], v[106:107], v[98:99] op_sel:[1,0,1]
	s_nop 0
	v_cvt_pk_bf16_f32 v85, v98, v99
	v_lshlrev_b32_e32 v98, 16, v91
	v_lshlrev_b32_e32 v99, 16, v95
	v_and_b32_e32 v91, 0xffff0000, v95
	v_pk_add_f32 v[98:99], v[98:99], v[110:111] neg_lo:[0,1] neg_hi:[0,1]
	v_pk_add_f32 v[90:91], v[90:91], v[110:111] neg_lo:[0,1] neg_hi:[0,1]
	v_pk_mul_f32 v[98:99], v[108:109], v[98:99]
	v_pk_mul_f32 v[90:91], v[108:109], v[90:91]
	ds_write_b32 v178, v85 offset:3424
	v_pk_fma_f32 v[98:99], v[104:105], v[98:99], v[100:101] op_sel_hi:[0,1,0]
	v_cvt_pk_bf16_f32 v85, v98, v99
	v_pk_fma_f32 v[90:91], v[160:161], v[90:91], v[162:163] op_sel_hi:[0,1,0]
	ds_write_b32 v178, v85 offset:5600
	v_cvt_pk_bf16_f32 v85, v90, v91
	v_lshlrev_b32_e32 v90, 16, v92
	v_lshlrev_b32_e32 v91, 16, v96
	v_pk_add_f32 v[90:91], v[90:91], v[110:111] neg_lo:[0,1] neg_hi:[0,1]
	ds_write_b32 v178, v85 offset:7776
	v_pk_mul_f32 v[90:91], v[108:109], v[90:91]
	s_nop 0
	v_pk_fma_f32 v[90:91], v[82:83], v[90:91], v[86:87] op_sel_hi:[0,1,0]
	v_cvt_pk_bf16_f32 v85, v90, v91
	v_and_b32_e32 v90, 0xffff0000, v92
	v_and_b32_e32 v91, 0xffff0000, v96
	v_pk_add_f32 v[90:91], v[90:91], v[110:111] neg_lo:[0,1] neg_hi:[0,1]
	ds_write_b32 v178, v85 offset:9952
	v_pk_mul_f32 v[90:91], v[108:109], v[90:91]
	s_nop 0
	v_pk_fma_f32 v[82:83], v[82:83], v[90:91], v[86:87] op_sel:[1,0,1]
	s_nop 0
	v_cvt_pk_bf16_f32 v82, v82, v83
	ds_write_b32 v178, v82 offset:12128
	v_lshlrev_b32_e32 v82, 16, v93
	v_lshlrev_b32_e32 v83, 16, v97
	v_pk_add_f32 v[82:83], v[82:83], v[110:111] neg_lo:[0,1] neg_hi:[0,1]
	s_nop 0
	v_pk_mul_f32 v[82:83], v[108:109], v[82:83]
	s_nop 0
	v_pk_fma_f32 v[82:83], v[84:85], v[82:83], v[88:89] op_sel_hi:[0,1,0]
	v_cvt_pk_bf16_f32 v82, v82, v83
	ds_write_b32 v178, v82 offset:14304
	v_and_b32_e32 v82, 0xffff0000, v93
	v_and_b32_e32 v83, 0xffff0000, v97
	v_pk_add_f32 v[82:83], v[82:83], v[110:111] neg_lo:[0,1] neg_hi:[0,1]
	v_or_b32_e32 v84, s16, v163
	v_pk_mul_f32 v[82:83], v[108:109], v[82:83]
	v_lshlrev_b32_e32 v84, 11, v84
	v_pk_fma_f32 v[82:83], v[164:165], v[82:83], v[166:167] op_sel_hi:[0,1,0]
	v_cvt_pk_bf16_f32 v82, v82, v83
	ds_write_b32 v178, v82 offset:16480
	v_lshl_add_u64 v[82:83], v[158:159], 1, v[150:151]
	v_mov_b32_e32 v85, v147
	v_lshl_add_u64 v[144:145], v[82:83], 0, v[84:85]
	global_load_dwordx2 v[158:159], v[144:145], off
	global_load_dwordx2 v[218:219], v[144:145], off offset:32
	global_load_dwordx2 v[220:221], v[144:145], off offset:64
	global_load_dwordx2 v[222:223], v[144:145], off offset:96
	v_add_co_u32_e32 v226, vcc, s40, v144
	s_waitcnt vmcnt(3)
	v_lshlrev_b32_e32 v160, 16, v158
	v_addc_co_u32_e32 v227, vcc, 0, v145, vcc
	global_load_dwordx2 v[224:225], v[226:227], off
	global_load_dwordx2 v[228:229], v[226:227], off offset:32
	global_load_dwordx2 v[230:231], v[226:227], off offset:64
	global_load_dwordx2 v[232:233], v[226:227], off offset:96
	v_add_co_u32_e32 v130, vcc, s41, v144
	v_and_b32_e32 v158, 0xffff0000, v158
	s_nop 0
	v_addc_co_u32_e32 v131, vcc, 0, v145, vcc
	v_add_co_u32_e32 v120, vcc, s44, v144
	global_load_dwordx2 v[234:235], v[130:131], off
	global_load_dwordx2 v[138:139], v[130:131], off offset:32
	global_load_dwordx2 v[136:137], v[130:131], off offset:64
	global_load_dwordx2 v[134:135], v[130:131], off offset:96
	v_addc_co_u32_e32 v121, vcc, 0, v145, vcc
	v_add_co_u32_e32 v110, vcc, s45, v144
	global_load_dwordx2 v[132:133], v[120:121], off
	global_load_dwordx2 v[128:129], v[120:121], off offset:32
	global_load_dwordx2 v[126:127], v[120:121], off offset:64
	global_load_dwordx2 v[124:125], v[120:121], off offset:96
	v_addc_co_u32_e32 v111, vcc, 0, v145, vcc
	v_add_co_u32_e32 v100, vcc, s46, v144
	global_load_dwordx2 v[122:123], v[110:111], off
	global_load_dwordx2 v[118:119], v[110:111], off offset:32
	global_load_dwordx2 v[116:117], v[110:111], off offset:64
	global_load_dwordx2 v[114:115], v[110:111], off offset:96
	v_addc_co_u32_e32 v101, vcc, 0, v145, vcc
	v_add_co_u32_e32 v90, vcc, s47, v144
	global_load_dwordx2 v[112:113], v[100:101], off
	global_load_dwordx2 v[108:109], v[100:101], off offset:32
	global_load_dwordx2 v[106:107], v[100:101], off offset:64
	global_load_dwordx2 v[104:105], v[100:101], off offset:96
	v_addc_co_u32_e32 v91, vcc, 0, v145, vcc
	v_add_co_u32_e32 v82, vcc, s59, v144
	global_load_dwordx2 v[102:103], v[90:91], off
	global_load_dwordx2 v[98:99], v[90:91], off offset:32
	global_load_dwordx2 v[96:97], v[90:91], off offset:64
	global_load_dwordx2 v[94:95], v[90:91], off offset:96
	v_addc_co_u32_e32 v83, vcc, 0, v145, vcc
	global_load_dwordx2 v[92:93], v[82:83], off
	global_load_dwordx2 v[88:89], v[82:83], off offset:32
	global_load_dwordx2 v[86:87], v[82:83], off offset:64
	global_load_dwordx2 v[84:85], v[82:83], off offset:96
	s_waitcnt lgkmcnt(0)
	ds_read_b128 v[140:143], v183 offset:1024
	ds_read_b128 v[206:209], v183 offset:1568
	s_waitcnt lgkmcnt(1)
; __device__ __forceinline__ unsigned cvt_pk_bf16(float lo, float hi) { unsigned r; asm volatile("v_cvt_pk_bf16_f32 %0, %1, %2" : "=v"(r) : "v"(lo), "v"(hi)); return r; }
; __device__ __forceinline__ float bf_lo(unsigned w) { return __uint_as_float(w << 16); }
; __device__ __forceinline__ float bf_hi(unsigned w) { return __uint_as_float(w & 0xffff0000u); }
; #define LAS __attribute__((address_space(3)))
; __device__ __forceinline__ void sgu_unit(LAS unsigned char* lds, bf16* U, const bf16* VS, const float* SGS, const float* lnw, const float* lnb, const v4u* WF, const float* bsl, int unit, int tid) {
;     ...
;         for (int mt = 0; mt < 8; ++mt) {
;             const int t = 16 * mt + fr;
;             f32x4 acc[4];
; #pragma unroll
;             for (int nt = 0; nt < 4; ++nt) acc[nt] = (f32x4){0.f, 0.f, 0.f, 0.f};
; #pragma unroll
;             for (int ks = 0; ks <= (mt >> 1); ++ks) {
;                 const int sb = 32 * ks + 8 * fq; const bf16x8_t wf = __builtin_bit_cast(bf16x8_t, wfr[q++]);
; #pragma unroll
;                 for (int nt = 0; nt < 4; ++nt) { const bf16x8_t vf = *(const LAS bf16x8_t*)(vt + ((fr >> 3) + 8 * (fr & 7) + 2 * nt) * SGU_VP + sb * 2);
;                     acc[nt] = __builtin_amdgcn_mfma_f32_16x16x32_bf16(vf, wf, acc[nt], 0, 0, 0); }
;             }
;             const float bb = bbv[mt];
; #pragma unroll
;             for (int nt = 0; nt < 4; ++nt) { const v2u u2 = uu[mt][nt]; v2u w; w.x = cvt_pk_bf16(bf_lo(u2.x) * (acc[nt][0] + bb), bf_hi(u2.x) * (acc[nt][1] + bb)); w.y = cvt_pk_bf16(bf_lo(u2.y) * (acc[nt][2] + bb), bf_hi(u2.y) * (acc[nt][3] + bb));
;                 *(v2u*)(U + (size_t)(r0 + t) * 1024 + colbase + 16 * nt + 4 * fq) = w; }
	v_mfma_f32_16x16x32_bf16 v[140:143], v[140:143], v[78:81], 0
	ds_read_b128 v[210:213], v183 offset:2112
	ds_read_b128 v[214:217], v183 offset:2656
	s_nop 5
	v_add_f32_e32 v140, v198, v140
	v_add_f32_e32 v141, v198, v141
	s_waitcnt lgkmcnt(2)
	v_mfma_f32_16x16x32_bf16 v[206:209], v[206:209], v[78:81], 0
	v_mul_f32_e32 v140, v140, v160
	v_mul_f32_e32 v141, v141, v158
	v_cvt_pk_bf16_f32 v140, v140, v141
	v_lshlrev_b32_e32 v141, 16, v159
	v_add_f32_e32 v142, v198, v142
	v_mul_f32_e32 v141, v142, v141
	v_and_b32_e32 v142, 0xffff0000, v159
	v_add_f32_e32 v143, v198, v143
	v_mul_f32_e32 v142, v143, v142
	v_cvt_pk_bf16_f32 v141, v141, v142
	global_store_dwordx2 v[144:145], v[140:141], off
	s_waitcnt vmcnt(31)
	v_lshlrev_b32_e32 v140, 16, v218
	v_add_f32_e32 v141, v198, v206
	v_mul_f32_e32 v140, v141, v140
	v_and_b32_e32 v141, 0xffff0000, v218
	v_add_f32_e32 v142, v198, v207
	s_waitcnt lgkmcnt(1)
	v_mfma_f32_16x16x32_bf16 v[210:213], v[210:213], v[78:81], 0
	v_mul_f32_e32 v141, v142, v141
	v_cvt_pk_bf16_f32 v140, v140, v141
	v_lshlrev_b32_e32 v141, 16, v219
	v_add_f32_e32 v142, v198, v208
	v_mul_f32_e32 v141, v142, v141
	v_and_b32_e32 v142, 0xffff0000, v219
	v_add_f32_e32 v143, v198, v209
	v_mul_f32_e32 v142, v143, v142
	v_cvt_pk_bf16_f32 v141, v141, v142
	global_store_dwordx2 v[144:145], v[140:141], off offset:32
	s_waitcnt vmcnt(31)
	v_lshlrev_b32_e32 v140, 16, v220
	v_add_f32_e32 v141, v198, v210
	s_waitcnt lgkmcnt(0)
	v_mfma_f32_16x16x32_bf16 v[78:81], v[214:217], v[78:81], 0
	v_mul_f32_e32 v140, v141, v140
	v_and_b32_e32 v141, 0xffff0000, v220
	v_add_f32_e32 v142, v198, v211
	v_mul_f32_e32 v141, v142, v141
	v_cvt_pk_bf16_f32 v140, v140, v141
	v_lshlrev_b32_e32 v141, 16, v221
	v_add_f32_e32 v142, v198, v212
	v_mul_f32_e32 v141, v142, v141
	v_and_b32_e32 v142, 0xffff0000, v221
	v_add_f32_e32 v143, v198, v213
	v_mul_f32_e32 v142, v143, v142
	v_cvt_pk_bf16_f32 v141, v141, v142
	global_store_dwordx2 v[144:145], v[140:141], off offset:64
	s_waitcnt vmcnt(31)
	v_lshlrev_b32_e32 v140, 16, v222
	v_add_f32_e32 v78, v198, v78
	v_mul_f32_e32 v78, v78, v140
	v_and_b32_e32 v140, 0xffff0000, v222
	v_add_f32_e32 v79, v198, v79
	v_mul_f32_e32 v79, v79, v140
	v_cvt_pk_bf16_f32 v158, v78, v79
	v_lshlrev_b32_e32 v78, 16, v223
	v_add_f32_e32 v79, v198, v80
	v_mul_f32_e32 v78, v79, v78
	v_and_b32_e32 v79, 0xffff0000, v223
	v_add_f32_e32 v80, v198, v81
	v_mul_f32_e32 v79, v80, v79
	v_cvt_pk_bf16_f32 v159, v78, v79
	ds_read_b128 v[78:81], v183 offset:1024
	ds_read_b128 v[140:143], v183 offset:1568
	s_waitcnt lgkmcnt(1)
	v_mfma_f32_16x16x32_bf16 v[78:81], v[78:81], v[74:77], 0
	ds_read_b128 v[206:209], v183 offset:2112
	ds_read_b128 v[210:213], v183 offset:2656
	global_store_dwordx2 v[144:145], v[158:159], off offset:96
	s_waitcnt vmcnt(31)
	v_lshlrev_b32_e32 v144, 16, v224
	s_nop 2
	v_add_f32_e32 v78, v197, v78
	v_mul_f32_e32 v78, v78, v144
	v_and_b32_e32 v144, 0xffff0000, v224
	v_add_f32_e32 v79, v197, v79
	s_waitcnt lgkmcnt(2)
	v_mfma_f32_16x16x32_bf16 v[140:143], v[140:143], v[74:77], 0
	v_mul_f32_e32 v79, v79, v144
	v_cvt_pk_bf16_f32 v78, v78, v79
	v_lshlrev_b32_e32 v79, 16, v225
	v_add_f32_e32 v80, v197, v80
	v_mul_f32_e32 v79, v80, v79
	v_and_b32_e32 v80, 0xffff0000, v225
	v_add_f32_e32 v81, v197, v81
	v_mul_f32_e32 v80, v81, v80
	v_cvt_pk_bf16_f32 v79, v79, v80
	global_store_dwordx2 v[226:227], v[78:79], off
	s_waitcnt vmcnt(31)
	v_lshlrev_b32_e32 v78, 16, v228
	v_add_f32_e32 v79, v197, v140
	v_mul_f32_e32 v78, v79, v78
	v_and_b32_e32 v79, 0xffff0000, v228
	v_add_f32_e32 v80, v197, v141
	s_waitcnt lgkmcnt(1)
	v_mfma_f32_16x16x32_bf16 v[206:209], v[206:209], v[74:77], 0
	v_mul_f32_e32 v79, v80, v79
	v_cvt_pk_bf16_f32 v78, v78, v79
	v_lshlrev_b32_e32 v79, 16, v229
	v_add_f32_e32 v80, v197, v142
	v_mul_f32_e32 v79, v80, v79
	v_and_b32_e32 v80, 0xffff0000, v229
	v_add_f32_e32 v81, v197, v143
	v_mul_f32_e32 v80, v81, v80
	v_cvt_pk_bf16_f32 v79, v79, v80
	global_store_dwordx2 v[226:227], v[78:79], off offset:32
	s_waitcnt vmcnt(31)
	v_lshlrev_b32_e32 v78, 16, v230
	v_add_f32_e32 v79, v197, v206
	s_waitcnt lgkmcnt(0)
	v_mfma_f32_16x16x32_bf16 v[74:77], v[210:213], v[74:77], 0
	v_mul_f32_e32 v78, v79, v78
	v_and_b32_e32 v79, 0xffff0000, v230
	v_add_f32_e32 v80, v197, v207
	v_mul_f32_e32 v79, v80, v79
	v_cvt_pk_bf16_f32 v78, v78, v79
	v_lshlrev_b32_e32 v79, 16, v231
	v_add_f32_e32 v80, v197, v208
	v_mul_f32_e32 v79, v80, v79
	v_and_b32_e32 v80, 0xffff0000, v231
	v_add_f32_e32 v81, v197, v209
	v_mul_f32_e32 v80, v81, v80
	v_cvt_pk_bf16_f32 v79, v79, v80
	global_store_dwordx2 v[226:227], v[78:79], off offset:64
	s_waitcnt vmcnt(31)
	v_lshlrev_b32_e32 v78, 16, v232
	v_add_f32_e32 v74, v197, v74
	v_mul_f32_e32 v74, v74, v78
	v_and_b32_e32 v78, 0xffff0000, v232
	v_add_f32_e32 v75, v197, v75
	v_mul_f32_e32 v75, v75, v78
	v_cvt_pk_bf16_f32 v144, v74, v75
	v_lshlrev_b32_e32 v74, 16, v233
	v_add_f32_e32 v75, v197, v76
	v_mul_f32_e32 v74, v75, v74
	v_and_b32_e32 v75, 0xffff0000, v233
	v_add_f32_e32 v76, v197, v77
	v_mul_f32_e32 v75, v76, v75
	v_cvt_pk_bf16_f32 v145, v74, v75
	ds_read_b128 v[74:77], v183 offset:1024
	ds_read_b128 v[78:81], v183 offset:1088
	s_waitcnt lgkmcnt(1)
	v_mfma_f32_16x16x32_bf16 v[74:77], v[74:77], v[70:73], 0
	ds_read_b128 v[140:143], v183 offset:1568
	ds_read_b128 v[206:209], v183 offset:1632
	ds_read_b128 v[210:213], v183 offset:2112
	ds_read_b128 v[214:217], v183 offset:2176
	ds_read_b128 v[218:221], v183 offset:2656
	ds_read_b128 v[222:225], v183 offset:2720
	s_waitcnt lgkmcnt(5)
	v_mfma_f32_16x16x32_bf16 v[140:143], v[140:143], v[70:73], 0
	global_store_dwordx2 v[226:227], v[144:145], off offset:96
	s_waitcnt lgkmcnt(3)
; __device__ __forceinline__ unsigned cvt_pk_bf16(float lo, float hi) { unsigned r; asm volatile("v_cvt_pk_bf16_f32 %0, %1, %2" : "=v"(r) : "v"(lo), "v"(hi)); return r; }
; __device__ __forceinline__ float bf_lo(unsigned w) { return __uint_as_float(w << 16); }
; __device__ __forceinline__ float bf_hi(unsigned w) { return __uint_as_float(w & 0xffff0000u); }
; #define LAS __attribute__((address_space(3)))
; __device__ __forceinline__ void sgu_unit(LAS unsigned char* lds, bf16* U, const bf16* VS, const float* SGS, const float* lnw, const float* lnb, const v4u* WF, const float* bsl, int unit, int tid) {
;     ...
;         for (int mt = 0; mt < 8; ++mt) {
;             const int t = 16 * mt + fr;
;             f32x4 acc[4];
; #pragma unroll
;             for (int nt = 0; nt < 4; ++nt) acc[nt] = (f32x4){0.f, 0.f, 0.f, 0.f};
; #pragma unroll
;             for (int ks = 0; ks <= (mt >> 1); ++ks) {
;                 const int sb = 32 * ks + 8 * fq; const bf16x8_t wf = __builtin_bit_cast(bf16x8_t, wfr[q++]);
; #pragma unroll
;                 for (int nt = 0; nt < 4; ++nt) { const bf16x8_t vf = *(const LAS bf16x8_t*)(vt + ((fr >> 3) + 8 * (fr & 7) + 2 * nt) * SGU_VP + sb * 2);
;                     acc[nt] = __builtin_amdgcn_mfma_f32_16x16x32_bf16(vf, wf, acc[nt], 0, 0, 0); }
;             }
;             const float bb = bbv[mt];
; #pragma unroll
;             for (int nt = 0; nt < 4; ++nt) { const v2u u2 = uu[mt][nt]; v2u w; w.x = cvt_pk_bf16(bf_lo(u2.x) * (acc[nt][0] + bb), bf_hi(u2.x) * (acc[nt][1] + bb)); w.y = cvt_pk_bf16(bf_lo(u2.y) * (acc[nt][2] + bb), bf_hi(u2.y) * (acc[nt][3] + bb));
;                 *(v2u*)(U + (size_t)(r0 + t) * 1024 + colbase + 16 * nt + 4 * fq) = w; }
	v_mfma_f32_16x16x32_bf16 v[210:213], v[210:213], v[70:73], 0
	s_waitcnt lgkmcnt(1)
	v_mfma_f32_16x16x32_bf16 v[70:73], v[218:221], v[70:73], 0
	v_mfma_f32_16x16x32_bf16 v[74:77], v[78:81], v[66:69], v[74:77]
	v_mfma_f32_16x16x32_bf16 v[78:81], v[206:209], v[66:69], v[140:143]
	v_mfma_f32_16x16x32_bf16 v[140:143], v[214:217], v[66:69], v[210:213]
	s_waitcnt lgkmcnt(0)
	v_mfma_f32_16x16x32_bf16 v[66:69], v[222:225], v[66:69], v[70:73]
	s_waitcnt vmcnt(31)
	s_nop 1
	v_lshlrev_b32_e32 v70, 16, v234
	v_add_f32_e32 v71, v196, v74
	v_mul_f32_e32 v70, v71, v70
	v_and_b32_e32 v71, 0xffff0000, v234
	v_add_f32_e32 v72, v196, v75
	v_mul_f32_e32 v71, v72, v71
	v_cvt_pk_bf16_f32 v70, v70, v71
	v_lshlrev_b32_e32 v71, 16, v235
	v_add_f32_e32 v72, v196, v76
	v_mul_f32_e32 v71, v72, v71
	v_and_b32_e32 v72, 0xffff0000, v235
	v_add_f32_e32 v73, v196, v77
	v_mul_f32_e32 v72, v73, v72
	v_cvt_pk_bf16_f32 v71, v71, v72
	global_store_dwordx2 v[130:131], v[70:71], off
	s_waitcnt vmcnt(31)
	v_lshlrev_b32_e32 v70, 16, v138
	v_add_f32_e32 v71, v196, v78
	v_mul_f32_e32 v70, v71, v70
	v_and_b32_e32 v71, 0xffff0000, v138
	v_add_f32_e32 v72, v196, v79
	v_mul_f32_e32 v71, v72, v71
	v_cvt_pk_bf16_f32 v70, v70, v71
	v_lshlrev_b32_e32 v71, 16, v139
	v_add_f32_e32 v72, v196, v80
	v_mul_f32_e32 v71, v72, v71
	v_and_b32_e32 v72, 0xffff0000, v139
	v_add_f32_e32 v73, v196, v81
	v_mul_f32_e32 v72, v73, v72
	v_cvt_pk_bf16_f32 v71, v71, v72
	global_store_dwordx2 v[130:131], v[70:71], off offset:32
	s_waitcnt vmcnt(31)
	v_lshlrev_b32_e32 v70, 16, v136
	v_add_f32_e32 v71, v196, v140
	v_mul_f32_e32 v70, v71, v70
	v_and_b32_e32 v71, 0xffff0000, v136
	v_add_f32_e32 v72, v196, v141
	v_mul_f32_e32 v71, v72, v71
	v_cvt_pk_bf16_f32 v70, v70, v71
	v_lshlrev_b32_e32 v71, 16, v137
	v_add_f32_e32 v72, v196, v142
	v_mul_f32_e32 v71, v72, v71
	v_and_b32_e32 v72, 0xffff0000, v137
	v_add_f32_e32 v73, v196, v143
	v_mul_f32_e32 v72, v73, v72
	v_cvt_pk_bf16_f32 v71, v71, v72
	global_store_dwordx2 v[130:131], v[70:71], off offset:64
	s_waitcnt vmcnt(31)
	v_lshlrev_b32_e32 v70, 16, v134
	v_add_f32_e32 v66, v196, v66
	v_mul_f32_e32 v66, v66, v70
	v_and_b32_e32 v70, 0xffff0000, v134
	v_add_f32_e32 v67, v196, v67
	v_mul_f32_e32 v67, v67, v70
	v_cvt_pk_bf16_f32 v158, v66, v67
	v_lshlrev_b32_e32 v66, 16, v135
	v_add_f32_e32 v67, v196, v68
	v_mul_f32_e32 v66, v67, v66
	v_and_b32_e32 v67, 0xffff0000, v135
	v_add_f32_e32 v68, v196, v69
	v_mul_f32_e32 v67, v68, v67
	v_cvt_pk_bf16_f32 v159, v66, v67
	ds_read_b128 v[66:69], v183 offset:1024
	ds_read_b128 v[70:73], v183 offset:1088
	s_waitcnt lgkmcnt(1)
	v_mfma_f32_16x16x32_bf16 v[66:69], v[66:69], v[62:65], 0
	ds_read_b128 v[74:77], v183 offset:1568
	ds_read_b128 v[78:81], v183 offset:1632
	ds_read_b128 v[134:137], v183 offset:2112
	ds_read_b128 v[138:141], v183 offset:2176
	ds_read_b128 v[142:145], v183 offset:2656
	ds_read_b128 v[196:199], v183 offset:2720
	s_waitcnt lgkmcnt(5)
	v_mfma_f32_16x16x32_bf16 v[74:77], v[74:77], v[62:65], 0
	global_store_dwordx2 v[130:131], v[158:159], off offset:96
	s_waitcnt lgkmcnt(3)
	v_mfma_f32_16x16x32_bf16 v[134:137], v[134:137], v[62:65], 0
	s_waitcnt lgkmcnt(1)
	v_mfma_f32_16x16x32_bf16 v[62:65], v[142:145], v[62:65], 0
	v_mfma_f32_16x16x32_bf16 v[66:69], v[70:73], v[58:61], v[66:69]
	v_mfma_f32_16x16x32_bf16 v[70:73], v[78:81], v[58:61], v[74:77]
	v_mfma_f32_16x16x32_bf16 v[74:77], v[138:141], v[58:61], v[134:137]
	s_waitcnt lgkmcnt(0)
	v_mfma_f32_16x16x32_bf16 v[58:61], v[196:199], v[58:61], v[62:65]
	s_waitcnt vmcnt(31)
	s_nop 1
	v_lshlrev_b32_e32 v62, 16, v132
	v_add_f32_e32 v63, v195, v66
	v_mul_f32_e32 v62, v63, v62
	v_and_b32_e32 v63, 0xffff0000, v132
	v_add_f32_e32 v64, v195, v67
	v_mul_f32_e32 v63, v64, v63
	v_cvt_pk_bf16_f32 v62, v62, v63
	v_lshlrev_b32_e32 v63, 16, v133
	v_add_f32_e32 v64, v195, v68
	v_mul_f32_e32 v63, v64, v63
	v_and_b32_e32 v64, 0xffff0000, v133
	v_add_f32_e32 v65, v195, v69
	v_mul_f32_e32 v64, v65, v64
	v_cvt_pk_bf16_f32 v63, v63, v64
	global_store_dwordx2 v[120:121], v[62:63], off
	s_waitcnt vmcnt(31)
	v_lshlrev_b32_e32 v62, 16, v128
	v_add_f32_e32 v63, v195, v70
	v_mul_f32_e32 v62, v63, v62
	v_and_b32_e32 v63, 0xffff0000, v128
	v_add_f32_e32 v64, v195, v71
	v_mul_f32_e32 v63, v64, v63
	v_cvt_pk_bf16_f32 v62, v62, v63
	v_lshlrev_b32_e32 v63, 16, v129
	v_add_f32_e32 v64, v195, v72
	v_mul_f32_e32 v63, v64, v63
	v_and_b32_e32 v64, 0xffff0000, v129
	v_add_f32_e32 v65, v195, v73
	v_mul_f32_e32 v64, v65, v64
	v_cvt_pk_bf16_f32 v63, v63, v64
	global_store_dwordx2 v[120:121], v[62:63], off offset:32
	s_waitcnt vmcnt(31)
	v_lshlrev_b32_e32 v62, 16, v126
	v_add_f32_e32 v63, v195, v74
	v_mul_f32_e32 v62, v63, v62
	v_and_b32_e32 v63, 0xffff0000, v126
	v_add_f32_e32 v64, v195, v75
	v_mul_f32_e32 v63, v64, v63
	v_cvt_pk_bf16_f32 v62, v62, v63
	v_lshlrev_b32_e32 v63, 16, v127
	v_add_f32_e32 v64, v195, v76
	v_mul_f32_e32 v63, v64, v63
	v_and_b32_e32 v64, 0xffff0000, v127
	v_add_f32_e32 v65, v195, v77
	v_mul_f32_e32 v64, v65, v64
	v_cvt_pk_bf16_f32 v63, v63, v64
	global_store_dwordx2 v[120:121], v[62:63], off offset:64
	s_waitcnt vmcnt(31)
	v_lshlrev_b32_e32 v62, 16, v124
	v_add_f32_e32 v58, v195, v58
	v_mul_f32_e32 v58, v58, v62
	v_and_b32_e32 v62, 0xffff0000, v124
	v_add_f32_e32 v59, v195, v59
	v_mul_f32_e32 v59, v59, v62
	v_cvt_pk_bf16_f32 v132, v58, v59
	v_lshlrev_b32_e32 v58, 16, v125
	v_add_f32_e32 v59, v195, v60
	v_mul_f32_e32 v58, v59, v58
	v_and_b32_e32 v59, 0xffff0000, v125
	v_add_f32_e32 v60, v195, v61
	v_mul_f32_e32 v59, v60, v59
	v_cvt_pk_bf16_f32 v133, v58, v59
	ds_read_b128 v[58:61], v183 offset:1024
	ds_read_b128 v[62:65], v183 offset:1088
	s_waitcnt lgkmcnt(1)
; __device__ __forceinline__ unsigned cvt_pk_bf16(float lo, float hi) { unsigned r; asm volatile("v_cvt_pk_bf16_f32 %0, %1, %2" : "=v"(r) : "v"(lo), "v"(hi)); return r; }
; __device__ __forceinline__ float bf_lo(unsigned w) { return __uint_as_float(w << 16); }
; __device__ __forceinline__ float bf_hi(unsigned w) { return __uint_as_float(w & 0xffff0000u); }
; #define LAS __attribute__((address_space(3)))
; __device__ __forceinline__ void sgu_unit(LAS unsigned char* lds, bf16* U, const bf16* VS, const float* SGS, const float* lnw, const float* lnb, const v4u* WF, const float* bsl, int unit, int tid) {
;     ...
;         for (int mt = 0; mt < 8; ++mt) {
;             const int t = 16 * mt + fr;
;             f32x4 acc[4];
; #pragma unroll
;             for (int nt = 0; nt < 4; ++nt) acc[nt] = (f32x4){0.f, 0.f, 0.f, 0.f};
; #pragma unroll
;             for (int ks = 0; ks <= (mt >> 1); ++ks) {
;                 const int sb = 32 * ks + 8 * fq; const bf16x8_t wf = __builtin_bit_cast(bf16x8_t, wfr[q++]);
; #pragma unroll
;                 for (int nt = 0; nt < 4; ++nt) { const bf16x8_t vf = *(const LAS bf16x8_t*)(vt + ((fr >> 3) + 8 * (fr & 7) + 2 * nt) * SGU_VP + sb * 2);
;                     acc[nt] = __builtin_amdgcn_mfma_f32_16x16x32_bf16(vf, wf, acc[nt], 0, 0, 0); }
;             }
;             const float bb = bbv[mt];
; #pragma unroll
;             for (int nt = 0; nt < 4; ++nt) { const v2u u2 = uu[mt][nt]; v2u w; w.x = cvt_pk_bf16(bf_lo(u2.x) * (acc[nt][0] + bb), bf_hi(u2.x) * (acc[nt][1] + bb)); w.y = cvt_pk_bf16(bf_lo(u2.y) * (acc[nt][2] + bb), bf_hi(u2.y) * (acc[nt][3] + bb));
;                 *(v2u*)(U + (size_t)(r0 + t) * 1024 + colbase + 16 * nt + 4 * fq) = w; }
	v_mfma_f32_16x16x32_bf16 v[58:61], v[58:61], v[50:53], 0
	ds_read_b128 v[66:69], v183 offset:1568
	ds_read_b128 v[70:73], v183 offset:1152
	ds_read_b128 v[74:77], v183 offset:2112
	ds_read_b128 v[78:81], v183 offset:2176
	ds_read_b128 v[124:127], v183 offset:2656
	ds_read_b128 v[128:131], v183 offset:2240
	s_waitcnt lgkmcnt(5)
	v_mfma_f32_16x16x32_bf16 v[66:69], v[66:69], v[50:53], 0
	s_waitcnt lgkmcnt(3)
	v_mfma_f32_16x16x32_bf16 v[74:77], v[74:77], v[50:53], 0
	s_waitcnt lgkmcnt(1)
	v_mfma_f32_16x16x32_bf16 v[50:53], v[124:127], v[50:53], 0
	v_mfma_f32_16x16x32_bf16 v[58:61], v[62:65], v[54:57], v[58:61]
	ds_read_b128 v[62:65], v183 offset:1632
	ds_read_b128 v[124:127], v183 offset:1696
	s_waitcnt lgkmcnt(1)
	v_mfma_f32_16x16x32_bf16 v[62:65], v[62:65], v[54:57], v[66:69]
	v_mfma_f32_16x16x32_bf16 v[66:69], v[78:81], v[54:57], v[74:77]
	s_nop 2
	ds_read_b128 v[74:77], v183 offset:2720
	ds_read_b128 v[78:81], v183 offset:2784
	global_store_dwordx2 v[120:121], v[132:133], off offset:96
	s_waitcnt lgkmcnt(1)
	v_mfma_f32_16x16x32_bf16 v[50:53], v[74:77], v[54:57], v[50:53]
	v_mfma_f32_16x16x32_bf16 v[54:57], v[70:73], v[46:49], v[58:61]
	v_mfma_f32_16x16x32_bf16 v[58:61], v[124:127], v[46:49], v[62:65]
	v_mfma_f32_16x16x32_bf16 v[62:65], v[128:131], v[46:49], v[66:69]
	s_waitcnt lgkmcnt(0)
	v_mfma_f32_16x16x32_bf16 v[46:49], v[78:81], v[46:49], v[50:53]
	s_waitcnt vmcnt(31)
	s_nop 1
	v_lshlrev_b32_e32 v50, 16, v122
	v_add_f32_e32 v51, v194, v54
	v_mul_f32_e32 v50, v51, v50
	v_and_b32_e32 v51, 0xffff0000, v122
	v_add_f32_e32 v52, v194, v55
	v_mul_f32_e32 v51, v52, v51
	v_cvt_pk_bf16_f32 v50, v50, v51
	v_lshlrev_b32_e32 v51, 16, v123
	v_add_f32_e32 v52, v194, v56
	v_mul_f32_e32 v51, v52, v51
	v_and_b32_e32 v52, 0xffff0000, v123
	v_add_f32_e32 v53, v194, v57
	v_mul_f32_e32 v52, v53, v52
	v_cvt_pk_bf16_f32 v51, v51, v52
	global_store_dwordx2 v[110:111], v[50:51], off
	s_waitcnt vmcnt(31)
	v_lshlrev_b32_e32 v50, 16, v118
	v_add_f32_e32 v51, v194, v58
	v_mul_f32_e32 v50, v51, v50
	v_and_b32_e32 v51, 0xffff0000, v118
	v_add_f32_e32 v52, v194, v59
	v_mul_f32_e32 v51, v52, v51
	v_cvt_pk_bf16_f32 v50, v50, v51
	v_lshlrev_b32_e32 v51, 16, v119
	v_add_f32_e32 v52, v194, v60
	v_mul_f32_e32 v51, v52, v51
	v_and_b32_e32 v52, 0xffff0000, v119
	v_add_f32_e32 v53, v194, v61
	v_mul_f32_e32 v52, v53, v52
	v_cvt_pk_bf16_f32 v51, v51, v52
	global_store_dwordx2 v[110:111], v[50:51], off offset:32
	s_waitcnt vmcnt(31)
	v_lshlrev_b32_e32 v50, 16, v116
	v_add_f32_e32 v51, v194, v62
	v_mul_f32_e32 v50, v51, v50
	v_and_b32_e32 v51, 0xffff0000, v116
	v_add_f32_e32 v52, v194, v63
	v_mul_f32_e32 v51, v52, v51
	v_cvt_pk_bf16_f32 v50, v50, v51
	v_lshlrev_b32_e32 v51, 16, v117
	v_add_f32_e32 v52, v194, v64
	v_mul_f32_e32 v51, v52, v51
	v_and_b32_e32 v52, 0xffff0000, v117
	v_add_f32_e32 v53, v194, v65
	v_mul_f32_e32 v52, v53, v52
	v_cvt_pk_bf16_f32 v51, v51, v52
	global_store_dwordx2 v[110:111], v[50:51], off offset:64
	s_waitcnt vmcnt(31)
	v_lshlrev_b32_e32 v50, 16, v114
	v_add_f32_e32 v46, v194, v46
	v_mul_f32_e32 v46, v46, v50
	v_and_b32_e32 v50, 0xffff0000, v114
	v_add_f32_e32 v47, v194, v47
	v_mul_f32_e32 v47, v47, v50
	v_cvt_pk_bf16_f32 v78, v46, v47
	v_lshlrev_b32_e32 v46, 16, v115
	v_add_f32_e32 v47, v194, v48
	v_mul_f32_e32 v46, v47, v46
	v_and_b32_e32 v47, 0xffff0000, v115
	v_add_f32_e32 v48, v194, v49
	v_mul_f32_e32 v47, v48, v47
	v_cvt_pk_bf16_f32 v79, v46, v47
	ds_read_b128 v[46:49], v183 offset:1024
	ds_read_b128 v[50:53], v183 offset:1088
	s_waitcnt lgkmcnt(1)
	v_mfma_f32_16x16x32_bf16 v[46:49], v[46:49], v[42:45], 0
	ds_read_b128 v[54:57], v183 offset:1568
	ds_read_b128 v[58:61], v183 offset:1152
	ds_read_b128 v[62:65], v183 offset:2112
	ds_read_b128 v[66:69], v183 offset:2176
	ds_read_b128 v[70:73], v183 offset:2656
	ds_read_b128 v[74:77], v183 offset:2240
	s_waitcnt lgkmcnt(5)
	v_mfma_f32_16x16x32_bf16 v[54:57], v[54:57], v[42:45], 0
	s_waitcnt lgkmcnt(3)
	v_mfma_f32_16x16x32_bf16 v[62:65], v[62:65], v[42:45], 0
	s_waitcnt lgkmcnt(1)
	v_mfma_f32_16x16x32_bf16 v[42:45], v[70:73], v[42:45], 0
	v_mfma_f32_16x16x32_bf16 v[46:49], v[50:53], v[34:37], v[46:49]
	ds_read_b128 v[50:53], v183 offset:1632
	ds_read_b128 v[70:73], v183 offset:1696
	s_waitcnt lgkmcnt(1)
	v_mfma_f32_16x16x32_bf16 v[50:53], v[50:53], v[34:37], v[54:57]
	v_mfma_f32_16x16x32_bf16 v[54:57], v[66:69], v[34:37], v[62:65]
	s_nop 2
	ds_read_b128 v[62:65], v183 offset:2720
	ds_read_b128 v[66:69], v183 offset:2784
	global_store_dwordx2 v[110:111], v[78:79], off offset:96
	s_waitcnt lgkmcnt(1)
	v_mfma_f32_16x16x32_bf16 v[34:37], v[62:65], v[34:37], v[42:45]
	v_mfma_f32_16x16x32_bf16 v[42:45], v[58:61], v[38:41], v[46:49]
	v_mfma_f32_16x16x32_bf16 v[46:49], v[70:73], v[38:41], v[50:53]
	v_mfma_f32_16x16x32_bf16 v[50:53], v[74:77], v[38:41], v[54:57]
	s_waitcnt lgkmcnt(0)
	v_mfma_f32_16x16x32_bf16 v[34:37], v[66:69], v[38:41], v[34:37]
	s_waitcnt vmcnt(31)
	v_lshlrev_b32_e32 v38, 16, v112
	s_nop 1
	v_add_f32_e32 v39, v193, v42
	v_mul_f32_e32 v38, v39, v38
	v_and_b32_e32 v39, 0xffff0000, v112
	v_add_f32_e32 v40, v193, v43
	v_mul_f32_e32 v39, v40, v39
	v_cvt_pk_bf16_f32 v38, v38, v39
	v_lshlrev_b32_e32 v39, 16, v113
	v_add_f32_e32 v40, v193, v44
	v_mul_f32_e32 v39, v40, v39
	v_and_b32_e32 v40, 0xffff0000, v113
	v_add_f32_e32 v41, v193, v45
	v_mul_f32_e32 v40, v41, v40
	v_cvt_pk_bf16_f32 v39, v39, v40
	global_store_dwordx2 v[100:101], v[38:39], off
	s_waitcnt vmcnt(31)
; __device__ __forceinline__ unsigned cvt_pk_bf16(float lo, float hi) { unsigned r; asm volatile("v_cvt_pk_bf16_f32 %0, %1, %2" : "=v"(r) : "v"(lo), "v"(hi)); return r; }
; __device__ __forceinline__ float bf_lo(unsigned w) { return __uint_as_float(w << 16); }
; __device__ __forceinline__ float bf_hi(unsigned w) { return __uint_as_float(w & 0xffff0000u); }
; #define LAS __attribute__((address_space(3)))
; __device__ __forceinline__ void sgu_unit(LAS unsigned char* lds, bf16* U, const bf16* VS, const float* SGS, const float* lnw, const float* lnb, const v4u* WF, const float* bsl, int unit, int tid) {
;     ...
;         for (int mt = 0; mt < 8; ++mt) {
;             const int t = 16 * mt + fr;
;             f32x4 acc[4];
; #pragma unroll
;             for (int nt = 0; nt < 4; ++nt) acc[nt] = (f32x4){0.f, 0.f, 0.f, 0.f};
; #pragma unroll
;             for (int ks = 0; ks <= (mt >> 1); ++ks) {
;                 const int sb = 32 * ks + 8 * fq; const bf16x8_t wf = __builtin_bit_cast(bf16x8_t, wfr[q++]);
; #pragma unroll
;                 for (int nt = 0; nt < 4; ++nt) { const bf16x8_t vf = *(const LAS bf16x8_t*)(vt + ((fr >> 3) + 8 * (fr & 7) + 2 * nt) * SGU_VP + sb * 2);
;                     acc[nt] = __builtin_amdgcn_mfma_f32_16x16x32_bf16(vf, wf, acc[nt], 0, 0, 0); }
;             }
;             const float bb = bbv[mt];
; #pragma unroll
;             for (int nt = 0; nt < 4; ++nt) { const v2u u2 = uu[mt][nt]; v2u w; w.x = cvt_pk_bf16(bf_lo(u2.x) * (acc[nt][0] + bb), bf_hi(u2.x) * (acc[nt][1] + bb)); w.y = cvt_pk_bf16(bf_lo(u2.y) * (acc[nt][2] + bb), bf_hi(u2.y) * (acc[nt][3] + bb));
;                 *(v2u*)(U + (size_t)(r0 + t) * 1024 + colbase + 16 * nt + 4 * fq) = w; }
	v_lshlrev_b32_e32 v38, 16, v108
	v_add_f32_e32 v39, v193, v46
	v_mul_f32_e32 v38, v39, v38
	v_and_b32_e32 v39, 0xffff0000, v108
	v_add_f32_e32 v40, v193, v47
	v_mul_f32_e32 v39, v40, v39
	v_cvt_pk_bf16_f32 v38, v38, v39
	v_lshlrev_b32_e32 v39, 16, v109
	v_add_f32_e32 v40, v193, v48
	v_mul_f32_e32 v39, v40, v39
	v_and_b32_e32 v40, 0xffff0000, v109
	v_add_f32_e32 v41, v193, v49
	v_mul_f32_e32 v40, v41, v40
	v_cvt_pk_bf16_f32 v39, v39, v40
	global_store_dwordx2 v[100:101], v[38:39], off offset:32
	s_waitcnt vmcnt(31)
	v_lshlrev_b32_e32 v38, 16, v106
	v_add_f32_e32 v39, v193, v50
	v_mul_f32_e32 v38, v39, v38
	v_and_b32_e32 v39, 0xffff0000, v106
	v_add_f32_e32 v40, v193, v51
	v_mul_f32_e32 v39, v40, v39
	v_cvt_pk_bf16_f32 v38, v38, v39
	v_lshlrev_b32_e32 v39, 16, v107
	v_add_f32_e32 v40, v193, v52
	v_mul_f32_e32 v39, v40, v39
	v_and_b32_e32 v40, 0xffff0000, v107
	v_add_f32_e32 v41, v193, v53
	v_mul_f32_e32 v40, v41, v40
	v_cvt_pk_bf16_f32 v39, v39, v40
	global_store_dwordx2 v[100:101], v[38:39], off offset:64
	s_waitcnt vmcnt(31)
	v_lshlrev_b32_e32 v38, 16, v104
	v_add_f32_e32 v34, v193, v34
	v_mul_f32_e32 v34, v34, v38
	v_and_b32_e32 v38, 0xffff0000, v104
	v_add_f32_e32 v35, v193, v35
	v_mul_f32_e32 v35, v35, v38
	v_cvt_pk_bf16_f32 v66, v34, v35
	v_lshlrev_b32_e32 v34, 16, v105
	v_add_f32_e32 v35, v193, v36
	v_mul_f32_e32 v34, v35, v34
	v_and_b32_e32 v35, 0xffff0000, v105
	v_add_f32_e32 v36, v193, v37
	v_mul_f32_e32 v35, v36, v35
	v_cvt_pk_bf16_f32 v67, v34, v35
	ds_read_b128 v[34:37], v183 offset:1024
	ds_read_b128 v[38:41], v183 offset:1088
	ds_read_b128 v[42:45], v183 offset:1568
	ds_read_b128 v[46:49], v183 offset:1632
	ds_read_b128 v[50:53], v183 offset:2112
	ds_read_b128 v[54:57], v183 offset:2176
	ds_read_b128 v[58:61], v183 offset:2656
	ds_read_b128 v[62:65], v183 offset:2720
	s_waitcnt lgkmcnt(7)
	v_mfma_f32_16x16x32_bf16 v[34:37], v[34:37], v[30:33], 0
	s_waitcnt lgkmcnt(5)
	v_mfma_f32_16x16x32_bf16 v[42:45], v[42:45], v[30:33], 0
	s_waitcnt lgkmcnt(3)
	v_mfma_f32_16x16x32_bf16 v[50:53], v[50:53], v[30:33], 0
	s_waitcnt lgkmcnt(1)
	v_mfma_f32_16x16x32_bf16 v[30:33], v[58:61], v[30:33], 0
	v_mfma_f32_16x16x32_bf16 v[34:37], v[38:41], v[26:29], v[34:37]
	v_mfma_f32_16x16x32_bf16 v[38:41], v[46:49], v[26:29], v[42:45]
	v_mfma_f32_16x16x32_bf16 v[42:45], v[54:57], v[26:29], v[50:53]
	s_waitcnt lgkmcnt(0)
	v_mfma_f32_16x16x32_bf16 v[26:29], v[62:65], v[26:29], v[30:33]
	s_nop 2
	ds_read_b128 v[30:33], v183 offset:1152
	ds_read_b128 v[46:49], v183 offset:1216
	s_waitcnt lgkmcnt(1)
	v_mfma_f32_16x16x32_bf16 v[30:33], v[30:33], v[22:25], v[34:37]
	s_nop 2
	ds_read_b128 v[34:37], v183 offset:1696
	ds_read_b128 v[50:53], v183 offset:1760
	s_waitcnt lgkmcnt(1)
	v_mfma_f32_16x16x32_bf16 v[34:37], v[34:37], v[22:25], v[38:41]
	s_nop 2
	ds_read_b128 v[38:41], v183 offset:2240
	ds_read_b128 v[54:57], v183 offset:2304
	s_waitcnt lgkmcnt(1)
	v_mfma_f32_16x16x32_bf16 v[38:41], v[38:41], v[22:25], v[42:45]
	s_nop 2
	ds_read_b128 v[42:45], v183 offset:2784
	ds_read_b128 v[58:61], v183 offset:2848
	global_store_dwordx2 v[100:101], v[66:67], off offset:96
	s_waitcnt lgkmcnt(1)
	v_mfma_f32_16x16x32_bf16 v[22:25], v[42:45], v[22:25], v[26:29]
	v_mfma_f32_16x16x32_bf16 v[26:29], v[46:49], v[18:21], v[30:33]
	v_mfma_f32_16x16x32_bf16 v[30:33], v[50:53], v[18:21], v[34:37]
	v_mfma_f32_16x16x32_bf16 v[34:37], v[54:57], v[18:21], v[38:41]
	s_waitcnt lgkmcnt(0)
	v_mfma_f32_16x16x32_bf16 v[18:21], v[58:61], v[18:21], v[22:25]
	s_waitcnt vmcnt(31)
	s_nop 1
	v_lshlrev_b32_e32 v22, 16, v102
	v_add_f32_e32 v23, v192, v26
	v_mul_f32_e32 v22, v23, v22
	v_and_b32_e32 v23, 0xffff0000, v102
	v_add_f32_e32 v24, v192, v27
	v_mul_f32_e32 v23, v24, v23
	v_cvt_pk_bf16_f32 v22, v22, v23
	v_lshlrev_b32_e32 v23, 16, v103
	v_add_f32_e32 v24, v192, v28
	v_mul_f32_e32 v23, v24, v23
	v_and_b32_e32 v24, 0xffff0000, v103
	v_add_f32_e32 v25, v192, v29
	v_mul_f32_e32 v24, v25, v24
	v_cvt_pk_bf16_f32 v23, v23, v24
	global_store_dwordx2 v[90:91], v[22:23], off
	s_waitcnt vmcnt(31)
	v_lshlrev_b32_e32 v22, 16, v98
	v_add_f32_e32 v23, v192, v30
	v_mul_f32_e32 v22, v23, v22
	v_and_b32_e32 v23, 0xffff0000, v98
	v_add_f32_e32 v24, v192, v31
	v_mul_f32_e32 v23, v24, v23
	v_cvt_pk_bf16_f32 v22, v22, v23
	v_lshlrev_b32_e32 v23, 16, v99
	v_add_f32_e32 v24, v192, v32
	v_mul_f32_e32 v23, v24, v23
	v_and_b32_e32 v24, 0xffff0000, v99
	v_add_f32_e32 v25, v192, v33
	v_mul_f32_e32 v24, v25, v24
	v_cvt_pk_bf16_f32 v23, v23, v24
	global_store_dwordx2 v[90:91], v[22:23], off offset:32
	s_waitcnt vmcnt(31)
; __device__ __forceinline__ unsigned cvt_pk_bf16(float lo, float hi) { unsigned r; asm volatile("v_cvt_pk_bf16_f32 %0, %1, %2" : "=v"(r) : "v"(lo), "v"(hi)); return r; }
; __device__ __forceinline__ float bf_lo(unsigned w) { return __uint_as_float(w << 16); }
; __device__ __forceinline__ float bf_hi(unsigned w) { return __uint_as_float(w & 0xffff0000u); }
; #define LAS __attribute__((address_space(3)))
; __device__ __forceinline__ void sgu_unit(LAS unsigned char* lds, bf16* U, const bf16* VS, const float* SGS, const float* lnw, const float* lnb, const v4u* WF, const float* bsl, int unit, int tid) {
;     ...
;         for (int mt = 0; mt < 8; ++mt) {
;             const int t = 16 * mt + fr;
;             f32x4 acc[4];
; #pragma unroll
;             for (int nt = 0; nt < 4; ++nt) acc[nt] = (f32x4){0.f, 0.f, 0.f, 0.f};
; #pragma unroll
;             for (int ks = 0; ks <= (mt >> 1); ++ks) {
;                 const int sb = 32 * ks + 8 * fq; const bf16x8_t wf = __builtin_bit_cast(bf16x8_t, wfr[q++]);
; #pragma unroll
;                 for (int nt = 0; nt < 4; ++nt) { const bf16x8_t vf = *(const LAS bf16x8_t*)(vt + ((fr >> 3) + 8 * (fr & 7) + 2 * nt) * SGU_VP + sb * 2);
;                     acc[nt] = __builtin_amdgcn_mfma_f32_16x16x32_bf16(vf, wf, acc[nt], 0, 0, 0); }
;             }
;             const float bb = bbv[mt];
; #pragma unroll
;             for (int nt = 0; nt < 4; ++nt) { const v2u u2 = uu[mt][nt]; v2u w; w.x = cvt_pk_bf16(bf_lo(u2.x) * (acc[nt][0] + bb), bf_hi(u2.x) * (acc[nt][1] + bb)); w.y = cvt_pk_bf16(bf_lo(u2.y) * (acc[nt][2] + bb), bf_hi(u2.y) * (acc[nt][3] + bb));
;                 *(v2u*)(U + (size_t)(r0 + t) * 1024 + colbase + 16 * nt + 4 * fq) = w; }
;         }
;     }
;     __syncthreads();
	v_lshlrev_b32_e32 v22, 16, v96
	v_add_f32_e32 v23, v192, v34
	v_mul_f32_e32 v22, v23, v22
	v_and_b32_e32 v23, 0xffff0000, v96
	v_add_f32_e32 v24, v192, v35
	v_mul_f32_e32 v23, v24, v23
	v_cvt_pk_bf16_f32 v22, v22, v23
	v_lshlrev_b32_e32 v23, 16, v97
	v_add_f32_e32 v24, v192, v36
	v_mul_f32_e32 v23, v24, v23
	v_and_b32_e32 v24, 0xffff0000, v97
	v_add_f32_e32 v25, v192, v37
	v_mul_f32_e32 v24, v25, v24
	v_cvt_pk_bf16_f32 v23, v23, v24
	global_store_dwordx2 v[90:91], v[22:23], off offset:64
	s_waitcnt vmcnt(31)
	v_lshlrev_b32_e32 v22, 16, v94
	v_add_f32_e32 v18, v192, v18
	v_mul_f32_e32 v18, v18, v22
	v_and_b32_e32 v22, 0xffff0000, v94
	v_add_f32_e32 v19, v192, v19
	v_mul_f32_e32 v19, v19, v22
	v_cvt_pk_bf16_f32 v50, v18, v19
	v_lshlrev_b32_e32 v18, 16, v95
	v_add_f32_e32 v19, v192, v20
	v_mul_f32_e32 v18, v19, v18
	v_and_b32_e32 v19, 0xffff0000, v95
	v_add_f32_e32 v20, v192, v21
	v_mul_f32_e32 v19, v20, v19
	v_cvt_pk_bf16_f32 v51, v18, v19
	ds_read_b128 v[18:21], v183 offset:1024
	ds_read_b128 v[22:25], v183 offset:1088
	ds_read_b128 v[26:29], v183 offset:1568
	ds_read_b128 v[30:33], v183 offset:1632
	ds_read_b128 v[34:37], v183 offset:2112
	ds_read_b128 v[38:41], v183 offset:2176
	ds_read_b128 v[42:45], v183 offset:2656
	ds_read_b128 v[46:49], v183 offset:2720
	s_waitcnt lgkmcnt(7)
	v_mfma_f32_16x16x32_bf16 v[18:21], v[18:21], v[14:17], 0
	s_waitcnt lgkmcnt(5)
	v_mfma_f32_16x16x32_bf16 v[26:29], v[26:29], v[14:17], 0
	s_waitcnt lgkmcnt(3)
	v_mfma_f32_16x16x32_bf16 v[34:37], v[34:37], v[14:17], 0
	s_waitcnt lgkmcnt(1)
	v_mfma_f32_16x16x32_bf16 v[14:17], v[42:45], v[14:17], 0
	v_mfma_f32_16x16x32_bf16 v[18:21], v[22:25], v[10:13], v[18:21]
	v_mfma_f32_16x16x32_bf16 v[22:25], v[30:33], v[10:13], v[26:29]
	v_mfma_f32_16x16x32_bf16 v[26:29], v[38:41], v[10:13], v[34:37]
	s_waitcnt lgkmcnt(0)
	v_mfma_f32_16x16x32_bf16 v[10:13], v[46:49], v[10:13], v[14:17]
	s_nop 2
	ds_read_b128 v[14:17], v183 offset:1152
	ds_read_b128 v[30:33], v183 offset:1216
	s_waitcnt lgkmcnt(1)
	v_mfma_f32_16x16x32_bf16 v[14:17], v[14:17], v[6:9], v[18:21]
	s_nop 2
	ds_read_b128 v[18:21], v183 offset:1696
	ds_read_b128 v[34:37], v183 offset:1760
	s_waitcnt lgkmcnt(1)
	v_mfma_f32_16x16x32_bf16 v[18:21], v[18:21], v[6:9], v[22:25]
	s_nop 2
	ds_read_b128 v[22:25], v183 offset:2240
	ds_read_b128 v[38:41], v183 offset:2304
	s_waitcnt lgkmcnt(1)
	v_mfma_f32_16x16x32_bf16 v[22:25], v[22:25], v[6:9], v[26:29]
	s_nop 2
	ds_read_b128 v[26:29], v183 offset:2784
	ds_read_b128 v[42:45], v183 offset:2848
	global_store_dwordx2 v[90:91], v[50:51], off offset:96
	s_waitcnt lgkmcnt(1)
	v_mfma_f32_16x16x32_bf16 v[6:9], v[26:29], v[6:9], v[10:13]
	v_mfma_f32_16x16x32_bf16 v[10:13], v[30:33], v[2:5], v[14:17]
	v_mfma_f32_16x16x32_bf16 v[14:17], v[34:37], v[2:5], v[18:21]
	v_mfma_f32_16x16x32_bf16 v[18:21], v[38:41], v[2:5], v[22:25]
	s_waitcnt lgkmcnt(0)
	v_mfma_f32_16x16x32_bf16 v[2:5], v[42:45], v[2:5], v[6:9]
	s_waitcnt vmcnt(31)
	s_nop 1
	v_lshlrev_b32_e32 v6, 16, v92
	v_add_f32_e32 v7, v157, v10
	v_mul_f32_e32 v6, v7, v6
	v_and_b32_e32 v7, 0xffff0000, v92
	v_add_f32_e32 v8, v157, v11
	v_mul_f32_e32 v7, v8, v7
	v_cvt_pk_bf16_f32 v6, v6, v7
	v_lshlrev_b32_e32 v7, 16, v93
	v_add_f32_e32 v8, v157, v12
	v_mul_f32_e32 v7, v8, v7
	v_and_b32_e32 v8, 0xffff0000, v93
	v_add_f32_e32 v9, v157, v13
	v_mul_f32_e32 v8, v9, v8
	v_cvt_pk_bf16_f32 v7, v7, v8
	global_store_dwordx2 v[82:83], v[6:7], off
	s_waitcnt vmcnt(31)
	v_lshlrev_b32_e32 v6, 16, v88
	v_add_f32_e32 v7, v157, v14
	v_mul_f32_e32 v6, v7, v6
	v_and_b32_e32 v7, 0xffff0000, v88
	v_add_f32_e32 v8, v157, v15
	v_mul_f32_e32 v7, v8, v7
	v_cvt_pk_bf16_f32 v6, v6, v7
	v_lshlrev_b32_e32 v7, 16, v89
	v_add_f32_e32 v8, v157, v16
	v_mul_f32_e32 v7, v8, v7
	v_and_b32_e32 v8, 0xffff0000, v89
	v_add_f32_e32 v9, v157, v17
	v_mul_f32_e32 v8, v9, v8
	v_cvt_pk_bf16_f32 v7, v7, v8
	global_store_dwordx2 v[82:83], v[6:7], off offset:32
	s_waitcnt vmcnt(31)
	v_lshlrev_b32_e32 v6, 16, v86
	v_add_f32_e32 v7, v157, v18
	v_mul_f32_e32 v6, v7, v6
	v_and_b32_e32 v7, 0xffff0000, v86
	v_add_f32_e32 v8, v157, v19
	v_mul_f32_e32 v7, v8, v7
	v_cvt_pk_bf16_f32 v6, v6, v7
	v_lshlrev_b32_e32 v7, 16, v87
	v_add_f32_e32 v8, v157, v20
	v_mul_f32_e32 v7, v8, v7
	v_and_b32_e32 v8, 0xffff0000, v87
	v_add_f32_e32 v9, v157, v21
	v_mul_f32_e32 v8, v9, v8
	v_cvt_pk_bf16_f32 v7, v7, v8
	global_store_dwordx2 v[82:83], v[6:7], off offset:64
	s_waitcnt vmcnt(31)
	v_lshlrev_b32_e32 v6, 16, v84
	v_add_f32_e32 v2, v157, v2
	v_mul_f32_e32 v2, v2, v6
	v_and_b32_e32 v6, 0xffff0000, v84
	v_add_f32_e32 v3, v157, v3
	v_mul_f32_e32 v3, v3, v6
	v_cvt_pk_bf16_f32 v2, v2, v3
	v_lshlrev_b32_e32 v3, 16, v85
	v_add_f32_e32 v4, v157, v4
	v_mul_f32_e32 v3, v4, v3
	v_and_b32_e32 v4, 0xffff0000, v85
	v_add_f32_e32 v5, v157, v5
	v_mul_f32_e32 v4, v5, v4
	v_cvt_pk_bf16_f32 v3, v3, v4
	global_store_dwordx2 v[82:83], v[2:3], off offset:96
	s_barrier

; __device__ __forceinline__ float sigm(float v) { return __builtin_amdgcn_rcpf(1.0f + __expf(-v)); }
;     __host__ __device__ bool next(int i, Unit& u) const { Unit b; if (!base.next(i >> 1, b)) return false; u.pm = b.pm; u.pn = b.pn + 4 * (i & 1); return true; }
; __device__ __forceinline__ unsigned f2bf(float f) { unsigned u = __builtin_bit_cast(unsigned, f); return (u + 0x7fffu + ((u >> 16) & 1u)) >> 16; }
; __global__ void __launch_bounds__(512, 2) fwd_mega(Args a) {
;     ...
;                 for (int i = 0; S.next(i, fu); ++i) {
;                     if ((fu.pm & 15) == 0) continue;
;                     for (int idx = threadIdx.x; idx < 2 * FF; idx += 512) {
;                         const int j = idx / FF, f = idx % FF; const size_t cur = (size_t)fu.pm * 2 * FF, prv = (size_t)(fu.pm - 1) * 2 * FF;
;                         const float a2 = RA[cur + j * FF + f], a1 = (j == 0) ? TA[prv + FF + f] : RA[cur + f], a0 = (j == 0) ? TA[prv + f] : TA[prv + FF + f];
;                         const float cv = cbp[f] + cw[f] * a0 + cw[FF + f] * a1 + cw[2 * FF + f] * a2;
;                         WSP(WS_ACT)[(size_t)(fu.pm * 256 + j) * FF + f] = (bf16)f2bf(cv * pg8::sigm(cv) * RU[cur + j * FF + f]);
.LBB0_914:
	v_subrev_co_u32_e32 v6, vcc, 0xb00, v17
	s_nop 0
	v_mov_b32_e32 v41, v7
	v_cndmask_b32_e32 v40, v6, v17, vcc
	v_cmp_lt_u32_e64 s[6:7], s25, v17
	v_cndmask_b32_e32 v45, v11, v12, vcc
	v_cndmask_b32_e32 v44, v13, v14, vcc
	v_lshlrev_b64 v[46:47], 2, v[40:41]
	v_cndmask_b32_e32 v49, v12, v15, vcc
	v_cndmask_b32_e32 v48, v14, v16, vcc
	v_cndmask_b32_e64 v6, 0, v10, s[6:7]
	v_lshl_add_u64 v[44:45], v[44:45], 0, v[46:47]
	v_lshl_add_u64 v[48:49], v[48:49], 0, v[46:47]
	v_lshl_add_u64 v[50:51], s[10:11], 0, v[46:47]
	v_lshl_add_u64 v[46:47], s[8:9], 0, v[46:47]
	v_lshl_add_u64 v[42:43], v[6:7], 0, s[18:19]
	global_load_dword v44, v[44:45], off
	s_nop 0
	global_load_dword v57, v[48:49], off
	global_load_dword v53, v[50:51], off
	global_load_dword v54, v[46:47], off
	v_add_co_u32_e32 v48, vcc, s30, v46
	v_lshl_add_u64 v[42:43], v[42:43], 0, v[40:41]
	s_nop 0
	v_addc_co_u32_e32 v49, vcc, 0, v47, vcc
	v_lshlrev_b64 v[42:43], 2, v[42:43]
	v_add_co_u32_e32 v46, vcc, s31, v46
	v_lshl_add_u64 v[50:51], s[14:15], 0, v[42:43]
	s_nop 0
	v_addc_co_u32_e32 v47, vcc, 0, v47, vcc
	global_load_dword v48, v[48:49], off offset:3072
	s_nop 0
	global_load_dword v49, v[46:47], off offset:2048
	global_load_dword v45, v[50:51], off
	v_lshl_add_u64 v[42:43], s[16:17], 0, v[42:43]
	global_load_dword v46, v[42:43], off
	v_cndmask_b32_e64 v52, 0, 1, s[6:7]
	v_add_u32_e32 v17, 0x200, v17
	v_subrev_co_u32_e32 v6, vcc, 0xb00, v17
	s_nop 0
	v_mov_b32_e32 v59, v7
	v_cndmask_b32_e32 v58, v6, v17, vcc
	v_cmp_lt_u32_e64 s[6:7], s25, v17
	v_cndmask_b32_e32 v63, v11, v12, vcc
	v_cndmask_b32_e32 v62, v13, v14, vcc
	v_lshlrev_b64 v[64:65], 2, v[58:59]
	v_cndmask_b32_e32 v67, v12, v15, vcc
	v_cndmask_b32_e32 v66, v14, v16, vcc
	v_cndmask_b32_e64 v6, 0, v10, s[6:7]
	v_lshl_add_u64 v[62:63], v[62:63], 0, v[64:65]
	v_lshl_add_u64 v[66:67], v[66:67], 0, v[64:65]
	v_lshl_add_u64 v[68:69], s[10:11], 0, v[64:65]
	v_lshl_add_u64 v[64:65], s[8:9], 0, v[64:65]
	v_lshl_add_u64 v[60:61], v[6:7], 0, s[18:19]
	global_load_dword v62, v[62:63], off
	s_nop 0
	global_load_dword v75, v[66:67], off
	global_load_dword v71, v[68:69], off
	global_load_dword v72, v[64:65], off
	v_add_co_u32_e32 v66, vcc, s30, v64
	v_lshl_add_u64 v[60:61], v[60:61], 0, v[58:59]
	s_nop 0
	v_addc_co_u32_e32 v67, vcc, 0, v65, vcc
	v_lshlrev_b64 v[60:61], 2, v[60:61]
	v_add_co_u32_e32 v64, vcc, s31, v64
	v_lshl_add_u64 v[68:69], s[14:15], 0, v[60:61]
	s_nop 0
	v_addc_co_u32_e32 v65, vcc, 0, v65, vcc
	global_load_dword v66, v[66:67], off offset:3072
	s_nop 0
	global_load_dword v67, v[64:65], off offset:2048
	global_load_dword v63, v[68:69], off
	v_lshl_add_u64 v[60:61], s[16:17], 0, v[60:61]
	global_load_dword v64, v[60:61], off
	v_cndmask_b32_e64 v70, 0, 1, s[6:7]
	v_add_u32_e32 v17, 0x200, v17
	v_subrev_co_u32_e32 v6, vcc, 0xb00, v17
	s_nop 0
	v_mov_b32_e32 v77, v7
	v_cndmask_b32_e32 v76, v6, v17, vcc
	v_cmp_lt_u32_e64 s[6:7], s25, v17
	v_cndmask_b32_e32 v81, v11, v12, vcc
	v_cndmask_b32_e32 v80, v13, v14, vcc
	v_lshlrev_b64 v[82:83], 2, v[76:77]
	v_cndmask_b32_e32 v85, v12, v15, vcc
	v_cndmask_b32_e32 v84, v14, v16, vcc
	v_cndmask_b32_e64 v6, 0, v10, s[6:7]
	v_lshl_add_u64 v[80:81], v[80:81], 0, v[82:83]
	v_lshl_add_u64 v[84:85], v[84:85], 0, v[82:83]
	v_lshl_add_u64 v[86:87], s[10:11], 0, v[82:83]
	v_lshl_add_u64 v[82:83], s[8:9], 0, v[82:83]
	v_lshl_add_u64 v[78:79], v[6:7], 0, s[18:19]
	global_load_dword v80, v[80:81], off
	s_nop 0
	global_load_dword v93, v[84:85], off
	global_load_dword v89, v[86:87], off
	global_load_dword v90, v[82:83], off
	v_add_co_u32_e32 v84, vcc, s30, v82
	v_lshl_add_u64 v[78:79], v[78:79], 0, v[76:77]
	s_nop 0
	v_addc_co_u32_e32 v85, vcc, 0, v83, vcc
	v_lshlrev_b64 v[78:79], 2, v[78:79]
	v_add_co_u32_e32 v82, vcc, s31, v82
	v_lshl_add_u64 v[86:87], s[14:15], 0, v[78:79]
	s_nop 0
	v_addc_co_u32_e32 v83, vcc, 0, v83, vcc
	global_load_dword v84, v[84:85], off offset:3072
	s_nop 0
	global_load_dword v85, v[82:83], off offset:2048
	global_load_dword v81, v[86:87], off
	v_lshl_add_u64 v[78:79], s[16:17], 0, v[78:79]
	global_load_dword v82, v[78:79], off
	v_cndmask_b32_e64 v88, 0, 1, s[6:7]
	v_add_u32_e32 v17, 0x200, v17
	v_subrev_co_u32_e32 v6, vcc, 0xb00, v17
	s_nop 0
	v_mov_b32_e32 v95, v7
	v_cndmask_b32_e32 v94, v6, v17, vcc
	v_cmp_lt_u32_e64 s[6:7], s25, v17
	v_cndmask_b32_e32 v99, v11, v12, vcc
	v_cndmask_b32_e32 v98, v13, v14, vcc
	v_lshlrev_b64 v[100:101], 2, v[94:95]
	v_cndmask_b32_e32 v103, v12, v15, vcc
	v_cndmask_b32_e32 v102, v14, v16, vcc
	v_cndmask_b32_e64 v6, 0, v10, s[6:7]
	v_lshl_add_u64 v[98:99], v[98:99], 0, v[100:101]
	v_lshl_add_u64 v[102:103], v[102:103], 0, v[100:101]
	v_lshl_add_u64 v[104:105], s[10:11], 0, v[100:101]
	v_lshl_add_u64 v[100:101], s[8:9], 0, v[100:101]
	v_lshl_add_u64 v[96:97], v[6:7], 0, s[18:19]
	global_load_dword v98, v[98:99], off
	s_nop 0
	global_load_dword v111, v[102:103], off
	global_load_dword v107, v[104:105], off
	global_load_dword v108, v[100:101], off
	v_add_co_u32_e32 v102, vcc, s30, v100
	v_lshl_add_u64 v[96:97], v[96:97], 0, v[94:95]
	s_nop 0
	v_addc_co_u32_e32 v103, vcc, 0, v101, vcc
	v_lshlrev_b64 v[96:97], 2, v[96:97]
	v_add_co_u32_e32 v100, vcc, s31, v100
	v_lshl_add_u64 v[104:105], s[14:15], 0, v[96:97]
	s_nop 0
	v_addc_co_u32_e32 v101, vcc, 0, v101, vcc
	global_load_dword v102, v[102:103], off offset:3072
	s_nop 0
	global_load_dword v103, v[100:101], off offset:2048
	global_load_dword v99, v[104:105], off
	v_lshl_add_u64 v[96:97], s[16:17], 0, v[96:97]
	global_load_dword v100, v[96:97], off
	v_cndmask_b32_e64 v106, 0, 1, s[6:7]
	v_add_u32_e32 v17, 0x200, v17
	v_subrev_co_u32_e32 v6, vcc, 0xb00, v17
	s_nop 0
	v_mov_b32_e32 v113, v7
; __device__ __forceinline__ float sigm(float v) { return __builtin_amdgcn_rcpf(1.0f + __expf(-v)); }
; __device__ __forceinline__ unsigned f2bf(float f) { unsigned u = __builtin_bit_cast(unsigned, f); return (u + 0x7fffu + ((u >> 16) & 1u)) >> 16; }
; __global__ void __launch_bounds__(512, 2) fwd_mega(Args a) {
;     ...
;                     for (int idx = threadIdx.x; idx < 2 * FF; idx += 512) {
;                         const int j = idx / FF, f = idx % FF; const size_t cur = (size_t)fu.pm * 2 * FF, prv = (size_t)(fu.pm - 1) * 2 * FF;
;                         const float a2 = RA[cur + j * FF + f], a1 = (j == 0) ? TA[prv + FF + f] : RA[cur + f], a0 = (j == 0) ? TA[prv + f] : TA[prv + FF + f];
;                         const float cv = cbp[f] + cw[f] * a0 + cw[FF + f] * a1 + cw[2 * FF + f] * a2;
;                         WSP(WS_ACT)[(size_t)(fu.pm * 256 + j) * FF + f] = (bf16)f2bf(cv * pg8::sigm(cv) * RU[cur + j * FF + f]);
	v_cndmask_b32_e32 v112, v6, v17, vcc
	v_cmp_lt_u32_e64 s[6:7], s25, v17
	v_cndmask_b32_e32 v117, v11, v12, vcc
	v_cndmask_b32_e32 v116, v13, v14, vcc
	v_lshlrev_b64 v[118:119], 2, v[112:113]
	v_cndmask_b32_e32 v121, v12, v15, vcc
	v_cndmask_b32_e32 v120, v14, v16, vcc
	v_cndmask_b32_e64 v6, 0, v10, s[6:7]
	v_lshl_add_u64 v[116:117], v[116:117], 0, v[118:119]
	v_lshl_add_u64 v[120:121], v[120:121], 0, v[118:119]
	v_lshl_add_u64 v[122:123], s[10:11], 0, v[118:119]
	v_lshl_add_u64 v[118:119], s[8:9], 0, v[118:119]
	v_lshl_add_u64 v[114:115], v[6:7], 0, s[18:19]
	global_load_dword v116, v[116:117], off
	s_nop 0
	global_load_dword v129, v[120:121], off
	global_load_dword v125, v[122:123], off
	global_load_dword v126, v[118:119], off
	v_add_co_u32_e32 v120, vcc, s30, v118
	v_lshl_add_u64 v[114:115], v[114:115], 0, v[112:113]
	s_nop 0
	v_addc_co_u32_e32 v121, vcc, 0, v119, vcc
	v_lshlrev_b64 v[114:115], 2, v[114:115]
	v_add_co_u32_e32 v118, vcc, s31, v118
	v_lshl_add_u64 v[122:123], s[14:15], 0, v[114:115]
	s_nop 0
	v_addc_co_u32_e32 v119, vcc, 0, v119, vcc
	global_load_dword v120, v[120:121], off offset:3072
	s_nop 0
	global_load_dword v121, v[118:119], off offset:2048
	global_load_dword v117, v[122:123], off
	v_lshl_add_u64 v[114:115], s[16:17], 0, v[114:115]
	global_load_dword v118, v[114:115], off
	v_cndmask_b32_e64 v124, 0, 1, s[6:7]
	v_add_u32_e32 v17, 0x200, v17
	v_subrev_co_u32_e32 v6, vcc, 0xb00, v17
	s_nop 0
	v_mov_b32_e32 v131, v7
	v_cndmask_b32_e32 v130, v6, v17, vcc
	v_cmp_lt_u32_e64 s[6:7], s25, v17
	v_cndmask_b32_e32 v135, v11, v12, vcc
	v_cndmask_b32_e32 v134, v13, v14, vcc
	v_lshlrev_b64 v[136:137], 2, v[130:131]
	v_cndmask_b32_e32 v139, v12, v15, vcc
	v_cndmask_b32_e32 v138, v14, v16, vcc
	v_cndmask_b32_e64 v6, 0, v10, s[6:7]
	v_lshl_add_u64 v[134:135], v[134:135], 0, v[136:137]
	v_lshl_add_u64 v[138:139], v[138:139], 0, v[136:137]
	v_lshl_add_u64 v[140:141], s[10:11], 0, v[136:137]
	v_lshl_add_u64 v[136:137], s[8:9], 0, v[136:137]
	v_lshl_add_u64 v[132:133], v[6:7], 0, s[18:19]
	global_load_dword v134, v[134:135], off
	s_nop 0
	global_load_dword v147, v[138:139], off
	global_load_dword v143, v[140:141], off
	global_load_dword v144, v[136:137], off
	v_add_co_u32_e32 v138, vcc, s30, v136
	v_lshl_add_u64 v[132:133], v[132:133], 0, v[130:131]
	s_nop 0
	v_addc_co_u32_e32 v139, vcc, 0, v137, vcc
	v_lshlrev_b64 v[132:133], 2, v[132:133]
	v_add_co_u32_e32 v136, vcc, s31, v136
	v_lshl_add_u64 v[140:141], s[14:15], 0, v[132:133]
	s_nop 0
	v_addc_co_u32_e32 v137, vcc, 0, v137, vcc
	global_load_dword v138, v[138:139], off offset:3072
	s_nop 0
	global_load_dword v139, v[136:137], off offset:2048
	global_load_dword v135, v[140:141], off
	v_lshl_add_u64 v[132:133], s[16:17], 0, v[132:133]
	global_load_dword v136, v[132:133], off
	v_cndmask_b32_e64 v142, 0, 1, s[6:7]
	v_add_u32_e32 v17, 0x200, v17
	s_waitcnt vmcnt(40)
	v_fmac_f32_e32 v53, v57, v54
	s_nop 0
	v_pk_mul_f32 v[42:43], v[44:45], v[48:49]
	s_nop 0
	v_add_f32_e32 v57, v53, v42
	v_add_f32_e32 v57, v57, v43
	v_mul_f32_e32 v42, 0xbfb8aa3b, v57
	v_exp_f32_e32 v42, v42
	v_or_b32_e32 v43, s37, v52
	v_add_f32_e32 v42, 1.0, v42
	v_rcp_f32_e32 v44, v42
	v_mad_i64_i32 v[42:43], s[6:7], v43, s24, v[8:9]
	v_lshl_add_u64 v[40:41], v[40:41], 1, v[42:43]
	v_mul_f32_e32 v57, v57, v44
	s_nop 0
	v_mul_f32_e32 v57, v46, v57
	v_bfe_u32 v42, v57, 16, 1
	v_add3_u32 v57, v57, v42, s34
	global_store_short_d16_hi v[40:41], v57, off
	s_waitcnt vmcnt(33)
	v_fmac_f32_e32 v71, v75, v72
	s_nop 0
	v_pk_mul_f32 v[60:61], v[62:63], v[66:67]
	s_nop 0
	v_add_f32_e32 v75, v71, v60
	v_add_f32_e32 v75, v75, v61
	v_mul_f32_e32 v60, 0xbfb8aa3b, v75
	v_exp_f32_e32 v60, v60
	v_or_b32_e32 v61, s37, v70
	v_add_f32_e32 v60, 1.0, v60
	v_rcp_f32_e32 v62, v60
	v_mad_i64_i32 v[60:61], s[6:7], v61, s24, v[8:9]
	v_lshl_add_u64 v[58:59], v[58:59], 1, v[60:61]
	v_mul_f32_e32 v75, v75, v62
	s_nop 0
	v_mul_f32_e32 v75, v64, v75
	v_bfe_u32 v60, v75, 16, 1
	v_add3_u32 v75, v75, v60, s34
	global_store_short_d16_hi v[58:59], v75, off
	s_waitcnt vmcnt(26)
	v_fmac_f32_e32 v89, v93, v90
	s_nop 0
	v_pk_mul_f32 v[78:79], v[80:81], v[84:85]
	s_nop 0
	v_add_f32_e32 v93, v89, v78
	v_add_f32_e32 v93, v93, v79
	v_mul_f32_e32 v78, 0xbfb8aa3b, v93
	v_exp_f32_e32 v78, v78
	v_or_b32_e32 v79, s37, v88
	v_add_f32_e32 v78, 1.0, v78
	v_rcp_f32_e32 v80, v78
	v_mad_i64_i32 v[78:79], s[6:7], v79, s24, v[8:9]
	v_lshl_add_u64 v[76:77], v[76:77], 1, v[78:79]
	v_mul_f32_e32 v93, v93, v80
	s_nop 0
	v_mul_f32_e32 v93, v82, v93
	v_bfe_u32 v78, v93, 16, 1
	v_add3_u32 v93, v93, v78, s34
	global_store_short_d16_hi v[76:77], v93, off
	s_waitcnt vmcnt(19)
	v_fmac_f32_e32 v107, v111, v108
	s_nop 0
	v_pk_mul_f32 v[96:97], v[98:99], v[102:103]
	s_nop 0
	v_add_f32_e32 v111, v107, v96
	v_add_f32_e32 v111, v111, v97
	v_mul_f32_e32 v96, 0xbfb8aa3b, v111
	v_exp_f32_e32 v96, v96
	v_or_b32_e32 v97, s37, v106
	v_add_f32_e32 v96, 1.0, v96
	v_rcp_f32_e32 v98, v96
	v_mad_i64_i32 v[96:97], s[6:7], v97, s24, v[8:9]
	v_lshl_add_u64 v[94:95], v[94:95], 1, v[96:97]
	v_mul_f32_e32 v111, v111, v98
	s_nop 0
	v_mul_f32_e32 v111, v100, v111
	v_bfe_u32 v96, v111, 16, 1
	v_add3_u32 v111, v111, v96, s34
	global_store_short_d16_hi v[94:95], v111, off
	s_waitcnt vmcnt(12)
	v_fmac_f32_e32 v125, v129, v126
	s_nop 0
	v_pk_mul_f32 v[114:115], v[116:117], v[120:121]
	s_nop 0
	v_add_f32_e32 v129, v125, v114
	v_add_f32_e32 v129, v129, v115
	v_mul_f32_e32 v114, 0xbfb8aa3b, v129
	v_exp_f32_e32 v114, v114
	v_or_b32_e32 v115, s37, v124
	v_add_f32_e32 v114, 1.0, v114
	v_rcp_f32_e32 v116, v114
	v_mad_i64_i32 v[114:115], s[6:7], v115, s24, v[8:9]
	v_lshl_add_u64 v[112:113], v[112:113], 1, v[114:115]
	v_mul_f32_e32 v129, v129, v116
	s_nop 0
	v_mul_f32_e32 v129, v118, v129
	v_bfe_u32 v114, v129, 16, 1
	v_add3_u32 v129, v129, v114, s34
	global_store_short_d16_hi v[112:113], v129, off
	s_waitcnt vmcnt(5)
; __device__ __forceinline__ float sigm(float v) { return __builtin_amdgcn_rcpf(1.0f + __expf(-v)); }
; __device__ __forceinline__ unsigned f2bf(float f) { unsigned u = __builtin_bit_cast(unsigned, f); return (u + 0x7fffu + ((u >> 16) & 1u)) >> 16; }
; __global__ void __launch_bounds__(512, 2) fwd_mega(Args a) {
;     ...
;                     for (int idx = threadIdx.x; idx < 2 * FF; idx += 512) {
;                         const int j = idx / FF, f = idx % FF; const size_t cur = (size_t)fu.pm * 2 * FF, prv = (size_t)(fu.pm - 1) * 2 * FF;
;                         const float a2 = RA[cur + j * FF + f], a1 = (j == 0) ? TA[prv + FF + f] : RA[cur + f], a0 = (j == 0) ? TA[prv + f] : TA[prv + FF + f];
;                         const float cv = cbp[f] + cw[f] * a0 + cw[FF + f] * a1 + cw[2 * FF + f] * a2;
;                         WSP(WS_ACT)[(size_t)(fu.pm * 256 + j) * FF + f] = (bf16)f2bf(cv * pg8::sigm(cv) * RU[cur + j * FF + f]);
	v_fmac_f32_e32 v143, v147, v144
	s_nop 0
	v_pk_mul_f32 v[132:133], v[134:135], v[138:139]
	s_nop 0
	v_add_f32_e32 v147, v143, v132
	v_add_f32_e32 v147, v147, v133
	v_mul_f32_e32 v132, 0xbfb8aa3b, v147
	v_exp_f32_e32 v132, v132
	v_or_b32_e32 v133, s37, v142
	v_add_f32_e32 v132, 1.0, v132
	v_rcp_f32_e32 v134, v132
	v_mad_i64_i32 v[132:133], s[6:7], v133, s24, v[8:9]
	v_lshl_add_u64 v[130:131], v[130:131], 1, v[132:133]
	v_mul_f32_e32 v147, v147, v134
	s_nop 0
	v_mul_f32_e32 v147, v136, v147
	v_bfe_u32 v132, v147, 16, 1
	v_add3_u32 v147, v147, v132, s34
	global_store_short_d16_hi v[130:131], v147, off
	v_subrev_co_u32_e32 v6, vcc, 0xb00, v17
	s_nop 0
	v_mov_b32_e32 v41, v7
	v_cndmask_b32_e32 v40, v6, v17, vcc
	v_cmp_lt_u32_e64 s[6:7], s25, v17
	v_cndmask_b32_e32 v45, v11, v12, vcc
	v_cndmask_b32_e32 v44, v13, v14, vcc
	v_lshlrev_b64 v[46:47], 2, v[40:41]
	v_cndmask_b32_e32 v49, v12, v15, vcc
	v_cndmask_b32_e32 v48, v14, v16, vcc
	v_cndmask_b32_e64 v6, 0, v10, s[6:7]
	v_lshl_add_u64 v[44:45], v[44:45], 0, v[46:47]
	v_lshl_add_u64 v[48:49], v[48:49], 0, v[46:47]
	v_lshl_add_u64 v[50:51], s[10:11], 0, v[46:47]
	v_lshl_add_u64 v[46:47], s[8:9], 0, v[46:47]
	v_lshl_add_u64 v[42:43], v[6:7], 0, s[18:19]
	global_load_dword v44, v[44:45], off
	s_nop 0
	global_load_dword v57, v[48:49], off
	global_load_dword v53, v[50:51], off
	global_load_dword v54, v[46:47], off
	v_add_co_u32_e32 v48, vcc, s30, v46
	v_lshl_add_u64 v[42:43], v[42:43], 0, v[40:41]
	s_nop 0
	v_addc_co_u32_e32 v49, vcc, 0, v47, vcc
	v_lshlrev_b64 v[42:43], 2, v[42:43]
	v_add_co_u32_e32 v46, vcc, s31, v46
	v_lshl_add_u64 v[50:51], s[14:15], 0, v[42:43]
	s_nop 0
	v_addc_co_u32_e32 v47, vcc, 0, v47, vcc
	global_load_dword v48, v[48:49], off offset:3072
	s_nop 0
	global_load_dword v49, v[46:47], off offset:2048
	global_load_dword v45, v[50:51], off
	v_lshl_add_u64 v[42:43], s[16:17], 0, v[42:43]
	global_load_dword v46, v[42:43], off
	v_cndmask_b32_e64 v52, 0, 1, s[6:7]
	v_add_u32_e32 v17, 0x200, v17
	v_subrev_co_u32_e32 v6, vcc, 0xb00, v17
	s_nop 0
	v_mov_b32_e32 v59, v7
	v_cndmask_b32_e32 v58, v6, v17, vcc
	v_cmp_lt_u32_e64 s[6:7], s25, v17
	v_cndmask_b32_e32 v63, v11, v12, vcc
	v_cndmask_b32_e32 v62, v13, v14, vcc
	v_lshlrev_b64 v[64:65], 2, v[58:59]
	v_cndmask_b32_e32 v67, v12, v15, vcc
	v_cndmask_b32_e32 v66, v14, v16, vcc
	v_cndmask_b32_e64 v6, 0, v10, s[6:7]
	v_lshl_add_u64 v[62:63], v[62:63], 0, v[64:65]
	v_lshl_add_u64 v[66:67], v[66:67], 0, v[64:65]
	v_lshl_add_u64 v[68:69], s[10:11], 0, v[64:65]
	v_lshl_add_u64 v[64:65], s[8:9], 0, v[64:65]
	v_lshl_add_u64 v[60:61], v[6:7], 0, s[18:19]
	global_load_dword v62, v[62:63], off
	s_nop 0
	global_load_dword v75, v[66:67], off
	global_load_dword v71, v[68:69], off
	global_load_dword v72, v[64:65], off
	v_add_co_u32_e32 v66, vcc, s30, v64
	v_lshl_add_u64 v[60:61], v[60:61], 0, v[58:59]
	s_nop 0
	v_addc_co_u32_e32 v67, vcc, 0, v65, vcc
	v_lshlrev_b64 v[60:61], 2, v[60:61]
	v_add_co_u32_e32 v64, vcc, s31, v64
	v_lshl_add_u64 v[68:69], s[14:15], 0, v[60:61]
	s_nop 0
	v_addc_co_u32_e32 v65, vcc, 0, v65, vcc
	global_load_dword v66, v[66:67], off offset:3072
	s_nop 0
	global_load_dword v67, v[64:65], off offset:2048
	global_load_dword v63, v[68:69], off
	v_lshl_add_u64 v[60:61], s[16:17], 0, v[60:61]
	global_load_dword v64, v[60:61], off
	v_cndmask_b32_e64 v70, 0, 1, s[6:7]
	v_add_u32_e32 v17, 0x200, v17
	v_subrev_co_u32_e32 v6, vcc, 0xb00, v17
	s_nop 0
	v_mov_b32_e32 v77, v7
	v_cndmask_b32_e32 v76, v6, v17, vcc
	v_cmp_lt_u32_e64 s[6:7], s25, v17
	v_cndmask_b32_e32 v81, v11, v12, vcc
	v_cndmask_b32_e32 v80, v13, v14, vcc
	v_lshlrev_b64 v[82:83], 2, v[76:77]
	v_cndmask_b32_e32 v85, v12, v15, vcc
	v_cndmask_b32_e32 v84, v14, v16, vcc
	v_cndmask_b32_e64 v6, 0, v10, s[6:7]
	v_lshl_add_u64 v[80:81], v[80:81], 0, v[82:83]
	v_lshl_add_u64 v[84:85], v[84:85], 0, v[82:83]
	v_lshl_add_u64 v[86:87], s[10:11], 0, v[82:83]
	v_lshl_add_u64 v[82:83], s[8:9], 0, v[82:83]
	v_lshl_add_u64 v[78:79], v[6:7], 0, s[18:19]
	global_load_dword v80, v[80:81], off
	s_nop 0
	global_load_dword v93, v[84:85], off
	global_load_dword v89, v[86:87], off
	global_load_dword v90, v[82:83], off
	v_add_co_u32_e32 v84, vcc, s30, v82
	v_lshl_add_u64 v[78:79], v[78:79], 0, v[76:77]
	s_nop 0
	v_addc_co_u32_e32 v85, vcc, 0, v83, vcc
	v_lshlrev_b64 v[78:79], 2, v[78:79]
	v_add_co_u32_e32 v82, vcc, s31, v82
	v_lshl_add_u64 v[86:87], s[14:15], 0, v[78:79]
	s_nop 0
	v_addc_co_u32_e32 v83, vcc, 0, v83, vcc
	global_load_dword v84, v[84:85], off offset:3072
	s_nop 0
	global_load_dword v85, v[82:83], off offset:2048
	global_load_dword v81, v[86:87], off
	v_lshl_add_u64 v[78:79], s[16:17], 0, v[78:79]
	global_load_dword v82, v[78:79], off
	v_cndmask_b32_e64 v88, 0, 1, s[6:7]
	v_add_u32_e32 v17, 0x200, v17
	v_subrev_co_u32_e32 v6, vcc, 0xb00, v17
	s_nop 0
	v_mov_b32_e32 v95, v7
	v_cndmask_b32_e32 v94, v6, v17, vcc
	v_cmp_lt_u32_e64 s[6:7], s25, v17
	v_cndmask_b32_e32 v99, v11, v12, vcc
	v_cndmask_b32_e32 v98, v13, v14, vcc
	v_lshlrev_b64 v[100:101], 2, v[94:95]
	v_cndmask_b32_e32 v103, v12, v15, vcc
	v_cndmask_b32_e32 v102, v14, v16, vcc
	v_cndmask_b32_e64 v6, 0, v10, s[6:7]
	v_lshl_add_u64 v[98:99], v[98:99], 0, v[100:101]
	v_lshl_add_u64 v[102:103], v[102:103], 0, v[100:101]
	v_lshl_add_u64 v[104:105], s[10:11], 0, v[100:101]
	v_lshl_add_u64 v[100:101], s[8:9], 0, v[100:101]
; __device__ __forceinline__ float sigm(float v) { return __builtin_amdgcn_rcpf(1.0f + __expf(-v)); }
; __device__ __forceinline__ unsigned f2bf(float f) { unsigned u = __builtin_bit_cast(unsigned, f); return (u + 0x7fffu + ((u >> 16) & 1u)) >> 16; }
; __global__ void __launch_bounds__(512, 2) fwd_mega(Args a) {
;     ...
;                     for (int idx = threadIdx.x; idx < 2 * FF; idx += 512) {
;                         const int j = idx / FF, f = idx % FF; const size_t cur = (size_t)fu.pm * 2 * FF, prv = (size_t)(fu.pm - 1) * 2 * FF;
;                         const float a2 = RA[cur + j * FF + f], a1 = (j == 0) ? TA[prv + FF + f] : RA[cur + f], a0 = (j == 0) ? TA[prv + f] : TA[prv + FF + f];
;                         const float cv = cbp[f] + cw[f] * a0 + cw[FF + f] * a1 + cw[2 * FF + f] * a2;
;                         WSP(WS_ACT)[(size_t)(fu.pm * 256 + j) * FF + f] = (bf16)f2bf(cv * pg8::sigm(cv) * RU[cur + j * FF + f]);
;                     }
;                 }
	v_lshl_add_u64 v[96:97], v[6:7], 0, s[18:19]
	global_load_dword v98, v[98:99], off
	s_nop 0
	global_load_dword v111, v[102:103], off
	global_load_dword v107, v[104:105], off
	global_load_dword v108, v[100:101], off
	v_add_co_u32_e32 v102, vcc, s30, v100
	v_lshl_add_u64 v[96:97], v[96:97], 0, v[94:95]
	s_nop 0
	v_addc_co_u32_e32 v103, vcc, 0, v101, vcc
	v_lshlrev_b64 v[96:97], 2, v[96:97]
	v_add_co_u32_e32 v100, vcc, s31, v100
	v_lshl_add_u64 v[104:105], s[14:15], 0, v[96:97]
	s_nop 0
	v_addc_co_u32_e32 v101, vcc, 0, v101, vcc
	global_load_dword v102, v[102:103], off offset:3072
	s_nop 0
	global_load_dword v103, v[100:101], off offset:2048
	global_load_dword v99, v[104:105], off
	v_lshl_add_u64 v[96:97], s[16:17], 0, v[96:97]
	global_load_dword v100, v[96:97], off
	v_cndmask_b32_e64 v106, 0, 1, s[6:7]
	v_add_u32_e32 v17, 0x200, v17
	v_subrev_co_u32_e32 v6, vcc, 0xb00, v17
	s_nop 0
	v_mov_b32_e32 v113, v7
	v_cndmask_b32_e32 v112, v6, v17, vcc
	v_cmp_lt_u32_e64 s[6:7], s25, v17
	v_cndmask_b32_e32 v117, v11, v12, vcc
	v_cndmask_b32_e32 v116, v13, v14, vcc
	v_lshlrev_b64 v[118:119], 2, v[112:113]
	v_cndmask_b32_e32 v121, v12, v15, vcc
	v_cndmask_b32_e32 v120, v14, v16, vcc
	v_cndmask_b32_e64 v6, 0, v10, s[6:7]
	v_lshl_add_u64 v[116:117], v[116:117], 0, v[118:119]
	v_lshl_add_u64 v[120:121], v[120:121], 0, v[118:119]
	v_lshl_add_u64 v[122:123], s[10:11], 0, v[118:119]
	v_lshl_add_u64 v[118:119], s[8:9], 0, v[118:119]
	v_lshl_add_u64 v[114:115], v[6:7], 0, s[18:19]
	global_load_dword v116, v[116:117], off
	s_nop 0
	global_load_dword v129, v[120:121], off
	global_load_dword v125, v[122:123], off
	global_load_dword v126, v[118:119], off
	v_add_co_u32_e32 v120, vcc, s30, v118
	v_lshl_add_u64 v[114:115], v[114:115], 0, v[112:113]
	s_nop 0
	v_addc_co_u32_e32 v121, vcc, 0, v119, vcc
	v_lshlrev_b64 v[114:115], 2, v[114:115]
	v_add_co_u32_e32 v118, vcc, s31, v118
	v_lshl_add_u64 v[122:123], s[14:15], 0, v[114:115]
	s_nop 0
	v_addc_co_u32_e32 v119, vcc, 0, v119, vcc
	global_load_dword v120, v[120:121], off offset:3072
	s_nop 0
	global_load_dword v121, v[118:119], off offset:2048
	global_load_dword v117, v[122:123], off
	v_lshl_add_u64 v[114:115], s[16:17], 0, v[114:115]
	global_load_dword v118, v[114:115], off
	v_cndmask_b32_e64 v124, 0, 1, s[6:7]
	v_add_u32_e32 v17, 0x200, v17
	s_waitcnt vmcnt(32)
	v_fmac_f32_e32 v53, v57, v54
	s_nop 0
	v_pk_mul_f32 v[42:43], v[44:45], v[48:49]
	s_nop 0
	v_add_f32_e32 v57, v53, v42
	v_add_f32_e32 v57, v57, v43
	v_mul_f32_e32 v42, 0xbfb8aa3b, v57
	v_exp_f32_e32 v42, v42
	v_or_b32_e32 v43, s37, v52
	v_add_f32_e32 v42, 1.0, v42
	v_rcp_f32_e32 v44, v42
	v_mad_i64_i32 v[42:43], s[6:7], v43, s24, v[8:9]
	v_lshl_add_u64 v[40:41], v[40:41], 1, v[42:43]
	v_mul_f32_e32 v57, v57, v44
	s_nop 0
	v_mul_f32_e32 v57, v46, v57
	v_bfe_u32 v42, v57, 16, 1
	v_add3_u32 v57, v57, v42, s34
	global_store_short_d16_hi v[40:41], v57, off
	s_waitcnt vmcnt(25)
	v_fmac_f32_e32 v71, v75, v72
	s_nop 0
	v_pk_mul_f32 v[60:61], v[62:63], v[66:67]
	s_nop 0
	v_add_f32_e32 v75, v71, v60
	v_add_f32_e32 v75, v75, v61
	v_mul_f32_e32 v60, 0xbfb8aa3b, v75
	v_exp_f32_e32 v60, v60
	v_or_b32_e32 v61, s37, v70
	v_add_f32_e32 v60, 1.0, v60
	v_rcp_f32_e32 v62, v60
	v_mad_i64_i32 v[60:61], s[6:7], v61, s24, v[8:9]
	v_lshl_add_u64 v[58:59], v[58:59], 1, v[60:61]
	v_mul_f32_e32 v75, v75, v62
	s_nop 0
	v_mul_f32_e32 v75, v64, v75
	v_bfe_u32 v60, v75, 16, 1
	v_add3_u32 v75, v75, v60, s34
	global_store_short_d16_hi v[58:59], v75, off
	s_waitcnt vmcnt(18)
	v_fmac_f32_e32 v89, v93, v90
	s_nop 0
	v_pk_mul_f32 v[78:79], v[80:81], v[84:85]
	s_nop 0
	v_add_f32_e32 v93, v89, v78
	v_add_f32_e32 v93, v93, v79
	v_mul_f32_e32 v78, 0xbfb8aa3b, v93
	v_exp_f32_e32 v78, v78
	v_or_b32_e32 v79, s37, v88
	v_add_f32_e32 v78, 1.0, v78
	v_rcp_f32_e32 v80, v78
	v_mad_i64_i32 v[78:79], s[6:7], v79, s24, v[8:9]
	v_lshl_add_u64 v[76:77], v[76:77], 1, v[78:79]
	v_mul_f32_e32 v93, v93, v80
	s_nop 0
	v_mul_f32_e32 v93, v82, v93
	v_bfe_u32 v78, v93, 16, 1
	v_add3_u32 v93, v93, v78, s34
	global_store_short_d16_hi v[76:77], v93, off
	s_waitcnt vmcnt(11)
	v_fmac_f32_e32 v107, v111, v108
	s_nop 0
	v_pk_mul_f32 v[96:97], v[98:99], v[102:103]
	s_nop 0
	v_add_f32_e32 v111, v107, v96
	v_add_f32_e32 v111, v111, v97
	v_mul_f32_e32 v96, 0xbfb8aa3b, v111
	v_exp_f32_e32 v96, v96
	v_or_b32_e32 v97, s37, v106
	v_add_f32_e32 v96, 1.0, v96
	v_rcp_f32_e32 v98, v96
	v_mad_i64_i32 v[96:97], s[6:7], v97, s24, v[8:9]
	v_lshl_add_u64 v[94:95], v[94:95], 1, v[96:97]
	v_mul_f32_e32 v111, v111, v98
	s_nop 0
	v_mul_f32_e32 v111, v100, v111
	v_bfe_u32 v96, v111, 16, 1
	v_add3_u32 v111, v111, v96, s34
	global_store_short_d16_hi v[94:95], v111, off
	s_waitcnt vmcnt(4)
	v_fmac_f32_e32 v125, v129, v126
	s_nop 0
	v_pk_mul_f32 v[114:115], v[116:117], v[120:121]
	s_nop 0
	v_add_f32_e32 v129, v125, v114
	v_add_f32_e32 v129, v129, v115
	v_mul_f32_e32 v114, 0xbfb8aa3b, v129
	v_exp_f32_e32 v114, v114
	v_or_b32_e32 v115, s37, v124
	v_add_f32_e32 v114, 1.0, v114
	v_rcp_f32_e32 v116, v114
	v_mad_i64_i32 v[114:115], s[6:7], v115, s24, v[8:9]
	v_lshl_add_u64 v[112:113], v[112:113], 1, v[114:115]
	v_mul_f32_e32 v129, v129, v116
	s_nop 0
	v_mul_f32_e32 v129, v118, v129
	v_bfe_u32 v114, v129, 16, 1
	v_add3_u32 v129, v129, v114, s34
	global_store_short_d16_hi v[112:113], v129, off
	s_or_b64 exec, exec, s[28:29]
	s_branch .LBB0_903

; #define LAS __attribute__((address_space(3)))
; __device__ __forceinline__ void attn_unit(LAS unsigned char* lds, bf16* Q, const bf16* Kg, const bf16* Vg, const float* snk, int unit, int tid) {
;     ...
;     for (int i = 0; i < 2; ++i) { const int idx = tid + 512 * i, j = (idx >> 3) * 2, c = idx & 7, p = n * 128 - 128 + j;
;         v4u w0 = zero4, w1 = zero4;
;         if (p >= 0) { w0 = *(const v4u*)(Vg + (size_t)(b * SEQ + p) * 128 + h * 64 + c * 8); w1 = *(const v4u*)(Vg + (size_t)(b * SEQ + p + 1) * 128 + h * 64 + c * 8); }
;         const unsigned A0[4] = {w0.x, w0.y, w0.z, w0.w}, A1[4] = {w1.x, w1.y, w1.z, w1.w};
; #pragma unroll
;         for (int e = 0; e < 8; ++e) { const unsigned lo = (e & 1) ? (A0[e >> 1] >> 16) : (A0[e >> 1] & 0xffffu), hi = (e & 1) ? (A1[e >> 1] & 0xffff0000u) : (A1[e >> 1] << 16);
;             *(LAS unsigned*)(lds + ATT_VOFF + (8 * c + e) * ATT_VP + j * 2) = lo | hi; } }
;     __syncthreads();
;     const float sink = snk[hq] * 1.4426950408889634f;
;     bool lo_ok[4];
; #pragma unroll
;     for (int i = 0; i < 4; ++i) lo_ok[i] = (4 * fq + i - fr) > 0;
; #pragma unroll
;     for (int mt = 0; mt < 8; ++mt) {
;         f32x4 st[9];
; #pragma unroll
;         for (int kb = 0; kb < 9; ++kb) { const LAS unsigned char* kp = lds + (16 * (mt + kb) + fr) * ATT_KP + 16 * fq;
;             const bf16x8_t k0 = *(const LAS bf16x8_t*)kp, k1 = *(const LAS bf16x8_t*)(kp + 64);
;             f32x4 z = {0.f, 0.f, 0.f, 0.f}; z = __builtin_amdgcn_mfma_f32_16x16x32_bf16(k0, qf[mt][0], z, 0, 0, 0); z = __builtin_amdgcn_mfma_f32_16x16x32_bf16(k1, qf[mt][1], z, 0, 0, 0); st[kb] = z; }
.LBB0_1396:
	s_or_b64 exec, exec, s[16:17]
	s_waitcnt vmcnt(0)
	v_lshlrev_b32_e32 v74, 16, v66
	v_and_or_b32 v74, v70, s60, v74
	v_lshrrev_b32_e32 v70, 16, v70
	v_and_or_b32 v66, v66, s59, v70
	v_add_u32_e32 v70, 0x9000, v188
	ds_write2_b32 v70, v74, v66 offset1:132
	v_lshlrev_b32_e32 v66, 16, v67
	v_lshrrev_b32_e32 v70, 16, v71
	v_and_or_b32 v66, v71, s60, v66
	v_and_or_b32 v67, v67, s59, v70
	v_add_u32_e32 v70, 0x9400, v188
	ds_write2_b32 v70, v66, v67 offset0:8 offset1:140
	v_lshlrev_b32_e32 v66, 16, v68
	v_lshrrev_b32_e32 v67, 16, v72
	v_and_or_b32 v66, v72, s60, v66
	v_and_or_b32 v67, v68, s59, v67
	v_add_u32_e32 v68, 0x9800, v188
	ds_write2_b32 v68, v66, v67 offset0:16 offset1:148
	v_lshlrev_b32_e32 v66, 16, v69
	v_lshrrev_b32_e32 v67, 16, v73
	v_and_or_b32 v66, v73, s60, v66
	v_and_or_b32 v67, v69, s59, v67
	v_add_u32_e32 v68, 0x9c00, v188
	ds_write2_b32 v68, v66, v67 offset0:24 offset1:156
	s_waitcnt lgkmcnt(0)
	s_barrier
	ds_read_b128 v[66:69], v178
	ds_read_b128 v[70:73], v178 offset:64
	s_waitcnt lgkmcnt(1)
	v_mfma_f32_16x16x32_bf16 v[66:69], v[66:69], v[62:65], 0
	ds_read_b128 v[80:83], v178 offset:2304
	ds_read_b128 v[84:87], v178 offset:4608
	ds_read_b128 v[88:91], v178 offset:6912
	s_waitcnt lgkmcnt(3)
	v_mfma_f32_16x16x32_bf16 v[66:69], v[70:73], v[58:61], v[66:69]
	ds_read_b128 v[70:73], v178 offset:2368
	ds_read_b128 v[92:95], v178 offset:9216
	ds_read_b128 v[96:99], v178 offset:11520
	s_waitcnt lgkmcnt(5)
	v_mfma_f32_16x16x32_bf16 v[80:83], v[80:83], v[62:65], 0
	ds_read_b128 v[100:103], v178 offset:13824
	v_ashrrev_i32_e32 v79, 31, v78
	s_cmp_lg_u32 s63, 0
	s_waitcnt lgkmcnt(3)
	v_mfma_f32_16x16x32_bf16 v[72:75], v[70:73], v[58:61], v[80:83]
	v_lshl_add_u64 v[70:71], v[78:79], 2, s[28:29]
	s_cselect_b64 s[16:17], -1, 0
	s_and_b64 s[20:21], s[16:17], s[8:9]
	ds_read_b128 v[80:83], v178 offset:4672
	v_mfma_f32_16x16x32_bf16 v[84:87], v[84:87], v[62:65], 0
	s_and_b64 s[18:19], s[16:17], s[12:13]
	s_and_b64 s[22:23], s[16:17], s[14:15]
	v_cndmask_b32_e64 v68, v190, v68, s[18:19]
	s_waitcnt lgkmcnt(0)
	v_mfma_f32_16x16x32_bf16 v[80:83], v[80:83], v[58:61], v[84:87]
	s_nop 2
	ds_read_b128 v[84:87], v178 offset:6976
	v_cndmask_b32_e64 v69, v190, v69, s[22:23]
	s_cmp_eq_u32 s63, 0
	v_mfma_f32_16x16x32_bf16 v[88:91], v[88:91], v[62:65], 0
	s_nop 0
	v_cndmask_b32_e64 v78, v190, v80, s[16:17]
	v_cndmask_b32_e64 v79, v190, v81, s[16:17]
	v_cndmask_b32_e64 v80, v190, v82, s[16:17]
	s_waitcnt lgkmcnt(0)
	v_mfma_f32_16x16x32_bf16 v[84:87], v[84:87], v[58:61], v[88:91]
	v_cndmask_b32_e64 v81, v190, v83, s[16:17]
	s_nop 1
	ds_read_b128 v[88:91], v178 offset:9280
	v_mov_b32_e32 v157, v147
	v_mfma_f32_16x16x32_bf16 v[92:95], v[92:95], v[62:65], 0
	s_nop 1
	v_cndmask_b32_e64 v82, v190, v84, s[16:17]
	v_cndmask_b32_e64 v83, v190, v85, s[16:17]
	v_cndmask_b32_e64 v84, v190, v86, s[16:17]
	s_waitcnt lgkmcnt(0)
	v_mfma_f32_16x16x32_bf16 v[88:91], v[88:91], v[58:61], v[92:95]
	v_cndmask_b32_e64 v85, v190, v87, s[16:17]
	s_nop 1
	ds_read_b128 v[92:95], v178 offset:11584
	s_nop 3
	v_cndmask_b32_e64 v86, v190, v88, s[16:17]
	v_mfma_f32_16x16x32_bf16 v[96:99], v[96:99], v[62:65], 0
	v_cndmask_b32_e64 v87, v190, v89, s[16:17]
	v_cndmask_b32_e64 v88, v190, v90, s[16:17]
	v_cndmask_b32_e64 v89, v190, v91, s[16:17]
	s_waitcnt lgkmcnt(0)
	v_mfma_f32_16x16x32_bf16 v[92:95], v[92:95], v[58:61], v[96:99]
	s_nop 2
	ds_read_b128 v[96:99], v178 offset:16128
	ds_read_b128 v[104:107], v178 offset:13888
	ds_read_b128 v[108:111], v178 offset:18432
	ds_read_b128 v[112:115], v178 offset:16192
	ds_read_b128 v[116:119], v178 offset:18496
	v_mfma_f32_16x16x32_bf16 v[100:103], v[100:103], v[62:65], 0
	s_waitcnt lgkmcnt(4)
	v_mfma_f32_16x16x32_bf16 v[96:99], v[96:99], v[62:65], 0
	s_waitcnt lgkmcnt(2)
	v_mfma_f32_16x16x32_bf16 v[108:111], v[108:111], v[62:65], 0
	global_load_dword v64, v[70:71], off offset:64
	v_and_b32_e32 v63, 64, v189
	v_xor_b32_e32 v62, 16, v189
	v_add_u32_e32 v63, 64, v63
	v_cmp_lt_i32_e32 vcc, v62, v63
	v_cndmask_b32_e64 v70, v190, v72, s[16:17]
	v_cndmask_b32_e64 v72, v190, v73, s[16:17]
	v_cndmask_b32_e32 v62, v189, v62, vcc
	v_lshlrev_b32_e32 v65, 2, v62
	v_cndmask_b32_e64 v62, v67, v190, s[10:11]
	v_cndmask_b32_e64 v62, v190, v62, s[16:17]
	v_cndmask_b32_e64 v67, v190, v66, s[20:21]
	v_cndmask_b32_e64 v73, v190, v74, s[16:17]
	v_cndmask_b32_e64 v74, v190, v75, s[16:17]
	v_mfma_f32_16x16x32_bf16 v[100:103], v[104:107], v[58:61], v[100:103]
	v_cndmask_b32_e64 v106, v190, v92, s[16:17]
	v_cndmask_b32_e64 v107, v190, v93, s[16:17]
	s_cselect_b64 vcc, -1, 0
	s_waitcnt lgkmcnt(1)
	v_mfma_f32_16x16x32_bf16 v[96:99], v[112:115], v[58:61], v[96:99]
	s_waitcnt vmcnt(0)
; __device__ __forceinline__ unsigned cvt_pk_bf16(float lo, float hi) { unsigned r; asm volatile("v_cvt_pk_bf16_f32 %0, %1, %2" : "=v"(r) : "v"(lo), "v"(hi)); return r; }
; __device__ __forceinline__ void attn_unit(LAS unsigned char* lds, bf16* Q, const bf16* Kg, const bf16* Vg, const float* snk, int unit, int tid) {
;     ...
;         float mx = sink;
; #pragma unroll
;         for (int kb = 0; kb < 9; ++kb) {
;             const bool tile_ok = (n > 0) || (mt + kb >= 8);
; #pragma unroll
;             for (int i = 0; i < 4; ++i) { const bool ok = tile_ok && (kb == 0 ? lo_ok[i] : (kb == 8 ? !lo_ok[i] : true));
;                 st[kb][i] = ok ? st[kb][i] : -INFINITY; mx = fmaxf(mx, st[kb][i]); }
;         }
;         mx = fmaxf(mx, __shfl_xor(mx, 16)); mx = fmaxf(mx, __shfl_xor(mx, 32));
;         f32x4 ls4 = {0.f, 0.f, 0.f, 0.f};
; #pragma unroll
;         for (int kb = 0; kb < 9; ++kb) { f32x4 d = st[kb] - mx;
; #pragma unroll
;             for (int i = 0; i < 4; ++i) d[i] = __builtin_amdgcn_exp2f(d[i]);
;             st[kb] = d; ls4 = ls4 + d; }
;         float ls = (ls4[0] + ls4[1]) + (ls4[2] + ls4[3]);
;         ls += __shfl_xor(ls, 16); ls += __shfl_xor(ls, 32);
;         const float inv = 1.f / (ls + __builtin_amdgcn_exp2f(sink - mx));
;         f32x4 o[4];
; #pragma unroll
;         for (int dt = 0; dt < 4; ++dt) o[dt] = (f32x4){0.f, 0.f, 0.f, 0.f};
; #pragma unroll
;         for (int kp = 0; kp < 5; ++kp) {
;             v4u pw; pw.x = cvt_pk_bf16(st[2 * kp][0], st[2 * kp][1]); pw.y = cvt_pk_bf16(st[2 * kp][2], st[2 * kp][3]);
;             if (kp < 4) { pw.z = cvt_pk_bf16(st[(2 * kp + 1) % 9][0], st[(2 * kp + 1) % 9][1]); pw.w = cvt_pk_bf16(st[(2 * kp + 1) % 9][2], st[(2 * kp + 1) % 9][3]); } else { pw.z = 0u; pw.w = 0u; }
; __device__ __forceinline__ void sgu_unit(LAS unsigned char* lds, bf16* U, const bf16* VS, const float* SGS, const float* lnw, const float* lnb, const v4u* WF, const float* bsl, int unit, int tid) {
;     ...
;         const int c8 = lane & 7, rp = lane >> 3, col = colbase + 8 * c8;
;         v4u sl[8][2];
; #pragma unroll
;         for (int i = 0; i < 8; ++i) { const int s0 = 2 * (rp + 8 * i); sl[i][0] = *(const v4u*)(VS + (size_t)(r0 + s0) * 1024 + col); sl[i][1] = *(const v4u*)(VS + (size_t)(r0 + s0 + 1) * 1024 + col); }
	s_cselect_b32 s100, 1, 0
	s_and_b32 s98, s4, 4
	v_add_u32_e32 v254, s98, v165
	v_lshlrev_b32_e32 v254, 7, v254
	v_or_b32_e32 v254, v254, v168
	v_or_b32_e32 v254, v254, v170
	s_and_b32 s98, s24, 0x3f80
	v_lshl_or_b32 v252, s98, 11, v180
	v_mov_b32_e32 v253, 0
	v_lshl_add_u64 v[252:253], s[38:39], 0, v[252:253]
	v_mov_b32_e32 v255, 0
	v_lshl_add_u64 v[252:253], v[254:255], 1, v[252:253]
	global_load_dwordx4 v[198:201], v[252:253], off
	global_load_dwordx4 v[202:205], v[252:253], off offset:2048
	s_mov_b64 s[98:99], 0x8000
	v_lshl_add_u64 v[254:255], v[252:253], 0, s[98:99]
	global_load_dwordx4 v[206:209], v[254:255], off
	global_load_dwordx4 v[210:213], v[254:255], off offset:2048
	s_mov_b64 s[98:99], 0x10000
	v_lshl_add_u64 v[254:255], v[252:253], 0, s[98:99]
	global_load_dwordx4 v[138:141], v[254:255], off
	global_load_dwordx4 v[142:145], v[254:255], off offset:2048
	s_mov_b64 s[98:99], 0x18000
	v_lshl_add_u64 v[254:255], v[252:253], 0, s[98:99]
	global_load_dwordx4 v[130:133], v[254:255], off
	global_load_dwordx4 v[134:137], v[254:255], off offset:2048
	s_mov_b64 s[98:99], 0x20000
	v_lshl_add_u64 v[254:255], v[252:253], 0, s[98:99]
	global_load_dwordx4 v[214:217], v[254:255], off
	global_load_dwordx4 v[218:221], v[254:255], off offset:2048
	s_mov_b64 s[98:99], 0x28000
	v_lshl_add_u64 v[254:255], v[252:253], 0, s[98:99]
	global_load_dwordx4 v[222:225], v[254:255], off
	global_load_dwordx4 v[226:229], v[254:255], off offset:2048
	s_mov_b64 s[98:99], 0x30000
	v_lshl_add_u64 v[254:255], v[252:253], 0, s[98:99]
	global_load_dwordx4 v[230:233], v[254:255], off
	global_load_dwordx4 v[234:237], v[254:255], off offset:2048
	s_mov_b64 s[98:99], 0x38000
	v_lshl_add_u64 v[254:255], v[252:253], 0, s[98:99]
	global_load_dwordx4 v[248:251], v[254:255], off
	global_load_dwordx4 v[252:255], v[254:255], off offset:2048
	s_cmp_lg_u32 s100, 0
	v_mul_f32_e32 v71, 0x3fb8aa3b, v64
	v_max3_f32 v66, v71, v67, v62
	v_max3_f32 v66, v66, v68, v69
	v_max3_f32 v66, v66, v70, v72
	v_max3_f32 v66, v66, v73, v74
	v_max3_f32 v66, v66, v78, v79
	v_max3_f32 v66, v66, v80, v81
	v_max3_f32 v66, v66, v82, v83
	v_max3_f32 v66, v66, v84, v85
	v_max3_f32 v66, v66, v86, v87
	v_max3_f32 v66, v66, v88, v89
	s_waitcnt lgkmcnt(0)
	v_mfma_f32_16x16x32_bf16 v[58:61], v[116:119], v[58:61], v[108:111]
	v_max3_f32 v66, v66, v106, v107
	v_cndmask_b32_e64 v100, v190, v100, s[16:17]
	v_cndmask_b32_e64 v101, v190, v101, s[16:17]
	v_cndmask_b32_e64 v108, v190, v94, s[16:17]
	v_cndmask_b32_e64 v109, v190, v95, s[16:17]
	v_max3_f32 v66, v66, v108, v109
	v_max3_f32 v66, v66, v100, v101
	v_cndmask_b32_e64 v110, v190, v102, s[16:17]
	v_cndmask_b32_e64 v111, v190, v103, s[16:17]
	v_max3_f32 v66, v66, v110, v111
	v_cndmask_b32_e32 v116, v96, v190, vcc
	v_cndmask_b32_e32 v117, v97, v190, vcc
	v_max3_f32 v66, v66, v116, v117
	v_cndmask_b32_e32 v98, v98, v190, vcc
	v_cndmask_b32_e32 v99, v99, v190, vcc
	v_max3_f32 v66, v66, v98, v99
	v_cndmask_b32_e64 v120, v58, v190, s[8:9]
	v_cndmask_b32_e64 v121, v190, v59, s[10:11]
	v_max3_f32 v58, v66, v120, v121
	v_cndmask_b32_e64 v122, v60, v190, s[12:13]
	v_cndmask_b32_e64 v123, v61, v190, s[14:15]
	v_max3_f32 v58, v58, v122, v123
	ds_bpermute_b32 v59, v65, v58
	v_xor_b32_e32 v60, 32, v189
	v_cmp_lt_i32_e32 vcc, v60, v63
	s_waitcnt lgkmcnt(0)
	v_max_f32_e32 v59, v59, v59
	v_cndmask_b32_e32 v60, v189, v60, vcc
	v_lshlrev_b32_e32 v66, 2, v60
	v_max_f32_e32 v58, v58, v59
	ds_bpermute_b32 v59, v66, v58
	s_waitcnt lgkmcnt(0)
	v_max_f32_e32 v59, v59, v59
	v_max_f32_e32 v124, v58, v59
	v_sub_f32_e32 v59, v69, v124
	v_sub_f32_e32 v62, v62, v124
	v_sub_f32_e32 v58, v67, v124
	v_exp_f32_e32 v58, v58
	v_exp_f32_e32 v61, v59
	v_exp_f32_e32 v59, v62
	v_sub_f32_e32 v67, v74, v124
	v_sub_f32_e32 v74, v73, v124
	v_sub_f32_e32 v73, v72, v124
	v_sub_f32_e32 v70, v70, v124
	v_exp_f32_e32 v72, v70
	v_exp_f32_e32 v73, v73
	v_sub_f32_e32 v79, v79, v124
	v_sub_f32_e32 v78, v78, v124
	v_exp_f32_e32 v90, v78
	v_exp_f32_e32 v91, v79
	v_sub_f32_e32 v78, v83, v124
	v_sub_f32_e32 v79, v82, v124
	v_exp_f32_e32 v94, v79
	v_exp_f32_e32 v95, v78
	v_sub_f32_e32 v78, v87, v124
	v_sub_f32_e32 v79, v86, v124
	v_sub_f32_e32 v60, v68, v124
	v_pk_add_f32 v[68:69], v[58:59], 0 op_sel_hi:[1,0]
	v_exp_f32_e32 v102, v79
	v_exp_f32_e32 v103, v78
	v_exp_f32_e32 v75, v67
	v_sub_f32_e32 v67, v81, v124
	v_sub_f32_e32 v70, v80, v124
	v_pk_add_f32 v[68:69], v[72:73], v[68:69]
	v_exp_f32_e32 v60, v60
	v_exp_f32_e32 v92, v70
	v_exp_f32_e32 v93, v67
	v_pk_add_f32 v[68:69], v[90:91], v[68:69]
	v_sub_f32_e32 v67, v85, v124
	v_sub_f32_e32 v70, v84, v124
	v_exp_f32_e32 v74, v74
	v_exp_f32_e32 v96, v70
	v_exp_f32_e32 v97, v67
	v_sub_f32_e32 v67, v89, v124
	v_sub_f32_e32 v70, v88, v124
	v_pk_add_f32 v[68:69], v[94:95], v[68:69]
	v_exp_f32_e32 v104, v70
	v_exp_f32_e32 v105, v67
	v_pk_add_f32 v[82:83], v[102:103], v[68:69]
	v_sub_f32_e32 v67, v109, v124
	v_sub_f32_e32 v69, v107, v124
	v_sub_f32_e32 v70, v106, v124
	v_sub_f32_e32 v68, v108, v124
	v_exp_f32_e32 v106, v70
	v_exp_f32_e32 v107, v69
	v_exp_f32_e32 v109, v67
	v_sub_f32_e32 v67, v101, v124
	v_sub_f32_e32 v70, v100, v124
	v_pk_add_f32 v[62:63], v[60:61], 0 op_sel_hi:[1,0]
	v_exp_f32_e32 v108, v68
	v_sub_f32_e32 v68, v111, v124
	v_sub_f32_e32 v69, v110, v124
	v_exp_f32_e32 v110, v70
	v_exp_f32_e32 v111, v67
	v_add_u32_e32 v67, 0x9000, v179
	v_pk_add_f32 v[62:63], v[74:75], v[62:63]
	v_cvt_pk_bf16_f32 v58, v58, v59
	v_cvt_pk_bf16_f32 v59, v60, v61
	v_cvt_pk_bf16_f32 v60, v72, v73
	v_cvt_pk_bf16_f32 v61, v74, v75
	ds_read2_b64 v[72:75], v67 offset1:4
	v_exp_f32_e32 v112, v69
	v_exp_f32_e32 v113, v68
	v_add_u32_e32 v68, 0xb000, v179
	v_pk_add_f32 v[82:83], v[106:107], v[82:83]
	v_add_u32_e32 v70, 0xd000, v179
	v_add_u32_e32 v69, 0xf000, v179
	v_pk_add_f32 v[62:63], v[92:93], v[62:63]
	ds_read2_b64 v[78:81], v68 offset0:32 offset1:36
	v_pk_add_f32 v[114:115], v[110:111], v[82:83]
	ds_read2_b64 v[82:85], v70 offset0:64 offset1:68
	ds_read2_b64 v[86:89], v69 offset0:96 offset1:100
	v_pk_add_f32 v[62:63], v[96:97], v[62:63]
	v_cvt_pk_bf16_f32 v90, v90, v91
	v_cvt_pk_bf16_f32 v91, v92, v93
	v_cvt_pk_bf16_f32 v92, v94, v95
	v_cvt_pk_bf16_f32 v93, v96, v97
	ds_read2_b64 v[94:97], v67 offset0:8 offset1:12
	s_waitcnt lgkmcnt(4)
; __device__ __forceinline__ unsigned cvt_pk_bf16(float lo, float hi) { unsigned r; asm volatile("v_cvt_pk_bf16_f32 %0, %1, %2" : "=v"(r) : "v"(lo), "v"(hi)); return r; }
; #define LAS __attribute__((address_space(3)))
; __device__ __forceinline__ void attn_unit(LAS unsigned char* lds, bf16* Q, const bf16* Kg, const bf16* Vg, const float* snk, int unit, int tid) {
;     ...
; #pragma unroll
;         for (int kp = 0; kp < 5; ++kp) {
;             v4u pw; pw.x = cvt_pk_bf16(st[2 * kp][0], st[2 * kp][1]); pw.y = cvt_pk_bf16(st[2 * kp][2], st[2 * kp][3]);
;             if (kp < 4) { pw.z = cvt_pk_bf16(st[(2 * kp + 1) % 9][0], st[(2 * kp + 1) % 9][1]); pw.w = cvt_pk_bf16(st[(2 * kp + 1) % 9][2], st[(2 * kp + 1) % 9][3]); } else { pw.z = 0u; pw.w = 0u; }
;             const bf16x8_t pb = __builtin_bit_cast(bf16x8_t, pw);
; #pragma unroll
;             for (int dt = 0; dt < 4; ++dt) { const LAS unsigned char* vp = lds + ATT_VOFF + (16 * dt + fr) * ATT_VP + (16 * (mt + 2 * kp) + 4 * fq) * 2;
;                 const v2u lo = *(const LAS v2u*)vp; v2u hi = {0u, 0u}; if (kp < 4) hi = *(const LAS v2u*)(vp + 32);
;                 v4u aw; aw.x = lo.x; aw.y = lo.y; aw.z = hi.x; aw.w = hi.y;
;                 o[dt] = __builtin_amdgcn_mfma_f32_16x16x32_bf16(__builtin_bit_cast(bf16x8_t, aw), pb, o[dt], 0, 0, 0); }
;         }
; #pragma unroll
;         for (int dt = 0; dt < 4; ++dt) { const f32x4 y = o[dt] * inv; v2u w; w.x = cvt_pk_bf16(y[0], y[1]); w.y = cvt_pk_bf16(y[2], y[3]); *(v2u*)(qbase + (size_t)mt * 16 * 1024 + 16 * dt + 4 * fq) = w; }
	v_mfma_f32_16x16x32_bf16 v[72:75], v[72:75], v[58:61], 0
	v_sub_f32_e32 v119, v99, v124
	v_sub_f32_e32 v118, v98, v124
	ds_read2_b64 v[98:101], v68 offset0:40 offset1:44
	s_waitcnt lgkmcnt(4)
	v_mfma_f32_16x16x32_bf16 v[78:81], v[78:81], v[58:61], 0
	v_add_f32_e64 v62, v104, v62
	v_add_f32_e64 v63, v105, v63
	v_sub_f32_e32 v117, v117, v124
	v_pk_add_f32 v[62:63], v[108:109], v[62:63]
	s_waitcnt lgkmcnt(3)
	v_mfma_f32_16x16x32_bf16 v[82:85], v[82:85], v[58:61], 0
	v_exp_f32_e32 v117, v117
	v_exp_f32_e32 v118, v118
	v_exp_f32_e32 v119, v119
	s_waitcnt lgkmcnt(2)
	v_mfma_f32_16x16x32_bf16 v[58:61], v[86:89], v[58:61], 0
	v_sub_f32_e32 v86, v116, v124
	v_exp_f32_e32 v116, v86
	ds_read2_b64 v[86:89], v70 offset0:72 offset1:76
	s_waitcnt lgkmcnt(2)
	v_mfma_f32_16x16x32_bf16 v[72:75], v[94:97], v[90:93], v[72:75]
	ds_read2_b64 v[94:97], v69 offset0:104 offset1:108
	v_pk_add_f32 v[62:63], v[112:113], v[62:63]
	s_waitcnt lgkmcnt(2)
	v_mfma_f32_16x16x32_bf16 v[78:81], v[98:101], v[90:93], v[78:81]
	v_cvt_pk_bf16_f32 v98, v102, v103
	v_cvt_pk_bf16_f32 v99, v104, v105
	v_cvt_pk_bf16_f32 v100, v106, v107
	v_cvt_pk_bf16_f32 v101, v108, v109
	s_waitcnt lgkmcnt(1)
	v_mfma_f32_16x16x32_bf16 v[82:85], v[86:89], v[90:93], v[82:85]
	ds_read2_b64 v[86:89], v68 offset0:48 offset1:52
	ds_read2_b64 v[102:105], v67 offset0:16 offset1:20
	v_pk_add_f32 v[106:107], v[116:117], v[114:115]
	s_waitcnt lgkmcnt(2)
	v_mfma_f32_16x16x32_bf16 v[58:61], v[94:97], v[90:93], v[58:61]
	ds_read2_b64 v[90:93], v70 offset0:80 offset1:84
	v_sub_f32_e32 v94, v120, v124
	v_exp_f32_e32 v108, v94
	s_waitcnt lgkmcnt(2)
	v_mfma_f32_16x16x32_bf16 v[78:81], v[86:89], v[98:101], v[78:81]
	ds_read2_b64 v[86:89], v69 offset0:112 offset1:116
	v_cvt_pk_bf16_f32 v94, v110, v111
	v_cvt_pk_bf16_f32 v95, v112, v113
	v_cvt_pk_bf16_f32 v96, v116, v117
	v_cvt_pk_bf16_f32 v97, v118, v119
	s_waitcnt lgkmcnt(1)
	v_mfma_f32_16x16x32_bf16 v[82:85], v[90:93], v[98:101], v[82:85]
	ds_read2_b64 v[90:93], v68 offset0:56 offset1:60
	v_sub_f32_e32 v109, v123, v124
	v_sub_f32_e32 v114, v122, v124
	s_waitcnt lgkmcnt(1)
	v_mfma_f32_16x16x32_bf16 v[58:61], v[86:89], v[98:101], v[58:61]
	ds_read2_b64 v[86:89], v70 offset0:88 offset1:92
	v_sub_f32_e32 v115, v121, v124
	v_exp_f32_e32 v110, v114
	s_waitcnt lgkmcnt(1)
	v_mfma_f32_16x16x32_bf16 v[78:81], v[90:93], v[94:97], v[78:81]
	ds_read2_b64 v[90:93], v69 offset0:120 offset1:124
	v_exp_f32_e32 v111, v109
	v_exp_f32_e32 v109, v115
	v_mfma_f32_16x16x32_bf16 v[72:75], v[102:105], v[98:101], v[72:75]
	ds_read2_b64 v[102:105], v67 offset0:24 offset1:28
	v_pk_add_f32 v[62:63], v[118:119], v[62:63]
	v_pk_add_f32 v[98:99], v[108:109], v[106:107]
	v_pk_add_f32 v[62:63], v[110:111], v[62:63]
	s_waitcnt lgkmcnt(2)
	v_mfma_f32_16x16x32_bf16 v[82:85], v[86:89], v[94:97], v[82:85]
	v_pk_mov_b32 v[100:101], v[98:99], v[62:63] op_sel:[1,0]
	v_mov_b32_e32 v99, v63
	v_pk_add_f32 v[62:63], v[100:101], v[98:99]
	s_waitcnt lgkmcnt(1)
	v_mfma_f32_16x16x32_bf16 v[58:61], v[90:93], v[94:97], v[58:61]
	v_cvt_pk_bf16_f32 v86, v108, v109
	v_cvt_pk_bf16_f32 v87, v110, v111
	ds_read_b64 v[90:91], v179 offset:37120
	v_add_f32_e32 v62, v62, v63
	ds_bpermute_b32 v63, v65, v62
	v_mov_b32_e32 v92, v147
	v_mov_b32_e32 v93, v147
	s_waitcnt lgkmcnt(2)
	v_mfma_f32_16x16x32_bf16 v[72:75], v[102:105], v[94:97], v[72:75]
	v_mov_b32_e32 v88, v147
	s_waitcnt lgkmcnt(0)
	v_add_f32_e32 v62, v62, v63
	v_mov_b32_e32 v89, v147
	ds_bpermute_b32 v63, v66, v62
	ds_read_b64 v[94:95], v179 offset:45568
	v_mfma_f32_16x16x32_bf16 v[72:75], v[90:93], v[86:89], v[72:75]
	v_fma_f32 v90, v64, s61, -v124
	v_exp_f32_e32 v90, v90
	s_waitcnt lgkmcnt(1)
	v_add_f32_e32 v62, v62, v63
	v_mov_b32_e32 v96, v147
	v_mov_b32_e32 v97, v147
	v_add_f32_e32 v90, v90, v62
	v_div_scale_f32 v91, s[68:69], v90, v90, 1.0
	v_rcp_f32_e32 v92, v91
	ds_read_b64 v[98:99], v179 offset:54016
	ds_read_b64 v[102:103], v179 offset:62464
	v_mov_b32_e32 v100, v147
	v_mov_b32_e32 v101, v147
	v_mov_b32_e32 v104, v147
	v_mov_b32_e32 v105, v147
	v_lshl_add_u64 v[62:63], v[76:77], 0, v[156:157]
	v_fma_f32 v76, -v91, v92, 1.0
	v_fmac_f32_e32 v92, v76, v92
	v_div_scale_f32 v76, vcc, 1.0, v90, 1.0
	v_mul_f32_e32 v77, v76, v92
	s_waitcnt lgkmcnt(2)
	v_mfma_f32_16x16x32_bf16 v[78:81], v[94:97], v[86:89], v[78:81]
	s_waitcnt lgkmcnt(1)
	v_mfma_f32_16x16x32_bf16 v[82:85], v[98:101], v[86:89], v[82:85]
	s_waitcnt lgkmcnt(0)
	v_mfma_f32_16x16x32_bf16 v[58:61], v[102:105], v[86:89], v[58:61]
	v_fma_f32 v86, -v91, v77, v76
	v_fmac_f32_e32 v77, v86, v92
	v_fma_f32 v76, -v91, v77, v76
	v_div_fmas_f32 v76, v76, v92, v77
	v_div_fixup_f32 v76, v76, v90, 1.0
	v_pk_mul_f32 v[74:75], v[76:77], v[74:75] op_sel_hi:[0,1]
	v_pk_mul_f32 v[72:73], v[76:77], v[72:73] op_sel_hi:[0,1]
	v_cvt_pk_bf16_f32 v72, v72, v73
	v_cvt_pk_bf16_f32 v73, v74, v75
	v_pk_mul_f32 v[74:75], v[76:77], v[78:79] op_sel_hi:[0,1]
	global_store_dwordx2 v[62:63], v[72:73], off
	v_pk_mul_f32 v[72:73], v[76:77], v[80:81] op_sel_hi:[0,1]
	v_cvt_pk_bf16_f32 v74, v74, v75
	v_cvt_pk_bf16_f32 v75, v72, v73
	global_store_dwordx2 v[62:63], v[74:75], off offset:32
	v_pk_mul_f32 v[74:75], v[76:77], v[82:83] op_sel_hi:[0,1]
	v_pk_mul_f32 v[72:73], v[76:77], v[84:85] op_sel_hi:[0,1]
	v_cvt_pk_bf16_f32 v74, v74, v75
	v_cvt_pk_bf16_f32 v75, v72, v73
	v_pk_mul_f32 v[60:61], v[76:77], v[60:61] op_sel_hi:[0,1]
	v_pk_mul_f32 v[58:59], v[76:77], v[58:59] op_sel_hi:[0,1]
	global_store_dwordx2 v[62:63], v[74:75], off offset:64
	v_cvt_pk_bf16_f32 v108, v58, v59
	v_cvt_pk_bf16_f32 v109, v60, v61
	ds_read_b128 v[58:61], v178 offset:2304
	ds_read_b128 v[72:75], v178 offset:2368
	s_waitcnt lgkmcnt(1)
; #define LAS __attribute__((address_space(3)))
; __device__ __forceinline__ void attn_unit(LAS unsigned char* lds, bf16* Q, const bf16* Kg, const bf16* Vg, const float* snk, int unit, int tid) {
;     ...
;         for (int kb = 0; kb < 9; ++kb) { const LAS unsigned char* kp = lds + (16 * (mt + kb) + fr) * ATT_KP + 16 * fq;
;             const bf16x8_t k0 = *(const LAS bf16x8_t*)kp, k1 = *(const LAS bf16x8_t*)(kp + 64);
;             f32x4 z = {0.f, 0.f, 0.f, 0.f}; z = __builtin_amdgcn_mfma_f32_16x16x32_bf16(k0, qf[mt][0], z, 0, 0, 0); z = __builtin_amdgcn_mfma_f32_16x16x32_bf16(k1, qf[mt][1], z, 0, 0, 0); st[kb] = z; }
;         float mx = sink;
; #pragma unroll
;         for (int kb = 0; kb < 9; ++kb) {
;             const bool tile_ok = (n > 0) || (mt + kb >= 8);
; #pragma unroll
;             for (int i = 0; i < 4; ++i) { const bool ok = tile_ok && (kb == 0 ? lo_ok[i] : (kb == 8 ? !lo_ok[i] : true));
;                 st[kb][i] = ok ? st[kb][i] : -INFINITY; mx = fmaxf(mx, st[kb][i]); }
;         }
;         mx = fmaxf(mx, __shfl_xor(mx, 16)); mx = fmaxf(mx, __shfl_xor(mx, 32));
	v_mfma_f32_16x16x32_bf16 v[58:61], v[58:61], v[50:53], 0
	ds_read_b128 v[76:79], v178 offset:4608
	ds_read_b128 v[80:83], v178 offset:6912
	ds_read_b128 v[84:87], v178 offset:9216
	s_waitcnt lgkmcnt(3)
	v_mfma_f32_16x16x32_bf16 v[72:75], v[72:75], v[54:57], v[58:61]
	ds_read_b128 v[88:91], v178 offset:11520
	ds_read_b128 v[92:95], v178 offset:13824
	ds_read_b128 v[96:99], v178 offset:16128
	ds_read_b128 v[58:61], v178 offset:4672
	s_waitcnt lgkmcnt(6)
	v_mfma_f32_16x16x32_bf16 v[76:79], v[76:79], v[50:53], 0
	ds_read_b128 v[100:103], v178 offset:18432
	ds_read_b128 v[104:107], v178 offset:20736
	global_store_dwordx2 v[62:63], v[108:109], off offset:96
	s_waitcnt lgkmcnt(2)
	v_mfma_f32_16x16x32_bf16 v[76:79], v[58:61], v[54:57], v[76:79]
	ds_read_b128 v[58:61], v178 offset:6976
	v_mfma_f32_16x16x32_bf16 v[80:83], v[80:83], v[50:53], 0
	s_waitcnt lgkmcnt(0)
	v_mfma_f32_16x16x32_bf16 v[80:83], v[58:61], v[54:57], v[80:83]
	ds_read_b128 v[58:61], v178 offset:9280
	v_mfma_f32_16x16x32_bf16 v[84:87], v[84:87], v[50:53], 0
	s_waitcnt lgkmcnt(0)
	v_mfma_f32_16x16x32_bf16 v[84:87], v[58:61], v[54:57], v[84:87]
	ds_read_b128 v[58:61], v178 offset:11584
	v_mfma_f32_16x16x32_bf16 v[88:91], v[88:91], v[50:53], 0
	s_waitcnt lgkmcnt(0)
	v_mfma_f32_16x16x32_bf16 v[88:91], v[58:61], v[54:57], v[88:91]
	ds_read_b128 v[58:61], v178 offset:13888
	v_mfma_f32_16x16x32_bf16 v[92:95], v[92:95], v[50:53], 0
	s_waitcnt lgkmcnt(0)
	v_mfma_f32_16x16x32_bf16 v[92:95], v[58:61], v[54:57], v[92:95]
	ds_read_b128 v[58:61], v178 offset:16192
	v_mfma_f32_16x16x32_bf16 v[96:99], v[96:99], v[50:53], 0
	s_nop 5
	v_cndmask_b32_e64 v92, v190, v92, s[16:17]
	v_cndmask_b32_e64 v93, v190, v93, s[16:17]
	v_cndmask_b32_e64 v94, v190, v94, s[16:17]
	s_waitcnt lgkmcnt(0)
	v_mfma_f32_16x16x32_bf16 v[96:99], v[58:61], v[54:57], v[96:99]
	ds_read_b128 v[58:61], v178 offset:18496
	v_cndmask_b32_e64 v95, v190, v95, s[16:17]
	v_mfma_f32_16x16x32_bf16 v[100:103], v[100:103], v[50:53], 0
	s_nop 4
	v_cndmask_b32_e64 v110, v190, v99, s[16:17]
	s_waitcnt lgkmcnt(0)
	v_mfma_f32_16x16x32_bf16 v[58:61], v[58:61], v[54:57], v[100:103]
	s_nop 2
	ds_read_b128 v[100:103], v178 offset:20800
	v_mfma_f32_16x16x32_bf16 v[50:53], v[104:107], v[50:53], 0
	v_cndmask_b32_e64 v104, v190, v91, s[16:17]
	v_cndmask_b32_e64 v105, v190, v96, s[16:17]
	v_cndmask_b32_e64 v106, v190, v97, s[16:17]
	s_waitcnt lgkmcnt(0)
	v_mfma_f32_16x16x32_bf16 v[50:53], v[100:103], v[54:57], v[50:53]
	v_cndmask_b32_e64 v55, v73, v190, s[10:11]
	v_cndmask_b32_e64 v54, v190, v72, s[20:21]
	v_cndmask_b32_e64 v55, v190, v55, s[16:17]
	v_max3_f32 v56, v71, v54, v55
	v_cndmask_b32_e64 v57, v190, v74, s[18:19]
	v_cndmask_b32_e64 v72, v190, v75, s[22:23]
	v_max3_f32 v56, v56, v57, v72
	v_cndmask_b32_e64 v73, v190, v76, s[16:17]
	v_cndmask_b32_e64 v74, v190, v77, s[16:17]
	v_max3_f32 v56, v56, v73, v74
	v_cndmask_b32_e64 v75, v190, v78, s[16:17]
	v_cndmask_b32_e64 v76, v190, v79, s[16:17]
	v_max3_f32 v56, v56, v75, v76
	v_cndmask_b32_e64 v77, v190, v80, s[16:17]
	v_cndmask_b32_e64 v78, v190, v81, s[16:17]
	v_max3_f32 v56, v56, v77, v78
	v_cndmask_b32_e64 v79, v190, v82, s[16:17]
	v_cndmask_b32_e64 v80, v190, v83, s[16:17]
	v_max3_f32 v56, v56, v79, v80
	v_cndmask_b32_e64 v81, v190, v84, s[16:17]
	v_cndmask_b32_e64 v82, v190, v85, s[16:17]
	v_max3_f32 v56, v56, v81, v82
	v_cndmask_b32_e64 v83, v190, v86, s[16:17]
	v_cndmask_b32_e64 v100, v190, v87, s[16:17]
	v_max3_f32 v56, v56, v83, v100
	v_cndmask_b32_e64 v101, v190, v88, s[16:17]
	v_cndmask_b32_e64 v102, v190, v89, s[16:17]
	v_max3_f32 v56, v56, v101, v102
	v_cndmask_b32_e64 v103, v190, v90, s[16:17]
	v_max3_f32 v56, v56, v103, v104
	v_max3_f32 v56, v56, v92, v93
	v_max3_f32 v56, v56, v94, v95
	v_max3_f32 v56, v56, v105, v106
	v_cndmask_b32_e64 v107, v190, v98, s[16:17]
	v_max3_f32 v56, v56, v107, v110
	v_max3_f32 v56, v56, v58, v59
	v_max3_f32 v56, v56, v60, v61
	v_cndmask_b32_e64 v116, v50, v190, s[8:9]
	v_cndmask_b32_e64 v117, v190, v51, s[10:11]
	v_max3_f32 v50, v56, v116, v117
	v_cndmask_b32_e64 v118, v52, v190, s[12:13]
	v_cndmask_b32_e64 v119, v53, v190, s[14:15]
	v_max3_f32 v50, v50, v118, v119
	ds_bpermute_b32 v51, v65, v50
	s_waitcnt lgkmcnt(0)
	v_max_f32_e32 v51, v51, v51
	v_max_f32_e32 v50, v50, v51
	ds_bpermute_b32 v51, v66, v50
	s_waitcnt lgkmcnt(0)
; __device__ __forceinline__ unsigned cvt_pk_bf16(float lo, float hi) { unsigned r; asm volatile("v_cvt_pk_bf16_f32 %0, %1, %2" : "=v"(r) : "v"(lo), "v"(hi)); return r; }
; #define LAS __attribute__((address_space(3)))
; __device__ __forceinline__ void attn_unit(LAS unsigned char* lds, bf16* Q, const bf16* Kg, const bf16* Vg, const float* snk, int unit, int tid) {
;     ...
;         mx = fmaxf(mx, __shfl_xor(mx, 16)); mx = fmaxf(mx, __shfl_xor(mx, 32));
;         f32x4 ls4 = {0.f, 0.f, 0.f, 0.f};
; #pragma unroll
;         for (int kb = 0; kb < 9; ++kb) { f32x4 d = st[kb] - mx;
; #pragma unroll
;             for (int i = 0; i < 4; ++i) d[i] = __builtin_amdgcn_exp2f(d[i]);
;             st[kb] = d; ls4 = ls4 + d; }
;         float ls = (ls4[0] + ls4[1]) + (ls4[2] + ls4[3]);
;         ls += __shfl_xor(ls, 16); ls += __shfl_xor(ls, 32);
;         const float inv = 1.f / (ls + __builtin_amdgcn_exp2f(sink - mx));
;         f32x4 o[4];
; #pragma unroll
;         for (int dt = 0; dt < 4; ++dt) o[dt] = (f32x4){0.f, 0.f, 0.f, 0.f};
; #pragma unroll
;         for (int kp = 0; kp < 5; ++kp) {
;             v4u pw; pw.x = cvt_pk_bf16(st[2 * kp][0], st[2 * kp][1]); pw.y = cvt_pk_bf16(st[2 * kp][2], st[2 * kp][3]);
;             if (kp < 4) { pw.z = cvt_pk_bf16(st[(2 * kp + 1) % 9][0], st[(2 * kp + 1) % 9][1]); pw.w = cvt_pk_bf16(st[(2 * kp + 1) % 9][2], st[(2 * kp + 1) % 9][3]); } else { pw.z = 0u; pw.w = 0u; }
;             const bf16x8_t pb = __builtin_bit_cast(bf16x8_t, pw);
; #pragma unroll
;             for (int dt = 0; dt < 4; ++dt) { const LAS unsigned char* vp = lds + ATT_VOFF + (16 * dt + fr) * ATT_VP + (16 * (mt + 2 * kp) + 4 * fq) * 2;
;                 const v2u lo = *(const LAS v2u*)vp; v2u hi = {0u, 0u}; if (kp < 4) hi = *(const LAS v2u*)(vp + 32);
;                 v4u aw; aw.x = lo.x; aw.y = lo.y; aw.z = hi.x; aw.w = hi.y;
;                 o[dt] = __builtin_amdgcn_mfma_f32_16x16x32_bf16(__builtin_bit_cast(bf16x8_t, aw), pb, o[dt], 0, 0, 0); }
	v_max_f32_e32 v51, v51, v51
	v_max_f32_e32 v120, v50, v51
	v_sub_f32_e32 v51, v72, v120
	v_sub_f32_e32 v52, v57, v120
	v_sub_f32_e32 v55, v55, v120
	v_sub_f32_e32 v50, v54, v120
	v_exp_f32_e32 v50, v50
	v_exp_f32_e32 v52, v52
	v_exp_f32_e32 v53, v51
	v_exp_f32_e32 v51, v55
	v_sub_f32_e32 v76, v76, v120
	v_sub_f32_e32 v75, v75, v120
	v_sub_f32_e32 v74, v74, v120
	v_sub_f32_e32 v72, v73, v120
	v_exp_f32_e32 v72, v72
	v_exp_f32_e32 v73, v74
	v_exp_f32_e32 v74, v75
	v_exp_f32_e32 v75, v76
	v_sub_f32_e32 v76, v80, v120
	v_sub_f32_e32 v79, v79, v120
	v_sub_f32_e32 v78, v78, v120
	v_sub_f32_e32 v77, v77, v120
	v_exp_f32_e32 v84, v77
	v_exp_f32_e32 v86, v79
	v_exp_f32_e32 v87, v76
	v_exp_f32_e32 v85, v78
	v_sub_f32_e32 v76, v100, v120
	v_sub_f32_e32 v77, v83, v120
	v_sub_f32_e32 v78, v82, v120
	v_sub_f32_e32 v79, v81, v120
	v_exp_f32_e32 v88, v79
	v_exp_f32_e32 v89, v78
	v_exp_f32_e32 v90, v77
	v_exp_f32_e32 v91, v76
	v_sub_f32_e32 v76, v104, v120
	v_sub_f32_e32 v77, v103, v120
	v_sub_f32_e32 v78, v102, v120
	v_sub_f32_e32 v79, v101, v120
	v_pk_add_f32 v[54:55], v[52:53], 0 op_sel_hi:[1,0]
	v_pk_add_f32 v[56:57], v[50:51], 0 op_sel_hi:[1,0]
	v_exp_f32_e32 v96, v79
	v_exp_f32_e32 v98, v77
	v_exp_f32_e32 v99, v76
	v_exp_f32_e32 v97, v78
	v_pk_add_f32 v[56:57], v[72:73], v[56:57]
	v_pk_add_f32 v[54:55], v[74:75], v[54:55]
	v_pk_add_f32 v[56:57], v[84:85], v[56:57]
	v_pk_add_f32 v[54:55], v[86:87], v[54:55]
	v_pk_add_f32 v[56:57], v[88:89], v[56:57]
	v_pk_add_f32 v[54:55], v[90:91], v[54:55]
	v_sub_f32_e32 v78, v92, v120
	v_pk_add_f32 v[76:77], v[98:99], v[54:55]
	v_pk_add_f32 v[54:55], v[96:97], v[56:57]
	v_sub_f32_e32 v57, v93, v120
	v_sub_f32_e32 v56, v95, v120
	v_exp_f32_e32 v101, v57
	v_sub_f32_e32 v57, v94, v120
	v_exp_f32_e32 v100, v78
	v_exp_f32_e32 v102, v57
	v_exp_f32_e32 v103, v56
	v_sub_f32_e32 v80, v110, v120
	v_sub_f32_e32 v81, v107, v120
	v_sub_f32_e32 v82, v106, v120
	v_sub_f32_e32 v83, v105, v120
	v_exp_f32_e32 v104, v81
	v_exp_f32_e32 v105, v80
	v_exp_f32_e32 v106, v83
	v_exp_f32_e32 v107, v82
	v_pk_add_f32 v[78:79], v[100:101], v[54:55]
	v_pk_add_f32 v[76:77], v[102:103], v[76:77]
	v_cvt_pk_bf16_f32 v50, v50, v51
	v_cvt_pk_bf16_f32 v51, v52, v53
	v_cvt_pk_bf16_f32 v52, v72, v73
	v_cvt_pk_bf16_f32 v53, v74, v75
	ds_read2_b64 v[54:57], v67 offset0:4 offset1:8
	ds_read2_b64 v[72:75], v68 offset0:36 offset1:40
	v_pk_add_f32 v[108:109], v[104:105], v[76:77]
	v_pk_add_f32 v[110:111], v[106:107], v[78:79]
	ds_read2_b64 v[76:79], v70 offset0:68 offset1:72
	ds_read2_b64 v[80:83], v69 offset0:100 offset1:104
	v_sub_f32_e32 v60, v60, v120
	v_sub_f32_e32 v59, v59, v120
	v_sub_f32_e32 v58, v58, v120
	v_sub_f32_e32 v115, v61, v120
	v_cvt_pk_bf16_f32 v84, v84, v85
	v_cvt_pk_bf16_f32 v85, v86, v87
	v_cvt_pk_bf16_f32 v86, v88, v89
	v_cvt_pk_bf16_f32 v87, v90, v91
	ds_read2_b64 v[88:91], v67 offset0:12 offset1:16
	v_exp_f32_e32 v112, v58
	v_exp_f32_e32 v113, v59
	v_exp_f32_e32 v114, v60
	ds_read2_b64 v[58:61], v70 offset0:76 offset1:80
	s_waitcnt lgkmcnt(5)
	v_mfma_f32_16x16x32_bf16 v[54:57], v[54:57], v[50:53], 0
	ds_read2_b64 v[92:95], v68 offset0:44 offset1:48
	v_exp_f32_e32 v115, v115
	s_waitcnt lgkmcnt(5)
	v_mfma_f32_16x16x32_bf16 v[72:75], v[72:75], v[50:53], 0
	s_waitcnt lgkmcnt(4)
	v_mfma_f32_16x16x32_bf16 v[76:79], v[76:79], v[50:53], 0
	s_waitcnt lgkmcnt(3)
	v_mfma_f32_16x16x32_bf16 v[50:53], v[80:83], v[50:53], 0
	ds_read2_b64 v[80:83], v69 offset0:108 offset1:112
	s_waitcnt lgkmcnt(3)
	v_mfma_f32_16x16x32_bf16 v[54:57], v[88:91], v[84:87], v[54:57]
	v_cvt_pk_bf16_f32 v88, v96, v97
	v_cvt_pk_bf16_f32 v89, v98, v99
	v_cvt_pk_bf16_f32 v90, v100, v101
	v_cvt_pk_bf16_f32 v91, v102, v103
	s_waitcnt lgkmcnt(2)
	v_mfma_f32_16x16x32_bf16 v[58:61], v[58:61], v[84:87], v[76:79]
	v_add_f32_e64 v98, v114, v108
	v_add_f32_e64 v99, v115, v109
	v_sub_f32_e32 v101, v119, v120
	v_sub_f32_e32 v102, v118, v120
	ds_read2_b64 v[76:79], v68 offset0:52 offset1:56
	s_waitcnt lgkmcnt(2)
	v_mfma_f32_16x16x32_bf16 v[72:75], v[92:95], v[84:87], v[72:75]
	ds_read2_b64 v[92:95], v67 offset0:20 offset1:24
	v_sub_f32_e32 v108, v117, v120
	v_exp_f32_e32 v102, v102
	s_waitcnt lgkmcnt(2)
	v_mfma_f32_16x16x32_bf16 v[50:53], v[80:83], v[84:87], v[50:53]
	ds_read2_b64 v[80:83], v70 offset0:84 offset1:88
	v_sub_f32_e32 v84, v116, v120
	v_exp_f32_e32 v100, v84
	s_waitcnt lgkmcnt(2)
	v_mfma_f32_16x16x32_bf16 v[72:75], v[76:79], v[88:91], v[72:75]
	ds_read2_b64 v[76:79], v69 offset0:116 offset1:120
	v_cvt_pk_bf16_f32 v84, v106, v107
	v_cvt_pk_bf16_f32 v85, v104, v105
	v_cvt_pk_bf16_f32 v86, v112, v113
	v_cvt_pk_bf16_f32 v87, v114, v115
	s_waitcnt lgkmcnt(1)
	v_mfma_f32_16x16x32_bf16 v[58:61], v[80:83], v[88:91], v[58:61]
	ds_read2_b64 v[80:83], v68 offset0:60 offset1:64
	v_exp_f32_e32 v103, v101
	v_exp_f32_e32 v101, v108
	v_mfma_f32_16x16x32_bf16 v[54:57], v[92:95], v[88:91], v[54:57]
	ds_read2_b64 v[92:95], v67 offset0:28 offset1:32
	v_pk_add_f32 v[96:97], v[112:113], v[110:111]
	s_waitcnt lgkmcnt(2)
	v_mfma_f32_16x16x32_bf16 v[50:53], v[76:79], v[88:91], v[50:53]
	ds_read2_b64 v[76:79], v70 offset0:92 offset1:96
	v_pk_add_f32 v[88:89], v[102:103], v[98:99]
	v_pk_add_f32 v[90:91], v[100:101], v[96:97]
	s_waitcnt lgkmcnt(2)
	v_mfma_f32_16x16x32_bf16 v[72:75], v[80:83], v[84:87], v[72:75]
	ds_read2_b64 v[80:83], v69 offset0:124 offset1:128
	s_waitcnt lgkmcnt(2)
	v_mfma_f32_16x16x32_bf16 v[54:57], v[92:95], v[84:87], v[54:57]
	v_pk_mov_b32 v[92:93], v[90:91], v[88:89] op_sel:[1,0]
	v_mov_b32_e32 v91, v89
	v_pk_add_f32 v[88:89], v[92:93], v[90:91]
	s_waitcnt lgkmcnt(1)
	v_mfma_f32_16x16x32_bf16 v[58:61], v[76:79], v[84:87], v[58:61]
	v_add_f32_e32 v88, v88, v89
	ds_bpermute_b32 v76, v65, v88
	v_mov_b32_e32 v78, v147
	s_waitcnt lgkmcnt(1)
; __device__ __forceinline__ unsigned cvt_pk_bf16(float lo, float hi) { unsigned r; asm volatile("v_cvt_pk_bf16_f32 %0, %1, %2" : "=v"(r) : "v"(lo), "v"(hi)); return r; }
; #define LAS __attribute__((address_space(3)))
; __device__ __forceinline__ void attn_unit(LAS unsigned char* lds, bf16* Q, const bf16* Kg, const bf16* Vg, const float* snk, int unit, int tid) {
;     ...
;         const float inv = 1.f / (ls + __builtin_amdgcn_exp2f(sink - mx));
;         f32x4 o[4];
; #pragma unroll
;         for (int dt = 0; dt < 4; ++dt) o[dt] = (f32x4){0.f, 0.f, 0.f, 0.f};
; #pragma unroll
;         for (int kp = 0; kp < 5; ++kp) {
;             v4u pw; pw.x = cvt_pk_bf16(st[2 * kp][0], st[2 * kp][1]); pw.y = cvt_pk_bf16(st[2 * kp][2], st[2 * kp][3]);
;             if (kp < 4) { pw.z = cvt_pk_bf16(st[(2 * kp + 1) % 9][0], st[(2 * kp + 1) % 9][1]); pw.w = cvt_pk_bf16(st[(2 * kp + 1) % 9][2], st[(2 * kp + 1) % 9][3]); } else { pw.z = 0u; pw.w = 0u; }
;             const bf16x8_t pb = __builtin_bit_cast(bf16x8_t, pw);
; #pragma unroll
;             for (int dt = 0; dt < 4; ++dt) { const LAS unsigned char* vp = lds + ATT_VOFF + (16 * dt + fr) * ATT_VP + (16 * (mt + 2 * kp) + 4 * fq) * 2;
;                 const v2u lo = *(const LAS v2u*)vp; v2u hi = {0u, 0u}; if (kp < 4) hi = *(const LAS v2u*)(vp + 32);
;                 v4u aw; aw.x = lo.x; aw.y = lo.y; aw.z = hi.x; aw.w = hi.y;
;                 o[dt] = __builtin_amdgcn_mfma_f32_16x16x32_bf16(__builtin_bit_cast(bf16x8_t, aw), pb, o[dt], 0, 0, 0); }
;         }
; #pragma unroll
;         for (int dt = 0; dt < 4; ++dt) { const f32x4 y = o[dt] * inv; v2u w; w.x = cvt_pk_bf16(y[0], y[1]); w.y = cvt_pk_bf16(y[2], y[3]); *(v2u*)(qbase + (size_t)mt * 16 * 1024 + 16 * dt + 4 * fq) = w; }
	v_mfma_f32_16x16x32_bf16 v[50:53], v[80:83], v[84:87], v[50:53]
	v_mov_b32_e32 v82, v147
	v_mov_b32_e32 v83, v147
	s_waitcnt lgkmcnt(0)
	v_add_f32_e32 v94, v88, v76
	v_cvt_pk_bf16_f32 v76, v100, v101
	v_cvt_pk_bf16_f32 v77, v102, v103
	ds_read_b64 v[80:81], v179 offset:37152
	ds_read_b64 v[84:85], v179 offset:45600
	v_mov_b32_e32 v79, v147
	v_mov_b32_e32 v86, v147
	v_mov_b32_e32 v87, v147
	s_waitcnt lgkmcnt(1)
	v_mfma_f32_16x16x32_bf16 v[54:57], v[80:83], v[76:79], v[54:57]
	ds_bpermute_b32 v80, v66, v94
	v_fma_f32 v81, v64, s61, -v120
	v_exp_f32_e32 v81, v81
	ds_read_b64 v[88:89], v179 offset:54048
	ds_read_b64 v[92:93], v179 offset:62496
	v_mov_b32_e32 v90, v147
	s_waitcnt lgkmcnt(2)
	v_add_f32_e32 v80, v94, v80
	v_add_f32_e32 v80, v81, v80
	v_mov_b32_e32 v91, v147
	v_mov_b32_e32 v94, v147
	v_mov_b32_e32 v95, v147
	v_div_scale_f32 v81, s[68:69], v80, v80, 1.0
	v_rcp_f32_e32 v82, v81
	v_mfma_f32_16x16x32_bf16 v[72:75], v[84:87], v[76:79], v[72:75]
	s_waitcnt lgkmcnt(1)
	v_mfma_f32_16x16x32_bf16 v[58:61], v[88:91], v[76:79], v[58:61]
	s_waitcnt lgkmcnt(0)
	v_mfma_f32_16x16x32_bf16 v[50:53], v[92:95], v[76:79], v[50:53]
	v_fma_f32 v76, -v81, v82, 1.0
	v_fmac_f32_e32 v82, v76, v82
	v_div_scale_f32 v76, vcc, 1.0, v80, 1.0
	v_mul_f32_e32 v77, v76, v82
	v_fma_f32 v78, -v81, v77, v76
	v_fmac_f32_e32 v77, v78, v82
	v_fma_f32 v76, -v81, v77, v76
	v_div_fmas_f32 v76, v76, v82, v77
	v_div_fixup_f32 v76, v76, v80, 1.0
	v_pk_mul_f32 v[56:57], v[76:77], v[56:57] op_sel_hi:[0,1]
	v_pk_mul_f32 v[54:55], v[76:77], v[54:55] op_sel_hi:[0,1]
	v_add_co_u32_e32 v100, vcc, s43, v62
	v_cvt_pk_bf16_f32 v54, v54, v55
	v_cvt_pk_bf16_f32 v55, v56, v57
	v_pk_mul_f32 v[56:57], v[76:77], v[72:73] op_sel_hi:[0,1]
	s_nop 0
	v_addc_co_u32_e32 v101, vcc, 0, v63, vcc
	global_store_dwordx2 v[100:101], v[54:55], off
	v_pk_mul_f32 v[54:55], v[76:77], v[74:75] op_sel_hi:[0,1]
	v_cvt_pk_bf16_f32 v56, v56, v57
	v_cvt_pk_bf16_f32 v57, v54, v55
	global_store_dwordx2 v[100:101], v[56:57], off offset:32
	v_pk_mul_f32 v[56:57], v[76:77], v[58:59] op_sel_hi:[0,1]
	v_pk_mul_f32 v[54:55], v[76:77], v[60:61] op_sel_hi:[0,1]
	v_cvt_pk_bf16_f32 v56, v56, v57
	v_cvt_pk_bf16_f32 v57, v54, v55
	v_pk_mul_f32 v[52:53], v[76:77], v[52:53] op_sel_hi:[0,1]
	v_pk_mul_f32 v[50:51], v[76:77], v[50:51] op_sel_hi:[0,1]
	global_store_dwordx2 v[100:101], v[56:57], off offset:64
	v_cvt_pk_bf16_f32 v102, v50, v51
	v_cvt_pk_bf16_f32 v103, v52, v53
	ds_read_b128 v[50:53], v178 offset:4608
	ds_read_b128 v[54:57], v178 offset:4672
	s_waitcnt lgkmcnt(1)
	v_mfma_f32_16x16x32_bf16 v[50:53], v[50:53], v[42:45], 0
	ds_read_b128 v[58:61], v178 offset:6912
	ds_read_b128 v[96:99], v178 offset:23040
	global_store_dwordx2 v[100:101], v[102:103], off offset:96
	s_waitcnt lgkmcnt(2)
	v_mfma_f32_16x16x32_bf16 v[72:75], v[54:57], v[46:49], v[50:53]
	s_nop 2
	ds_read_b128 v[50:53], v178 offset:6976
	s_waitcnt lgkmcnt(2)
	v_mfma_f32_16x16x32_bf16 v[54:57], v[58:61], v[42:45], 0
	ds_read_b128 v[58:61], v178 offset:9216
	s_waitcnt lgkmcnt(1)
	v_mfma_f32_16x16x32_bf16 v[76:79], v[50:53], v[46:49], v[54:57]
	ds_read_b128 v[50:53], v178 offset:9280
	s_waitcnt lgkmcnt(1)
	v_mfma_f32_16x16x32_bf16 v[54:57], v[58:61], v[42:45], 0
	ds_read_b128 v[58:61], v178 offset:11520
	s_waitcnt lgkmcnt(1)
	v_mfma_f32_16x16x32_bf16 v[80:83], v[50:53], v[46:49], v[54:57]
	ds_read_b128 v[50:53], v178 offset:11584
	s_waitcnt lgkmcnt(1)
	v_mfma_f32_16x16x32_bf16 v[54:57], v[58:61], v[42:45], 0
	ds_read_b128 v[58:61], v178 offset:13824
	s_waitcnt lgkmcnt(1)
	v_mfma_f32_16x16x32_bf16 v[84:87], v[50:53], v[46:49], v[54:57]
	ds_read_b128 v[50:53], v178 offset:13888
	s_waitcnt lgkmcnt(1)
	v_mfma_f32_16x16x32_bf16 v[54:57], v[58:61], v[42:45], 0
	ds_read_b128 v[58:61], v178 offset:16128
	s_waitcnt lgkmcnt(1)
	v_mfma_f32_16x16x32_bf16 v[88:91], v[50:53], v[46:49], v[54:57]
	ds_read_b128 v[50:53], v178 offset:16192
	s_waitcnt lgkmcnt(1)
	v_mfma_f32_16x16x32_bf16 v[54:57], v[58:61], v[42:45], 0
	ds_read_b128 v[58:61], v178 offset:18432
	s_waitcnt lgkmcnt(1)
	v_mfma_f32_16x16x32_bf16 v[92:95], v[50:53], v[46:49], v[54:57]
	ds_read_b128 v[50:53], v178 offset:18496
	s_waitcnt lgkmcnt(1)
	v_mfma_f32_16x16x32_bf16 v[54:57], v[58:61], v[42:45], 0
	ds_read_b128 v[58:61], v178 offset:20736
	s_nop 3
	v_cndmask_b32_e64 v92, v190, v92, s[16:17]
	v_cndmask_b32_e64 v93, v190, v93, s[16:17]
	s_waitcnt lgkmcnt(1)
	v_mfma_f32_16x16x32_bf16 v[54:57], v[50:53], v[46:49], v[54:57]
	ds_read_b128 v[50:53], v178 offset:20800
	v_cndmask_b32_e64 v94, v190, v94, s[16:17]
	v_cndmask_b32_e64 v95, v190, v95, s[16:17]
	s_waitcnt lgkmcnt(1)
	v_mfma_f32_16x16x32_bf16 v[58:61], v[58:61], v[42:45], 0
	s_waitcnt lgkmcnt(0)
	v_mfma_f32_16x16x32_bf16 v[50:53], v[50:53], v[46:49], v[58:61]
	s_nop 5
	ds_read_b128 v[58:61], v178 offset:23104
	v_mfma_f32_16x16x32_bf16 v[42:45], v[96:99], v[42:45], 0
	s_waitcnt lgkmcnt(0)
; __device__ __forceinline__ unsigned cvt_pk_bf16(float lo, float hi) { unsigned r; asm volatile("v_cvt_pk_bf16_f32 %0, %1, %2" : "=v"(r) : "v"(lo), "v"(hi)); return r; }
; #define LAS __attribute__((address_space(3)))
; __device__ __forceinline__ void attn_unit(LAS unsigned char* lds, bf16* Q, const bf16* Kg, const bf16* Vg, const float* snk, int unit, int tid) {
;     ...
;         float mx = sink;
; #pragma unroll
;         for (int kb = 0; kb < 9; ++kb) {
;             const bool tile_ok = (n > 0) || (mt + kb >= 8);
; #pragma unroll
;             for (int i = 0; i < 4; ++i) { const bool ok = tile_ok && (kb == 0 ? lo_ok[i] : (kb == 8 ? !lo_ok[i] : true));
;                 st[kb][i] = ok ? st[kb][i] : -INFINITY; mx = fmaxf(mx, st[kb][i]); }
;         }
;         mx = fmaxf(mx, __shfl_xor(mx, 16)); mx = fmaxf(mx, __shfl_xor(mx, 32));
;         f32x4 ls4 = {0.f, 0.f, 0.f, 0.f};
; #pragma unroll
;         for (int kb = 0; kb < 9; ++kb) { f32x4 d = st[kb] - mx;
; #pragma unroll
;             for (int i = 0; i < 4; ++i) d[i] = __builtin_amdgcn_exp2f(d[i]);
;             st[kb] = d; ls4 = ls4 + d; }
;         float ls = (ls4[0] + ls4[1]) + (ls4[2] + ls4[3]);
;         ls += __shfl_xor(ls, 16); ls += __shfl_xor(ls, 32);
;         const float inv = 1.f / (ls + __builtin_amdgcn_exp2f(sink - mx));
;         f32x4 o[4];
; #pragma unroll
;         for (int dt = 0; dt < 4; ++dt) o[dt] = (f32x4){0.f, 0.f, 0.f, 0.f};
; #pragma unroll
;         for (int kp = 0; kp < 5; ++kp) {
;             v4u pw; pw.x = cvt_pk_bf16(st[2 * kp][0], st[2 * kp][1]); pw.y = cvt_pk_bf16(st[2 * kp][2], st[2 * kp][3]);
;             if (kp < 4) { pw.z = cvt_pk_bf16(st[(2 * kp + 1) % 9][0], st[(2 * kp + 1) % 9][1]); pw.w = cvt_pk_bf16(st[(2 * kp + 1) % 9][2], st[(2 * kp + 1) % 9][3]); } else { pw.z = 0u; pw.w = 0u; }
;             const bf16x8_t pb = __builtin_bit_cast(bf16x8_t, pw);
; #pragma unroll
;             for (int dt = 0; dt < 4; ++dt) { const LAS unsigned char* vp = lds + ATT_VOFF + (16 * dt + fr) * ATT_VP + (16 * (mt + 2 * kp) + 4 * fq) * 2;
;                 const v2u lo = *(const LAS v2u*)vp; v2u hi = {0u, 0u}; if (kp < 4) hi = *(const LAS v2u*)(vp + 32);
;                 v4u aw; aw.x = lo.x; aw.y = lo.y; aw.z = hi.x; aw.w = hi.y;
;                 o[dt] = __builtin_amdgcn_mfma_f32_16x16x32_bf16(__builtin_bit_cast(bf16x8_t, aw), pb, o[dt], 0, 0, 0); }
	v_mfma_f32_16x16x32_bf16 v[42:45], v[58:61], v[46:49], v[42:45]
	v_cndmask_b32_e64 v47, v73, v190, s[10:11]
	v_cndmask_b32_e64 v46, v190, v72, s[20:21]
	v_cndmask_b32_e64 v47, v190, v47, s[16:17]
	v_max3_f32 v48, v71, v46, v47
	v_cndmask_b32_e64 v49, v190, v74, s[18:19]
	v_cndmask_b32_e64 v58, v190, v75, s[22:23]
	v_max3_f32 v48, v48, v49, v58
	v_cndmask_b32_e64 v59, v190, v76, s[16:17]
	v_cndmask_b32_e64 v60, v190, v77, s[16:17]
	v_max3_f32 v48, v48, v59, v60
	v_cndmask_b32_e64 v61, v190, v78, s[16:17]
	v_cndmask_b32_e64 v72, v190, v79, s[16:17]
	v_max3_f32 v48, v48, v61, v72
	v_cndmask_b32_e64 v73, v190, v80, s[16:17]
	v_cndmask_b32_e64 v74, v190, v81, s[16:17]
	v_max3_f32 v48, v48, v73, v74
	v_cndmask_b32_e64 v75, v190, v82, s[16:17]
	v_cndmask_b32_e64 v76, v190, v83, s[16:17]
	v_max3_f32 v48, v48, v75, v76
	v_cndmask_b32_e64 v80, v190, v84, s[16:17]
	v_cndmask_b32_e64 v81, v190, v85, s[16:17]
	v_max3_f32 v48, v48, v80, v81
	v_cndmask_b32_e64 v82, v190, v86, s[16:17]
	v_cndmask_b32_e64 v83, v190, v87, s[16:17]
	v_max3_f32 v48, v48, v82, v83
	v_cndmask_b32_e64 v84, v190, v88, s[16:17]
	v_cndmask_b32_e64 v85, v190, v89, s[16:17]
	v_max3_f32 v48, v48, v84, v85
	v_cndmask_b32_e64 v86, v190, v90, s[16:17]
	v_cndmask_b32_e64 v87, v190, v91, s[16:17]
	v_max3_f32 v48, v48, v86, v87
	v_max3_f32 v48, v48, v92, v93
	v_max3_f32 v48, v48, v94, v95
	v_max3_f32 v48, v48, v54, v55
	v_max3_f32 v48, v48, v56, v57
	v_max3_f32 v48, v48, v50, v51
	v_max3_f32 v48, v48, v52, v53
	v_cndmask_b32_e64 v108, v42, v190, s[8:9]
	v_cndmask_b32_e64 v109, v190, v43, s[10:11]
	v_max3_f32 v42, v48, v108, v109
	v_cndmask_b32_e64 v110, v44, v190, s[12:13]
	v_cndmask_b32_e64 v111, v45, v190, s[14:15]
	v_max3_f32 v42, v42, v110, v111
	ds_bpermute_b32 v43, v65, v42
	s_waitcnt lgkmcnt(0)
	v_max_f32_e32 v43, v43, v43
	v_max_f32_e32 v42, v42, v43
	ds_bpermute_b32 v43, v66, v42
	s_waitcnt lgkmcnt(0)
	v_max_f32_e32 v43, v43, v43
	v_max_f32_e32 v112, v42, v43
	v_sub_f32_e32 v43, v58, v112
	v_sub_f32_e32 v44, v49, v112
	v_sub_f32_e32 v47, v47, v112
	v_sub_f32_e32 v42, v46, v112
	v_exp_f32_e32 v42, v42
	v_exp_f32_e32 v44, v44
	v_exp_f32_e32 v45, v43
	v_exp_f32_e32 v43, v47
	v_sub_f32_e32 v72, v72, v112
	v_sub_f32_e32 v61, v61, v112
	v_sub_f32_e32 v60, v60, v112
	v_sub_f32_e32 v58, v59, v112
	v_exp_f32_e32 v58, v58
	v_exp_f32_e32 v59, v60
	v_exp_f32_e32 v60, v61
	v_exp_f32_e32 v61, v72
	v_sub_f32_e32 v72, v76, v112
	v_sub_f32_e32 v75, v75, v112
	v_sub_f32_e32 v74, v74, v112
	v_sub_f32_e32 v73, v73, v112
	v_exp_f32_e32 v76, v73
	v_exp_f32_e32 v78, v75
	v_exp_f32_e32 v79, v72
	v_exp_f32_e32 v77, v74
	v_sub_f32_e32 v72, v83, v112
	v_sub_f32_e32 v73, v82, v112
	v_sub_f32_e32 v74, v81, v112
	v_sub_f32_e32 v75, v80, v112
	v_exp_f32_e32 v80, v75
	v_exp_f32_e32 v81, v74
	v_exp_f32_e32 v82, v73
	v_exp_f32_e32 v83, v72
	v_sub_f32_e32 v72, v87, v112
	v_sub_f32_e32 v73, v86, v112
	v_sub_f32_e32 v74, v85, v112
	v_sub_f32_e32 v75, v84, v112
	v_pk_add_f32 v[46:47], v[44:45], 0 op_sel_hi:[1,0]
	v_pk_add_f32 v[48:49], v[42:43], 0 op_sel_hi:[1,0]
	v_exp_f32_e32 v88, v75
	v_exp_f32_e32 v90, v73
	v_exp_f32_e32 v91, v72
	v_exp_f32_e32 v89, v74
	v_pk_add_f32 v[48:49], v[58:59], v[48:49]
	v_pk_add_f32 v[46:47], v[60:61], v[46:47]
	v_pk_add_f32 v[48:49], v[76:77], v[48:49]
	v_pk_add_f32 v[46:47], v[78:79], v[46:47]
	v_pk_add_f32 v[48:49], v[80:81], v[48:49]
	v_pk_add_f32 v[46:47], v[82:83], v[46:47]
	v_sub_f32_e32 v74, v92, v112
	v_pk_add_f32 v[72:73], v[90:91], v[46:47]
	v_pk_add_f32 v[46:47], v[88:89], v[48:49]
	v_sub_f32_e32 v49, v93, v112
	v_sub_f32_e32 v48, v95, v112
	v_exp_f32_e32 v93, v49
	v_sub_f32_e32 v49, v94, v112
	v_exp_f32_e32 v92, v74
	v_exp_f32_e32 v94, v49
	v_exp_f32_e32 v95, v48
	v_sub_f32_e32 v57, v57, v112
	v_sub_f32_e32 v56, v56, v112
	v_sub_f32_e32 v84, v55, v112
	v_cvt_pk_bf16_f32 v42, v42, v43
	v_cvt_pk_bf16_f32 v43, v44, v45
	v_cvt_pk_bf16_f32 v44, v58, v59
	v_sub_f32_e32 v58, v54, v112
	v_exp_f32_e32 v96, v56
	v_exp_f32_e32 v97, v57
	v_exp_f32_e32 v98, v58
	v_exp_f32_e32 v99, v84
	v_pk_add_f32 v[74:75], v[92:93], v[46:47]
	v_pk_add_f32 v[58:59], v[94:95], v[72:73]
	v_cvt_pk_bf16_f32 v45, v60, v61
	ds_read2_b64 v[46:49], v67 offset0:8 offset1:12
	ds_read2_b64 v[54:57], v68 offset0:40 offset1:44
	v_pk_add_f32 v[100:101], v[96:97], v[58:59]
	v_pk_add_f32 v[102:103], v[98:99], v[74:75]
	ds_read2_b64 v[58:61], v70 offset0:72 offset1:76
	ds_read2_b64 v[72:75], v69 offset0:104 offset1:108
	v_sub_f32_e32 v52, v52, v112
	v_sub_f32_e32 v51, v51, v112
	v_sub_f32_e32 v50, v50, v112
	v_sub_f32_e32 v107, v53, v112
	v_cvt_pk_bf16_f32 v76, v76, v77
	v_cvt_pk_bf16_f32 v77, v78, v79
	v_cvt_pk_bf16_f32 v78, v80, v81
	v_cvt_pk_bf16_f32 v79, v82, v83
	ds_read2_b64 v[80:83], v67 offset0:16 offset1:20
	v_exp_f32_e32 v104, v50
	v_exp_f32_e32 v105, v51
	v_exp_f32_e32 v106, v52
	ds_read2_b64 v[50:53], v70 offset0:80 offset1:84
	s_waitcnt lgkmcnt(5)
	v_mfma_f32_16x16x32_bf16 v[46:49], v[46:49], v[42:45], 0
	ds_read2_b64 v[84:87], v68 offset0:48 offset1:52
	v_exp_f32_e32 v107, v107
	s_waitcnt lgkmcnt(5)
	v_mfma_f32_16x16x32_bf16 v[54:57], v[54:57], v[42:45], 0
	s_waitcnt lgkmcnt(4)
	v_mfma_f32_16x16x32_bf16 v[58:61], v[58:61], v[42:45], 0
	s_waitcnt lgkmcnt(3)
	v_mfma_f32_16x16x32_bf16 v[42:45], v[72:75], v[42:45], 0
	ds_read2_b64 v[72:75], v69 offset0:112 offset1:116
	s_waitcnt lgkmcnt(3)
	v_mfma_f32_16x16x32_bf16 v[46:49], v[80:83], v[76:79], v[46:49]
	v_cvt_pk_bf16_f32 v80, v88, v89
	v_cvt_pk_bf16_f32 v81, v90, v91
	v_cvt_pk_bf16_f32 v82, v92, v93
	v_cvt_pk_bf16_f32 v83, v94, v95
	s_waitcnt lgkmcnt(2)
; __device__ __forceinline__ unsigned cvt_pk_bf16(float lo, float hi) { unsigned r; asm volatile("v_cvt_pk_bf16_f32 %0, %1, %2" : "=v"(r) : "v"(lo), "v"(hi)); return r; }
; #define LAS __attribute__((address_space(3)))
; __device__ __forceinline__ void attn_unit(LAS unsigned char* lds, bf16* Q, const bf16* Kg, const bf16* Vg, const float* snk, int unit, int tid) {
;     ...
; #pragma unroll
;         for (int kp = 0; kp < 5; ++kp) {
;             v4u pw; pw.x = cvt_pk_bf16(st[2 * kp][0], st[2 * kp][1]); pw.y = cvt_pk_bf16(st[2 * kp][2], st[2 * kp][3]);
;             if (kp < 4) { pw.z = cvt_pk_bf16(st[(2 * kp + 1) % 9][0], st[(2 * kp + 1) % 9][1]); pw.w = cvt_pk_bf16(st[(2 * kp + 1) % 9][2], st[(2 * kp + 1) % 9][3]); } else { pw.z = 0u; pw.w = 0u; }
;             const bf16x8_t pb = __builtin_bit_cast(bf16x8_t, pw);
; #pragma unroll
;             for (int dt = 0; dt < 4; ++dt) { const LAS unsigned char* vp = lds + ATT_VOFF + (16 * dt + fr) * ATT_VP + (16 * (mt + 2 * kp) + 4 * fq) * 2;
;                 const v2u lo = *(const LAS v2u*)vp; v2u hi = {0u, 0u}; if (kp < 4) hi = *(const LAS v2u*)(vp + 32);
;                 v4u aw; aw.x = lo.x; aw.y = lo.y; aw.z = hi.x; aw.w = hi.y;
;                 o[dt] = __builtin_amdgcn_mfma_f32_16x16x32_bf16(__builtin_bit_cast(bf16x8_t, aw), pb, o[dt], 0, 0, 0); }
;         }
; #pragma unroll
;         for (int dt = 0; dt < 4; ++dt) { const f32x4 y = o[dt] * inv; v2u w; w.x = cvt_pk_bf16(y[0], y[1]); w.y = cvt_pk_bf16(y[2], y[3]); *(v2u*)(qbase + (size_t)mt * 16 * 1024 + 16 * dt + 4 * fq) = w; }
	v_mfma_f32_16x16x32_bf16 v[50:53], v[50:53], v[76:79], v[58:61]
	v_add_f32_e64 v90, v106, v100
	v_add_f32_e64 v91, v107, v101
	v_sub_f32_e32 v93, v111, v112
	v_sub_f32_e32 v94, v110, v112
	ds_read2_b64 v[58:61], v68 offset0:56 offset1:60
	s_waitcnt lgkmcnt(2)
	v_mfma_f32_16x16x32_bf16 v[54:57], v[84:87], v[76:79], v[54:57]
	ds_read2_b64 v[84:87], v67 offset0:24 offset1:28
	v_sub_f32_e32 v100, v109, v112
	v_exp_f32_e32 v94, v94
	s_waitcnt lgkmcnt(2)
	v_mfma_f32_16x16x32_bf16 v[42:45], v[72:75], v[76:79], v[42:45]
	ds_read2_b64 v[72:75], v70 offset0:88 offset1:92
	v_sub_f32_e32 v76, v108, v112
	v_exp_f32_e32 v92, v76
	s_waitcnt lgkmcnt(2)
	v_mfma_f32_16x16x32_bf16 v[54:57], v[58:61], v[80:83], v[54:57]
	ds_read2_b64 v[58:61], v69 offset0:120 offset1:124
	v_cvt_pk_bf16_f32 v76, v98, v99
	v_cvt_pk_bf16_f32 v77, v96, v97
	v_cvt_pk_bf16_f32 v78, v104, v105
	v_cvt_pk_bf16_f32 v79, v106, v107
	s_waitcnt lgkmcnt(1)
	v_mfma_f32_16x16x32_bf16 v[50:53], v[72:75], v[80:83], v[50:53]
	ds_read2_b64 v[72:75], v68 offset0:64 offset1:68
	v_exp_f32_e32 v95, v93
	v_exp_f32_e32 v93, v100
	v_mfma_f32_16x16x32_bf16 v[46:49], v[84:87], v[80:83], v[46:49]
	ds_read2_b64 v[84:87], v67 offset0:32 offset1:36
	v_pk_add_f32 v[88:89], v[104:105], v[102:103]
	s_waitcnt lgkmcnt(2)
	v_mfma_f32_16x16x32_bf16 v[42:45], v[58:61], v[80:83], v[42:45]
	ds_read2_b64 v[58:61], v70 offset0:96 offset1:100
	v_pk_add_f32 v[80:81], v[94:95], v[90:91]
	v_pk_add_f32 v[82:83], v[92:93], v[88:89]
	s_waitcnt lgkmcnt(2)
	v_mfma_f32_16x16x32_bf16 v[54:57], v[72:75], v[76:79], v[54:57]
	ds_read2_b64 v[72:75], v69 offset0:128 offset1:132
	s_waitcnt lgkmcnt(2)
	v_mfma_f32_16x16x32_bf16 v[46:49], v[84:87], v[76:79], v[46:49]
	v_pk_mov_b32 v[84:85], v[82:83], v[80:81] op_sel:[1,0]
	v_mov_b32_e32 v83, v81
	v_pk_add_f32 v[80:81], v[84:85], v[82:83]
	s_waitcnt lgkmcnt(1)
	v_mfma_f32_16x16x32_bf16 v[50:53], v[58:61], v[76:79], v[50:53]
	v_add_f32_e32 v80, v80, v81
	ds_bpermute_b32 v58, v65, v80
	v_mov_b32_e32 v60, v147
	s_waitcnt lgkmcnt(1)
	v_mfma_f32_16x16x32_bf16 v[42:45], v[72:75], v[76:79], v[42:45]
	v_mov_b32_e32 v74, v147
	v_mov_b32_e32 v75, v147
	s_waitcnt lgkmcnt(0)
	v_add_f32_e32 v86, v80, v58
	v_cvt_pk_bf16_f32 v58, v92, v93
	v_cvt_pk_bf16_f32 v59, v94, v95
	ds_read_b64 v[72:73], v179 offset:37184
	ds_read_b64 v[76:77], v179 offset:45632
	v_mov_b32_e32 v61, v147
	v_mov_b32_e32 v78, v147
	v_mov_b32_e32 v79, v147
	s_waitcnt lgkmcnt(1)
	v_mfma_f32_16x16x32_bf16 v[46:49], v[72:75], v[58:61], v[46:49]
	ds_bpermute_b32 v72, v66, v86
	v_fma_f32 v73, v64, s61, -v112
	v_exp_f32_e32 v73, v73
	ds_read_b64 v[80:81], v179 offset:54080
	ds_read_b64 v[84:85], v179 offset:62528
	v_mov_b32_e32 v82, v147
	s_waitcnt lgkmcnt(2)
	v_add_f32_e32 v72, v86, v72
	v_add_f32_e32 v72, v73, v72
	v_mov_b32_e32 v83, v147
	v_mov_b32_e32 v86, v147
	v_mov_b32_e32 v87, v147
	v_div_scale_f32 v73, s[68:69], v72, v72, 1.0
	v_rcp_f32_e32 v74, v73
	v_mfma_f32_16x16x32_bf16 v[54:57], v[76:79], v[58:61], v[54:57]
	s_waitcnt lgkmcnt(1)
	v_mfma_f32_16x16x32_bf16 v[50:53], v[80:83], v[58:61], v[50:53]
	s_waitcnt lgkmcnt(0)
	v_mfma_f32_16x16x32_bf16 v[42:45], v[84:87], v[58:61], v[42:45]
	v_fma_f32 v58, -v73, v74, 1.0
	v_fmac_f32_e32 v74, v58, v74
	v_div_scale_f32 v58, vcc, 1.0, v72, 1.0
	v_mul_f32_e32 v59, v58, v74
	v_fma_f32 v60, -v73, v59, v58
	v_fmac_f32_e32 v59, v60, v74
	v_fma_f32 v58, -v73, v59, v58
	v_div_fmas_f32 v58, v58, v74, v59
	v_div_fixup_f32 v58, v58, v72, 1.0
	v_pk_mul_f32 v[48:49], v[58:59], v[48:49] op_sel_hi:[0,1]
	v_pk_mul_f32 v[46:47], v[58:59], v[46:47] op_sel_hi:[0,1]
	v_add_co_u32_e32 v92, vcc, s53, v62
	v_cvt_pk_bf16_f32 v46, v46, v47
	v_cvt_pk_bf16_f32 v47, v48, v49
	v_pk_mul_f32 v[48:49], v[58:59], v[54:55] op_sel_hi:[0,1]
	s_nop 0
	v_addc_co_u32_e32 v93, vcc, 0, v63, vcc
	global_store_dwordx2 v[92:93], v[46:47], off
	v_pk_mul_f32 v[46:47], v[58:59], v[56:57] op_sel_hi:[0,1]
	v_cvt_pk_bf16_f32 v48, v48, v49
	v_cvt_pk_bf16_f32 v49, v46, v47
	global_store_dwordx2 v[92:93], v[48:49], off offset:32
	v_pk_mul_f32 v[48:49], v[58:59], v[50:51] op_sel_hi:[0,1]
	v_pk_mul_f32 v[46:47], v[58:59], v[52:53] op_sel_hi:[0,1]
	v_cvt_pk_bf16_f32 v48, v48, v49
	v_cvt_pk_bf16_f32 v49, v46, v47
	v_pk_mul_f32 v[44:45], v[58:59], v[44:45] op_sel_hi:[0,1]
	v_pk_mul_f32 v[42:43], v[58:59], v[42:43] op_sel_hi:[0,1]
	global_store_dwordx2 v[92:93], v[48:49], off offset:64
	v_cvt_pk_bf16_f32 v94, v42, v43
	v_cvt_pk_bf16_f32 v95, v44, v45
	ds_read_b128 v[42:45], v178 offset:6912
	ds_read_b128 v[46:49], v178 offset:6976
	s_waitcnt lgkmcnt(1)
	v_mfma_f32_16x16x32_bf16 v[42:45], v[42:45], v[34:37], 0
	ds_read_b128 v[50:53], v178 offset:9216
	ds_read_b128 v[54:57], v178 offset:11520
	ds_read_b128 v[58:61], v178 offset:13824
	s_waitcnt lgkmcnt(3)
	v_mfma_f32_16x16x32_bf16 v[46:49], v[46:49], v[38:41], v[42:45]
	ds_read_b128 v[72:75], v178 offset:16128
	ds_read_b128 v[76:79], v178 offset:18432
	ds_read_b128 v[80:83], v178 offset:20736
	ds_read_b128 v[42:45], v178 offset:9280
	s_waitcnt lgkmcnt(6)
	v_mfma_f32_16x16x32_bf16 v[50:53], v[50:53], v[34:37], 0
	ds_read_b128 v[84:87], v178 offset:23040
	ds_read_b128 v[88:91], v178 offset:25344
	global_store_dwordx2 v[92:93], v[94:95], off offset:96
	s_waitcnt lgkmcnt(2)
	v_mfma_f32_16x16x32_bf16 v[50:53], v[42:45], v[38:41], v[50:53]
	ds_read_b128 v[42:45], v178 offset:11584
	v_mfma_f32_16x16x32_bf16 v[54:57], v[54:57], v[34:37], 0
	s_waitcnt lgkmcnt(0)
	v_mfma_f32_16x16x32_bf16 v[54:57], v[42:45], v[38:41], v[54:57]
	ds_read_b128 v[42:45], v178 offset:13888
	v_mfma_f32_16x16x32_bf16 v[58:61], v[58:61], v[34:37], 0
	s_waitcnt lgkmcnt(0)
; __device__ __forceinline__ unsigned cvt_pk_bf16(float lo, float hi) { unsigned r; asm volatile("v_cvt_pk_bf16_f32 %0, %1, %2" : "=v"(r) : "v"(lo), "v"(hi)); return r; }
; #define LAS __attribute__((address_space(3)))
; __device__ __forceinline__ void attn_unit(LAS unsigned char* lds, bf16* Q, const bf16* Kg, const bf16* Vg, const float* snk, int unit, int tid) {
;     ...
;         for (int kb = 0; kb < 9; ++kb) { const LAS unsigned char* kp = lds + (16 * (mt + kb) + fr) * ATT_KP + 16 * fq;
;             const bf16x8_t k0 = *(const LAS bf16x8_t*)kp, k1 = *(const LAS bf16x8_t*)(kp + 64);
;             f32x4 z = {0.f, 0.f, 0.f, 0.f}; z = __builtin_amdgcn_mfma_f32_16x16x32_bf16(k0, qf[mt][0], z, 0, 0, 0); z = __builtin_amdgcn_mfma_f32_16x16x32_bf16(k1, qf[mt][1], z, 0, 0, 0); st[kb] = z; }
;         float mx = sink;
; #pragma unroll
;         for (int kb = 0; kb < 9; ++kb) {
;             const bool tile_ok = (n > 0) || (mt + kb >= 8);
; #pragma unroll
;             for (int i = 0; i < 4; ++i) { const bool ok = tile_ok && (kb == 0 ? lo_ok[i] : (kb == 8 ? !lo_ok[i] : true));
;                 st[kb][i] = ok ? st[kb][i] : -INFINITY; mx = fmaxf(mx, st[kb][i]); }
;         }
;         mx = fmaxf(mx, __shfl_xor(mx, 16)); mx = fmaxf(mx, __shfl_xor(mx, 32));
;         f32x4 ls4 = {0.f, 0.f, 0.f, 0.f};
; #pragma unroll
;         for (int kb = 0; kb < 9; ++kb) { f32x4 d = st[kb] - mx;
; #pragma unroll
;             for (int i = 0; i < 4; ++i) d[i] = __builtin_amdgcn_exp2f(d[i]);
;             st[kb] = d; ls4 = ls4 + d; }
;         float ls = (ls4[0] + ls4[1]) + (ls4[2] + ls4[3]);
;         ls += __shfl_xor(ls, 16); ls += __shfl_xor(ls, 32);
;         const float inv = 1.f / (ls + __builtin_amdgcn_exp2f(sink - mx));
;         f32x4 o[4];
; #pragma unroll
;         for (int dt = 0; dt < 4; ++dt) o[dt] = (f32x4){0.f, 0.f, 0.f, 0.f};
; #pragma unroll
;         for (int kp = 0; kp < 5; ++kp) {
;             v4u pw; pw.x = cvt_pk_bf16(st[2 * kp][0], st[2 * kp][1]); pw.y = cvt_pk_bf16(st[2 * kp][2], st[2 * kp][3]);
;             if (kp < 4) { pw.z = cvt_pk_bf16(st[(2 * kp + 1) % 9][0], st[(2 * kp + 1) % 9][1]); pw.w = cvt_pk_bf16(st[(2 * kp + 1) % 9][2], st[(2 * kp + 1) % 9][3]); } else { pw.z = 0u; pw.w = 0u; }
	v_mfma_f32_16x16x32_bf16 v[58:61], v[42:45], v[38:41], v[58:61]
	ds_read_b128 v[42:45], v178 offset:16192
	v_mfma_f32_16x16x32_bf16 v[72:75], v[72:75], v[34:37], 0
	s_waitcnt lgkmcnt(0)
	v_mfma_f32_16x16x32_bf16 v[72:75], v[42:45], v[38:41], v[72:75]
	ds_read_b128 v[42:45], v178 offset:18496
	v_mfma_f32_16x16x32_bf16 v[76:79], v[76:79], v[34:37], 0
	s_waitcnt lgkmcnt(0)
	v_mfma_f32_16x16x32_bf16 v[76:79], v[42:45], v[38:41], v[76:79]
	ds_read_b128 v[42:45], v178 offset:20800
	v_mfma_f32_16x16x32_bf16 v[80:83], v[80:83], v[34:37], 0
	s_waitcnt lgkmcnt(0)
	v_mfma_f32_16x16x32_bf16 v[80:83], v[42:45], v[38:41], v[80:83]
	ds_read_b128 v[42:45], v178 offset:23104
	v_mfma_f32_16x16x32_bf16 v[84:87], v[84:87], v[34:37], 0
	s_waitcnt lgkmcnt(0)
	v_mfma_f32_16x16x32_bf16 v[42:45], v[42:45], v[38:41], v[84:87]
	s_nop 5
	ds_read_b128 v[84:87], v178 offset:25408
	v_mfma_f32_16x16x32_bf16 v[34:37], v[88:91], v[34:37], 0
	v_cndmask_b32_e64 v88, v190, v75, s[16:17]
	s_waitcnt lgkmcnt(0)
	v_mfma_f32_16x16x32_bf16 v[34:37], v[84:87], v[38:41], v[34:37]
	v_cndmask_b32_e64 v39, v47, v190, s[10:11]
	v_cndmask_b32_e64 v38, v190, v46, s[20:21]
	v_cndmask_b32_e64 v39, v190, v39, s[16:17]
	v_max3_f32 v40, v71, v38, v39
	v_cndmask_b32_e64 v41, v190, v48, s[18:19]
	v_cndmask_b32_e64 v46, v190, v49, s[22:23]
	v_max3_f32 v40, v40, v41, v46
	v_cndmask_b32_e64 v47, v190, v50, s[16:17]
	v_cndmask_b32_e64 v48, v190, v51, s[16:17]
	v_max3_f32 v40, v40, v47, v48
	v_cndmask_b32_e64 v49, v190, v52, s[16:17]
	v_cndmask_b32_e64 v50, v190, v53, s[16:17]
	v_max3_f32 v40, v40, v49, v50
	v_cndmask_b32_e64 v51, v190, v54, s[16:17]
	v_cndmask_b32_e64 v52, v190, v55, s[16:17]
	v_max3_f32 v40, v40, v51, v52
	v_cndmask_b32_e64 v53, v190, v56, s[16:17]
	v_cndmask_b32_e64 v54, v190, v57, s[16:17]
	v_max3_f32 v40, v40, v53, v54
	v_cndmask_b32_e64 v55, v190, v58, s[16:17]
	v_cndmask_b32_e64 v56, v190, v59, s[16:17]
	v_max3_f32 v40, v40, v55, v56
	v_cndmask_b32_e64 v57, v190, v60, s[16:17]
	v_cndmask_b32_e64 v84, v190, v61, s[16:17]
	v_max3_f32 v40, v40, v57, v84
	v_cndmask_b32_e64 v85, v190, v72, s[16:17]
	v_cndmask_b32_e64 v86, v190, v73, s[16:17]
	v_max3_f32 v40, v40, v85, v86
	v_cndmask_b32_e64 v87, v190, v74, s[16:17]
	v_max3_f32 v40, v40, v87, v88
	v_max3_f32 v40, v40, v76, v77
	v_max3_f32 v40, v40, v78, v79
	v_max3_f32 v40, v40, v80, v81
	v_max3_f32 v40, v40, v82, v83
	v_max3_f32 v40, v40, v42, v43
	v_max3_f32 v40, v40, v44, v45
	v_cndmask_b32_e64 v100, v34, v190, s[8:9]
	v_cndmask_b32_e64 v101, v190, v35, s[10:11]
	v_max3_f32 v34, v40, v100, v101
	v_cndmask_b32_e64 v102, v36, v190, s[12:13]
	v_cndmask_b32_e64 v103, v37, v190, s[14:15]
	v_max3_f32 v34, v34, v102, v103
	ds_bpermute_b32 v35, v65, v34
	s_waitcnt lgkmcnt(0)
	v_max_f32_e32 v35, v35, v35
	v_max_f32_e32 v34, v34, v35
	ds_bpermute_b32 v35, v66, v34
	s_waitcnt lgkmcnt(0)
	v_max_f32_e32 v35, v35, v35
	v_max_f32_e32 v104, v34, v35
	v_sub_f32_e32 v35, v46, v104
	v_sub_f32_e32 v36, v41, v104
	v_sub_f32_e32 v39, v39, v104
	v_sub_f32_e32 v34, v38, v104
	v_exp_f32_e32 v34, v34
	v_exp_f32_e32 v36, v36
	v_exp_f32_e32 v37, v35
	v_exp_f32_e32 v35, v39
	v_sub_f32_e32 v50, v50, v104
	v_sub_f32_e32 v49, v49, v104
	v_sub_f32_e32 v48, v48, v104
	v_sub_f32_e32 v46, v47, v104
	v_exp_f32_e32 v46, v46
	v_exp_f32_e32 v47, v48
	v_exp_f32_e32 v48, v49
	v_exp_f32_e32 v49, v50
	v_sub_f32_e32 v50, v54, v104
	v_sub_f32_e32 v53, v53, v104
	v_sub_f32_e32 v52, v52, v104
	v_sub_f32_e32 v51, v51, v104
	v_exp_f32_e32 v58, v51
	v_exp_f32_e32 v60, v53
	v_exp_f32_e32 v61, v50
	v_exp_f32_e32 v59, v52
	v_sub_f32_e32 v50, v84, v104
	v_sub_f32_e32 v51, v57, v104
	v_sub_f32_e32 v52, v56, v104
	v_sub_f32_e32 v53, v55, v104
	v_exp_f32_e32 v72, v53
	v_exp_f32_e32 v73, v52
	v_exp_f32_e32 v74, v51
	v_exp_f32_e32 v75, v50
	v_sub_f32_e32 v50, v88, v104
	v_sub_f32_e32 v51, v87, v104
	v_sub_f32_e32 v52, v86, v104
	v_sub_f32_e32 v53, v85, v104
	v_pk_add_f32 v[38:39], v[36:37], 0 op_sel_hi:[1,0]
	v_pk_add_f32 v[40:41], v[34:35], 0 op_sel_hi:[1,0]
	v_exp_f32_e32 v84, v53
	v_exp_f32_e32 v86, v51
	v_exp_f32_e32 v87, v50
	v_exp_f32_e32 v85, v52
	v_pk_add_f32 v[40:41], v[46:47], v[40:41]
	v_pk_add_f32 v[38:39], v[48:49], v[38:39]
	v_pk_add_f32 v[40:41], v[58:59], v[40:41]
	v_pk_add_f32 v[38:39], v[60:61], v[38:39]
	v_pk_add_f32 v[40:41], v[72:73], v[40:41]
	v_pk_add_f32 v[38:39], v[74:75], v[38:39]
	v_sub_f32_e32 v52, v76, v104
	v_pk_add_f32 v[50:51], v[86:87], v[38:39]
	v_pk_add_f32 v[38:39], v[84:85], v[40:41]
	v_sub_f32_e32 v41, v77, v104
	v_sub_f32_e32 v40, v79, v104
	v_exp_f32_e32 v89, v41
	v_sub_f32_e32 v41, v78, v104
	v_exp_f32_e32 v88, v52
	v_exp_f32_e32 v90, v41
	v_exp_f32_e32 v91, v40
	v_sub_f32_e32 v54, v83, v104
	v_sub_f32_e32 v55, v82, v104
	v_sub_f32_e32 v56, v81, v104
	v_sub_f32_e32 v57, v80, v104
	v_exp_f32_e32 v80, v55
	v_exp_f32_e32 v81, v54
	v_exp_f32_e32 v82, v57
	v_exp_f32_e32 v83, v56
	v_pk_add_f32 v[52:53], v[88:89], v[38:39]
	v_pk_add_f32 v[50:51], v[90:91], v[50:51]
	v_cvt_pk_bf16_f32 v34, v34, v35
	v_cvt_pk_bf16_f32 v35, v36, v37
	v_cvt_pk_bf16_f32 v36, v46, v47
	v_cvt_pk_bf16_f32 v37, v48, v49
	ds_read2_b64 v[38:41], v67 offset0:12 offset1:16
	ds_read2_b64 v[46:49], v68 offset0:44 offset1:48
	v_pk_add_f32 v[92:93], v[80:81], v[50:51]
	v_pk_add_f32 v[94:95], v[82:83], v[52:53]
	ds_read2_b64 v[50:53], v70 offset0:76 offset1:80
	ds_read2_b64 v[54:57], v69 offset0:108 offset1:112
	v_sub_f32_e32 v44, v44, v104
	v_sub_f32_e32 v43, v43, v104
	v_sub_f32_e32 v42, v42, v104
	v_sub_f32_e32 v99, v45, v104
	v_cvt_pk_bf16_f32 v58, v58, v59
	v_cvt_pk_bf16_f32 v59, v60, v61
	v_cvt_pk_bf16_f32 v60, v72, v73
	v_cvt_pk_bf16_f32 v61, v74, v75
	ds_read2_b64 v[72:75], v67 offset0:20 offset1:24
	v_exp_f32_e32 v96, v42
	v_exp_f32_e32 v97, v43
	v_exp_f32_e32 v98, v44
	ds_read2_b64 v[42:45], v70 offset0:84 offset1:88
	s_waitcnt lgkmcnt(5)
; __device__ __forceinline__ unsigned cvt_pk_bf16(float lo, float hi) { unsigned r; asm volatile("v_cvt_pk_bf16_f32 %0, %1, %2" : "=v"(r) : "v"(lo), "v"(hi)); return r; }
; #define LAS __attribute__((address_space(3)))
; __device__ __forceinline__ void attn_unit(LAS unsigned char* lds, bf16* Q, const bf16* Kg, const bf16* Vg, const float* snk, int unit, int tid) {
;     ...
; #pragma unroll
;         for (int kp = 0; kp < 5; ++kp) {
;             v4u pw; pw.x = cvt_pk_bf16(st[2 * kp][0], st[2 * kp][1]); pw.y = cvt_pk_bf16(st[2 * kp][2], st[2 * kp][3]);
;             if (kp < 4) { pw.z = cvt_pk_bf16(st[(2 * kp + 1) % 9][0], st[(2 * kp + 1) % 9][1]); pw.w = cvt_pk_bf16(st[(2 * kp + 1) % 9][2], st[(2 * kp + 1) % 9][3]); } else { pw.z = 0u; pw.w = 0u; }
;             const bf16x8_t pb = __builtin_bit_cast(bf16x8_t, pw);
; #pragma unroll
;             for (int dt = 0; dt < 4; ++dt) { const LAS unsigned char* vp = lds + ATT_VOFF + (16 * dt + fr) * ATT_VP + (16 * (mt + 2 * kp) + 4 * fq) * 2;
;                 const v2u lo = *(const LAS v2u*)vp; v2u hi = {0u, 0u}; if (kp < 4) hi = *(const LAS v2u*)(vp + 32);
;                 v4u aw; aw.x = lo.x; aw.y = lo.y; aw.z = hi.x; aw.w = hi.y;
;                 o[dt] = __builtin_amdgcn_mfma_f32_16x16x32_bf16(__builtin_bit_cast(bf16x8_t, aw), pb, o[dt], 0, 0, 0); }
;         }
; #pragma unroll
;         for (int dt = 0; dt < 4; ++dt) { const f32x4 y = o[dt] * inv; v2u w; w.x = cvt_pk_bf16(y[0], y[1]); w.y = cvt_pk_bf16(y[2], y[3]); *(v2u*)(qbase + (size_t)mt * 16 * 1024 + 16 * dt + 4 * fq) = w; }
	v_mfma_f32_16x16x32_bf16 v[38:41], v[38:41], v[34:37], 0
	ds_read2_b64 v[76:79], v68 offset0:52 offset1:56
	v_exp_f32_e32 v99, v99
	s_waitcnt lgkmcnt(5)
	v_mfma_f32_16x16x32_bf16 v[46:49], v[46:49], v[34:37], 0
	s_waitcnt lgkmcnt(4)
	v_mfma_f32_16x16x32_bf16 v[50:53], v[50:53], v[34:37], 0
	s_waitcnt lgkmcnt(3)
	v_mfma_f32_16x16x32_bf16 v[34:37], v[54:57], v[34:37], 0
	ds_read2_b64 v[54:57], v69 offset0:116 offset1:120
	s_waitcnt lgkmcnt(3)
	v_mfma_f32_16x16x32_bf16 v[38:41], v[72:75], v[58:61], v[38:41]
	v_cvt_pk_bf16_f32 v72, v84, v85
	v_cvt_pk_bf16_f32 v73, v86, v87
	v_cvt_pk_bf16_f32 v74, v88, v89
	v_cvt_pk_bf16_f32 v75, v90, v91
	s_waitcnt lgkmcnt(2)
	v_mfma_f32_16x16x32_bf16 v[42:45], v[42:45], v[58:61], v[50:53]
	v_sub_f32_e32 v89, v103, v104
	v_sub_f32_e32 v90, v102, v104
	v_sub_f32_e32 v91, v101, v104
	ds_read2_b64 v[50:53], v68 offset0:60 offset1:64
	s_waitcnt lgkmcnt(2)
	v_mfma_f32_16x16x32_bf16 v[46:49], v[76:79], v[58:61], v[46:49]
	ds_read2_b64 v[76:79], v67 offset0:28 offset1:32
	v_pk_add_f32 v[84:85], v[96:97], v[94:95]
	v_pk_add_f32 v[86:87], v[98:99], v[92:93]
	s_waitcnt lgkmcnt(2)
	v_mfma_f32_16x16x32_bf16 v[34:37], v[54:57], v[58:61], v[34:37]
	ds_read2_b64 v[54:57], v70 offset0:92 offset1:96
	v_sub_f32_e32 v58, v100, v104
	v_exp_f32_e32 v88, v58
	s_waitcnt lgkmcnt(2)
	v_mfma_f32_16x16x32_bf16 v[46:49], v[50:53], v[72:75], v[46:49]
	ds_read2_b64 v[50:53], v69 offset0:124 offset1:128
	v_cvt_pk_bf16_f32 v58, v82, v83
	v_cvt_pk_bf16_f32 v59, v80, v81
	v_cvt_pk_bf16_f32 v60, v96, v97
	v_cvt_pk_bf16_f32 v61, v98, v99
	s_waitcnt lgkmcnt(1)
	v_mfma_f32_16x16x32_bf16 v[42:45], v[54:57], v[72:75], v[42:45]
	ds_read2_b64 v[54:57], v68 offset0:68 offset1:72
	v_exp_f32_e32 v80, v90
	v_exp_f32_e32 v81, v89
	v_mfma_f32_16x16x32_bf16 v[38:41], v[76:79], v[72:75], v[38:41]
	ds_read2_b64 v[76:79], v67 offset0:36 offset1:40
	v_exp_f32_e32 v89, v91
	s_waitcnt lgkmcnt(2)
	v_mfma_f32_16x16x32_bf16 v[34:37], v[50:53], v[72:75], v[34:37]
	ds_read2_b64 v[50:53], v70 offset0:100 offset1:104
	v_pk_add_f32 v[72:73], v[80:81], v[86:87]
	v_pk_add_f32 v[74:75], v[88:89], v[84:85]
	s_waitcnt lgkmcnt(2)
	v_mfma_f32_16x16x32_bf16 v[46:49], v[54:57], v[58:61], v[46:49]
	ds_read2_b64 v[54:57], v69 offset0:132 offset1:136
	s_waitcnt lgkmcnt(2)
	v_mfma_f32_16x16x32_bf16 v[38:41], v[76:79], v[58:61], v[38:41]
	v_pk_mov_b32 v[76:77], v[74:75], v[72:73] op_sel:[1,0]
	v_mov_b32_e32 v75, v73
	v_pk_add_f32 v[72:73], v[76:77], v[74:75]
	s_waitcnt lgkmcnt(1)
	v_mfma_f32_16x16x32_bf16 v[42:45], v[50:53], v[58:61], v[42:45]
	v_add_f32_e32 v72, v72, v73
	ds_bpermute_b32 v50, v65, v72
	v_mov_b32_e32 v52, v147
	s_waitcnt lgkmcnt(1)
	v_mfma_f32_16x16x32_bf16 v[34:37], v[54:57], v[58:61], v[34:37]
	v_mov_b32_e32 v56, v147
	v_mov_b32_e32 v57, v147
	s_waitcnt lgkmcnt(0)
	v_add_f32_e32 v78, v72, v50
	v_cvt_pk_bf16_f32 v50, v88, v89
	v_cvt_pk_bf16_f32 v51, v80, v81
	ds_read_b64 v[54:55], v179 offset:37216
	ds_read_b64 v[58:59], v179 offset:45664
	v_mov_b32_e32 v53, v147
	v_mov_b32_e32 v60, v147
	v_mov_b32_e32 v61, v147
	s_waitcnt lgkmcnt(1)
	v_mfma_f32_16x16x32_bf16 v[38:41], v[54:57], v[50:53], v[38:41]
	ds_bpermute_b32 v54, v66, v78
	v_fma_f32 v55, v64, s61, -v104
	v_exp_f32_e32 v55, v55
	ds_read_b64 v[72:73], v179 offset:54112
	ds_read_b64 v[76:77], v179 offset:62560
	v_mov_b32_e32 v74, v147
	s_waitcnt lgkmcnt(2)
	v_add_f32_e32 v54, v78, v54
	v_add_f32_e32 v54, v55, v54
	v_mov_b32_e32 v75, v147
	v_mov_b32_e32 v78, v147
	v_mov_b32_e32 v79, v147
	v_div_scale_f32 v55, s[68:69], v54, v54, 1.0
	v_rcp_f32_e32 v56, v55
	v_mfma_f32_16x16x32_bf16 v[46:49], v[58:61], v[50:53], v[46:49]
	s_waitcnt lgkmcnt(1)
	v_mfma_f32_16x16x32_bf16 v[42:45], v[72:75], v[50:53], v[42:45]
	s_waitcnt lgkmcnt(0)
	v_mfma_f32_16x16x32_bf16 v[34:37], v[76:79], v[50:53], v[34:37]
	v_fma_f32 v50, -v55, v56, 1.0
	v_fmac_f32_e32 v56, v50, v56
	v_div_scale_f32 v50, vcc, 1.0, v54, 1.0
	v_mul_f32_e32 v51, v50, v56
	v_fma_f32 v52, -v55, v51, v50
	v_fmac_f32_e32 v51, v52, v56
	v_fma_f32 v50, -v55, v51, v50
	v_div_fmas_f32 v50, v50, v56, v51
	v_div_fixup_f32 v50, v50, v54, 1.0
	v_pk_mul_f32 v[40:41], v[50:51], v[40:41] op_sel_hi:[0,1]
	v_pk_mul_f32 v[38:39], v[50:51], v[38:39] op_sel_hi:[0,1]
	v_add_co_u32_e32 v84, vcc, s54, v62
	v_cvt_pk_bf16_f32 v38, v38, v39
	v_cvt_pk_bf16_f32 v39, v40, v41
	v_pk_mul_f32 v[40:41], v[50:51], v[46:47] op_sel_hi:[0,1]
	s_nop 0
	v_addc_co_u32_e32 v85, vcc, 0, v63, vcc
	global_store_dwordx2 v[84:85], v[38:39], off
	v_pk_mul_f32 v[38:39], v[50:51], v[48:49] op_sel_hi:[0,1]
	v_cvt_pk_bf16_f32 v40, v40, v41
	v_cvt_pk_bf16_f32 v41, v38, v39
	global_store_dwordx2 v[84:85], v[40:41], off offset:32
	v_pk_mul_f32 v[40:41], v[50:51], v[42:43] op_sel_hi:[0,1]
	v_pk_mul_f32 v[38:39], v[50:51], v[44:45] op_sel_hi:[0,1]
	v_cvt_pk_bf16_f32 v40, v40, v41
	v_cvt_pk_bf16_f32 v41, v38, v39
	v_pk_mul_f32 v[36:37], v[50:51], v[36:37] op_sel_hi:[0,1]
	v_pk_mul_f32 v[34:35], v[50:51], v[34:35] op_sel_hi:[0,1]
	global_store_dwordx2 v[84:85], v[40:41], off offset:64
	v_cvt_pk_bf16_f32 v86, v34, v35
	v_cvt_pk_bf16_f32 v87, v36, v37
	ds_read_b128 v[34:37], v178 offset:9216
	ds_read_b128 v[38:41], v178 offset:9280
	s_waitcnt lgkmcnt(1)
	v_mfma_f32_16x16x32_bf16 v[34:37], v[34:37], v[26:29], 0
	ds_read_b128 v[42:45], v178 offset:11520
	ds_read_b128 v[46:49], v178 offset:13824
	ds_read_b128 v[50:53], v178 offset:16128
	s_waitcnt lgkmcnt(3)
	v_mfma_f32_16x16x32_bf16 v[38:41], v[38:41], v[30:33], v[34:37]
	ds_read_b128 v[54:57], v178 offset:18432
	ds_read_b128 v[58:61], v178 offset:20736
	ds_read_b128 v[72:75], v178 offset:23040
	ds_read_b128 v[34:37], v178 offset:11584
	s_waitcnt lgkmcnt(6)
; #define LAS __attribute__((address_space(3)))
; __device__ __forceinline__ void attn_unit(LAS unsigned char* lds, bf16* Q, const bf16* Kg, const bf16* Vg, const float* snk, int unit, int tid) {
;     ...
;         for (int kb = 0; kb < 9; ++kb) { const LAS unsigned char* kp = lds + (16 * (mt + kb) + fr) * ATT_KP + 16 * fq;
;             const bf16x8_t k0 = *(const LAS bf16x8_t*)kp, k1 = *(const LAS bf16x8_t*)(kp + 64);
;             f32x4 z = {0.f, 0.f, 0.f, 0.f}; z = __builtin_amdgcn_mfma_f32_16x16x32_bf16(k0, qf[mt][0], z, 0, 0, 0); z = __builtin_amdgcn_mfma_f32_16x16x32_bf16(k1, qf[mt][1], z, 0, 0, 0); st[kb] = z; }
;         float mx = sink;
; #pragma unroll
;         for (int kb = 0; kb < 9; ++kb) {
;             const bool tile_ok = (n > 0) || (mt + kb >= 8);
; #pragma unroll
;             for (int i = 0; i < 4; ++i) { const bool ok = tile_ok && (kb == 0 ? lo_ok[i] : (kb == 8 ? !lo_ok[i] : true));
;                 st[kb][i] = ok ? st[kb][i] : -INFINITY; mx = fmaxf(mx, st[kb][i]); }
;         }
;         mx = fmaxf(mx, __shfl_xor(mx, 16)); mx = fmaxf(mx, __shfl_xor(mx, 32));
;         f32x4 ls4 = {0.f, 0.f, 0.f, 0.f};
; #pragma unroll
;         for (int kb = 0; kb < 9; ++kb) { f32x4 d = st[kb] - mx;
; #pragma unroll
;             for (int i = 0; i < 4; ++i) d[i] = __builtin_amdgcn_exp2f(d[i]);
;             st[kb] = d; ls4 = ls4 + d; }
;         float ls = (ls4[0] + ls4[1]) + (ls4[2] + ls4[3]);
;         ls += __shfl_xor(ls, 16); ls += __shfl_xor(ls, 32);
;         const float inv = 1.f / (ls + __builtin_amdgcn_exp2f(sink - mx));
	v_mfma_f32_16x16x32_bf16 v[42:45], v[42:45], v[26:29], 0
	ds_read_b128 v[76:79], v178 offset:25344
	ds_read_b128 v[80:83], v178 offset:27648
	global_store_dwordx2 v[84:85], v[86:87], off offset:96
	s_waitcnt lgkmcnt(2)
	v_mfma_f32_16x16x32_bf16 v[42:45], v[34:37], v[30:33], v[42:45]
	ds_read_b128 v[34:37], v178 offset:13888
	v_mfma_f32_16x16x32_bf16 v[46:49], v[46:49], v[26:29], 0
	s_waitcnt lgkmcnt(0)
	v_mfma_f32_16x16x32_bf16 v[46:49], v[34:37], v[30:33], v[46:49]
	ds_read_b128 v[34:37], v178 offset:16192
	v_mfma_f32_16x16x32_bf16 v[50:53], v[50:53], v[26:29], 0
	s_waitcnt lgkmcnt(0)
	v_mfma_f32_16x16x32_bf16 v[50:53], v[34:37], v[30:33], v[50:53]
	ds_read_b128 v[34:37], v178 offset:18496
	v_mfma_f32_16x16x32_bf16 v[54:57], v[54:57], v[26:29], 0
	s_waitcnt lgkmcnt(0)
	v_mfma_f32_16x16x32_bf16 v[54:57], v[34:37], v[30:33], v[54:57]
	ds_read_b128 v[34:37], v178 offset:20800
	v_mfma_f32_16x16x32_bf16 v[58:61], v[58:61], v[26:29], 0
	s_waitcnt lgkmcnt(0)
	v_mfma_f32_16x16x32_bf16 v[58:61], v[34:37], v[30:33], v[58:61]
	ds_read_b128 v[34:37], v178 offset:23104
	v_mfma_f32_16x16x32_bf16 v[72:75], v[72:75], v[26:29], 0
	s_waitcnt lgkmcnt(0)
	v_mfma_f32_16x16x32_bf16 v[72:75], v[34:37], v[30:33], v[72:75]
	ds_read_b128 v[34:37], v178 offset:25408
	v_mfma_f32_16x16x32_bf16 v[76:79], v[76:79], v[26:29], 0
	s_waitcnt lgkmcnt(0)
	v_mfma_f32_16x16x32_bf16 v[34:37], v[34:37], v[30:33], v[76:79]
	s_nop 5
	ds_read_b128 v[76:79], v178 offset:27712
	v_mfma_f32_16x16x32_bf16 v[26:29], v[80:83], v[26:29], 0
	s_waitcnt lgkmcnt(0)
	v_mfma_f32_16x16x32_bf16 v[26:29], v[76:79], v[30:33], v[26:29]
	v_cndmask_b32_e64 v31, v39, v190, s[10:11]
	v_cndmask_b32_e64 v30, v190, v38, s[20:21]
	v_cndmask_b32_e64 v31, v190, v31, s[16:17]
	v_max3_f32 v32, v71, v30, v31
	v_cndmask_b32_e64 v33, v190, v40, s[18:19]
	v_cndmask_b32_e64 v38, v190, v41, s[22:23]
	v_max3_f32 v32, v32, v33, v38
	v_cndmask_b32_e64 v39, v190, v42, s[16:17]
	v_cndmask_b32_e64 v40, v190, v43, s[16:17]
	v_max3_f32 v32, v32, v39, v40
	v_cndmask_b32_e64 v41, v190, v44, s[16:17]
	v_cndmask_b32_e64 v42, v190, v45, s[16:17]
	v_max3_f32 v32, v32, v41, v42
	v_cndmask_b32_e64 v43, v190, v46, s[16:17]
	v_cndmask_b32_e64 v44, v190, v47, s[16:17]
	v_max3_f32 v32, v32, v43, v44
	v_cndmask_b32_e64 v45, v190, v48, s[16:17]
	v_cndmask_b32_e64 v46, v190, v49, s[16:17]
	v_max3_f32 v32, v32, v45, v46
	v_cndmask_b32_e64 v47, v190, v50, s[16:17]
	v_cndmask_b32_e64 v48, v190, v51, s[16:17]
	v_max3_f32 v32, v32, v47, v48
	v_cndmask_b32_e64 v49, v190, v52, s[16:17]
	v_cndmask_b32_e64 v76, v190, v53, s[16:17]
	v_max3_f32 v32, v32, v49, v76
	v_max3_f32 v32, v32, v54, v55
	v_max3_f32 v32, v32, v56, v57
	v_max3_f32 v32, v32, v58, v59
	v_max3_f32 v32, v32, v60, v61
	v_max3_f32 v32, v32, v72, v73
	v_max3_f32 v32, v32, v74, v75
	v_max3_f32 v32, v32, v34, v35
	v_max3_f32 v32, v32, v36, v37
	v_cndmask_b32_e64 v92, v26, v190, s[8:9]
	v_cndmask_b32_e64 v93, v190, v27, s[10:11]
	v_max3_f32 v26, v32, v92, v93
	v_cndmask_b32_e64 v94, v28, v190, s[12:13]
	v_cndmask_b32_e64 v95, v29, v190, s[14:15]
	v_max3_f32 v26, v26, v94, v95
	ds_bpermute_b32 v27, v65, v26
	s_waitcnt lgkmcnt(0)
	v_max_f32_e32 v27, v27, v27
	v_max_f32_e32 v26, v26, v27
	ds_bpermute_b32 v27, v66, v26
	s_waitcnt lgkmcnt(0)
	v_max_f32_e32 v27, v27, v27
	v_max_f32_e32 v96, v26, v27
	v_sub_f32_e32 v27, v38, v96
	v_sub_f32_e32 v28, v33, v96
	v_sub_f32_e32 v31, v31, v96
	v_sub_f32_e32 v26, v30, v96
	v_exp_f32_e32 v26, v26
	v_exp_f32_e32 v28, v28
	v_exp_f32_e32 v29, v27
	v_exp_f32_e32 v27, v31
	v_sub_f32_e32 v42, v42, v96
	v_sub_f32_e32 v41, v41, v96
	v_sub_f32_e32 v40, v40, v96
	v_sub_f32_e32 v38, v39, v96
	v_exp_f32_e32 v38, v38
	v_exp_f32_e32 v39, v40
	v_exp_f32_e32 v40, v41
	v_exp_f32_e32 v41, v42
	v_sub_f32_e32 v42, v46, v96
	v_sub_f32_e32 v45, v45, v96
	v_sub_f32_e32 v44, v44, v96
	v_sub_f32_e32 v43, v43, v96
	v_exp_f32_e32 v50, v43
	v_exp_f32_e32 v52, v45
	v_exp_f32_e32 v53, v42
	v_exp_f32_e32 v51, v44
	v_sub_f32_e32 v42, v76, v96
	v_sub_f32_e32 v43, v49, v96
	v_sub_f32_e32 v44, v48, v96
	v_sub_f32_e32 v45, v47, v96
	v_exp_f32_e32 v76, v45
	v_exp_f32_e32 v77, v44
	v_exp_f32_e32 v78, v43
	v_exp_f32_e32 v79, v42
	v_sub_f32_e32 v42, v57, v96
	v_sub_f32_e32 v43, v56, v96
	v_sub_f32_e32 v44, v55, v96
	v_sub_f32_e32 v45, v54, v96
	v_pk_add_f32 v[30:31], v[28:29], 0 op_sel_hi:[1,0]
	v_pk_add_f32 v[32:33], v[26:27], 0 op_sel_hi:[1,0]
	v_exp_f32_e32 v80, v45
	v_exp_f32_e32 v82, v43
	v_exp_f32_e32 v83, v42
	v_exp_f32_e32 v81, v44
	v_pk_add_f32 v[32:33], v[38:39], v[32:33]
	v_pk_add_f32 v[30:31], v[40:41], v[30:31]
	v_pk_add_f32 v[32:33], v[50:51], v[32:33]
	v_pk_add_f32 v[30:31], v[52:53], v[30:31]
	v_pk_add_f32 v[32:33], v[76:77], v[32:33]
	v_pk_add_f32 v[30:31], v[78:79], v[30:31]
	v_sub_f32_e32 v44, v58, v96
	v_pk_add_f32 v[42:43], v[82:83], v[30:31]
	v_pk_add_f32 v[30:31], v[80:81], v[32:33]
	v_sub_f32_e32 v33, v59, v96
	v_sub_f32_e32 v32, v61, v96
	v_exp_f32_e32 v85, v33
	v_sub_f32_e32 v33, v60, v96
	v_exp_f32_e32 v84, v44
	v_exp_f32_e32 v86, v33
	v_exp_f32_e32 v87, v32
	v_sub_f32_e32 v46, v75, v96
	v_sub_f32_e32 v47, v74, v96
	v_sub_f32_e32 v48, v73, v96
	v_sub_f32_e32 v49, v72, v96
	v_exp_f32_e32 v72, v47
	v_exp_f32_e32 v73, v46
	v_exp_f32_e32 v74, v49
	v_exp_f32_e32 v75, v48
	v_pk_add_f32 v[44:45], v[84:85], v[30:31]
	v_pk_add_f32 v[42:43], v[86:87], v[42:43]
	v_cvt_pk_bf16_f32 v26, v26, v27
	v_cvt_pk_bf16_f32 v27, v28, v29
	v_cvt_pk_bf16_f32 v28, v38, v39
	v_cvt_pk_bf16_f32 v29, v40, v41
	ds_read2_b64 v[30:33], v67 offset0:16 offset1:20
	ds_read2_b64 v[38:41], v68 offset0:48 offset1:52
	v_pk_add_f32 v[88:89], v[72:73], v[42:43]
	v_pk_add_f32 v[90:91], v[74:75], v[44:45]
	ds_read2_b64 v[42:45], v70 offset0:80 offset1:84
	ds_read2_b64 v[46:49], v69 offset0:112 offset1:116
	v_sub_f32_e32 v36, v36, v96
	v_sub_f32_e32 v35, v35, v96
	v_sub_f32_e32 v34, v34, v96
	v_sub_f32_e32 v97, v37, v96
	v_cvt_pk_bf16_f32 v50, v50, v51
	v_cvt_pk_bf16_f32 v51, v52, v53
	v_cvt_pk_bf16_f32 v52, v76, v77
	v_cvt_pk_bf16_f32 v53, v78, v79
	ds_read2_b64 v[54:57], v67 offset0:24 offset1:28
	v_exp_f32_e32 v76, v34
	v_exp_f32_e32 v77, v35
	v_exp_f32_e32 v78, v36
	ds_read2_b64 v[34:37], v70 offset0:88 offset1:92
	s_waitcnt lgkmcnt(5)
; __device__ __forceinline__ unsigned cvt_pk_bf16(float lo, float hi) { unsigned r; asm volatile("v_cvt_pk_bf16_f32 %0, %1, %2" : "=v"(r) : "v"(lo), "v"(hi)); return r; }
; #define LAS __attribute__((address_space(3)))
; __device__ __forceinline__ void attn_unit(LAS unsigned char* lds, bf16* Q, const bf16* Kg, const bf16* Vg, const float* snk, int unit, int tid) {
;     ...
; #pragma unroll
;         for (int kp = 0; kp < 5; ++kp) {
;             v4u pw; pw.x = cvt_pk_bf16(st[2 * kp][0], st[2 * kp][1]); pw.y = cvt_pk_bf16(st[2 * kp][2], st[2 * kp][3]);
;             if (kp < 4) { pw.z = cvt_pk_bf16(st[(2 * kp + 1) % 9][0], st[(2 * kp + 1) % 9][1]); pw.w = cvt_pk_bf16(st[(2 * kp + 1) % 9][2], st[(2 * kp + 1) % 9][3]); } else { pw.z = 0u; pw.w = 0u; }
;             const bf16x8_t pb = __builtin_bit_cast(bf16x8_t, pw);
; #pragma unroll
;             for (int dt = 0; dt < 4; ++dt) { const LAS unsigned char* vp = lds + ATT_VOFF + (16 * dt + fr) * ATT_VP + (16 * (mt + 2 * kp) + 4 * fq) * 2;
;                 const v2u lo = *(const LAS v2u*)vp; v2u hi = {0u, 0u}; if (kp < 4) hi = *(const LAS v2u*)(vp + 32);
;                 v4u aw; aw.x = lo.x; aw.y = lo.y; aw.z = hi.x; aw.w = hi.y;
;                 o[dt] = __builtin_amdgcn_mfma_f32_16x16x32_bf16(__builtin_bit_cast(bf16x8_t, aw), pb, o[dt], 0, 0, 0); }
;         }
; #pragma unroll
;         for (int dt = 0; dt < 4; ++dt) { const f32x4 y = o[dt] * inv; v2u w; w.x = cvt_pk_bf16(y[0], y[1]); w.y = cvt_pk_bf16(y[2], y[3]); *(v2u*)(qbase + (size_t)mt * 16 * 1024 + 16 * dt + 4 * fq) = w; }
	v_mfma_f32_16x16x32_bf16 v[30:33], v[30:33], v[26:29], 0
	ds_read2_b64 v[58:61], v68 offset0:56 offset1:60
	v_exp_f32_e32 v79, v97
	s_waitcnt lgkmcnt(5)
	v_mfma_f32_16x16x32_bf16 v[38:41], v[38:41], v[26:29], 0
	s_waitcnt lgkmcnt(4)
	v_mfma_f32_16x16x32_bf16 v[42:45], v[42:45], v[26:29], 0
	s_waitcnt lgkmcnt(3)
	v_mfma_f32_16x16x32_bf16 v[26:29], v[46:49], v[26:29], 0
	ds_read2_b64 v[46:49], v69 offset0:120 offset1:124
	s_waitcnt lgkmcnt(3)
	v_mfma_f32_16x16x32_bf16 v[30:33], v[54:57], v[50:53], v[30:33]
	v_cvt_pk_bf16_f32 v54, v80, v81
	v_cvt_pk_bf16_f32 v55, v82, v83
	v_cvt_pk_bf16_f32 v56, v84, v85
	v_cvt_pk_bf16_f32 v57, v86, v87
	s_waitcnt lgkmcnt(2)
	v_mfma_f32_16x16x32_bf16 v[34:37], v[34:37], v[50:53], v[42:45]
	v_sub_f32_e32 v85, v95, v96
	v_sub_f32_e32 v86, v94, v96
	v_sub_f32_e32 v87, v93, v96
	ds_read2_b64 v[42:45], v68 offset0:64 offset1:68
	s_waitcnt lgkmcnt(2)
	v_mfma_f32_16x16x32_bf16 v[38:41], v[58:61], v[50:53], v[38:41]
	ds_read2_b64 v[58:61], v67 offset0:32 offset1:36
	v_pk_add_f32 v[80:81], v[76:77], v[90:91]
	v_pk_add_f32 v[82:83], v[78:79], v[88:89]
	s_waitcnt lgkmcnt(2)
	v_mfma_f32_16x16x32_bf16 v[26:29], v[46:49], v[50:53], v[26:29]
	ds_read2_b64 v[46:49], v70 offset0:96 offset1:100
	v_sub_f32_e32 v50, v92, v96
	v_exp_f32_e32 v84, v50
	s_waitcnt lgkmcnt(2)
	v_mfma_f32_16x16x32_bf16 v[38:41], v[42:45], v[54:57], v[38:41]
	ds_read2_b64 v[42:45], v69 offset0:128 offset1:132
	v_cvt_pk_bf16_f32 v50, v74, v75
	v_cvt_pk_bf16_f32 v51, v72, v73
	v_cvt_pk_bf16_f32 v52, v76, v77
	v_cvt_pk_bf16_f32 v53, v78, v79
	s_waitcnt lgkmcnt(1)
	v_mfma_f32_16x16x32_bf16 v[34:37], v[46:49], v[54:57], v[34:37]
	ds_read2_b64 v[46:49], v68 offset0:72 offset1:76
	v_exp_f32_e32 v72, v86
	v_exp_f32_e32 v73, v85
	v_mfma_f32_16x16x32_bf16 v[30:33], v[58:61], v[54:57], v[30:33]
	ds_read2_b64 v[58:61], v67 offset0:40 offset1:44
	v_exp_f32_e32 v85, v87
	s_waitcnt lgkmcnt(2)
	v_mfma_f32_16x16x32_bf16 v[26:29], v[42:45], v[54:57], v[26:29]
	ds_read2_b64 v[42:45], v70 offset0:104 offset1:108
	v_pk_add_f32 v[54:55], v[72:73], v[82:83]
	v_pk_add_f32 v[56:57], v[84:85], v[80:81]
	s_waitcnt lgkmcnt(2)
	v_mfma_f32_16x16x32_bf16 v[38:41], v[46:49], v[50:53], v[38:41]
	ds_read2_b64 v[46:49], v69 offset0:136 offset1:140
	s_waitcnt lgkmcnt(2)
	v_mfma_f32_16x16x32_bf16 v[30:33], v[58:61], v[50:53], v[30:33]
	v_pk_mov_b32 v[58:59], v[56:57], v[54:55] op_sel:[1,0]
	v_mov_b32_e32 v57, v55
	v_pk_add_f32 v[54:55], v[58:59], v[56:57]
	s_waitcnt lgkmcnt(1)
	v_mfma_f32_16x16x32_bf16 v[34:37], v[42:45], v[50:53], v[34:37]
	v_add_f32_e32 v54, v54, v55
	ds_bpermute_b32 v42, v65, v54
	v_mov_b32_e32 v44, v147
	s_waitcnt lgkmcnt(1)
	v_mfma_f32_16x16x32_bf16 v[26:29], v[46:49], v[50:53], v[26:29]
	v_mov_b32_e32 v48, v147
	v_mov_b32_e32 v49, v147
	s_waitcnt lgkmcnt(0)
	v_add_f32_e32 v60, v54, v42
	v_cvt_pk_bf16_f32 v42, v84, v85
	v_cvt_pk_bf16_f32 v43, v72, v73
	ds_read_b64 v[46:47], v179 offset:37248
	ds_read_b64 v[50:51], v179 offset:45696
	v_mov_b32_e32 v45, v147
	v_mov_b32_e32 v52, v147
	v_mov_b32_e32 v53, v147
	s_waitcnt lgkmcnt(1)
	v_mfma_f32_16x16x32_bf16 v[30:33], v[46:49], v[42:45], v[30:33]
	ds_bpermute_b32 v46, v66, v60
	v_fma_f32 v47, v64, s61, -v96
	v_exp_f32_e32 v47, v47
	ds_read_b64 v[54:55], v179 offset:54144
	ds_read_b64 v[58:59], v179 offset:62592
	v_mov_b32_e32 v56, v147
	s_waitcnt lgkmcnt(2)
	v_add_f32_e32 v46, v60, v46
	v_add_f32_e32 v46, v47, v46
	v_mov_b32_e32 v57, v147
	v_mov_b32_e32 v60, v147
	v_mov_b32_e32 v61, v147
	v_div_scale_f32 v47, s[68:69], v46, v46, 1.0
	v_rcp_f32_e32 v48, v47
	v_mfma_f32_16x16x32_bf16 v[38:41], v[50:53], v[42:45], v[38:41]
	s_waitcnt lgkmcnt(1)
	v_mfma_f32_16x16x32_bf16 v[34:37], v[54:57], v[42:45], v[34:37]
	s_waitcnt lgkmcnt(0)
	v_mfma_f32_16x16x32_bf16 v[26:29], v[58:61], v[42:45], v[26:29]
	v_fma_f32 v42, -v47, v48, 1.0
	v_fmac_f32_e32 v48, v42, v48
	v_div_scale_f32 v42, vcc, 1.0, v46, 1.0
	v_mul_f32_e32 v43, v42, v48
	v_fma_f32 v44, -v47, v43, v42
	v_fmac_f32_e32 v43, v44, v48
	v_fma_f32 v42, -v47, v43, v42
	v_div_fmas_f32 v42, v42, v48, v43
	v_div_fixup_f32 v42, v42, v46, 1.0
	v_pk_mul_f32 v[32:33], v[42:43], v[32:33] op_sel_hi:[0,1]
	v_pk_mul_f32 v[30:31], v[42:43], v[30:31] op_sel_hi:[0,1]
	v_add_co_u32_e32 v76, vcc, s55, v62
	v_cvt_pk_bf16_f32 v30, v30, v31
	v_cvt_pk_bf16_f32 v31, v32, v33
	v_pk_mul_f32 v[32:33], v[42:43], v[38:39] op_sel_hi:[0,1]
	s_nop 0
	v_addc_co_u32_e32 v77, vcc, 0, v63, vcc
	global_store_dwordx2 v[76:77], v[30:31], off
	v_pk_mul_f32 v[30:31], v[42:43], v[40:41] op_sel_hi:[0,1]
	v_cvt_pk_bf16_f32 v32, v32, v33
	v_cvt_pk_bf16_f32 v33, v30, v31
	global_store_dwordx2 v[76:77], v[32:33], off offset:32
	v_pk_mul_f32 v[32:33], v[42:43], v[34:35] op_sel_hi:[0,1]
	v_pk_mul_f32 v[30:31], v[42:43], v[36:37] op_sel_hi:[0,1]
	v_cvt_pk_bf16_f32 v32, v32, v33
	v_cvt_pk_bf16_f32 v33, v30, v31
	v_pk_mul_f32 v[28:29], v[42:43], v[28:29] op_sel_hi:[0,1]
	v_pk_mul_f32 v[26:27], v[42:43], v[26:27] op_sel_hi:[0,1]
	global_store_dwordx2 v[76:77], v[32:33], off offset:64
	v_cvt_pk_bf16_f32 v78, v26, v27
	v_cvt_pk_bf16_f32 v79, v28, v29
	ds_read_b128 v[26:29], v178 offset:11520
	ds_read_b128 v[30:33], v178 offset:11584
	s_waitcnt lgkmcnt(1)
	v_mfma_f32_16x16x32_bf16 v[26:29], v[26:29], v[18:21], 0
	ds_read_b128 v[34:37], v178 offset:13824
	ds_read_b128 v[38:41], v178 offset:16128
	ds_read_b128 v[42:45], v178 offset:18432
	s_waitcnt lgkmcnt(3)
	v_mfma_f32_16x16x32_bf16 v[30:33], v[30:33], v[22:25], v[26:29]
	ds_read_b128 v[46:49], v178 offset:20736
	ds_read_b128 v[50:53], v178 offset:23040
	ds_read_b128 v[54:57], v178 offset:25344
	ds_read_b128 v[26:29], v178 offset:13888
	s_waitcnt lgkmcnt(6)
; #define LAS __attribute__((address_space(3)))
; __device__ __forceinline__ void attn_unit(LAS unsigned char* lds, bf16* Q, const bf16* Kg, const bf16* Vg, const float* snk, int unit, int tid) {
;     ...
;     for (int mt = 0; mt < 8; ++mt) {
;         f32x4 st[9];
; #pragma unroll
;         for (int kb = 0; kb < 9; ++kb) { const LAS unsigned char* kp = lds + (16 * (mt + kb) + fr) * ATT_KP + 16 * fq;
;             const bf16x8_t k0 = *(const LAS bf16x8_t*)kp, k1 = *(const LAS bf16x8_t*)(kp + 64);
;             f32x4 z = {0.f, 0.f, 0.f, 0.f}; z = __builtin_amdgcn_mfma_f32_16x16x32_bf16(k0, qf[mt][0], z, 0, 0, 0); z = __builtin_amdgcn_mfma_f32_16x16x32_bf16(k1, qf[mt][1], z, 0, 0, 0); st[kb] = z; }
;         float mx = sink;
; #pragma unroll
;         for (int kb = 0; kb < 9; ++kb) {
;             const bool tile_ok = (n > 0) || (mt + kb >= 8);
; #pragma unroll
;             for (int i = 0; i < 4; ++i) { const bool ok = tile_ok && (kb == 0 ? lo_ok[i] : (kb == 8 ? !lo_ok[i] : true));
;                 st[kb][i] = ok ? st[kb][i] : -INFINITY; mx = fmaxf(mx, st[kb][i]); }
;         }
;         mx = fmaxf(mx, __shfl_xor(mx, 16)); mx = fmaxf(mx, __shfl_xor(mx, 32));
;         f32x4 ls4 = {0.f, 0.f, 0.f, 0.f};
; #pragma unroll
;         for (int kb = 0; kb < 9; ++kb) { f32x4 d = st[kb] - mx;
; #pragma unroll
;             for (int i = 0; i < 4; ++i) d[i] = __builtin_amdgcn_exp2f(d[i]);
;             st[kb] = d; ls4 = ls4 + d; }
;         float ls = (ls4[0] + ls4[1]) + (ls4[2] + ls4[3]);
;         ls += __shfl_xor(ls, 16); ls += __shfl_xor(ls, 32);
;         const float inv = 1.f / (ls + __builtin_amdgcn_exp2f(sink - mx));
	v_mfma_f32_16x16x32_bf16 v[34:37], v[34:37], v[18:21], 0
	ds_read_b128 v[58:61], v178 offset:27648
	ds_read_b128 v[72:75], v178 offset:29952
	global_store_dwordx2 v[76:77], v[78:79], off offset:96
	s_waitcnt lgkmcnt(2)
	v_mfma_f32_16x16x32_bf16 v[34:37], v[26:29], v[22:25], v[34:37]
	ds_read_b128 v[26:29], v178 offset:16192
	v_mfma_f32_16x16x32_bf16 v[38:41], v[38:41], v[18:21], 0
	s_waitcnt lgkmcnt(0)
	v_mfma_f32_16x16x32_bf16 v[38:41], v[26:29], v[22:25], v[38:41]
	ds_read_b128 v[26:29], v178 offset:18496
	v_mfma_f32_16x16x32_bf16 v[42:45], v[42:45], v[18:21], 0
	s_waitcnt lgkmcnt(0)
	v_mfma_f32_16x16x32_bf16 v[42:45], v[26:29], v[22:25], v[42:45]
	ds_read_b128 v[26:29], v178 offset:20800
	v_mfma_f32_16x16x32_bf16 v[46:49], v[46:49], v[18:21], 0
	s_waitcnt lgkmcnt(0)
	v_mfma_f32_16x16x32_bf16 v[46:49], v[26:29], v[22:25], v[46:49]
	ds_read_b128 v[26:29], v178 offset:23104
	v_mfma_f32_16x16x32_bf16 v[50:53], v[50:53], v[18:21], 0
	s_waitcnt lgkmcnt(0)
	v_mfma_f32_16x16x32_bf16 v[50:53], v[26:29], v[22:25], v[50:53]
	ds_read_b128 v[26:29], v178 offset:25408
	v_mfma_f32_16x16x32_bf16 v[54:57], v[54:57], v[18:21], 0
	s_waitcnt lgkmcnt(0)
	v_mfma_f32_16x16x32_bf16 v[54:57], v[26:29], v[22:25], v[54:57]
	ds_read_b128 v[26:29], v178 offset:27712
	v_mfma_f32_16x16x32_bf16 v[58:61], v[58:61], v[18:21], 0
	s_waitcnt lgkmcnt(0)
	v_mfma_f32_16x16x32_bf16 v[26:29], v[26:29], v[22:25], v[58:61]
	s_nop 5
	ds_read_b128 v[58:61], v178 offset:30016
	v_mfma_f32_16x16x32_bf16 v[18:21], v[72:75], v[18:21], 0
	s_waitcnt lgkmcnt(0)
	v_mfma_f32_16x16x32_bf16 v[18:21], v[58:61], v[22:25], v[18:21]
	v_cndmask_b32_e64 v23, v31, v190, s[10:11]
	v_cndmask_b32_e64 v22, v190, v30, s[20:21]
	v_cndmask_b32_e64 v23, v190, v23, s[16:17]
	v_max3_f32 v24, v71, v22, v23
	v_cndmask_b32_e64 v25, v190, v32, s[18:19]
	v_cndmask_b32_e64 v30, v190, v33, s[22:23]
	v_max3_f32 v24, v24, v25, v30
	v_cndmask_b32_e64 v31, v190, v34, s[16:17]
	v_cndmask_b32_e64 v32, v190, v35, s[16:17]
	v_max3_f32 v24, v24, v31, v32
	v_cndmask_b32_e64 v33, v190, v36, s[16:17]
	v_cndmask_b32_e64 v34, v190, v37, s[16:17]
	v_max3_f32 v24, v24, v33, v34
	v_cndmask_b32_e64 v35, v190, v38, s[16:17]
	v_cndmask_b32_e64 v36, v190, v39, s[16:17]
	v_max3_f32 v24, v24, v35, v36
	v_cndmask_b32_e64 v37, v190, v40, s[16:17]
	v_cndmask_b32_e64 v38, v190, v41, s[16:17]
	v_max3_f32 v24, v24, v37, v38
	v_max3_f32 v24, v24, v42, v43
	v_max3_f32 v24, v24, v44, v45
	v_max3_f32 v24, v24, v46, v47
	v_max3_f32 v24, v24, v48, v49
	v_max3_f32 v24, v24, v50, v51
	v_max3_f32 v24, v24, v52, v53
	v_max3_f32 v24, v24, v54, v55
	v_max3_f32 v24, v24, v56, v57
	v_max3_f32 v24, v24, v26, v27
	v_max3_f32 v24, v24, v28, v29
	v_cndmask_b32_e64 v86, v18, v190, s[8:9]
	v_cndmask_b32_e64 v87, v190, v19, s[10:11]
	v_max3_f32 v18, v24, v86, v87
	v_cndmask_b32_e64 v88, v20, v190, s[12:13]
	v_cndmask_b32_e64 v89, v21, v190, s[14:15]
	v_max3_f32 v18, v18, v88, v89
	ds_bpermute_b32 v19, v65, v18
	s_waitcnt lgkmcnt(0)
	v_max_f32_e32 v19, v19, v19
	v_max_f32_e32 v18, v18, v19
	ds_bpermute_b32 v19, v66, v18
	s_waitcnt lgkmcnt(0)
	v_max_f32_e32 v19, v19, v19
	v_max_f32_e32 v90, v18, v19
	v_sub_f32_e32 v19, v30, v90
	v_sub_f32_e32 v20, v25, v90
	v_sub_f32_e32 v23, v23, v90
	v_sub_f32_e32 v18, v22, v90
	v_exp_f32_e32 v18, v18
	v_exp_f32_e32 v20, v20
	v_exp_f32_e32 v21, v19
	v_exp_f32_e32 v19, v23
	v_sub_f32_e32 v34, v34, v90
	v_sub_f32_e32 v33, v33, v90
	v_sub_f32_e32 v32, v32, v90
	v_sub_f32_e32 v30, v31, v90
	v_exp_f32_e32 v30, v30
	v_exp_f32_e32 v31, v32
	v_exp_f32_e32 v32, v33
	v_exp_f32_e32 v33, v34
	v_sub_f32_e32 v34, v38, v90
	v_sub_f32_e32 v37, v37, v90
	v_sub_f32_e32 v36, v36, v90
	v_sub_f32_e32 v35, v35, v90
	v_exp_f32_e32 v58, v35
	v_exp_f32_e32 v60, v37
	v_exp_f32_e32 v61, v34
	v_exp_f32_e32 v59, v36
	v_sub_f32_e32 v34, v45, v90
	v_sub_f32_e32 v35, v44, v90
	v_sub_f32_e32 v36, v43, v90
	v_sub_f32_e32 v37, v42, v90
	v_exp_f32_e32 v44, v37
	v_exp_f32_e32 v45, v36
	v_exp_f32_e32 v72, v35
	v_exp_f32_e32 v73, v34
	v_sub_f32_e32 v34, v49, v90
	v_sub_f32_e32 v35, v48, v90
	v_sub_f32_e32 v36, v47, v90
	v_sub_f32_e32 v37, v46, v90
	v_pk_add_f32 v[22:23], v[20:21], 0 op_sel_hi:[1,0]
	v_pk_add_f32 v[24:25], v[18:19], 0 op_sel_hi:[1,0]
	v_exp_f32_e32 v74, v37
	v_exp_f32_e32 v76, v35
	v_exp_f32_e32 v77, v34
	v_exp_f32_e32 v75, v36
	v_pk_add_f32 v[24:25], v[30:31], v[24:25]
	v_pk_add_f32 v[22:23], v[32:33], v[22:23]
	v_pk_add_f32 v[24:25], v[58:59], v[24:25]
	v_pk_add_f32 v[22:23], v[60:61], v[22:23]
	v_pk_add_f32 v[24:25], v[44:45], v[24:25]
	v_pk_add_f32 v[22:23], v[72:73], v[22:23]
	v_sub_f32_e32 v36, v50, v90
	v_pk_add_f32 v[34:35], v[76:77], v[22:23]
	v_pk_add_f32 v[22:23], v[74:75], v[24:25]
	v_sub_f32_e32 v25, v51, v90
	v_sub_f32_e32 v24, v53, v90
	v_exp_f32_e32 v79, v25
	v_sub_f32_e32 v25, v52, v90
	v_exp_f32_e32 v78, v36
	v_exp_f32_e32 v80, v25
	v_exp_f32_e32 v81, v24
	v_sub_f32_e32 v38, v57, v90
	v_sub_f32_e32 v39, v56, v90
	v_sub_f32_e32 v40, v55, v90
	v_sub_f32_e32 v41, v54, v90
	v_exp_f32_e32 v54, v39
	v_exp_f32_e32 v55, v38
	v_exp_f32_e32 v56, v41
	v_exp_f32_e32 v57, v40
	v_pk_add_f32 v[36:37], v[78:79], v[22:23]
	v_pk_add_f32 v[34:35], v[80:81], v[34:35]
	v_cvt_pk_bf16_f32 v18, v18, v19
	v_cvt_pk_bf16_f32 v19, v20, v21
	v_cvt_pk_bf16_f32 v20, v30, v31
	v_cvt_pk_bf16_f32 v21, v32, v33
	ds_read2_b64 v[22:25], v67 offset0:20 offset1:24
	ds_read2_b64 v[30:33], v68 offset0:52 offset1:56
	v_pk_add_f32 v[82:83], v[54:55], v[34:35]
	v_pk_add_f32 v[84:85], v[56:57], v[36:37]
	ds_read2_b64 v[34:37], v70 offset0:84 offset1:88
	ds_read2_b64 v[38:41], v69 offset0:116 offset1:120
	v_sub_f32_e32 v28, v28, v90
	v_sub_f32_e32 v27, v27, v90
	v_sub_f32_e32 v26, v26, v90
	v_sub_f32_e32 v91, v29, v90
	v_cvt_pk_bf16_f32 v42, v58, v59
	v_cvt_pk_bf16_f32 v43, v60, v61
	v_cvt_pk_bf16_f32 v44, v44, v45
	v_cvt_pk_bf16_f32 v45, v72, v73
	ds_read2_b64 v[46:49], v67 offset0:28 offset1:32
	v_exp_f32_e32 v58, v26
	v_exp_f32_e32 v59, v27
	v_exp_f32_e32 v60, v28
	ds_read2_b64 v[26:29], v70 offset0:92 offset1:96
	s_waitcnt lgkmcnt(5)
; __device__ __forceinline__ unsigned cvt_pk_bf16(float lo, float hi) { unsigned r; asm volatile("v_cvt_pk_bf16_f32 %0, %1, %2" : "=v"(r) : "v"(lo), "v"(hi)); return r; }
; #define LAS __attribute__((address_space(3)))
; __device__ __forceinline__ void attn_unit(LAS unsigned char* lds, bf16* Q, const bf16* Kg, const bf16* Vg, const float* snk, int unit, int tid) {
;     ...
; #pragma unroll
;         for (int kp = 0; kp < 5; ++kp) {
;             v4u pw; pw.x = cvt_pk_bf16(st[2 * kp][0], st[2 * kp][1]); pw.y = cvt_pk_bf16(st[2 * kp][2], st[2 * kp][3]);
;             if (kp < 4) { pw.z = cvt_pk_bf16(st[(2 * kp + 1) % 9][0], st[(2 * kp + 1) % 9][1]); pw.w = cvt_pk_bf16(st[(2 * kp + 1) % 9][2], st[(2 * kp + 1) % 9][3]); } else { pw.z = 0u; pw.w = 0u; }
;             const bf16x8_t pb = __builtin_bit_cast(bf16x8_t, pw);
; #pragma unroll
;             for (int dt = 0; dt < 4; ++dt) { const LAS unsigned char* vp = lds + ATT_VOFF + (16 * dt + fr) * ATT_VP + (16 * (mt + 2 * kp) + 4 * fq) * 2;
;                 const v2u lo = *(const LAS v2u*)vp; v2u hi = {0u, 0u}; if (kp < 4) hi = *(const LAS v2u*)(vp + 32);
;                 v4u aw; aw.x = lo.x; aw.y = lo.y; aw.z = hi.x; aw.w = hi.y;
;                 o[dt] = __builtin_amdgcn_mfma_f32_16x16x32_bf16(__builtin_bit_cast(bf16x8_t, aw), pb, o[dt], 0, 0, 0); }
;         }
; #pragma unroll
;         for (int dt = 0; dt < 4; ++dt) { const f32x4 y = o[dt] * inv; v2u w; w.x = cvt_pk_bf16(y[0], y[1]); w.y = cvt_pk_bf16(y[2], y[3]); *(v2u*)(qbase + (size_t)mt * 16 * 1024 + 16 * dt + 4 * fq) = w; }
	v_mfma_f32_16x16x32_bf16 v[22:25], v[22:25], v[18:21], 0
	ds_read2_b64 v[50:53], v68 offset0:60 offset1:64
	v_exp_f32_e32 v61, v91
	v_pk_add_f32 v[72:73], v[58:59], v[84:85]
	s_waitcnt lgkmcnt(5)
	v_mfma_f32_16x16x32_bf16 v[30:33], v[30:33], v[18:21], 0
	s_waitcnt lgkmcnt(4)
	v_mfma_f32_16x16x32_bf16 v[34:37], v[34:37], v[18:21], 0
	s_waitcnt lgkmcnt(3)
	v_mfma_f32_16x16x32_bf16 v[18:21], v[38:41], v[18:21], 0
	ds_read2_b64 v[38:41], v69 offset0:124 offset1:128
	s_waitcnt lgkmcnt(3)
	v_mfma_f32_16x16x32_bf16 v[22:25], v[46:49], v[42:45], v[22:25]
	v_cvt_pk_bf16_f32 v46, v74, v75
	v_cvt_pk_bf16_f32 v47, v76, v77
	v_cvt_pk_bf16_f32 v48, v78, v79
	v_cvt_pk_bf16_f32 v49, v80, v81
	s_waitcnt lgkmcnt(2)
	v_mfma_f32_16x16x32_bf16 v[26:29], v[26:29], v[42:45], v[34:37]
	v_sub_f32_e32 v77, v89, v90
	v_sub_f32_e32 v78, v88, v90
	v_sub_f32_e32 v79, v87, v90
	ds_read2_b64 v[34:37], v68 offset0:68 offset1:72
	s_waitcnt lgkmcnt(2)
	v_mfma_f32_16x16x32_bf16 v[30:33], v[50:53], v[42:45], v[30:33]
	ds_read2_b64 v[50:53], v67 offset0:36 offset1:40
	v_pk_add_f32 v[74:75], v[60:61], v[82:83]
	s_waitcnt lgkmcnt(2)
	v_mfma_f32_16x16x32_bf16 v[18:21], v[38:41], v[42:45], v[18:21]
	ds_read2_b64 v[38:41], v70 offset0:100 offset1:104
	v_sub_f32_e32 v42, v86, v90
	v_exp_f32_e32 v76, v42
	s_waitcnt lgkmcnt(2)
	v_mfma_f32_16x16x32_bf16 v[30:33], v[34:37], v[46:49], v[30:33]
	ds_read2_b64 v[34:37], v69 offset0:132 offset1:136
	v_cvt_pk_bf16_f32 v42, v56, v57
	v_cvt_pk_bf16_f32 v43, v54, v55
	v_cvt_pk_bf16_f32 v44, v58, v59
	v_cvt_pk_bf16_f32 v45, v60, v61
	s_waitcnt lgkmcnt(1)
	v_mfma_f32_16x16x32_bf16 v[26:29], v[38:41], v[46:49], v[26:29]
	ds_read2_b64 v[38:41], v68 offset0:76 offset1:80
	v_exp_f32_e32 v54, v78
	v_exp_f32_e32 v55, v77
	v_mfma_f32_16x16x32_bf16 v[22:25], v[50:53], v[46:49], v[22:25]
	ds_read2_b64 v[50:53], v67 offset0:44 offset1:48
	v_exp_f32_e32 v77, v79
	s_waitcnt lgkmcnt(2)
	v_mfma_f32_16x16x32_bf16 v[18:21], v[34:37], v[46:49], v[18:21]
	ds_read2_b64 v[34:37], v70 offset0:108 offset1:112
	v_pk_add_f32 v[46:47], v[54:55], v[74:75]
	v_pk_add_f32 v[48:49], v[76:77], v[72:73]
	s_waitcnt lgkmcnt(2)
	v_mfma_f32_16x16x32_bf16 v[30:33], v[38:41], v[42:45], v[30:33]
	ds_read2_b64 v[38:41], v69 offset0:140 offset1:144
	s_waitcnt lgkmcnt(2)
	v_mfma_f32_16x16x32_bf16 v[22:25], v[50:53], v[42:45], v[22:25]
	v_pk_mov_b32 v[50:51], v[48:49], v[46:47] op_sel:[1,0]
	v_mov_b32_e32 v49, v47
	v_pk_add_f32 v[46:47], v[50:51], v[48:49]
	s_waitcnt lgkmcnt(1)
	v_mfma_f32_16x16x32_bf16 v[26:29], v[34:37], v[42:45], v[26:29]
	v_add_f32_e32 v46, v46, v47
	ds_bpermute_b32 v34, v65, v46
	v_mov_b32_e32 v36, v147
	s_waitcnt lgkmcnt(1)
	v_mfma_f32_16x16x32_bf16 v[18:21], v[38:41], v[42:45], v[18:21]
	v_mov_b32_e32 v40, v147
	v_mov_b32_e32 v41, v147
	s_waitcnt lgkmcnt(0)
	v_add_f32_e32 v52, v46, v34
	v_cvt_pk_bf16_f32 v34, v76, v77
	v_cvt_pk_bf16_f32 v35, v54, v55
	ds_read_b64 v[38:39], v179 offset:37280
	ds_read_b64 v[42:43], v179 offset:45728
	v_mov_b32_e32 v37, v147
	v_mov_b32_e32 v44, v147
	v_mov_b32_e32 v45, v147
	s_waitcnt lgkmcnt(1)
	v_mfma_f32_16x16x32_bf16 v[22:25], v[38:41], v[34:37], v[22:25]
	ds_bpermute_b32 v38, v66, v52
	v_fma_f32 v39, v64, s61, -v90
	v_exp_f32_e32 v39, v39
	ds_read_b64 v[46:47], v179 offset:54176
	ds_read_b64 v[50:51], v179 offset:62624
	v_mov_b32_e32 v48, v147
	s_waitcnt lgkmcnt(2)
	v_add_f32_e32 v38, v52, v38
	v_add_f32_e32 v38, v39, v38
	v_mov_b32_e32 v49, v147
	v_mov_b32_e32 v52, v147
	v_mov_b32_e32 v53, v147
	v_div_scale_f32 v39, s[68:69], v38, v38, 1.0
	v_rcp_f32_e32 v40, v39
	v_mfma_f32_16x16x32_bf16 v[30:33], v[42:45], v[34:37], v[30:33]
	s_waitcnt lgkmcnt(1)
	v_mfma_f32_16x16x32_bf16 v[26:29], v[46:49], v[34:37], v[26:29]
	s_waitcnt lgkmcnt(0)
	v_mfma_f32_16x16x32_bf16 v[18:21], v[50:53], v[34:37], v[18:21]
	v_fma_f32 v34, -v39, v40, 1.0
	v_fmac_f32_e32 v40, v34, v40
	v_div_scale_f32 v34, vcc, 1.0, v38, 1.0
	v_mul_f32_e32 v35, v34, v40
	v_fma_f32 v36, -v39, v35, v34
	v_fmac_f32_e32 v35, v36, v40
	v_fma_f32 v34, -v39, v35, v34
	v_div_fmas_f32 v34, v34, v40, v35
	v_div_fixup_f32 v34, v34, v38, 1.0
	v_pk_mul_f32 v[24:25], v[34:35], v[24:25] op_sel_hi:[0,1]
	v_pk_mul_f32 v[22:23], v[34:35], v[22:23] op_sel_hi:[0,1]
	v_add_co_u32_e32 v58, vcc, s56, v62
	v_cvt_pk_bf16_f32 v22, v22, v23
	v_cvt_pk_bf16_f32 v23, v24, v25
	v_pk_mul_f32 v[24:25], v[34:35], v[30:31] op_sel_hi:[0,1]
	s_nop 0
	v_addc_co_u32_e32 v59, vcc, 0, v63, vcc
	global_store_dwordx2 v[58:59], v[22:23], off
	v_pk_mul_f32 v[22:23], v[34:35], v[32:33] op_sel_hi:[0,1]
	v_cvt_pk_bf16_f32 v24, v24, v25
	v_cvt_pk_bf16_f32 v25, v22, v23
	global_store_dwordx2 v[58:59], v[24:25], off offset:32
	v_pk_mul_f32 v[24:25], v[34:35], v[26:27] op_sel_hi:[0,1]
	v_pk_mul_f32 v[22:23], v[34:35], v[28:29] op_sel_hi:[0,1]
	v_cvt_pk_bf16_f32 v24, v24, v25
	v_cvt_pk_bf16_f32 v25, v22, v23
	v_pk_mul_f32 v[20:21], v[34:35], v[20:21] op_sel_hi:[0,1]
	v_pk_mul_f32 v[18:19], v[34:35], v[18:19] op_sel_hi:[0,1]
	global_store_dwordx2 v[58:59], v[24:25], off offset:64
	v_cvt_pk_bf16_f32 v60, v18, v19
	v_cvt_pk_bf16_f32 v61, v20, v21
	ds_read_b128 v[18:21], v178 offset:13824
	ds_read_b128 v[22:25], v178 offset:13888
	s_waitcnt lgkmcnt(1)
	v_mfma_f32_16x16x32_bf16 v[18:21], v[18:21], v[10:13], 0
	ds_read_b128 v[26:29], v178 offset:16128
	ds_read_b128 v[30:33], v178 offset:18432
	ds_read_b128 v[34:37], v178 offset:20736
	s_waitcnt lgkmcnt(3)
	v_mfma_f32_16x16x32_bf16 v[22:25], v[22:25], v[14:17], v[18:21]
	ds_read_b128 v[38:41], v178 offset:23040
	ds_read_b128 v[42:45], v178 offset:25344
	ds_read_b128 v[46:49], v178 offset:27648
	ds_read_b128 v[18:21], v178 offset:16192
	s_waitcnt lgkmcnt(6)
; #define LAS __attribute__((address_space(3)))
; __device__ __forceinline__ void attn_unit(LAS unsigned char* lds, bf16* Q, const bf16* Kg, const bf16* Vg, const float* snk, int unit, int tid) {
;     ...
;     for (int mt = 0; mt < 8; ++mt) {
;         f32x4 st[9];
; #pragma unroll
;         for (int kb = 0; kb < 9; ++kb) { const LAS unsigned char* kp = lds + (16 * (mt + kb) + fr) * ATT_KP + 16 * fq;
;             const bf16x8_t k0 = *(const LAS bf16x8_t*)kp, k1 = *(const LAS bf16x8_t*)(kp + 64);
;             f32x4 z = {0.f, 0.f, 0.f, 0.f}; z = __builtin_amdgcn_mfma_f32_16x16x32_bf16(k0, qf[mt][0], z, 0, 0, 0); z = __builtin_amdgcn_mfma_f32_16x16x32_bf16(k1, qf[mt][1], z, 0, 0, 0); st[kb] = z; }
;         float mx = sink;
; #pragma unroll
;         for (int kb = 0; kb < 9; ++kb) {
;             const bool tile_ok = (n > 0) || (mt + kb >= 8);
; #pragma unroll
;             for (int i = 0; i < 4; ++i) { const bool ok = tile_ok && (kb == 0 ? lo_ok[i] : (kb == 8 ? !lo_ok[i] : true));
;                 st[kb][i] = ok ? st[kb][i] : -INFINITY; mx = fmaxf(mx, st[kb][i]); }
;         }
;         mx = fmaxf(mx, __shfl_xor(mx, 16)); mx = fmaxf(mx, __shfl_xor(mx, 32));
;         f32x4 ls4 = {0.f, 0.f, 0.f, 0.f};
; #pragma unroll
;         for (int kb = 0; kb < 9; ++kb) { f32x4 d = st[kb] - mx;
; #pragma unroll
;             for (int i = 0; i < 4; ++i) d[i] = __builtin_amdgcn_exp2f(d[i]);
;             st[kb] = d; ls4 = ls4 + d; }
;         float ls = (ls4[0] + ls4[1]) + (ls4[2] + ls4[3]);
;         ls += __shfl_xor(ls, 16); ls += __shfl_xor(ls, 32);
;         const float inv = 1.f / (ls + __builtin_amdgcn_exp2f(sink - mx));
	v_mfma_f32_16x16x32_bf16 v[26:29], v[26:29], v[10:13], 0
	ds_read_b128 v[50:53], v178 offset:29952
	ds_read_b128 v[54:57], v178 offset:32256
	global_store_dwordx2 v[58:59], v[60:61], off offset:96
	s_waitcnt lgkmcnt(2)
	v_mfma_f32_16x16x32_bf16 v[26:29], v[18:21], v[14:17], v[26:29]
	ds_read_b128 v[18:21], v178 offset:18496
	v_mfma_f32_16x16x32_bf16 v[30:33], v[30:33], v[10:13], 0
	s_waitcnt lgkmcnt(0)
	v_mfma_f32_16x16x32_bf16 v[30:33], v[18:21], v[14:17], v[30:33]
	ds_read_b128 v[18:21], v178 offset:20800
	v_mfma_f32_16x16x32_bf16 v[34:37], v[34:37], v[10:13], 0
	s_waitcnt lgkmcnt(0)
	v_mfma_f32_16x16x32_bf16 v[34:37], v[18:21], v[14:17], v[34:37]
	ds_read_b128 v[18:21], v178 offset:23104
	v_mfma_f32_16x16x32_bf16 v[38:41], v[38:41], v[10:13], 0
	s_waitcnt lgkmcnt(0)
	v_mfma_f32_16x16x32_bf16 v[38:41], v[18:21], v[14:17], v[38:41]
	ds_read_b128 v[18:21], v178 offset:25408
	v_mfma_f32_16x16x32_bf16 v[42:45], v[42:45], v[10:13], 0
	s_waitcnt lgkmcnt(0)
	v_mfma_f32_16x16x32_bf16 v[42:45], v[18:21], v[14:17], v[42:45]
	ds_read_b128 v[18:21], v178 offset:27712
	v_mfma_f32_16x16x32_bf16 v[46:49], v[46:49], v[10:13], 0
	s_waitcnt lgkmcnt(0)
	v_mfma_f32_16x16x32_bf16 v[46:49], v[18:21], v[14:17], v[46:49]
	ds_read_b128 v[18:21], v178 offset:30016
	v_mfma_f32_16x16x32_bf16 v[50:53], v[50:53], v[10:13], 0
	s_waitcnt lgkmcnt(0)
	v_mfma_f32_16x16x32_bf16 v[18:21], v[18:21], v[14:17], v[50:53]
	s_nop 5
	ds_read_b128 v[50:53], v178 offset:32320
	v_mfma_f32_16x16x32_bf16 v[10:13], v[54:57], v[10:13], 0
	s_waitcnt lgkmcnt(0)
	v_mfma_f32_16x16x32_bf16 v[10:13], v[50:53], v[14:17], v[10:13]
	v_cndmask_b32_e64 v15, v23, v190, s[10:11]
	v_cndmask_b32_e64 v14, v190, v22, s[20:21]
	v_cndmask_b32_e64 v15, v190, v15, s[16:17]
	v_max3_f32 v16, v71, v14, v15
	v_cndmask_b32_e64 v17, v190, v24, s[18:19]
	v_cndmask_b32_e64 v22, v190, v25, s[22:23]
	v_max3_f32 v16, v16, v17, v22
	v_cndmask_b32_e64 v23, v190, v26, s[16:17]
	v_cndmask_b32_e64 v24, v190, v27, s[16:17]
	v_max3_f32 v16, v16, v23, v24
	v_cndmask_b32_e64 v25, v190, v28, s[16:17]
	v_cndmask_b32_e64 v26, v190, v29, s[16:17]
	v_max3_f32 v16, v16, v25, v26
	v_max3_f32 v16, v16, v30, v31
	v_max3_f32 v16, v16, v32, v33
	v_max3_f32 v16, v16, v34, v35
	v_max3_f32 v16, v16, v36, v37
	v_max3_f32 v16, v16, v38, v39
	v_max3_f32 v16, v16, v40, v41
	v_max3_f32 v16, v16, v42, v43
	v_max3_f32 v16, v16, v44, v45
	v_max3_f32 v16, v16, v46, v47
	v_max3_f32 v16, v16, v48, v49
	v_max3_f32 v16, v16, v18, v19
	v_max3_f32 v16, v16, v20, v21
	v_cndmask_b32_e64 v78, v10, v190, s[8:9]
	v_cndmask_b32_e64 v79, v190, v11, s[10:11]
	v_max3_f32 v10, v16, v78, v79
	v_cndmask_b32_e64 v80, v12, v190, s[12:13]
	v_cndmask_b32_e64 v81, v13, v190, s[14:15]
	v_max3_f32 v10, v10, v80, v81
	ds_bpermute_b32 v11, v65, v10
	s_waitcnt lgkmcnt(0)
	v_max_f32_e32 v11, v11, v11
	v_max_f32_e32 v10, v10, v11
	ds_bpermute_b32 v11, v66, v10
	s_waitcnt lgkmcnt(0)
	v_max_f32_e32 v11, v11, v11
	v_max_f32_e32 v82, v10, v11
	v_sub_f32_e32 v11, v22, v82
	v_sub_f32_e32 v12, v17, v82
	v_sub_f32_e32 v15, v15, v82
	v_sub_f32_e32 v10, v14, v82
	v_exp_f32_e32 v10, v10
	v_exp_f32_e32 v12, v12
	v_exp_f32_e32 v13, v11
	v_exp_f32_e32 v11, v15
	v_sub_f32_e32 v26, v26, v82
	v_sub_f32_e32 v25, v25, v82
	v_sub_f32_e32 v24, v24, v82
	v_sub_f32_e32 v22, v23, v82
	v_exp_f32_e32 v22, v22
	v_exp_f32_e32 v23, v24
	v_exp_f32_e32 v24, v25
	v_exp_f32_e32 v25, v26
	v_sub_f32_e32 v26, v33, v82
	v_sub_f32_e32 v27, v32, v82
	v_sub_f32_e32 v28, v31, v82
	v_sub_f32_e32 v29, v30, v82
	v_exp_f32_e32 v50, v29
	v_exp_f32_e32 v52, v27
	v_exp_f32_e32 v53, v26
	v_exp_f32_e32 v51, v28
	v_sub_f32_e32 v26, v37, v82
	v_sub_f32_e32 v27, v36, v82
	v_sub_f32_e32 v28, v35, v82
	v_sub_f32_e32 v29, v34, v82
	v_exp_f32_e32 v36, v29
	v_exp_f32_e32 v37, v28
	v_exp_f32_e32 v54, v27
	v_exp_f32_e32 v55, v26
	v_sub_f32_e32 v26, v41, v82
	v_sub_f32_e32 v27, v40, v82
	v_sub_f32_e32 v28, v39, v82
	v_sub_f32_e32 v29, v38, v82
	v_pk_add_f32 v[14:15], v[12:13], 0 op_sel_hi:[1,0]
	v_pk_add_f32 v[16:17], v[10:11], 0 op_sel_hi:[1,0]
	v_exp_f32_e32 v56, v29
	v_exp_f32_e32 v58, v27
	v_exp_f32_e32 v59, v26
	v_exp_f32_e32 v57, v28
	v_pk_add_f32 v[16:17], v[22:23], v[16:17]
	v_pk_add_f32 v[14:15], v[24:25], v[14:15]
	v_pk_add_f32 v[16:17], v[50:51], v[16:17]
	v_pk_add_f32 v[14:15], v[52:53], v[14:15]
	v_pk_add_f32 v[16:17], v[36:37], v[16:17]
	v_pk_add_f32 v[14:15], v[54:55], v[14:15]
	v_sub_f32_e32 v28, v42, v82
	v_pk_add_f32 v[26:27], v[58:59], v[14:15]
	v_pk_add_f32 v[14:15], v[56:57], v[16:17]
	v_sub_f32_e32 v17, v43, v82
	v_sub_f32_e32 v16, v45, v82
	v_exp_f32_e32 v61, v17
	v_sub_f32_e32 v17, v44, v82
	v_exp_f32_e32 v60, v28
	v_exp_f32_e32 v72, v17
	v_exp_f32_e32 v73, v16
	v_sub_f32_e32 v30, v49, v82
	v_sub_f32_e32 v31, v48, v82
	v_sub_f32_e32 v32, v47, v82
	v_sub_f32_e32 v33, v46, v82
	v_exp_f32_e32 v46, v31
	v_exp_f32_e32 v47, v30
	v_exp_f32_e32 v48, v33
	v_exp_f32_e32 v49, v32
	v_pk_add_f32 v[28:29], v[60:61], v[14:15]
	v_pk_add_f32 v[26:27], v[72:73], v[26:27]
	v_cvt_pk_bf16_f32 v10, v10, v11
	v_cvt_pk_bf16_f32 v11, v12, v13
	v_cvt_pk_bf16_f32 v12, v22, v23
	v_cvt_pk_bf16_f32 v13, v24, v25
	ds_read2_b64 v[14:17], v67 offset0:24 offset1:28
	ds_read2_b64 v[22:25], v68 offset0:56 offset1:60
	v_pk_add_f32 v[74:75], v[46:47], v[26:27]
	v_pk_add_f32 v[76:77], v[48:49], v[28:29]
	ds_read2_b64 v[26:29], v70 offset0:88 offset1:92
	ds_read2_b64 v[30:33], v69 offset0:120 offset1:124
	v_sub_f32_e32 v20, v20, v82
	v_sub_f32_e32 v19, v19, v82
	v_sub_f32_e32 v18, v18, v82
	v_sub_f32_e32 v83, v21, v82
	v_cvt_pk_bf16_f32 v34, v50, v51
	v_cvt_pk_bf16_f32 v35, v52, v53
	v_cvt_pk_bf16_f32 v36, v36, v37
	v_cvt_pk_bf16_f32 v37, v54, v55
	ds_read2_b64 v[38:41], v67 offset0:32 offset1:36
	v_exp_f32_e32 v50, v18
	v_exp_f32_e32 v51, v19
	v_exp_f32_e32 v52, v20
	ds_read2_b64 v[18:21], v70 offset0:96 offset1:100
	s_waitcnt lgkmcnt(5)
; __device__ __forceinline__ unsigned cvt_pk_bf16(float lo, float hi) { unsigned r; asm volatile("v_cvt_pk_bf16_f32 %0, %1, %2" : "=v"(r) : "v"(lo), "v"(hi)); return r; }
; #define LAS __attribute__((address_space(3)))
; __device__ __forceinline__ void attn_unit(LAS unsigned char* lds, bf16* Q, const bf16* Kg, const bf16* Vg, const float* snk, int unit, int tid) {
;     ...
; #pragma unroll
;         for (int kp = 0; kp < 5; ++kp) {
;             v4u pw; pw.x = cvt_pk_bf16(st[2 * kp][0], st[2 * kp][1]); pw.y = cvt_pk_bf16(st[2 * kp][2], st[2 * kp][3]);
;             if (kp < 4) { pw.z = cvt_pk_bf16(st[(2 * kp + 1) % 9][0], st[(2 * kp + 1) % 9][1]); pw.w = cvt_pk_bf16(st[(2 * kp + 1) % 9][2], st[(2 * kp + 1) % 9][3]); } else { pw.z = 0u; pw.w = 0u; }
;             const bf16x8_t pb = __builtin_bit_cast(bf16x8_t, pw);
; #pragma unroll
;             for (int dt = 0; dt < 4; ++dt) { const LAS unsigned char* vp = lds + ATT_VOFF + (16 * dt + fr) * ATT_VP + (16 * (mt + 2 * kp) + 4 * fq) * 2;
;                 const v2u lo = *(const LAS v2u*)vp; v2u hi = {0u, 0u}; if (kp < 4) hi = *(const LAS v2u*)(vp + 32);
;                 v4u aw; aw.x = lo.x; aw.y = lo.y; aw.z = hi.x; aw.w = hi.y;
;                 o[dt] = __builtin_amdgcn_mfma_f32_16x16x32_bf16(__builtin_bit_cast(bf16x8_t, aw), pb, o[dt], 0, 0, 0); }
;         }
; #pragma unroll
;         for (int dt = 0; dt < 4; ++dt) { const f32x4 y = o[dt] * inv; v2u w; w.x = cvt_pk_bf16(y[0], y[1]); w.y = cvt_pk_bf16(y[2], y[3]); *(v2u*)(qbase + (size_t)mt * 16 * 1024 + 16 * dt + 4 * fq) = w; }
	v_mfma_f32_16x16x32_bf16 v[14:17], v[14:17], v[10:13], 0
	ds_read2_b64 v[42:45], v68 offset0:64 offset1:68
	v_exp_f32_e32 v53, v83
	v_pk_add_f32 v[54:55], v[50:51], v[76:77]
	s_waitcnt lgkmcnt(5)
	v_mfma_f32_16x16x32_bf16 v[22:25], v[22:25], v[10:13], 0
	s_waitcnt lgkmcnt(4)
	v_mfma_f32_16x16x32_bf16 v[26:29], v[26:29], v[10:13], 0
	s_waitcnt lgkmcnt(3)
	v_mfma_f32_16x16x32_bf16 v[10:13], v[30:33], v[10:13], 0
	ds_read2_b64 v[30:33], v69 offset0:128 offset1:132
	s_waitcnt lgkmcnt(3)
	v_mfma_f32_16x16x32_bf16 v[14:17], v[38:41], v[34:37], v[14:17]
	v_cvt_pk_bf16_f32 v38, v56, v57
	v_cvt_pk_bf16_f32 v39, v58, v59
	v_cvt_pk_bf16_f32 v40, v60, v61
	v_cvt_pk_bf16_f32 v41, v72, v73
	s_waitcnt lgkmcnt(2)
	v_mfma_f32_16x16x32_bf16 v[18:21], v[18:21], v[34:37], v[26:29]
	v_sub_f32_e32 v59, v81, v82
	v_sub_f32_e32 v60, v80, v82
	v_sub_f32_e32 v61, v79, v82
	ds_read2_b64 v[26:29], v68 offset0:72 offset1:76
	s_waitcnt lgkmcnt(2)
	v_mfma_f32_16x16x32_bf16 v[22:25], v[42:45], v[34:37], v[22:25]
	ds_read2_b64 v[42:45], v67 offset0:40 offset1:44
	v_pk_add_f32 v[56:57], v[52:53], v[74:75]
	s_waitcnt lgkmcnt(2)
	v_mfma_f32_16x16x32_bf16 v[10:13], v[30:33], v[34:37], v[10:13]
	ds_read2_b64 v[30:33], v70 offset0:104 offset1:108
	v_sub_f32_e32 v34, v78, v82
	v_exp_f32_e32 v58, v34
	s_waitcnt lgkmcnt(2)
	v_mfma_f32_16x16x32_bf16 v[22:25], v[26:29], v[38:41], v[22:25]
	ds_read2_b64 v[26:29], v69 offset0:136 offset1:140
	v_cvt_pk_bf16_f32 v34, v48, v49
	v_cvt_pk_bf16_f32 v35, v46, v47
	v_cvt_pk_bf16_f32 v36, v50, v51
	v_cvt_pk_bf16_f32 v37, v52, v53
	s_waitcnt lgkmcnt(1)
	v_mfma_f32_16x16x32_bf16 v[18:21], v[30:33], v[38:41], v[18:21]
	ds_read2_b64 v[30:33], v68 offset0:80 offset1:84
	v_exp_f32_e32 v46, v60
	v_exp_f32_e32 v47, v59
	v_mfma_f32_16x16x32_bf16 v[14:17], v[42:45], v[38:41], v[14:17]
	ds_read2_b64 v[42:45], v67 offset0:48 offset1:52
	v_exp_f32_e32 v59, v61
	s_waitcnt lgkmcnt(2)
	v_mfma_f32_16x16x32_bf16 v[10:13], v[26:29], v[38:41], v[10:13]
	ds_read2_b64 v[26:29], v70 offset0:112 offset1:116
	v_pk_add_f32 v[38:39], v[46:47], v[56:57]
	v_pk_add_f32 v[40:41], v[58:59], v[54:55]
	s_waitcnt lgkmcnt(2)
	v_mfma_f32_16x16x32_bf16 v[22:25], v[30:33], v[34:37], v[22:25]
	ds_read2_b64 v[30:33], v69 offset0:144 offset1:148
	s_waitcnt lgkmcnt(2)
	v_mfma_f32_16x16x32_bf16 v[14:17], v[42:45], v[34:37], v[14:17]
	v_pk_mov_b32 v[42:43], v[40:41], v[38:39] op_sel:[1,0]
	v_mov_b32_e32 v41, v39
	v_pk_add_f32 v[38:39], v[42:43], v[40:41]
	s_waitcnt lgkmcnt(1)
	v_mfma_f32_16x16x32_bf16 v[18:21], v[26:29], v[34:37], v[18:21]
	v_add_f32_e32 v38, v38, v39
	ds_bpermute_b32 v26, v65, v38
	v_mov_b32_e32 v28, v147
	s_waitcnt lgkmcnt(1)
	v_mfma_f32_16x16x32_bf16 v[10:13], v[30:33], v[34:37], v[10:13]
	v_mov_b32_e32 v32, v147
	v_mov_b32_e32 v33, v147
	s_waitcnt lgkmcnt(0)
	v_add_f32_e32 v44, v38, v26
	v_cvt_pk_bf16_f32 v26, v58, v59
	v_cvt_pk_bf16_f32 v27, v46, v47
	ds_read_b64 v[30:31], v179 offset:37312
	ds_read_b64 v[34:35], v179 offset:45760
	v_mov_b32_e32 v29, v147
	v_mov_b32_e32 v36, v147
	v_mov_b32_e32 v37, v147
	s_waitcnt lgkmcnt(1)
	v_mfma_f32_16x16x32_bf16 v[14:17], v[30:33], v[26:29], v[14:17]
	ds_bpermute_b32 v30, v66, v44
	v_fma_f32 v31, v64, s61, -v82
	v_exp_f32_e32 v31, v31
	ds_read_b64 v[38:39], v179 offset:54208
	ds_read_b64 v[42:43], v179 offset:62656
	v_mov_b32_e32 v40, v147
	s_waitcnt lgkmcnt(2)
	v_add_f32_e32 v30, v44, v30
	v_add_f32_e32 v30, v31, v30
	v_mov_b32_e32 v41, v147
	v_mov_b32_e32 v44, v147
	v_mov_b32_e32 v45, v147
	v_div_scale_f32 v31, s[68:69], v30, v30, 1.0
	v_rcp_f32_e32 v32, v31
	v_mfma_f32_16x16x32_bf16 v[22:25], v[34:37], v[26:29], v[22:25]
	s_waitcnt lgkmcnt(1)
	v_mfma_f32_16x16x32_bf16 v[18:21], v[38:41], v[26:29], v[18:21]
	s_waitcnt lgkmcnt(0)
	v_mfma_f32_16x16x32_bf16 v[10:13], v[42:45], v[26:29], v[10:13]
	v_fma_f32 v26, -v31, v32, 1.0
	v_fmac_f32_e32 v32, v26, v32
	v_div_scale_f32 v26, vcc, 1.0, v30, 1.0
	v_mul_f32_e32 v27, v26, v32
	v_fma_f32 v28, -v31, v27, v26
	v_fmac_f32_e32 v27, v28, v32
	v_fma_f32 v26, -v31, v27, v26
	v_div_fmas_f32 v26, v26, v32, v27
	v_div_fixup_f32 v26, v26, v30, 1.0
	v_pk_mul_f32 v[16:17], v[26:27], v[16:17] op_sel_hi:[0,1]
	v_pk_mul_f32 v[14:15], v[26:27], v[14:15] op_sel_hi:[0,1]
	v_add_co_u32_e32 v50, vcc, s57, v62
	v_cvt_pk_bf16_f32 v14, v14, v15
	v_cvt_pk_bf16_f32 v15, v16, v17
	v_pk_mul_f32 v[16:17], v[26:27], v[22:23] op_sel_hi:[0,1]
	s_nop 0
	v_addc_co_u32_e32 v51, vcc, 0, v63, vcc
	global_store_dwordx2 v[50:51], v[14:15], off
	v_pk_mul_f32 v[14:15], v[26:27], v[24:25] op_sel_hi:[0,1]
	v_cvt_pk_bf16_f32 v16, v16, v17
	v_cvt_pk_bf16_f32 v17, v14, v15
	global_store_dwordx2 v[50:51], v[16:17], off offset:32
	v_pk_mul_f32 v[16:17], v[26:27], v[18:19] op_sel_hi:[0,1]
	v_pk_mul_f32 v[14:15], v[26:27], v[20:21] op_sel_hi:[0,1]
	v_cvt_pk_bf16_f32 v16, v16, v17
	v_cvt_pk_bf16_f32 v17, v14, v15
	v_pk_mul_f32 v[12:13], v[26:27], v[12:13] op_sel_hi:[0,1]
	v_pk_mul_f32 v[10:11], v[26:27], v[10:11] op_sel_hi:[0,1]
	global_store_dwordx2 v[50:51], v[16:17], off offset:64
	v_cvt_pk_bf16_f32 v52, v10, v11
	v_cvt_pk_bf16_f32 v53, v12, v13
	ds_read_b128 v[10:13], v178 offset:16128
	ds_read_b128 v[14:17], v178 offset:16192
	s_waitcnt lgkmcnt(1)
	v_mfma_f32_16x16x32_bf16 v[10:13], v[10:13], v[2:5], 0
	ds_read_b128 v[18:21], v178 offset:18432
	ds_read_b128 v[22:25], v178 offset:20736
	ds_read_b128 v[26:29], v178 offset:23040
	s_waitcnt lgkmcnt(3)
	v_mfma_f32_16x16x32_bf16 v[14:17], v[14:17], v[6:9], v[10:13]
	ds_read_b128 v[30:33], v178 offset:25344
	ds_read_b128 v[34:37], v178 offset:27648
	ds_read_b128 v[38:41], v178 offset:29952
	ds_read_b128 v[10:13], v178 offset:18496
	s_waitcnt lgkmcnt(6)
; #define LAS __attribute__((address_space(3)))
; __device__ __forceinline__ void attn_unit(LAS unsigned char* lds, bf16* Q, const bf16* Kg, const bf16* Vg, const float* snk, int unit, int tid) {
;     ...
;     for (int mt = 0; mt < 8; ++mt) {
;         f32x4 st[9];
; #pragma unroll
;         for (int kb = 0; kb < 9; ++kb) { const LAS unsigned char* kp = lds + (16 * (mt + kb) + fr) * ATT_KP + 16 * fq;
;             const bf16x8_t k0 = *(const LAS bf16x8_t*)kp, k1 = *(const LAS bf16x8_t*)(kp + 64);
;             f32x4 z = {0.f, 0.f, 0.f, 0.f}; z = __builtin_amdgcn_mfma_f32_16x16x32_bf16(k0, qf[mt][0], z, 0, 0, 0); z = __builtin_amdgcn_mfma_f32_16x16x32_bf16(k1, qf[mt][1], z, 0, 0, 0); st[kb] = z; }
;         float mx = sink;
; #pragma unroll
;         for (int kb = 0; kb < 9; ++kb) {
;             const bool tile_ok = (n > 0) || (mt + kb >= 8);
; #pragma unroll
;             for (int i = 0; i < 4; ++i) { const bool ok = tile_ok && (kb == 0 ? lo_ok[i] : (kb == 8 ? !lo_ok[i] : true));
;                 st[kb][i] = ok ? st[kb][i] : -INFINITY; mx = fmaxf(mx, st[kb][i]); }
;         }
;         mx = fmaxf(mx, __shfl_xor(mx, 16)); mx = fmaxf(mx, __shfl_xor(mx, 32));
;         f32x4 ls4 = {0.f, 0.f, 0.f, 0.f};
; #pragma unroll
;         for (int kb = 0; kb < 9; ++kb) { f32x4 d = st[kb] - mx;
; #pragma unroll
;             for (int i = 0; i < 4; ++i) d[i] = __builtin_amdgcn_exp2f(d[i]);
;             st[kb] = d; ls4 = ls4 + d; }
;         float ls = (ls4[0] + ls4[1]) + (ls4[2] + ls4[3]);
;         ls += __shfl_xor(ls, 16); ls += __shfl_xor(ls, 32);
;         const float inv = 1.f / (ls + __builtin_amdgcn_exp2f(sink - mx));
	v_mfma_f32_16x16x32_bf16 v[18:21], v[18:21], v[2:5], 0
	ds_read_b128 v[42:45], v178 offset:32256
	ds_read_b128 v[46:49], v178 offset:34560
	global_store_dwordx2 v[50:51], v[52:53], off offset:96
	s_waitcnt lgkmcnt(2)
	v_mfma_f32_16x16x32_bf16 v[18:21], v[10:13], v[6:9], v[18:21]
	ds_read_b128 v[10:13], v178 offset:20800
	v_mfma_f32_16x16x32_bf16 v[22:25], v[22:25], v[2:5], 0
	s_waitcnt lgkmcnt(0)
	v_mfma_f32_16x16x32_bf16 v[22:25], v[10:13], v[6:9], v[22:25]
	ds_read_b128 v[10:13], v178 offset:23104
	v_mfma_f32_16x16x32_bf16 v[26:29], v[26:29], v[2:5], 0
	s_waitcnt lgkmcnt(0)
	v_mfma_f32_16x16x32_bf16 v[26:29], v[10:13], v[6:9], v[26:29]
	ds_read_b128 v[10:13], v178 offset:25408
	v_mfma_f32_16x16x32_bf16 v[30:33], v[30:33], v[2:5], 0
	s_waitcnt lgkmcnt(0)
	v_mfma_f32_16x16x32_bf16 v[30:33], v[10:13], v[6:9], v[30:33]
	ds_read_b128 v[10:13], v178 offset:27712
	v_mfma_f32_16x16x32_bf16 v[34:37], v[34:37], v[2:5], 0
	s_waitcnt lgkmcnt(0)
	v_mfma_f32_16x16x32_bf16 v[34:37], v[10:13], v[6:9], v[34:37]
	ds_read_b128 v[10:13], v178 offset:30016
	v_mfma_f32_16x16x32_bf16 v[38:41], v[38:41], v[2:5], 0
	s_waitcnt lgkmcnt(0)
	v_mfma_f32_16x16x32_bf16 v[38:41], v[10:13], v[6:9], v[38:41]
	ds_read_b128 v[10:13], v178 offset:32320
	v_mfma_f32_16x16x32_bf16 v[42:45], v[42:45], v[2:5], 0
	s_waitcnt lgkmcnt(0)
	v_mfma_f32_16x16x32_bf16 v[10:13], v[10:13], v[6:9], v[42:45]
	s_nop 5
	ds_read_b128 v[42:45], v178 offset:34624
	v_mfma_f32_16x16x32_bf16 v[2:5], v[46:49], v[2:5], 0
	s_waitcnt lgkmcnt(0)
	v_mfma_f32_16x16x32_bf16 v[2:5], v[42:45], v[6:9], v[2:5]
	v_cndmask_b32_e64 v7, v15, v190, s[10:11]
	v_cndmask_b32_e64 v6, v190, v14, s[20:21]
	v_cndmask_b32_e64 v7, v190, v7, s[16:17]
	v_max3_f32 v8, v71, v6, v7
	v_cndmask_b32_e64 v9, v190, v16, s[18:19]
	v_cndmask_b32_e64 v14, v190, v17, s[22:23]
	v_max3_f32 v8, v8, v9, v14
	v_max3_f32 v8, v8, v18, v19
	v_max3_f32 v8, v8, v20, v21
	v_max3_f32 v8, v8, v22, v23
	v_max3_f32 v8, v8, v24, v25
	v_max3_f32 v8, v8, v26, v27
	v_max3_f32 v8, v8, v28, v29
	v_max3_f32 v8, v8, v30, v31
	v_max3_f32 v8, v8, v32, v33
	v_max3_f32 v8, v8, v34, v35
	v_max3_f32 v8, v8, v36, v37
	v_max3_f32 v8, v8, v38, v39
	v_max3_f32 v8, v8, v40, v41
	v_max3_f32 v8, v8, v10, v11
	v_max3_f32 v8, v8, v12, v13
	v_cndmask_b32_e64 v60, v2, v190, s[8:9]
	v_cndmask_b32_e64 v61, v190, v3, s[10:11]
	v_max3_f32 v2, v8, v60, v61
	v_cndmask_b32_e64 v71, v4, v190, s[12:13]
	v_cndmask_b32_e64 v72, v5, v190, s[14:15]
	v_max3_f32 v2, v2, v71, v72
	ds_bpermute_b32 v3, v65, v2
	s_waitcnt lgkmcnt(0)
	v_max_f32_e32 v3, v3, v3
	v_max_f32_e32 v2, v2, v3
	ds_bpermute_b32 v3, v66, v2
	s_waitcnt lgkmcnt(0)
	v_max_f32_e32 v3, v3, v3
	v_max_f32_e32 v73, v2, v3
	v_sub_f32_e32 v3, v14, v73
	v_sub_f32_e32 v4, v9, v73
	v_sub_f32_e32 v7, v7, v73
	v_sub_f32_e32 v2, v6, v73
	v_exp_f32_e32 v2, v2
	v_exp_f32_e32 v4, v4
	v_exp_f32_e32 v5, v3
	v_exp_f32_e32 v3, v7
	v_sub_f32_e32 v17, v21, v73
	v_sub_f32_e32 v16, v20, v73
	v_sub_f32_e32 v15, v19, v73
	v_sub_f32_e32 v14, v18, v73
	v_exp_f32_e32 v14, v14
	v_exp_f32_e32 v15, v15
	v_exp_f32_e32 v16, v16
	v_exp_f32_e32 v17, v17
	v_sub_f32_e32 v18, v25, v73
	v_sub_f32_e32 v19, v24, v73
	v_sub_f32_e32 v20, v23, v73
	v_sub_f32_e32 v21, v22, v73
	v_exp_f32_e32 v42, v21
	v_exp_f32_e32 v44, v19
	v_exp_f32_e32 v45, v18
	v_exp_f32_e32 v43, v20
	v_sub_f32_e32 v18, v29, v73
	v_sub_f32_e32 v19, v28, v73
	v_sub_f32_e32 v20, v27, v73
	v_sub_f32_e32 v21, v26, v73
	v_exp_f32_e32 v28, v21
	v_exp_f32_e32 v29, v20
	v_exp_f32_e32 v46, v19
	v_exp_f32_e32 v47, v18
	v_sub_f32_e32 v18, v33, v73
	v_sub_f32_e32 v19, v32, v73
	v_sub_f32_e32 v20, v31, v73
	v_sub_f32_e32 v21, v30, v73
	v_pk_add_f32 v[6:7], v[4:5], 0 op_sel_hi:[1,0]
	v_pk_add_f32 v[8:9], v[2:3], 0 op_sel_hi:[1,0]
	v_exp_f32_e32 v48, v21
	v_exp_f32_e32 v50, v19
	v_exp_f32_e32 v51, v18
	v_exp_f32_e32 v49, v20
	v_pk_add_f32 v[8:9], v[14:15], v[8:9]
	v_pk_add_f32 v[6:7], v[16:17], v[6:7]
	v_pk_add_f32 v[8:9], v[42:43], v[8:9]
	v_pk_add_f32 v[6:7], v[44:45], v[6:7]
	v_pk_add_f32 v[8:9], v[28:29], v[8:9]
	v_pk_add_f32 v[6:7], v[46:47], v[6:7]
	v_sub_f32_e32 v20, v34, v73
	v_pk_add_f32 v[18:19], v[50:51], v[6:7]
	v_pk_add_f32 v[6:7], v[48:49], v[8:9]
	v_sub_f32_e32 v9, v35, v73
	v_sub_f32_e32 v8, v37, v73
	v_exp_f32_e32 v53, v9
	v_sub_f32_e32 v9, v36, v73
	v_exp_f32_e32 v52, v20
	v_exp_f32_e32 v54, v9
	v_exp_f32_e32 v55, v8
	v_sub_f32_e32 v22, v41, v73
	v_sub_f32_e32 v23, v40, v73
	v_sub_f32_e32 v24, v39, v73
	v_sub_f32_e32 v25, v38, v73
	v_exp_f32_e32 v38, v23
	v_exp_f32_e32 v39, v22
	v_exp_f32_e32 v40, v25
	v_exp_f32_e32 v41, v24
	v_pk_add_f32 v[20:21], v[52:53], v[6:7]
	v_pk_add_f32 v[18:19], v[54:55], v[18:19]
	v_cvt_pk_bf16_f32 v2, v2, v3
	v_cvt_pk_bf16_f32 v3, v4, v5
	v_cvt_pk_bf16_f32 v4, v14, v15
	v_cvt_pk_bf16_f32 v5, v16, v17
	ds_read2_b64 v[6:9], v67 offset0:28 offset1:32
	ds_read2_b64 v[14:17], v68 offset0:60 offset1:64
	v_pk_add_f32 v[56:57], v[38:39], v[18:19]
	v_pk_add_f32 v[58:59], v[40:41], v[20:21]
	ds_read2_b64 v[18:21], v70 offset0:92 offset1:96
	ds_read2_b64 v[22:25], v69 offset0:124 offset1:128
	v_sub_f32_e32 v12, v12, v73
	v_sub_f32_e32 v11, v11, v73
	v_sub_f32_e32 v10, v10, v73
	v_sub_f32_e32 v74, v13, v73
	v_cvt_pk_bf16_f32 v26, v42, v43
	v_cvt_pk_bf16_f32 v27, v44, v45
	v_cvt_pk_bf16_f32 v28, v28, v29
	v_cvt_pk_bf16_f32 v29, v46, v47
	ds_read2_b64 v[30:33], v67 offset0:36 offset1:40
	v_exp_f32_e32 v42, v10
	v_exp_f32_e32 v43, v11
	v_exp_f32_e32 v44, v12
	ds_read2_b64 v[10:13], v70 offset0:100 offset1:104
	s_waitcnt lgkmcnt(5)
; __device__ __forceinline__ unsigned cvt_pk_bf16(float lo, float hi) { unsigned r; asm volatile("v_cvt_pk_bf16_f32 %0, %1, %2" : "=v"(r) : "v"(lo), "v"(hi)); return r; }
; #define LAS __attribute__((address_space(3)))
; __device__ __forceinline__ void attn_unit(LAS unsigned char* lds, bf16* Q, const bf16* Kg, const bf16* Vg, const float* snk, int unit, int tid) {
;     ...
; #pragma unroll
;         for (int kp = 0; kp < 5; ++kp) {
;             v4u pw; pw.x = cvt_pk_bf16(st[2 * kp][0], st[2 * kp][1]); pw.y = cvt_pk_bf16(st[2 * kp][2], st[2 * kp][3]);
;             if (kp < 4) { pw.z = cvt_pk_bf16(st[(2 * kp + 1) % 9][0], st[(2 * kp + 1) % 9][1]); pw.w = cvt_pk_bf16(st[(2 * kp + 1) % 9][2], st[(2 * kp + 1) % 9][3]); } else { pw.z = 0u; pw.w = 0u; }
;             const bf16x8_t pb = __builtin_bit_cast(bf16x8_t, pw);
; #pragma unroll
;             for (int dt = 0; dt < 4; ++dt) { const LAS unsigned char* vp = lds + ATT_VOFF + (16 * dt + fr) * ATT_VP + (16 * (mt + 2 * kp) + 4 * fq) * 2;
;                 const v2u lo = *(const LAS v2u*)vp; v2u hi = {0u, 0u}; if (kp < 4) hi = *(const LAS v2u*)(vp + 32);
;                 v4u aw; aw.x = lo.x; aw.y = lo.y; aw.z = hi.x; aw.w = hi.y;
;                 o[dt] = __builtin_amdgcn_mfma_f32_16x16x32_bf16(__builtin_bit_cast(bf16x8_t, aw), pb, o[dt], 0, 0, 0); }
;         }
; #pragma unroll
;         for (int dt = 0; dt < 4; ++dt) { const f32x4 y = o[dt] * inv; v2u w; w.x = cvt_pk_bf16(y[0], y[1]); w.y = cvt_pk_bf16(y[2], y[3]); *(v2u*)(qbase + (size_t)mt * 16 * 1024 + 16 * dt + 4 * fq) = w; }
;     }
;     __syncthreads();
	v_mfma_f32_16x16x32_bf16 v[6:9], v[6:9], v[2:5], 0
	ds_read2_b64 v[34:37], v68 offset0:68 offset1:72
	v_exp_f32_e32 v45, v74
	v_pk_add_f32 v[46:47], v[42:43], v[58:59]
	s_waitcnt lgkmcnt(5)
	v_mfma_f32_16x16x32_bf16 v[14:17], v[14:17], v[2:5], 0
	s_waitcnt lgkmcnt(4)
	v_mfma_f32_16x16x32_bf16 v[18:21], v[18:21], v[2:5], 0
	s_waitcnt lgkmcnt(3)
	v_mfma_f32_16x16x32_bf16 v[2:5], v[22:25], v[2:5], 0
	ds_read2_b64 v[22:25], v69 offset0:132 offset1:136
	s_waitcnt lgkmcnt(3)
	v_mfma_f32_16x16x32_bf16 v[6:9], v[30:33], v[26:29], v[6:9]
	v_cvt_pk_bf16_f32 v30, v48, v49
	v_cvt_pk_bf16_f32 v31, v50, v51
	v_cvt_pk_bf16_f32 v32, v52, v53
	v_cvt_pk_bf16_f32 v33, v54, v55
	s_waitcnt lgkmcnt(2)
	v_mfma_f32_16x16x32_bf16 v[10:13], v[10:13], v[26:29], v[18:21]
	v_sub_f32_e32 v51, v72, v73
	v_sub_f32_e32 v52, v71, v73
	v_sub_f32_e32 v53, v61, v73
	ds_read2_b64 v[18:21], v68 offset0:76 offset1:80
	s_waitcnt lgkmcnt(2)
	v_mfma_f32_16x16x32_bf16 v[14:17], v[34:37], v[26:29], v[14:17]
	ds_read2_b64 v[34:37], v67 offset0:44 offset1:48
	v_pk_add_f32 v[48:49], v[44:45], v[56:57]
	s_waitcnt lgkmcnt(2)
	v_mfma_f32_16x16x32_bf16 v[2:5], v[22:25], v[26:29], v[2:5]
	ds_read2_b64 v[22:25], v70 offset0:108 offset1:112
	v_sub_f32_e32 v26, v60, v73
	v_exp_f32_e32 v50, v26
	s_waitcnt lgkmcnt(2)
	v_mfma_f32_16x16x32_bf16 v[14:17], v[18:21], v[30:33], v[14:17]
	ds_read2_b64 v[18:21], v69 offset0:140 offset1:144
	v_cvt_pk_bf16_f32 v26, v40, v41
	v_cvt_pk_bf16_f32 v27, v38, v39
	v_cvt_pk_bf16_f32 v28, v42, v43
	v_cvt_pk_bf16_f32 v29, v44, v45
	s_waitcnt lgkmcnt(1)
	v_mfma_f32_16x16x32_bf16 v[10:13], v[22:25], v[30:33], v[10:13]
	ds_read2_b64 v[22:25], v68 offset0:84 offset1:88
	v_exp_f32_e32 v38, v52
	v_exp_f32_e32 v39, v51
	v_mfma_f32_16x16x32_bf16 v[6:9], v[34:37], v[30:33], v[6:9]
	ds_read2_b64 v[34:37], v67 offset0:52 offset1:56
	v_exp_f32_e32 v51, v53
	s_waitcnt lgkmcnt(2)
	v_mfma_f32_16x16x32_bf16 v[2:5], v[18:21], v[30:33], v[2:5]
	ds_read2_b64 v[18:21], v70 offset0:116 offset1:120
	v_pk_add_f32 v[30:31], v[38:39], v[48:49]
	v_pk_add_f32 v[32:33], v[50:51], v[46:47]
	s_waitcnt lgkmcnt(2)
	v_mfma_f32_16x16x32_bf16 v[14:17], v[22:25], v[26:29], v[14:17]
	ds_read2_b64 v[22:25], v69 offset0:148 offset1:152
	s_waitcnt lgkmcnt(2)
	v_mfma_f32_16x16x32_bf16 v[6:9], v[34:37], v[26:29], v[6:9]
	v_pk_mov_b32 v[34:35], v[32:33], v[30:31] op_sel:[1,0]
	v_mov_b32_e32 v33, v31
	v_pk_add_f32 v[30:31], v[34:35], v[32:33]
	s_waitcnt lgkmcnt(1)
	v_mfma_f32_16x16x32_bf16 v[10:13], v[18:21], v[26:29], v[10:13]
	v_add_f32_e32 v30, v30, v31
	ds_bpermute_b32 v18, v65, v30
	v_mov_b32_e32 v20, v147
	s_waitcnt lgkmcnt(1)
	v_mfma_f32_16x16x32_bf16 v[2:5], v[22:25], v[26:29], v[2:5]
	v_mov_b32_e32 v24, v147
	v_mov_b32_e32 v25, v147
	s_waitcnt lgkmcnt(0)
	v_add_f32_e32 v36, v30, v18
	v_cvt_pk_bf16_f32 v18, v50, v51
	v_cvt_pk_bf16_f32 v19, v38, v39
	ds_read_b64 v[22:23], v179 offset:37344
	ds_read_b64 v[26:27], v179 offset:45792
	v_mov_b32_e32 v21, v147
	v_mov_b32_e32 v28, v147
	v_mov_b32_e32 v29, v147
	s_waitcnt lgkmcnt(1)
	v_mfma_f32_16x16x32_bf16 v[6:9], v[22:25], v[18:21], v[6:9]
	ds_bpermute_b32 v22, v66, v36
	v_fma_f32 v23, v64, s61, -v73
	v_exp_f32_e32 v23, v23
	ds_read_b64 v[30:31], v179 offset:54240
	ds_read_b64 v[34:35], v179 offset:62688
	v_mov_b32_e32 v32, v147
	s_waitcnt lgkmcnt(2)
	v_add_f32_e32 v22, v36, v22
	v_add_f32_e32 v22, v23, v22
	v_mov_b32_e32 v33, v147
	v_mov_b32_e32 v36, v147
	v_mov_b32_e32 v37, v147
	v_div_scale_f32 v23, s[16:17], v22, v22, 1.0
	v_rcp_f32_e32 v24, v23
	v_mfma_f32_16x16x32_bf16 v[14:17], v[26:29], v[18:21], v[14:17]
	s_waitcnt lgkmcnt(1)
	v_mfma_f32_16x16x32_bf16 v[10:13], v[30:33], v[18:21], v[10:13]
	s_waitcnt lgkmcnt(0)
	v_mfma_f32_16x16x32_bf16 v[2:5], v[34:37], v[18:21], v[2:5]
	v_fma_f32 v18, -v23, v24, 1.0
	v_fmac_f32_e32 v24, v18, v24
	v_div_scale_f32 v18, vcc, 1.0, v22, 1.0
	v_mul_f32_e32 v19, v18, v24
	v_fma_f32 v20, -v23, v19, v18
	v_fmac_f32_e32 v19, v20, v24
	v_fma_f32 v18, -v23, v19, v18
	v_div_fmas_f32 v18, v18, v24, v19
	v_div_fixup_f32 v18, v18, v22, 1.0
	v_pk_mul_f32 v[8:9], v[18:19], v[8:9] op_sel_hi:[0,1]
	v_pk_mul_f32 v[6:7], v[18:19], v[6:7] op_sel_hi:[0,1]
	v_cvt_pk_bf16_f32 v6, v6, v7
	v_cvt_pk_bf16_f32 v7, v8, v9
	v_add_co_u32_e32 v8, vcc, s58, v62
	v_pk_mul_f32 v[14:15], v[18:19], v[14:15] op_sel_hi:[0,1]
	s_nop 0
	v_addc_co_u32_e32 v9, vcc, 0, v63, vcc
	global_store_dwordx2 v[8:9], v[6:7], off
	v_pk_mul_f32 v[6:7], v[18:19], v[16:17] op_sel_hi:[0,1]
	v_pk_mul_f32 v[10:11], v[18:19], v[10:11] op_sel_hi:[0,1]
	v_pk_mul_f32 v[2:3], v[18:19], v[2:3] op_sel_hi:[0,1]
	v_cvt_pk_bf16_f32 v14, v14, v15
	v_cvt_pk_bf16_f32 v15, v6, v7
	global_store_dwordx2 v[8:9], v[14:15], off offset:32
	v_pk_mul_f32 v[6:7], v[18:19], v[12:13] op_sel_hi:[0,1]
	v_cvt_pk_bf16_f32 v10, v10, v11
	v_cvt_pk_bf16_f32 v11, v6, v7
	global_store_dwordx2 v[8:9], v[10:11], off offset:64
	v_pk_mul_f32 v[4:5], v[18:19], v[4:5] op_sel_hi:[0,1]
	v_cvt_pk_bf16_f32 v2, v2, v3
	v_cvt_pk_bf16_f32 v3, v4, v5
	global_store_dwordx2 v[8:9], v[2:3], off offset:96
	s_barrier

; #define LAS __attribute__((address_space(3)))
; __device__ __forceinline__ void sgu_unit(LAS unsigned char* lds, bf16* U, const bf16* VS, const float* SGS, const float* lnw, const float* lnb, const v4u* WF, const float* bsl, int unit, int tid) {
;     const int lane = tid & 63, wave = tid >> 6, fr = lane & 15, fq = lane >> 4;
;     const int ch = unit >> 1, hf = unit & 1, r0 = ch * 128, g = 4 * hf + (wave >> 1), colbase = g * 128 + (wave & 1) * 64;
;     LAS float* stat = (LAS float*)(lds + SGU_STAT);
;     v4u wfr[20]; float bbv[8];
; #pragma unroll
;     for (int q = 0; q < 20; ++q) wfr[q] = WF[(size_t)(g * 20 + q) * 64 + lane];
; #pragma unroll
;     for (int mt = 0; mt < 8; ++mt) bbv[mt] = bsl[g * 128 + 16 * mt + fr];
;     if (tid < 128) {
;         const f32x4* p = (const f32x4*)(SGS + (size_t)(r0 + tid) * 32);
;         float s = 0.f, ss = 0.f;
; #pragma unroll
;         for (int k = 0; k < 8; ++k) { const f32x4 v = p[k]; s += v.x + v.z; ss += v.y + v.w; }
;         const float mean = s * (1.f / 1024.f), var = fmaxf(ss * (1.f / 1024.f) - mean * mean, 0.f);
;         stat[2 * tid] = mean; stat[2 * tid + 1] = rsqrtf(var + 1e-6f);
;     }
; __global__ void __launch_bounds__(512, 2) fwd_mega(Args a) {
;     ...
;             for (int it = bx; it < 512; it += G) {
;                 if (it < 256) attn_unit(lds, WSP(WS_Q), WSP(WS_K), WSP(WS_V), INF(7) + l * 16, it, tid_);
;                 else sgu_unit(lds, WSP(WS_U), WSP(WS_VS), (const float*)(a.ws + WS_SGS), INF(8) + l * 1024, INF(9) + l * 1024, (const v4u*)(a.ws + WS_WF), INF(11) + l * 8 * 128, it - 256, tid_);
.LBB0_1398:
	s_cmpk_gt_i32 s62, 0xff
	s_mov_b64 s[16:17], -1
	s_cbranch_scc0 .LBB0_1402
	s_waitcnt vmcnt(0)
	s_and_b32 s16, s4, 4
	v_add_u32_e32 v82, s16, v165
	v_mul_lo_u32 v2, v82, 20
	v_or_b32_e32 v6, 1, v2
	v_ashrrev_i32_e32 v3, 31, v2
	v_ashrrev_i32_e32 v7, 31, v6
	v_lshlrev_b64 v[4:5], 10, v[2:3]
	v_lshlrev_b64 v[6:7], 10, v[6:7]
	v_lshl_add_u64 v[4:5], v[148:149], 0, v[4:5]
	v_lshl_add_u64 v[6:7], v[148:149], 0, v[6:7]
	global_load_dwordx4 v[78:81], v[4:5], off
	global_load_dwordx4 v[74:77], v[6:7], off
	v_or_b32_e32 v6, 2, v2
	v_or_b32_e32 v2, 3, v2
	v_ashrrev_i32_e32 v7, 31, v6
	v_ashrrev_i32_e32 v3, 31, v2
	v_lshlrev_b64 v[6:7], 10, v[6:7]
	v_lshlrev_b64 v[2:3], 10, v[2:3]
	v_lshl_add_u64 v[6:7], v[148:149], 0, v[6:7]
	v_lshl_add_u64 v[2:3], v[148:149], 0, v[2:3]
	global_load_dwordx4 v[70:73], v[6:7], off
	global_load_dwordx4 v[66:69], v[2:3], off
	v_add_co_u32_e32 v2, vcc, s34, v4
	v_lshlrev_b32_e32 v82, 7, v82
	s_nop 0
	v_addc_co_u32_e32 v3, vcc, 0, v5, vcc
	v_add_co_u32_e32 v6, vcc, s35, v4
	v_or_b32_e32 v84, v82, v163
	s_nop 0
	v_addc_co_u32_e32 v7, vcc, 0, v5, vcc
	v_add_co_u32_e32 v8, vcc, s36, v4
	global_load_dwordx4 v[58:61], v[2:3], off offset:1024
	global_load_dwordx4 v[50:53], v[2:3], off offset:2048
	global_load_dwordx4 v[62:65], v[6:7], off offset:-4096
	global_load_dwordx4 v[46:49], v[6:7], off
	global_load_dwordx4 v[42:45], v[6:7], off offset:1024
	global_load_dwordx4 v[34:37], v[6:7], off offset:2048
	v_addc_co_u32_e32 v9, vcc, 0, v5, vcc
	v_add_co_u32_e32 v4, vcc, s37, v4
	v_ashrrev_i32_e32 v85, 31, v84
	s_nop 0
	v_addc_co_u32_e32 v5, vcc, 0, v5, vcc
	global_load_dwordx4 v[38:41], v[6:7], off offset:3072
	global_load_dwordx4 v[30:33], v[4:5], off offset:-4096
	global_load_dwordx4 v[54:57], v[2:3], off offset:3072
	global_load_dwordx4 v[26:29], v[8:9], off offset:1024
	global_load_dwordx4 v[22:25], v[8:9], off offset:2048
	global_load_dwordx4 v[18:21], v[8:9], off offset:3072
	global_load_dwordx4 v[14:17], v[4:5], off
	global_load_dwordx4 v[10:13], v[4:5], off offset:1024
	s_nop 0
	global_load_dwordx4 v[6:9], v[4:5], off offset:2048
	s_nop 0
	global_load_dwordx4 v[2:5], v[4:5], off offset:3072
	v_lshl_add_u64 v[84:85], v[84:85], 2, s[44:45]
	global_load_dword v197, v[84:85], off
	global_load_dword v196, v[84:85], off offset:64
	global_load_dword v195, v[84:85], off offset:128
	global_load_dword v194, v[84:85], off offset:192
	global_load_dword v193, v[84:85], off offset:256
	global_load_dword v192, v[84:85], off offset:320
	global_load_dword v191, v[84:85], off offset:384
	global_load_dword v157, v[84:85], off offset:448
	s_add_i32 s16, s24, 0xffffc000
	s_and_b32 s18, s16, 0x3f80
	s_and_saveexec_b64 s[16:17], s[6:7]
	s_cbranch_execz .LBB0_1401
	v_add_u32_e32 v84, s18, v161
	v_ashrrev_i32_e32 v85, 31, v84
	v_lshlrev_b64 v[84:85], 7, v[84:85]
	v_lshl_add_u64 v[112:113], s[46:47], 0, v[84:85]
	global_load_dwordx4 v[84:87], v[112:113], off
	global_load_dwordx4 v[88:91], v[112:113], off offset:16
	global_load_dwordx4 v[92:95], v[112:113], off offset:32
	global_load_dwordx4 v[96:99], v[112:113], off offset:48
	global_load_dwordx4 v[100:103], v[112:113], off offset:64
	global_load_dwordx4 v[104:107], v[112:113], off offset:80
	global_load_dwordx4 v[108:111], v[112:113], off offset:96
	s_nop 0
	global_load_dwordx4 v[112:115], v[112:113], off offset:112
	s_waitcnt vmcnt(7)
	v_pk_add_f32 v[84:85], v[84:85], v[86:87]
	s_waitcnt vmcnt(6)
	v_pk_add_f32 v[86:87], v[88:89], v[90:91]
	v_pk_add_f32 v[84:85], v[84:85], 0 op_sel_hi:[1,0]
	s_waitcnt vmcnt(5)
	v_pk_add_f32 v[88:89], v[92:93], v[94:95]
	v_pk_add_f32 v[84:85], v[84:85], v[86:87]
	s_waitcnt vmcnt(4)
	v_pk_add_f32 v[90:91], v[96:97], v[98:99]
	v_pk_add_f32 v[84:85], v[84:85], v[88:89]
	s_waitcnt vmcnt(3)
	v_pk_add_f32 v[92:93], v[100:101], v[102:103]
	v_pk_add_f32 v[84:85], v[84:85], v[90:91]
	s_waitcnt vmcnt(2)
	v_pk_add_f32 v[94:95], v[104:105], v[106:107]
	v_pk_add_f32 v[84:85], v[84:85], v[92:93]
	s_waitcnt vmcnt(1)
	v_pk_add_f32 v[96:97], v[108:109], v[110:111]
	v_pk_add_f32 v[84:85], v[84:85], v[94:95]
	s_waitcnt vmcnt(0)
	v_pk_add_f32 v[98:99], v[112:113], v[114:115]
	v_pk_add_f32 v[84:85], v[84:85], v[96:97]
	v_add_u32_e32 v86, 0, v167
	v_pk_add_f32 v[84:85], v[84:85], v[98:99]
	s_nop 0
	v_pk_mul_f32 v[84:85], v[84:85], s[52:53] op_sel_hi:[1,0]
	s_nop 0
	v_fma_f32 v83, -v84, v84, v85
	v_max_f32_e32 v83, 0, v83
	v_add_f32_e32 v83, 0x358637bd, v83
	v_mul_f32_e32 v85, 0x4b800000, v83
	v_cmp_gt_f32_e32 vcc, s42, v83
	s_nop 1
	v_cndmask_b32_e32 v83, v83, v85, vcc
	v_rsq_f32_e32 v83, v83
	s_nop 0
	v_mul_f32_e32 v85, 0x45800000, v83
	v_cndmask_b32_e32 v85, v83, v85, vcc
	ds_write_b64 v86, v[84:85]
; __device__ __forceinline__ unsigned cvt_pk_bf16(float lo, float hi) { unsigned r; asm volatile("v_cvt_pk_bf16_f32 %0, %1, %2" : "=v"(r) : "v"(lo), "v"(hi)); return r; }
; __device__ __forceinline__ float bf_lo(unsigned w) { return __uint_as_float(w << 16); }
; __device__ __forceinline__ float bf_hi(unsigned w) { return __uint_as_float(w & 0xffff0000u); }
; #define LAS __attribute__((address_space(3)))
; __device__ __forceinline__ void sgu_unit(LAS unsigned char* lds, bf16* U, const bf16* VS, const float* SGS, const float* lnw, const float* lnb, const v4u* WF, const float* bsl, int unit, int tid) {
;     ...
;     LAS unsigned char* vt = lds + SGU_VT + wave * SGU_WREG;
;     {
;         const int c8 = lane & 7, rp = lane >> 3, col = colbase + 8 * c8;
;         v4u sl[8][2];
; #pragma unroll
;         for (int i = 0; i < 8; ++i) { const int s0 = 2 * (rp + 8 * i); sl[i][0] = *(const v4u*)(VS + (size_t)(r0 + s0) * 1024 + col); sl[i][1] = *(const v4u*)(VS + (size_t)(r0 + s0 + 1) * 1024 + col); }
;         const f32x4 lw0 = *(const f32x4*)(lnw + col), lw1 = *(const f32x4*)(lnw + col + 4), lb0 = *(const f32x4*)(lnb + col), lb1 = *(const f32x4*)(lnb + col + 4);
;         const float lw[8] = {lw0.x, lw0.y, lw0.z, lw0.w, lw1.x, lw1.y, lw1.z, lw1.w}, lb[8] = {lb0.x, lb0.y, lb0.z, lb0.w, lb1.x, lb1.y, lb1.z, lb1.w};
;         __syncthreads();
;         LAS unsigned char* wbase = vt + c8 * SGU_VP + rp * 4;
; #pragma unroll
;         for (int i = 0; i < 8; ++i) {
;             const f32x4 st4 = *(const LAS f32x4*)(stat + 4 * (rp + 8 * i));
;             const v4u w0 = sl[i][0], w1 = sl[i][1];
;             const unsigned A0[4] = {w0.x, w0.y, w0.z, w0.w}, A1[4] = {w1.x, w1.y, w1.z, w1.w};
; #pragma unroll
;             for (int e = 0; e < 8; ++e) { typedef float f32x2p __attribute__((ext_vector_type(2)));
;                 f32x2p v; v.x = (e & 1) ? bf_hi(A0[e >> 1]) : bf_lo(A0[e >> 1]); v.y = (e & 1) ? bf_hi(A1[e >> 1]) : bf_lo(A1[e >> 1]);
;                 const f32x2p mn = {st4.x, st4.z}, rs = {st4.y, st4.w};
;                 const f32x2p o = ((v - mn) * rs) * lw[e] + lb[e];
;                 *(LAS unsigned*)(wbase + e * 8 * SGU_VP + i * 32) = cvt_pk_bf16(o.x, o.y); }
;         }
;     }
.LBB0_1401:
	s_or_b64 exec, exec, s[16:17]
	v_mov_b32_e32 v122, v214
	v_mov_b32_e32 v123, v215
	v_mov_b32_e32 v124, v216
	v_mov_b32_e32 v125, v217
	v_mov_b32_e32 v126, v218
	v_mov_b32_e32 v127, v219
	v_mov_b32_e32 v128, v220
	v_mov_b32_e32 v129, v221
	v_mov_b32_e32 v114, v222
	v_mov_b32_e32 v115, v223
	v_mov_b32_e32 v116, v224
	v_mov_b32_e32 v117, v225
	v_mov_b32_e32 v118, v226
	v_mov_b32_e32 v119, v227
	v_mov_b32_e32 v120, v228
	v_mov_b32_e32 v121, v229
	v_mov_b32_e32 v106, v230
	v_mov_b32_e32 v107, v231
	v_mov_b32_e32 v108, v232
	v_mov_b32_e32 v109, v233
	v_mov_b32_e32 v110, v234
	v_mov_b32_e32 v111, v235
	v_mov_b32_e32 v112, v236
	v_mov_b32_e32 v113, v237
	v_or_b32_e32 v158, v82, v168
	v_or_b32_e32 v82, v158, v170
	v_lshl_or_b32 v84, s18, 11, v180
	v_mov_b32_e32 v85, v147
	v_ashrrev_i32_e32 v83, 31, v82
	v_lshl_add_u64 v[84:85], s[38:39], 0, v[84:85]
	v_lshl_add_u64 v[90:91], v[82:83], 1, v[84:85]
	v_lshlrev_b64 v[82:83], 2, v[82:83]
	v_lshl_add_u64 v[84:85], s[30:31], 0, v[82:83]
	v_lshl_add_u64 v[86:87], s[40:41], 0, v[82:83]
	global_load_dwordx4 v[98:101], v[86:87], off
	global_load_dwordx4 v[102:105], v[84:85], off
	s_nop 0
	global_load_dwordx4 v[82:85], v[84:85], off offset:16
	s_nop 0
	global_load_dwordx4 v[86:89], v[86:87], off offset:16
	v_add_co_u32_e32 v92, vcc, 0x8000, v90
	s_mov_b64 s[16:17], 0
	s_nop 0
	v_addc_co_u32_e32 v93, vcc, 0, v91, vcc
	v_add_co_u32_e32 v94, vcc, 0x10000, v90
	s_waitcnt vmcnt(7)
	v_and_b32_e32 v220, 0xffff0000, v198
	v_addc_co_u32_e32 v95, vcc, 0, v91, vcc
	v_add_co_u32_e32 v92, vcc, 0x18000, v90
	s_waitcnt vmcnt(8)
	v_and_b32_e32 v221, 0xffff0000, v202
	v_addc_co_u32_e32 v93, vcc, 0, v91, vcc
	v_add_co_u32_e32 v94, vcc, 0x20000, v90
	v_addc_co_u32_e32 v95, vcc, 0, v91, vcc
	v_add_co_u32_e32 v92, vcc, 0x28000, v90
	v_addc_co_u32_e32 v93, vcc, 0, v91, vcc
	v_add_co_u32_e32 v94, vcc, 0x30000, v90
	v_addc_co_u32_e32 v95, vcc, 0, v91, vcc
	v_add_co_u32_e32 v96, vcc, 0x38000, v90
	v_addc_co_u32_e32 v97, vcc, 0, v91, vcc
	v_mov_b32_e32 v90, v248
	v_mov_b32_e32 v91, v249
	v_mov_b32_e32 v92, v250
	v_mov_b32_e32 v93, v251
	s_nop 0
	v_mov_b32_e32 v94, v252
	v_mov_b32_e32 v95, v253
	v_mov_b32_e32 v96, v254
	v_mov_b32_e32 v97, v255
	s_waitcnt lgkmcnt(0)
	s_barrier
	ds_read_b128 v[214:217], v181
	v_lshlrev_b32_e32 v222, 16, v199
	v_lshlrev_b32_e32 v223, 16, v203
	s_waitcnt vmcnt(2)
	v_mov_b32_e32 v160, v105
	v_mov_b32_e32 v162, v101
	s_waitcnt lgkmcnt(0)
	v_mov_b32_e32 v218, v214
	v_mov_b32_e32 v219, v216
	v_mov_b32_e32 v216, v215
	v_lshlrev_b32_e32 v214, 16, v198
	v_lshlrev_b32_e32 v215, 16, v202
	v_pk_add_f32 v[214:215], v[214:215], v[218:219] neg_lo:[0,1] neg_hi:[0,1]
	v_and_b32_e32 v198, 0xffff0000, v199
	v_and_b32_e32 v199, 0xffff0000, v203
	v_pk_add_f32 v[220:221], v[220:221], v[218:219] neg_lo:[0,1] neg_hi:[0,1]
	v_pk_mul_f32 v[214:215], v[216:217], v[214:215]
	v_pk_add_f32 v[198:199], v[198:199], v[218:219] neg_lo:[0,1] neg_hi:[0,1]
	v_pk_add_f32 v[222:223], v[222:223], v[218:219] neg_lo:[0,1] neg_hi:[0,1]
	v_pk_mul_f32 v[220:221], v[216:217], v[220:221]
	v_pk_fma_f32 v[214:215], v[102:103], v[214:215], v[98:99] op_sel_hi:[0,1,0]
	v_cvt_pk_bf16_f32 v159, v214, v215
	v_pk_mul_f32 v[198:199], v[216:217], v[198:199]
	v_pk_mul_f32 v[222:223], v[216:217], v[222:223]
	v_pk_fma_f32 v[220:221], v[102:103], v[220:221], v[98:99] op_sel:[1,0,1]
	ds_write_b32 v177, v159 offset:1024
	v_cvt_pk_bf16_f32 v159, v220, v221
	v_pk_fma_f32 v[198:199], v[160:161], v[198:199], v[162:163] op_sel_hi:[0,1,0]
	v_pk_fma_f32 v[222:223], v[104:105], v[222:223], v[100:101] op_sel_hi:[0,1,0]
	ds_write_b32 v177, v159 offset:3200
	v_cvt_pk_bf16_f32 v159, v222, v223
	ds_write_b32 v177, v159 offset:5376
	v_cvt_pk_bf16_f32 v101, v198, v199
	v_lshlrev_b32_e32 v198, 16, v200
	v_lshlrev_b32_e32 v199, 16, v204
	v_pk_add_f32 v[198:199], v[198:199], v[218:219] neg_lo:[0,1] neg_hi:[0,1]
	ds_write_b32 v177, v101 offset:7552
	v_pk_mul_f32 v[198:199], v[216:217], v[198:199]
	s_waitcnt vmcnt(1)
	v_mov_b32_e32 v164, v85
	s_waitcnt vmcnt(0)
	v_pk_fma_f32 v[198:199], v[82:83], v[198:199], v[86:87] op_sel_hi:[0,1,0]
	v_cvt_pk_bf16_f32 v101, v198, v199
	v_and_b32_e32 v198, 0xffff0000, v200
	v_and_b32_e32 v199, 0xffff0000, v204
	v_pk_add_f32 v[198:199], v[198:199], v[218:219] neg_lo:[0,1] neg_hi:[0,1]
	ds_write_b32 v177, v101 offset:9728
	v_pk_mul_f32 v[198:199], v[216:217], v[198:199]
	v_mov_b32_e32 v166, v89
	v_pk_fma_f32 v[198:199], v[82:83], v[198:199], v[86:87] op_sel:[1,0,1]
	v_ashrrev_i32_e32 v159, 31, v158
	v_cvt_pk_bf16_f32 v101, v198, v199
	v_lshlrev_b32_e32 v198, 16, v201
	v_lshlrev_b32_e32 v199, 16, v205
	v_pk_add_f32 v[198:199], v[198:199], v[218:219] neg_lo:[0,1] neg_hi:[0,1]
	ds_write_b32 v177, v101 offset:11904
	v_pk_mul_f32 v[198:199], v[216:217], v[198:199]
	s_nop 0
	v_pk_fma_f32 v[198:199], v[84:85], v[198:199], v[88:89] op_sel_hi:[0,1,0]
	v_cvt_pk_bf16_f32 v101, v198, v199
	v_and_b32_e32 v198, 0xffff0000, v201
	v_and_b32_e32 v199, 0xffff0000, v205
	v_pk_add_f32 v[198:199], v[198:199], v[218:219] neg_lo:[0,1] neg_hi:[0,1]
	ds_write_b32 v177, v101 offset:14080
	v_pk_mul_f32 v[198:199], v[216:217], v[198:199]
	s_nop 0
	v_pk_fma_f32 v[198:199], v[164:165], v[198:199], v[166:167] op_sel_hi:[0,1,0]
	v_cvt_pk_bf16_f32 v85, v198, v199
	ds_write_b32 v177, v85 offset:16256
	ds_read_b128 v[198:201], v181 offset:128
	s_waitcnt lgkmcnt(0)
	v_mov_b32_e32 v202, v198
	v_mov_b32_e32 v203, v200
	v_mov_b32_e32 v200, v199
	s_waitcnt vmcnt(13)
	v_lshlrev_b32_e32 v198, 16, v206
	s_waitcnt vmcnt(12)
; __device__ __forceinline__ unsigned cvt_pk_bf16(float lo, float hi) { unsigned r; asm volatile("v_cvt_pk_bf16_f32 %0, %1, %2" : "=v"(r) : "v"(lo), "v"(hi)); return r; }
; __device__ __forceinline__ float bf_lo(unsigned w) { return __uint_as_float(w << 16); }
; __device__ __forceinline__ float bf_hi(unsigned w) { return __uint_as_float(w & 0xffff0000u); }
; #define LAS __attribute__((address_space(3)))
; __device__ __forceinline__ void sgu_unit(LAS unsigned char* lds, bf16* U, const bf16* VS, const float* SGS, const float* lnw, const float* lnb, const v4u* WF, const float* bsl, int unit, int tid) {
;     ...
;         for (int i = 0; i < 8; ++i) {
;             const f32x4 st4 = *(const LAS f32x4*)(stat + 4 * (rp + 8 * i));
;             const v4u w0 = sl[i][0], w1 = sl[i][1];
;             const unsigned A0[4] = {w0.x, w0.y, w0.z, w0.w}, A1[4] = {w1.x, w1.y, w1.z, w1.w};
; #pragma unroll
;             for (int e = 0; e < 8; ++e) { typedef float f32x2p __attribute__((ext_vector_type(2)));
;                 f32x2p v; v.x = (e & 1) ? bf_hi(A0[e >> 1]) : bf_lo(A0[e >> 1]); v.y = (e & 1) ? bf_hi(A1[e >> 1]) : bf_lo(A1[e >> 1]);
;                 const f32x2p mn = {st4.x, st4.z}, rs = {st4.y, st4.w};
;                 const f32x2p o = ((v - mn) * rs) * lw[e] + lb[e];
;                 *(LAS unsigned*)(wbase + e * 8 * SGU_VP + i * 32) = cvt_pk_bf16(o.x, o.y); }
;         }
	v_lshlrev_b32_e32 v199, 16, v210
	v_pk_add_f32 v[198:199], v[198:199], v[202:203] neg_lo:[0,1] neg_hi:[0,1]
	s_nop 0
	v_pk_mul_f32 v[198:199], v[200:201], v[198:199]
	s_nop 0
	v_pk_fma_f32 v[198:199], v[102:103], v[198:199], v[98:99] op_sel_hi:[0,1,0]
	v_cvt_pk_bf16_f32 v85, v198, v199
	v_and_b32_e32 v198, 0xffff0000, v206
	v_and_b32_e32 v199, 0xffff0000, v210
	v_pk_add_f32 v[198:199], v[198:199], v[202:203] neg_lo:[0,1] neg_hi:[0,1]
	ds_write_b32 v177, v85 offset:1056
	v_pk_mul_f32 v[198:199], v[200:201], v[198:199]
	s_nop 0
	v_pk_fma_f32 v[198:199], v[102:103], v[198:199], v[98:99] op_sel:[1,0,1]
	s_nop 0
	v_cvt_pk_bf16_f32 v85, v198, v199
	v_lshlrev_b32_e32 v198, 16, v207
	v_lshlrev_b32_e32 v199, 16, v211
	v_pk_add_f32 v[198:199], v[198:199], v[202:203] neg_lo:[0,1] neg_hi:[0,1]
	ds_write_b32 v177, v85 offset:3232
	v_pk_mul_f32 v[198:199], v[200:201], v[198:199]
	s_nop 0
	v_pk_fma_f32 v[198:199], v[104:105], v[198:199], v[100:101] op_sel_hi:[0,1,0]
	v_cvt_pk_bf16_f32 v85, v198, v199
	v_and_b32_e32 v198, 0xffff0000, v207
	v_and_b32_e32 v199, 0xffff0000, v211
	v_pk_add_f32 v[198:199], v[198:199], v[202:203] neg_lo:[0,1] neg_hi:[0,1]
	ds_write_b32 v177, v85 offset:5408
	v_pk_mul_f32 v[198:199], v[200:201], v[198:199]
	s_nop 0
	v_pk_fma_f32 v[198:199], v[160:161], v[198:199], v[162:163] op_sel_hi:[0,1,0]
	v_cvt_pk_bf16_f32 v85, v198, v199
	v_lshlrev_b32_e32 v198, 16, v208
	v_lshlrev_b32_e32 v199, 16, v212
	v_pk_add_f32 v[198:199], v[198:199], v[202:203] neg_lo:[0,1] neg_hi:[0,1]
	ds_write_b32 v177, v85 offset:7584
	v_pk_mul_f32 v[198:199], v[200:201], v[198:199]
	s_nop 0
	v_pk_fma_f32 v[198:199], v[82:83], v[198:199], v[86:87] op_sel_hi:[0,1,0]
	v_cvt_pk_bf16_f32 v85, v198, v199
	v_and_b32_e32 v198, 0xffff0000, v208
	v_and_b32_e32 v199, 0xffff0000, v212
	v_pk_add_f32 v[198:199], v[198:199], v[202:203] neg_lo:[0,1] neg_hi:[0,1]
	ds_write_b32 v177, v85 offset:9760
	v_pk_mul_f32 v[198:199], v[200:201], v[198:199]
	s_nop 0
	v_pk_fma_f32 v[198:199], v[82:83], v[198:199], v[86:87] op_sel:[1,0,1]
	s_nop 0
	v_cvt_pk_bf16_f32 v85, v198, v199
	v_lshlrev_b32_e32 v198, 16, v209
	v_lshlrev_b32_e32 v199, 16, v213
	v_pk_add_f32 v[198:199], v[198:199], v[202:203] neg_lo:[0,1] neg_hi:[0,1]
	ds_write_b32 v177, v85 offset:11936
	v_pk_mul_f32 v[198:199], v[200:201], v[198:199]
	s_nop 0
	v_pk_fma_f32 v[198:199], v[84:85], v[198:199], v[88:89] op_sel_hi:[0,1,0]
	v_cvt_pk_bf16_f32 v85, v198, v199
	v_and_b32_e32 v198, 0xffff0000, v209
	v_and_b32_e32 v199, 0xffff0000, v213
	v_pk_add_f32 v[198:199], v[198:199], v[202:203] neg_lo:[0,1] neg_hi:[0,1]
	ds_write_b32 v177, v85 offset:14112
	v_pk_mul_f32 v[198:199], v[200:201], v[198:199]
	s_nop 0
	v_pk_fma_f32 v[198:199], v[164:165], v[198:199], v[166:167] op_sel_hi:[0,1,0]
	v_cvt_pk_bf16_f32 v85, v198, v199
	ds_write_b32 v177, v85 offset:16288
	ds_read_b128 v[198:201], v181 offset:256
	s_waitcnt lgkmcnt(0)
	v_mov_b32_e32 v202, v198
	v_mov_b32_e32 v203, v200
	v_mov_b32_e32 v200, v199
	s_waitcnt vmcnt(11)
	v_lshlrev_b32_e32 v198, 16, v138
	s_waitcnt vmcnt(10)
	v_lshlrev_b32_e32 v199, 16, v142
	v_pk_add_f32 v[198:199], v[198:199], v[202:203] neg_lo:[0,1] neg_hi:[0,1]
	s_nop 0
	v_pk_mul_f32 v[198:199], v[200:201], v[198:199]
	s_nop 0
	v_pk_fma_f32 v[198:199], v[102:103], v[198:199], v[98:99] op_sel_hi:[0,1,0]
	v_cvt_pk_bf16_f32 v85, v198, v199
	v_and_b32_e32 v198, 0xffff0000, v138
	v_and_b32_e32 v199, 0xffff0000, v142
	v_pk_add_f32 v[198:199], v[198:199], v[202:203] neg_lo:[0,1] neg_hi:[0,1]
	ds_write_b32 v177, v85 offset:1088
	v_pk_mul_f32 v[198:199], v[200:201], v[198:199]
	v_and_b32_e32 v138, 0xffff0000, v139
	v_pk_fma_f32 v[198:199], v[102:103], v[198:199], v[98:99] op_sel:[1,0,1]
	s_nop 0
	v_cvt_pk_bf16_f32 v85, v198, v199
	v_lshlrev_b32_e32 v198, 16, v139
	v_lshlrev_b32_e32 v199, 16, v143
	v_and_b32_e32 v139, 0xffff0000, v143
	v_pk_add_f32 v[198:199], v[198:199], v[202:203] neg_lo:[0,1] neg_hi:[0,1]
	v_pk_add_f32 v[138:139], v[138:139], v[202:203] neg_lo:[0,1] neg_hi:[0,1]
	v_pk_mul_f32 v[198:199], v[200:201], v[198:199]
	v_pk_mul_f32 v[138:139], v[200:201], v[138:139]
	ds_write_b32 v177, v85 offset:3264
	v_pk_fma_f32 v[198:199], v[104:105], v[198:199], v[100:101] op_sel_hi:[0,1,0]
	v_cvt_pk_bf16_f32 v85, v198, v199
	v_pk_fma_f32 v[138:139], v[160:161], v[138:139], v[162:163] op_sel_hi:[0,1,0]
	ds_write_b32 v177, v85 offset:5440
	v_cvt_pk_bf16_f32 v85, v138, v139
	v_lshlrev_b32_e32 v138, 16, v140
	v_lshlrev_b32_e32 v139, 16, v144
	v_pk_add_f32 v[138:139], v[138:139], v[202:203] neg_lo:[0,1] neg_hi:[0,1]
	ds_write_b32 v177, v85 offset:7616
	v_pk_mul_f32 v[138:139], v[200:201], v[138:139]
	s_nop 0
	v_pk_fma_f32 v[138:139], v[82:83], v[138:139], v[86:87] op_sel_hi:[0,1,0]
	v_cvt_pk_bf16_f32 v85, v138, v139
	v_and_b32_e32 v138, 0xffff0000, v140
	v_and_b32_e32 v139, 0xffff0000, v144
	v_pk_add_f32 v[138:139], v[138:139], v[202:203] neg_lo:[0,1] neg_hi:[0,1]
	ds_write_b32 v177, v85 offset:9792
	v_pk_mul_f32 v[138:139], v[200:201], v[138:139]
	s_nop 0
	v_pk_fma_f32 v[138:139], v[82:83], v[138:139], v[86:87] op_sel:[1,0,1]
	s_nop 0
	v_cvt_pk_bf16_f32 v85, v138, v139
	v_lshlrev_b32_e32 v138, 16, v141
	v_lshlrev_b32_e32 v139, 16, v145
	v_pk_add_f32 v[138:139], v[138:139], v[202:203] neg_lo:[0,1] neg_hi:[0,1]
	ds_write_b32 v177, v85 offset:11968
	v_pk_mul_f32 v[138:139], v[200:201], v[138:139]
	s_nop 0
	v_pk_fma_f32 v[138:139], v[84:85], v[138:139], v[88:89] op_sel_hi:[0,1,0]
	v_cvt_pk_bf16_f32 v85, v138, v139
	v_and_b32_e32 v138, 0xffff0000, v141
	v_and_b32_e32 v139, 0xffff0000, v145
	v_pk_add_f32 v[138:139], v[138:139], v[202:203] neg_lo:[0,1] neg_hi:[0,1]
	ds_write_b32 v177, v85 offset:14144
	v_pk_mul_f32 v[138:139], v[200:201], v[138:139]
	s_nop 0
	v_pk_fma_f32 v[138:139], v[164:165], v[138:139], v[166:167] op_sel_hi:[0,1,0]
	v_cvt_pk_bf16_f32 v85, v138, v139
	ds_write_b32 v177, v85 offset:16320
	ds_read_b128 v[138:141], v181 offset:384
	s_waitcnt lgkmcnt(0)
; __device__ __forceinline__ unsigned cvt_pk_bf16(float lo, float hi) { unsigned r; asm volatile("v_cvt_pk_bf16_f32 %0, %1, %2" : "=v"(r) : "v"(lo), "v"(hi)); return r; }
; __device__ __forceinline__ float bf_lo(unsigned w) { return __uint_as_float(w << 16); }
; __device__ __forceinline__ float bf_hi(unsigned w) { return __uint_as_float(w & 0xffff0000u); }
; #define LAS __attribute__((address_space(3)))
; __device__ __forceinline__ void sgu_unit(LAS unsigned char* lds, bf16* U, const bf16* VS, const float* SGS, const float* lnw, const float* lnb, const v4u* WF, const float* bsl, int unit, int tid) {
;     ...
;         for (int i = 0; i < 8; ++i) {
;             const f32x4 st4 = *(const LAS f32x4*)(stat + 4 * (rp + 8 * i));
;             const v4u w0 = sl[i][0], w1 = sl[i][1];
;             const unsigned A0[4] = {w0.x, w0.y, w0.z, w0.w}, A1[4] = {w1.x, w1.y, w1.z, w1.w};
; #pragma unroll
;             for (int e = 0; e < 8; ++e) { typedef float f32x2p __attribute__((ext_vector_type(2)));
;                 f32x2p v; v.x = (e & 1) ? bf_hi(A0[e >> 1]) : bf_lo(A0[e >> 1]); v.y = (e & 1) ? bf_hi(A1[e >> 1]) : bf_lo(A1[e >> 1]);
;                 const f32x2p mn = {st4.x, st4.z}, rs = {st4.y, st4.w};
;                 const f32x2p o = ((v - mn) * rs) * lw[e] + lb[e];
;                 *(LAS unsigned*)(wbase + e * 8 * SGU_VP + i * 32) = cvt_pk_bf16(o.x, o.y); }
;         }
	v_mov_b32_e32 v142, v138
	v_mov_b32_e32 v143, v140
	v_mov_b32_e32 v140, v139
	s_waitcnt vmcnt(9)
	v_lshlrev_b32_e32 v138, 16, v130
	s_waitcnt vmcnt(8)
	v_lshlrev_b32_e32 v139, 16, v134
	v_pk_add_f32 v[138:139], v[138:139], v[142:143] neg_lo:[0,1] neg_hi:[0,1]
	s_nop 0
	v_pk_mul_f32 v[138:139], v[140:141], v[138:139]
	s_nop 0
	v_pk_fma_f32 v[138:139], v[102:103], v[138:139], v[98:99] op_sel_hi:[0,1,0]
	v_cvt_pk_bf16_f32 v85, v138, v139
	v_and_b32_e32 v138, 0xffff0000, v130
	v_and_b32_e32 v139, 0xffff0000, v134
	v_pk_add_f32 v[138:139], v[138:139], v[142:143] neg_lo:[0,1] neg_hi:[0,1]
	ds_write_b32 v177, v85 offset:1120
	v_pk_mul_f32 v[138:139], v[140:141], v[138:139]
	v_and_b32_e32 v130, 0xffff0000, v131
	v_pk_fma_f32 v[138:139], v[102:103], v[138:139], v[98:99] op_sel:[1,0,1]
	s_nop 0
	v_cvt_pk_bf16_f32 v85, v138, v139
	v_lshlrev_b32_e32 v138, 16, v131
	v_lshlrev_b32_e32 v139, 16, v135
	v_and_b32_e32 v131, 0xffff0000, v135
	v_pk_add_f32 v[138:139], v[138:139], v[142:143] neg_lo:[0,1] neg_hi:[0,1]
	v_pk_add_f32 v[130:131], v[130:131], v[142:143] neg_lo:[0,1] neg_hi:[0,1]
	v_pk_mul_f32 v[138:139], v[140:141], v[138:139]
	v_pk_mul_f32 v[130:131], v[140:141], v[130:131]
	ds_write_b32 v177, v85 offset:3296
	v_pk_fma_f32 v[138:139], v[104:105], v[138:139], v[100:101] op_sel_hi:[0,1,0]
	v_cvt_pk_bf16_f32 v85, v138, v139
	v_pk_fma_f32 v[130:131], v[160:161], v[130:131], v[162:163] op_sel_hi:[0,1,0]
	ds_write_b32 v177, v85 offset:5472
	v_cvt_pk_bf16_f32 v85, v130, v131
	v_lshlrev_b32_e32 v130, 16, v132
	v_lshlrev_b32_e32 v131, 16, v136
	v_pk_add_f32 v[130:131], v[130:131], v[142:143] neg_lo:[0,1] neg_hi:[0,1]
	ds_write_b32 v177, v85 offset:7648
	v_pk_mul_f32 v[130:131], v[140:141], v[130:131]
	s_nop 0
	v_pk_fma_f32 v[130:131], v[82:83], v[130:131], v[86:87] op_sel_hi:[0,1,0]
	v_cvt_pk_bf16_f32 v85, v130, v131
	v_and_b32_e32 v130, 0xffff0000, v132
	v_and_b32_e32 v131, 0xffff0000, v136
	v_pk_add_f32 v[130:131], v[130:131], v[142:143] neg_lo:[0,1] neg_hi:[0,1]
	ds_write_b32 v177, v85 offset:9824
	v_pk_mul_f32 v[130:131], v[140:141], v[130:131]
	s_nop 0
	v_pk_fma_f32 v[130:131], v[82:83], v[130:131], v[86:87] op_sel:[1,0,1]
	s_nop 0
	v_cvt_pk_bf16_f32 v85, v130, v131
	v_lshlrev_b32_e32 v130, 16, v133
	v_lshlrev_b32_e32 v131, 16, v137
	v_pk_add_f32 v[130:131], v[130:131], v[142:143] neg_lo:[0,1] neg_hi:[0,1]
	ds_write_b32 v177, v85 offset:12000
	v_pk_mul_f32 v[130:131], v[140:141], v[130:131]
	s_nop 0
	v_pk_fma_f32 v[130:131], v[84:85], v[130:131], v[88:89] op_sel_hi:[0,1,0]
	v_cvt_pk_bf16_f32 v85, v130, v131
	v_and_b32_e32 v130, 0xffff0000, v133
	v_and_b32_e32 v131, 0xffff0000, v137
	v_pk_add_f32 v[130:131], v[130:131], v[142:143] neg_lo:[0,1] neg_hi:[0,1]
	ds_write_b32 v177, v85 offset:14176
	v_pk_mul_f32 v[130:131], v[140:141], v[130:131]
	s_nop 0
	v_pk_fma_f32 v[130:131], v[164:165], v[130:131], v[166:167] op_sel_hi:[0,1,0]
	v_cvt_pk_bf16_f32 v85, v130, v131
	ds_write_b32 v177, v85 offset:16352
	ds_read_b128 v[130:133], v181 offset:512
	s_waitcnt lgkmcnt(0)
	v_mov_b32_e32 v134, v130
	v_mov_b32_e32 v135, v132
	v_mov_b32_e32 v132, v131
	s_waitcnt vmcnt(7)
	v_lshlrev_b32_e32 v130, 16, v122
	s_waitcnt vmcnt(6)
	v_lshlrev_b32_e32 v131, 16, v126
	v_pk_add_f32 v[130:131], v[130:131], v[134:135] neg_lo:[0,1] neg_hi:[0,1]
	s_nop 0
	v_pk_mul_f32 v[130:131], v[132:133], v[130:131]
	s_nop 0
	v_pk_fma_f32 v[130:131], v[102:103], v[130:131], v[98:99] op_sel_hi:[0,1,0]
	v_cvt_pk_bf16_f32 v85, v130, v131
	v_and_b32_e32 v130, 0xffff0000, v122
	v_and_b32_e32 v131, 0xffff0000, v126
	v_pk_add_f32 v[130:131], v[130:131], v[134:135] neg_lo:[0,1] neg_hi:[0,1]
	ds_write_b32 v177, v85 offset:1152
	v_pk_mul_f32 v[130:131], v[132:133], v[130:131]
	v_and_b32_e32 v122, 0xffff0000, v123
	v_pk_fma_f32 v[130:131], v[102:103], v[130:131], v[98:99] op_sel:[1,0,1]
	s_nop 0
	v_cvt_pk_bf16_f32 v85, v130, v131
	v_lshlrev_b32_e32 v130, 16, v123
	v_lshlrev_b32_e32 v131, 16, v127
	v_and_b32_e32 v123, 0xffff0000, v127
	v_pk_add_f32 v[130:131], v[130:131], v[134:135] neg_lo:[0,1] neg_hi:[0,1]
	v_pk_add_f32 v[122:123], v[122:123], v[134:135] neg_lo:[0,1] neg_hi:[0,1]
	v_pk_mul_f32 v[130:131], v[132:133], v[130:131]
	v_pk_mul_f32 v[122:123], v[132:133], v[122:123]
	ds_write_b32 v177, v85 offset:3328
	v_pk_fma_f32 v[130:131], v[104:105], v[130:131], v[100:101] op_sel_hi:[0,1,0]
	v_cvt_pk_bf16_f32 v85, v130, v131
	v_pk_fma_f32 v[122:123], v[160:161], v[122:123], v[162:163] op_sel_hi:[0,1,0]
	ds_write_b32 v177, v85 offset:5504
	v_cvt_pk_bf16_f32 v85, v122, v123
	v_lshlrev_b32_e32 v122, 16, v124
	v_lshlrev_b32_e32 v123, 16, v128
	v_pk_add_f32 v[122:123], v[122:123], v[134:135] neg_lo:[0,1] neg_hi:[0,1]
	ds_write_b32 v177, v85 offset:7680
	v_pk_mul_f32 v[122:123], v[132:133], v[122:123]
	s_nop 0
	v_pk_fma_f32 v[122:123], v[82:83], v[122:123], v[86:87] op_sel_hi:[0,1,0]
	v_cvt_pk_bf16_f32 v85, v122, v123
	v_and_b32_e32 v122, 0xffff0000, v124
	v_and_b32_e32 v123, 0xffff0000, v128
	v_pk_add_f32 v[122:123], v[122:123], v[134:135] neg_lo:[0,1] neg_hi:[0,1]
	ds_write_b32 v177, v85 offset:9856
	v_pk_mul_f32 v[122:123], v[132:133], v[122:123]
	s_nop 0
	v_pk_fma_f32 v[122:123], v[82:83], v[122:123], v[86:87] op_sel:[1,0,1]
	s_nop 0
	v_cvt_pk_bf16_f32 v85, v122, v123
	v_lshlrev_b32_e32 v122, 16, v125
	v_lshlrev_b32_e32 v123, 16, v129
	v_pk_add_f32 v[122:123], v[122:123], v[134:135] neg_lo:[0,1] neg_hi:[0,1]
	ds_write_b32 v177, v85 offset:12032
	v_pk_mul_f32 v[122:123], v[132:133], v[122:123]
	s_nop 0
	v_pk_fma_f32 v[122:123], v[84:85], v[122:123], v[88:89] op_sel_hi:[0,1,0]
	v_cvt_pk_bf16_f32 v85, v122, v123
	v_and_b32_e32 v122, 0xffff0000, v125
	v_and_b32_e32 v123, 0xffff0000, v129
	v_pk_add_f32 v[122:123], v[122:123], v[134:135] neg_lo:[0,1] neg_hi:[0,1]
	ds_write_b32 v177, v85 offset:14208
	v_pk_mul_f32 v[122:123], v[132:133], v[122:123]
	s_nop 0
	v_pk_fma_f32 v[122:123], v[164:165], v[122:123], v[166:167] op_sel_hi:[0,1,0]
	v_cvt_pk_bf16_f32 v85, v122, v123
	ds_write_b32 v177, v85 offset:16384
	ds_read_b128 v[122:125], v181 offset:640
	s_waitcnt lgkmcnt(0)
; __device__ __forceinline__ unsigned cvt_pk_bf16(float lo, float hi) { unsigned r; asm volatile("v_cvt_pk_bf16_f32 %0, %1, %2" : "=v"(r) : "v"(lo), "v"(hi)); return r; }
; __device__ __forceinline__ float bf_lo(unsigned w) { return __uint_as_float(w << 16); }
; __device__ __forceinline__ float bf_hi(unsigned w) { return __uint_as_float(w & 0xffff0000u); }
; #define LAS __attribute__((address_space(3)))
; __device__ __forceinline__ void sgu_unit(LAS unsigned char* lds, bf16* U, const bf16* VS, const float* SGS, const float* lnw, const float* lnb, const v4u* WF, const float* bsl, int unit, int tid) {
;     ...
;         for (int i = 0; i < 8; ++i) {
;             const f32x4 st4 = *(const LAS f32x4*)(stat + 4 * (rp + 8 * i));
;             const v4u w0 = sl[i][0], w1 = sl[i][1];
;             const unsigned A0[4] = {w0.x, w0.y, w0.z, w0.w}, A1[4] = {w1.x, w1.y, w1.z, w1.w};
; #pragma unroll
;             for (int e = 0; e < 8; ++e) { typedef float f32x2p __attribute__((ext_vector_type(2)));
;                 f32x2p v; v.x = (e & 1) ? bf_hi(A0[e >> 1]) : bf_lo(A0[e >> 1]); v.y = (e & 1) ? bf_hi(A1[e >> 1]) : bf_lo(A1[e >> 1]);
;                 const f32x2p mn = {st4.x, st4.z}, rs = {st4.y, st4.w};
;                 const f32x2p o = ((v - mn) * rs) * lw[e] + lb[e];
;                 *(LAS unsigned*)(wbase + e * 8 * SGU_VP + i * 32) = cvt_pk_bf16(o.x, o.y); }
;         }
	v_mov_b32_e32 v126, v122
	v_mov_b32_e32 v127, v124
	v_mov_b32_e32 v124, v123
	s_waitcnt vmcnt(5)
	v_lshlrev_b32_e32 v122, 16, v114
	s_waitcnt vmcnt(4)
	v_lshlrev_b32_e32 v123, 16, v118
	v_pk_add_f32 v[122:123], v[122:123], v[126:127] neg_lo:[0,1] neg_hi:[0,1]
	s_nop 0
	v_pk_mul_f32 v[122:123], v[124:125], v[122:123]
	s_nop 0
	v_pk_fma_f32 v[122:123], v[102:103], v[122:123], v[98:99] op_sel_hi:[0,1,0]
	v_cvt_pk_bf16_f32 v85, v122, v123
	v_and_b32_e32 v122, 0xffff0000, v114
	v_and_b32_e32 v123, 0xffff0000, v118
	v_pk_add_f32 v[122:123], v[122:123], v[126:127] neg_lo:[0,1] neg_hi:[0,1]
	ds_write_b32 v177, v85 offset:1184
	v_pk_mul_f32 v[122:123], v[124:125], v[122:123]
	v_and_b32_e32 v114, 0xffff0000, v115
	v_pk_fma_f32 v[122:123], v[102:103], v[122:123], v[98:99] op_sel:[1,0,1]
	s_nop 0
	v_cvt_pk_bf16_f32 v85, v122, v123
	v_lshlrev_b32_e32 v122, 16, v115
	v_lshlrev_b32_e32 v123, 16, v119
	v_and_b32_e32 v115, 0xffff0000, v119
	v_pk_add_f32 v[122:123], v[122:123], v[126:127] neg_lo:[0,1] neg_hi:[0,1]
	v_pk_add_f32 v[114:115], v[114:115], v[126:127] neg_lo:[0,1] neg_hi:[0,1]
	v_pk_mul_f32 v[122:123], v[124:125], v[122:123]
	v_pk_mul_f32 v[114:115], v[124:125], v[114:115]
	ds_write_b32 v177, v85 offset:3360
	v_pk_fma_f32 v[122:123], v[104:105], v[122:123], v[100:101] op_sel_hi:[0,1,0]
	v_cvt_pk_bf16_f32 v85, v122, v123
	v_pk_fma_f32 v[114:115], v[160:161], v[114:115], v[162:163] op_sel_hi:[0,1,0]
	ds_write_b32 v177, v85 offset:5536
	v_cvt_pk_bf16_f32 v85, v114, v115
	v_lshlrev_b32_e32 v114, 16, v116
	v_lshlrev_b32_e32 v115, 16, v120
	v_pk_add_f32 v[114:115], v[114:115], v[126:127] neg_lo:[0,1] neg_hi:[0,1]
	ds_write_b32 v177, v85 offset:7712
	v_pk_mul_f32 v[114:115], v[124:125], v[114:115]
	s_nop 0
	v_pk_fma_f32 v[114:115], v[82:83], v[114:115], v[86:87] op_sel_hi:[0,1,0]
	v_cvt_pk_bf16_f32 v85, v114, v115
	v_and_b32_e32 v114, 0xffff0000, v116
	v_and_b32_e32 v115, 0xffff0000, v120
	v_pk_add_f32 v[114:115], v[114:115], v[126:127] neg_lo:[0,1] neg_hi:[0,1]
	ds_write_b32 v177, v85 offset:9888
	v_pk_mul_f32 v[114:115], v[124:125], v[114:115]
	s_nop 0
	v_pk_fma_f32 v[114:115], v[82:83], v[114:115], v[86:87] op_sel:[1,0,1]
	s_nop 0
	v_cvt_pk_bf16_f32 v85, v114, v115
	v_lshlrev_b32_e32 v114, 16, v117
	v_lshlrev_b32_e32 v115, 16, v121
	v_pk_add_f32 v[114:115], v[114:115], v[126:127] neg_lo:[0,1] neg_hi:[0,1]
	ds_write_b32 v177, v85 offset:12064
	v_pk_mul_f32 v[114:115], v[124:125], v[114:115]
	s_nop 0
	v_pk_fma_f32 v[114:115], v[84:85], v[114:115], v[88:89] op_sel_hi:[0,1,0]
	v_cvt_pk_bf16_f32 v85, v114, v115
	v_and_b32_e32 v114, 0xffff0000, v117
	v_and_b32_e32 v115, 0xffff0000, v121
	v_pk_add_f32 v[114:115], v[114:115], v[126:127] neg_lo:[0,1] neg_hi:[0,1]
	ds_write_b32 v177, v85 offset:14240
	v_pk_mul_f32 v[114:115], v[124:125], v[114:115]
	s_nop 0
	v_pk_fma_f32 v[114:115], v[164:165], v[114:115], v[166:167] op_sel_hi:[0,1,0]
	v_cvt_pk_bf16_f32 v85, v114, v115
	ds_write_b32 v177, v85 offset:16416
	ds_read_b128 v[114:117], v181 offset:768
	s_waitcnt lgkmcnt(0)
	v_mov_b32_e32 v118, v114
	v_mov_b32_e32 v119, v116
	v_mov_b32_e32 v116, v115
	s_waitcnt vmcnt(3)
	v_lshlrev_b32_e32 v114, 16, v106
	s_waitcnt vmcnt(2)
	v_lshlrev_b32_e32 v115, 16, v110
	v_pk_add_f32 v[114:115], v[114:115], v[118:119] neg_lo:[0,1] neg_hi:[0,1]
	s_nop 0
	v_pk_mul_f32 v[114:115], v[116:117], v[114:115]
	s_nop 0
	v_pk_fma_f32 v[114:115], v[102:103], v[114:115], v[98:99] op_sel_hi:[0,1,0]
	v_cvt_pk_bf16_f32 v85, v114, v115
	v_and_b32_e32 v114, 0xffff0000, v106
	v_and_b32_e32 v115, 0xffff0000, v110
	v_pk_add_f32 v[114:115], v[114:115], v[118:119] neg_lo:[0,1] neg_hi:[0,1]
	ds_write_b32 v177, v85 offset:1216
	v_pk_mul_f32 v[114:115], v[116:117], v[114:115]
	v_and_b32_e32 v106, 0xffff0000, v107
	v_pk_fma_f32 v[114:115], v[102:103], v[114:115], v[98:99] op_sel:[1,0,1]
	s_nop 0
	v_cvt_pk_bf16_f32 v85, v114, v115
	v_lshlrev_b32_e32 v114, 16, v107
	v_lshlrev_b32_e32 v115, 16, v111
	v_and_b32_e32 v107, 0xffff0000, v111
	v_pk_add_f32 v[114:115], v[114:115], v[118:119] neg_lo:[0,1] neg_hi:[0,1]
	v_pk_add_f32 v[106:107], v[106:107], v[118:119] neg_lo:[0,1] neg_hi:[0,1]
	v_pk_mul_f32 v[114:115], v[116:117], v[114:115]
	v_pk_mul_f32 v[106:107], v[116:117], v[106:107]
	ds_write_b32 v177, v85 offset:3392
	v_pk_fma_f32 v[114:115], v[104:105], v[114:115], v[100:101] op_sel_hi:[0,1,0]
	v_cvt_pk_bf16_f32 v85, v114, v115
	v_pk_fma_f32 v[106:107], v[160:161], v[106:107], v[162:163] op_sel_hi:[0,1,0]
	ds_write_b32 v177, v85 offset:5568
	v_cvt_pk_bf16_f32 v85, v106, v107
	v_lshlrev_b32_e32 v106, 16, v108
	v_lshlrev_b32_e32 v107, 16, v112
	v_pk_add_f32 v[106:107], v[106:107], v[118:119] neg_lo:[0,1] neg_hi:[0,1]
	ds_write_b32 v177, v85 offset:7744
	v_pk_mul_f32 v[106:107], v[116:117], v[106:107]
	s_nop 0
	v_pk_fma_f32 v[106:107], v[82:83], v[106:107], v[86:87] op_sel_hi:[0,1,0]
	v_cvt_pk_bf16_f32 v85, v106, v107
	v_and_b32_e32 v106, 0xffff0000, v108
	v_and_b32_e32 v107, 0xffff0000, v112
	v_pk_add_f32 v[106:107], v[106:107], v[118:119] neg_lo:[0,1] neg_hi:[0,1]
	ds_write_b32 v177, v85 offset:9920
	v_pk_mul_f32 v[106:107], v[116:117], v[106:107]
	s_nop 0
	v_pk_fma_f32 v[106:107], v[82:83], v[106:107], v[86:87] op_sel:[1,0,1]
	s_nop 0
	v_cvt_pk_bf16_f32 v85, v106, v107
	v_lshlrev_b32_e32 v106, 16, v109
	v_lshlrev_b32_e32 v107, 16, v113
	v_pk_add_f32 v[106:107], v[106:107], v[118:119] neg_lo:[0,1] neg_hi:[0,1]
	ds_write_b32 v177, v85 offset:12096
	v_pk_mul_f32 v[106:107], v[116:117], v[106:107]
	s_nop 0
	v_pk_fma_f32 v[106:107], v[84:85], v[106:107], v[88:89] op_sel_hi:[0,1,0]
	v_cvt_pk_bf16_f32 v85, v106, v107
	v_and_b32_e32 v106, 0xffff0000, v109
	v_and_b32_e32 v107, 0xffff0000, v113
	v_pk_add_f32 v[106:107], v[106:107], v[118:119] neg_lo:[0,1] neg_hi:[0,1]
	ds_write_b32 v177, v85 offset:14272
	v_pk_mul_f32 v[106:107], v[116:117], v[106:107]
	s_nop 0
	v_pk_fma_f32 v[106:107], v[164:165], v[106:107], v[166:167] op_sel_hi:[0,1,0]
	v_cvt_pk_bf16_f32 v85, v106, v107
	ds_write_b32 v177, v85 offset:16448
	ds_read_b128 v[106:109], v181 offset:896
	s_waitcnt lgkmcnt(0)
; __device__ __forceinline__ unsigned cvt_pk_bf16(float lo, float hi) { unsigned r; asm volatile("v_cvt_pk_bf16_f32 %0, %1, %2" : "=v"(r) : "v"(lo), "v"(hi)); return r; }
; __device__ __forceinline__ float bf_lo(unsigned w) { return __uint_as_float(w << 16); }
; __device__ __forceinline__ float bf_hi(unsigned w) { return __uint_as_float(w & 0xffff0000u); }
; #define LAS __attribute__((address_space(3)))
; #define LDS_WAIT() asm volatile("s_waitcnt lgkmcnt(0)" ::: "memory")
; __device__ __forceinline__ void sgu_unit(LAS unsigned char* lds, bf16* U, const bf16* VS, const float* SGS, const float* lnw, const float* lnb, const v4u* WF, const float* bsl, int unit, int tid) {
;     ...
;         for (int i = 0; i < 8; ++i) {
;             const f32x4 st4 = *(const LAS f32x4*)(stat + 4 * (rp + 8 * i));
;             const v4u w0 = sl[i][0], w1 = sl[i][1];
;             const unsigned A0[4] = {w0.x, w0.y, w0.z, w0.w}, A1[4] = {w1.x, w1.y, w1.z, w1.w};
; #pragma unroll
;             for (int e = 0; e < 8; ++e) { typedef float f32x2p __attribute__((ext_vector_type(2)));
;                 f32x2p v; v.x = (e & 1) ? bf_hi(A0[e >> 1]) : bf_lo(A0[e >> 1]); v.y = (e & 1) ? bf_hi(A1[e >> 1]) : bf_lo(A1[e >> 1]);
;                 const f32x2p mn = {st4.x, st4.z}, rs = {st4.y, st4.w};
;                 const f32x2p o = ((v - mn) * rs) * lw[e] + lb[e];
;                 *(LAS unsigned*)(wbase + e * 8 * SGU_VP + i * 32) = cvt_pk_bf16(o.x, o.y); }
;         }
;     }
;     v2u uu[8][4];
; #pragma unroll
;     for (int mt = 0; mt < 8; ++mt)
; #pragma unroll
;         for (int nt = 0; nt < 4; ++nt) uu[mt][nt] = *(const v2u*)(U + (size_t)(r0 + 16 * mt + fr) * 1024 + colbase + 16 * nt + 4 * fq);
;     LDS_WAIT(); asm volatile("" ::: "memory");
	v_mov_b32_e32 v110, v106
	v_mov_b32_e32 v111, v108
	v_mov_b32_e32 v108, v107
	s_waitcnt vmcnt(1)
	v_lshlrev_b32_e32 v106, 16, v90
	s_waitcnt vmcnt(0)
	v_lshlrev_b32_e32 v107, 16, v94
	v_pk_add_f32 v[106:107], v[106:107], v[110:111] neg_lo:[0,1] neg_hi:[0,1]
	s_nop 0
	v_pk_mul_f32 v[106:107], v[108:109], v[106:107]
	s_nop 0
	v_pk_fma_f32 v[106:107], v[102:103], v[106:107], v[98:99] op_sel_hi:[0,1,0]
	v_cvt_pk_bf16_f32 v85, v106, v107
	v_and_b32_e32 v106, 0xffff0000, v90
	v_and_b32_e32 v107, 0xffff0000, v94
	v_pk_add_f32 v[106:107], v[106:107], v[110:111] neg_lo:[0,1] neg_hi:[0,1]
	ds_write_b32 v177, v85 offset:1248
	v_pk_mul_f32 v[106:107], v[108:109], v[106:107]
	v_and_b32_e32 v90, 0xffff0000, v91
	v_pk_fma_f32 v[98:99], v[102:103], v[106:107], v[98:99] op_sel:[1,0,1]
	s_nop 0
	v_cvt_pk_bf16_f32 v85, v98, v99
	v_lshlrev_b32_e32 v98, 16, v91
	v_lshlrev_b32_e32 v99, 16, v95
	v_and_b32_e32 v91, 0xffff0000, v95
	v_pk_add_f32 v[98:99], v[98:99], v[110:111] neg_lo:[0,1] neg_hi:[0,1]
	v_pk_add_f32 v[90:91], v[90:91], v[110:111] neg_lo:[0,1] neg_hi:[0,1]
	v_pk_mul_f32 v[98:99], v[108:109], v[98:99]
	v_pk_mul_f32 v[90:91], v[108:109], v[90:91]
	ds_write_b32 v177, v85 offset:3424
	v_pk_fma_f32 v[98:99], v[104:105], v[98:99], v[100:101] op_sel_hi:[0,1,0]
	v_cvt_pk_bf16_f32 v85, v98, v99
	v_pk_fma_f32 v[90:91], v[160:161], v[90:91], v[162:163] op_sel_hi:[0,1,0]
	ds_write_b32 v177, v85 offset:5600
	v_cvt_pk_bf16_f32 v85, v90, v91
	v_lshlrev_b32_e32 v90, 16, v92
	v_lshlrev_b32_e32 v91, 16, v96
	v_pk_add_f32 v[90:91], v[90:91], v[110:111] neg_lo:[0,1] neg_hi:[0,1]
	ds_write_b32 v177, v85 offset:7776
	v_pk_mul_f32 v[90:91], v[108:109], v[90:91]
	s_nop 0
	v_pk_fma_f32 v[90:91], v[82:83], v[90:91], v[86:87] op_sel_hi:[0,1,0]
	v_cvt_pk_bf16_f32 v85, v90, v91
	v_and_b32_e32 v90, 0xffff0000, v92
	v_and_b32_e32 v91, 0xffff0000, v96
	v_pk_add_f32 v[90:91], v[90:91], v[110:111] neg_lo:[0,1] neg_hi:[0,1]
	ds_write_b32 v177, v85 offset:9952
	v_pk_mul_f32 v[90:91], v[108:109], v[90:91]
	s_nop 0
	v_pk_fma_f32 v[82:83], v[82:83], v[90:91], v[86:87] op_sel:[1,0,1]
	s_nop 0
	v_cvt_pk_bf16_f32 v82, v82, v83
	ds_write_b32 v177, v82 offset:12128
	v_lshlrev_b32_e32 v82, 16, v93
	v_lshlrev_b32_e32 v83, 16, v97
	v_pk_add_f32 v[82:83], v[82:83], v[110:111] neg_lo:[0,1] neg_hi:[0,1]
	s_nop 0
	v_pk_mul_f32 v[82:83], v[108:109], v[82:83]
	s_nop 0
	v_pk_fma_f32 v[82:83], v[84:85], v[82:83], v[88:89] op_sel_hi:[0,1,0]
	v_cvt_pk_bf16_f32 v82, v82, v83
	ds_write_b32 v177, v82 offset:14304
	v_and_b32_e32 v82, 0xffff0000, v93
	v_and_b32_e32 v83, 0xffff0000, v97
	v_pk_add_f32 v[82:83], v[82:83], v[110:111] neg_lo:[0,1] neg_hi:[0,1]
	v_or_b32_e32 v84, s18, v163
	v_pk_mul_f32 v[82:83], v[108:109], v[82:83]
	v_lshlrev_b32_e32 v84, 11, v84
	v_pk_fma_f32 v[82:83], v[164:165], v[82:83], v[166:167] op_sel_hi:[0,1,0]
	v_cvt_pk_bf16_f32 v82, v82, v83
	ds_write_b32 v177, v82 offset:16480
	v_lshl_add_u64 v[82:83], v[158:159], 1, v[150:151]
	v_mov_b32_e32 v85, v147
	v_lshl_add_u64 v[144:145], v[82:83], 0, v[84:85]
	global_load_dwordx2 v[158:159], v[144:145], off
	global_load_dwordx2 v[210:211], v[144:145], off offset:32
	global_load_dwordx2 v[212:213], v[144:145], off offset:64
	global_load_dwordx2 v[214:215], v[144:145], off offset:96
	v_add_co_u32_e32 v216, vcc, s43, v144
	s_waitcnt vmcnt(3)
	v_lshlrev_b32_e32 v160, 16, v158
	v_addc_co_u32_e32 v217, vcc, 0, v145, vcc
	global_load_dwordx2 v[218:219], v[216:217], off
	global_load_dwordx2 v[220:221], v[216:217], off offset:32
	global_load_dwordx2 v[222:223], v[216:217], off offset:64
	global_load_dwordx2 v[224:225], v[216:217], off offset:96
	v_add_co_u32_e32 v130, vcc, s53, v144
	v_and_b32_e32 v158, 0xffff0000, v158
	s_nop 0
	v_addc_co_u32_e32 v131, vcc, 0, v145, vcc
	v_add_co_u32_e32 v120, vcc, s54, v144
	global_load_dwordx2 v[226:227], v[130:131], off
	global_load_dwordx2 v[138:139], v[130:131], off offset:32
	global_load_dwordx2 v[136:137], v[130:131], off offset:64
	global_load_dwordx2 v[134:135], v[130:131], off offset:96
	v_addc_co_u32_e32 v121, vcc, 0, v145, vcc
	v_add_co_u32_e32 v110, vcc, s55, v144
	global_load_dwordx2 v[132:133], v[120:121], off
	global_load_dwordx2 v[128:129], v[120:121], off offset:32
	global_load_dwordx2 v[126:127], v[120:121], off offset:64
	global_load_dwordx2 v[124:125], v[120:121], off offset:96
	v_addc_co_u32_e32 v111, vcc, 0, v145, vcc
	v_add_co_u32_e32 v100, vcc, s56, v144
	global_load_dwordx2 v[122:123], v[110:111], off
	global_load_dwordx2 v[118:119], v[110:111], off offset:32
	global_load_dwordx2 v[116:117], v[110:111], off offset:64
	global_load_dwordx2 v[114:115], v[110:111], off offset:96
	v_addc_co_u32_e32 v101, vcc, 0, v145, vcc
	v_add_co_u32_e32 v90, vcc, s57, v144
	global_load_dwordx2 v[112:113], v[100:101], off
	global_load_dwordx2 v[108:109], v[100:101], off offset:32
	global_load_dwordx2 v[106:107], v[100:101], off offset:64
	global_load_dwordx2 v[104:105], v[100:101], off offset:96
	v_addc_co_u32_e32 v91, vcc, 0, v145, vcc
	v_add_co_u32_e32 v82, vcc, s58, v144
	global_load_dwordx2 v[102:103], v[90:91], off
	global_load_dwordx2 v[98:99], v[90:91], off offset:32
	global_load_dwordx2 v[96:97], v[90:91], off offset:64
	global_load_dwordx2 v[94:95], v[90:91], off offset:96
	v_addc_co_u32_e32 v83, vcc, 0, v145, vcc
	global_load_dwordx2 v[92:93], v[82:83], off
	global_load_dwordx2 v[88:89], v[82:83], off offset:32
	global_load_dwordx2 v[86:87], v[82:83], off offset:64
	global_load_dwordx2 v[84:85], v[82:83], off offset:96
	s_waitcnt lgkmcnt(0)
	ds_read_b128 v[140:143], v182 offset:1024
	ds_read_b128 v[198:201], v182 offset:1568
	s_waitcnt lgkmcnt(1)
; __device__ __forceinline__ unsigned cvt_pk_bf16(float lo, float hi) { unsigned r; asm volatile("v_cvt_pk_bf16_f32 %0, %1, %2" : "=v"(r) : "v"(lo), "v"(hi)); return r; }
; __device__ __forceinline__ float bf_lo(unsigned w) { return __uint_as_float(w << 16); }
; __device__ __forceinline__ float bf_hi(unsigned w) { return __uint_as_float(w & 0xffff0000u); }
; #define LAS __attribute__((address_space(3)))
; __device__ __forceinline__ void sgu_unit(LAS unsigned char* lds, bf16* U, const bf16* VS, const float* SGS, const float* lnw, const float* lnb, const v4u* WF, const float* bsl, int unit, int tid) {
;     ...
;     {
;         int q = 0;
; #pragma unroll
;         for (int mt = 0; mt < 8; ++mt) {
;             const int t = 16 * mt + fr;
;             f32x4 acc[4];
; #pragma unroll
;             for (int nt = 0; nt < 4; ++nt) acc[nt] = (f32x4){0.f, 0.f, 0.f, 0.f};
; #pragma unroll
;             for (int ks = 0; ks <= (mt >> 1); ++ks) {
;                 const int sb = 32 * ks + 8 * fq; const bf16x8_t wf = __builtin_bit_cast(bf16x8_t, wfr[q++]);
; #pragma unroll
;                 for (int nt = 0; nt < 4; ++nt) { const bf16x8_t vf = *(const LAS bf16x8_t*)(vt + ((fr >> 3) + 8 * (fr & 7) + 2 * nt) * SGU_VP + sb * 2);
;                     acc[nt] = __builtin_amdgcn_mfma_f32_16x16x32_bf16(vf, wf, acc[nt], 0, 0, 0); }
;             }
;             const float bb = bbv[mt];
; #pragma unroll
;             for (int nt = 0; nt < 4; ++nt) { const v2u u2 = uu[mt][nt]; v2u w; w.x = cvt_pk_bf16(bf_lo(u2.x) * (acc[nt][0] + bb), bf_hi(u2.x) * (acc[nt][1] + bb)); w.y = cvt_pk_bf16(bf_lo(u2.y) * (acc[nt][2] + bb), bf_hi(u2.y) * (acc[nt][3] + bb));
;                 *(v2u*)(U + (size_t)(r0 + t) * 1024 + colbase + 16 * nt + 4 * fq) = w; }
;         }
	v_mfma_f32_16x16x32_bf16 v[140:143], v[140:143], v[78:81], 0
	ds_read_b128 v[202:205], v182 offset:2112
	ds_read_b128 v[206:209], v182 offset:2656
	s_nop 5
	v_add_f32_e32 v140, v197, v140
	v_add_f32_e32 v141, v197, v141
	s_waitcnt lgkmcnt(2)
	v_mfma_f32_16x16x32_bf16 v[198:201], v[198:201], v[78:81], 0
	v_mul_f32_e32 v140, v140, v160
	v_mul_f32_e32 v141, v141, v158
	v_cvt_pk_bf16_f32 v140, v140, v141
	v_lshlrev_b32_e32 v141, 16, v159
	v_add_f32_e32 v142, v197, v142
	v_mul_f32_e32 v141, v142, v141
	v_and_b32_e32 v142, 0xffff0000, v159
	v_add_f32_e32 v143, v197, v143
	v_mul_f32_e32 v142, v143, v142
	v_cvt_pk_bf16_f32 v141, v141, v142
	global_store_dwordx2 v[144:145], v[140:141], off
	s_waitcnt vmcnt(31)
	v_lshlrev_b32_e32 v140, 16, v210
	v_add_f32_e32 v141, v197, v198
	v_mul_f32_e32 v140, v141, v140
	v_and_b32_e32 v141, 0xffff0000, v210
	v_add_f32_e32 v142, v197, v199
	s_waitcnt lgkmcnt(1)
	v_mfma_f32_16x16x32_bf16 v[202:205], v[202:205], v[78:81], 0
	v_mul_f32_e32 v141, v142, v141
	v_cvt_pk_bf16_f32 v140, v140, v141
	v_lshlrev_b32_e32 v141, 16, v211
	v_add_f32_e32 v142, v197, v200
	v_mul_f32_e32 v141, v142, v141
	v_and_b32_e32 v142, 0xffff0000, v211
	v_add_f32_e32 v143, v197, v201
	v_mul_f32_e32 v142, v143, v142
	v_cvt_pk_bf16_f32 v141, v141, v142
	global_store_dwordx2 v[144:145], v[140:141], off offset:32
	s_waitcnt vmcnt(31)
	v_lshlrev_b32_e32 v140, 16, v212
	v_add_f32_e32 v141, v197, v202
	s_waitcnt lgkmcnt(0)
	v_mfma_f32_16x16x32_bf16 v[78:81], v[206:209], v[78:81], 0
	v_mul_f32_e32 v140, v141, v140
	v_and_b32_e32 v141, 0xffff0000, v212
	v_add_f32_e32 v142, v197, v203
	v_mul_f32_e32 v141, v142, v141
	v_cvt_pk_bf16_f32 v140, v140, v141
	v_lshlrev_b32_e32 v141, 16, v213
	v_add_f32_e32 v142, v197, v204
	v_mul_f32_e32 v141, v142, v141
	v_and_b32_e32 v142, 0xffff0000, v213
	v_add_f32_e32 v143, v197, v205
	v_mul_f32_e32 v142, v143, v142
	v_cvt_pk_bf16_f32 v141, v141, v142
	global_store_dwordx2 v[144:145], v[140:141], off offset:64
	s_waitcnt vmcnt(31)
	v_lshlrev_b32_e32 v140, 16, v214
	v_add_f32_e32 v78, v197, v78
	v_mul_f32_e32 v78, v78, v140
	v_and_b32_e32 v140, 0xffff0000, v214
	v_add_f32_e32 v79, v197, v79
	v_mul_f32_e32 v79, v79, v140
	v_cvt_pk_bf16_f32 v158, v78, v79
	v_lshlrev_b32_e32 v78, 16, v215
	v_add_f32_e32 v79, v197, v80
	v_mul_f32_e32 v78, v79, v78
	v_and_b32_e32 v79, 0xffff0000, v215
	v_add_f32_e32 v80, v197, v81
	v_mul_f32_e32 v79, v80, v79
	v_cvt_pk_bf16_f32 v159, v78, v79
	ds_read_b128 v[78:81], v182 offset:1024
	ds_read_b128 v[140:143], v182 offset:1568
	s_waitcnt lgkmcnt(1)
	v_mfma_f32_16x16x32_bf16 v[78:81], v[78:81], v[74:77], 0
	ds_read_b128 v[198:201], v182 offset:2112
	ds_read_b128 v[202:205], v182 offset:2656
	global_store_dwordx2 v[144:145], v[158:159], off offset:96
	s_waitcnt vmcnt(31)
	v_lshlrev_b32_e32 v144, 16, v218
	s_nop 2
	v_add_f32_e32 v78, v196, v78
	v_mul_f32_e32 v78, v78, v144
	v_and_b32_e32 v144, 0xffff0000, v218
	v_add_f32_e32 v79, v196, v79
	s_waitcnt lgkmcnt(2)
	v_mfma_f32_16x16x32_bf16 v[140:143], v[140:143], v[74:77], 0
	v_mul_f32_e32 v79, v79, v144
	v_cvt_pk_bf16_f32 v78, v78, v79
	v_lshlrev_b32_e32 v79, 16, v219
	v_add_f32_e32 v80, v196, v80
	v_mul_f32_e32 v79, v80, v79
	v_and_b32_e32 v80, 0xffff0000, v219
	v_add_f32_e32 v81, v196, v81
	v_mul_f32_e32 v80, v81, v80
	v_cvt_pk_bf16_f32 v79, v79, v80
	global_store_dwordx2 v[216:217], v[78:79], off
	s_waitcnt vmcnt(31)
	v_lshlrev_b32_e32 v78, 16, v220
	v_add_f32_e32 v79, v196, v140
	v_mul_f32_e32 v78, v79, v78
	v_and_b32_e32 v79, 0xffff0000, v220
	v_add_f32_e32 v80, v196, v141
	s_waitcnt lgkmcnt(1)
	v_mfma_f32_16x16x32_bf16 v[198:201], v[198:201], v[74:77], 0
	v_mul_f32_e32 v79, v80, v79
	v_cvt_pk_bf16_f32 v78, v78, v79
	v_lshlrev_b32_e32 v79, 16, v221
	v_add_f32_e32 v80, v196, v142
	v_mul_f32_e32 v79, v80, v79
	v_and_b32_e32 v80, 0xffff0000, v221
	v_add_f32_e32 v81, v196, v143
	v_mul_f32_e32 v80, v81, v80
	v_cvt_pk_bf16_f32 v79, v79, v80
	global_store_dwordx2 v[216:217], v[78:79], off offset:32
	s_waitcnt vmcnt(31)
	v_lshlrev_b32_e32 v78, 16, v222
	v_add_f32_e32 v79, v196, v198
	s_waitcnt lgkmcnt(0)
	v_mfma_f32_16x16x32_bf16 v[74:77], v[202:205], v[74:77], 0
	v_mul_f32_e32 v78, v79, v78
	v_and_b32_e32 v79, 0xffff0000, v222
	v_add_f32_e32 v80, v196, v199
	v_mul_f32_e32 v79, v80, v79
	v_cvt_pk_bf16_f32 v78, v78, v79
	v_lshlrev_b32_e32 v79, 16, v223
	v_add_f32_e32 v80, v196, v200
	v_mul_f32_e32 v79, v80, v79
	v_and_b32_e32 v80, 0xffff0000, v223
	v_add_f32_e32 v81, v196, v201
	v_mul_f32_e32 v80, v81, v80
	v_cvt_pk_bf16_f32 v79, v79, v80
	global_store_dwordx2 v[216:217], v[78:79], off offset:64
	s_waitcnt vmcnt(31)
	v_lshlrev_b32_e32 v78, 16, v224
	v_add_f32_e32 v74, v196, v74
	v_mul_f32_e32 v74, v74, v78
	v_and_b32_e32 v78, 0xffff0000, v224
	v_add_f32_e32 v75, v196, v75
	v_mul_f32_e32 v75, v75, v78
	v_cvt_pk_bf16_f32 v144, v74, v75
	v_lshlrev_b32_e32 v74, 16, v225
	v_add_f32_e32 v75, v196, v76
	v_mul_f32_e32 v74, v75, v74
	v_and_b32_e32 v75, 0xffff0000, v225
	v_add_f32_e32 v76, v196, v77
	v_mul_f32_e32 v75, v76, v75
	v_cvt_pk_bf16_f32 v145, v74, v75
	ds_read_b128 v[74:77], v182 offset:1024
	ds_read_b128 v[78:81], v182 offset:1088
	s_waitcnt lgkmcnt(1)
	v_mfma_f32_16x16x32_bf16 v[74:77], v[74:77], v[70:73], 0
	ds_read_b128 v[140:143], v182 offset:1568
	ds_read_b128 v[196:199], v182 offset:1632
	ds_read_b128 v[200:203], v182 offset:2112
	ds_read_b128 v[204:207], v182 offset:2176
	ds_read_b128 v[208:211], v182 offset:2656
	ds_read_b128 v[212:215], v182 offset:2720
	s_waitcnt lgkmcnt(5)
	v_mfma_f32_16x16x32_bf16 v[140:143], v[140:143], v[70:73], 0
	global_store_dwordx2 v[216:217], v[144:145], off offset:96
	s_waitcnt lgkmcnt(3)
; __device__ __forceinline__ unsigned cvt_pk_bf16(float lo, float hi) { unsigned r; asm volatile("v_cvt_pk_bf16_f32 %0, %1, %2" : "=v"(r) : "v"(lo), "v"(hi)); return r; }
; __device__ __forceinline__ float bf_lo(unsigned w) { return __uint_as_float(w << 16); }
; __device__ __forceinline__ float bf_hi(unsigned w) { return __uint_as_float(w & 0xffff0000u); }
; #define LAS __attribute__((address_space(3)))
; __device__ __forceinline__ void sgu_unit(LAS unsigned char* lds, bf16* U, const bf16* VS, const float* SGS, const float* lnw, const float* lnb, const v4u* WF, const float* bsl, int unit, int tid) {
;     ...
;     {
;         int q = 0;
; #pragma unroll
;         for (int mt = 0; mt < 8; ++mt) {
;             const int t = 16 * mt + fr;
;             f32x4 acc[4];
; #pragma unroll
;             for (int nt = 0; nt < 4; ++nt) acc[nt] = (f32x4){0.f, 0.f, 0.f, 0.f};
; #pragma unroll
;             for (int ks = 0; ks <= (mt >> 1); ++ks) {
;                 const int sb = 32 * ks + 8 * fq; const bf16x8_t wf = __builtin_bit_cast(bf16x8_t, wfr[q++]);
; #pragma unroll
;                 for (int nt = 0; nt < 4; ++nt) { const bf16x8_t vf = *(const LAS bf16x8_t*)(vt + ((fr >> 3) + 8 * (fr & 7) + 2 * nt) * SGU_VP + sb * 2);
;                     acc[nt] = __builtin_amdgcn_mfma_f32_16x16x32_bf16(vf, wf, acc[nt], 0, 0, 0); }
;             }
;             const float bb = bbv[mt];
; #pragma unroll
;             for (int nt = 0; nt < 4; ++nt) { const v2u u2 = uu[mt][nt]; v2u w; w.x = cvt_pk_bf16(bf_lo(u2.x) * (acc[nt][0] + bb), bf_hi(u2.x) * (acc[nt][1] + bb)); w.y = cvt_pk_bf16(bf_lo(u2.y) * (acc[nt][2] + bb), bf_hi(u2.y) * (acc[nt][3] + bb));
;                 *(v2u*)(U + (size_t)(r0 + t) * 1024 + colbase + 16 * nt + 4 * fq) = w; }
;         }
	v_mfma_f32_16x16x32_bf16 v[200:203], v[200:203], v[70:73], 0
	s_waitcnt lgkmcnt(1)
	v_mfma_f32_16x16x32_bf16 v[70:73], v[208:211], v[70:73], 0
	v_mfma_f32_16x16x32_bf16 v[74:77], v[78:81], v[66:69], v[74:77]
	v_mfma_f32_16x16x32_bf16 v[78:81], v[196:199], v[66:69], v[140:143]
	v_mfma_f32_16x16x32_bf16 v[140:143], v[204:207], v[66:69], v[200:203]
	s_waitcnt lgkmcnt(0)
	v_mfma_f32_16x16x32_bf16 v[66:69], v[212:215], v[66:69], v[70:73]
	s_waitcnt vmcnt(31)
	s_nop 1
	v_lshlrev_b32_e32 v70, 16, v226
	v_add_f32_e32 v71, v195, v74
	v_mul_f32_e32 v70, v71, v70
	v_and_b32_e32 v71, 0xffff0000, v226
	v_add_f32_e32 v72, v195, v75
	v_mul_f32_e32 v71, v72, v71
	v_cvt_pk_bf16_f32 v70, v70, v71
	v_lshlrev_b32_e32 v71, 16, v227
	v_add_f32_e32 v72, v195, v76
	v_mul_f32_e32 v71, v72, v71
	v_and_b32_e32 v72, 0xffff0000, v227
	v_add_f32_e32 v73, v195, v77
	v_mul_f32_e32 v72, v73, v72
	v_cvt_pk_bf16_f32 v71, v71, v72
	global_store_dwordx2 v[130:131], v[70:71], off
	s_waitcnt vmcnt(31)
	v_lshlrev_b32_e32 v70, 16, v138
	v_add_f32_e32 v71, v195, v78
	v_mul_f32_e32 v70, v71, v70
	v_and_b32_e32 v71, 0xffff0000, v138
	v_add_f32_e32 v72, v195, v79
	v_mul_f32_e32 v71, v72, v71
	v_cvt_pk_bf16_f32 v70, v70, v71
	v_lshlrev_b32_e32 v71, 16, v139
	v_add_f32_e32 v72, v195, v80
	v_mul_f32_e32 v71, v72, v71
	v_and_b32_e32 v72, 0xffff0000, v139
	v_add_f32_e32 v73, v195, v81
	v_mul_f32_e32 v72, v73, v72
	v_cvt_pk_bf16_f32 v71, v71, v72
	global_store_dwordx2 v[130:131], v[70:71], off offset:32
	s_waitcnt vmcnt(31)
	v_lshlrev_b32_e32 v70, 16, v136
	v_add_f32_e32 v71, v195, v140
	v_mul_f32_e32 v70, v71, v70
	v_and_b32_e32 v71, 0xffff0000, v136
	v_add_f32_e32 v72, v195, v141
	v_mul_f32_e32 v71, v72, v71
	v_cvt_pk_bf16_f32 v70, v70, v71
	v_lshlrev_b32_e32 v71, 16, v137
	v_add_f32_e32 v72, v195, v142
	v_mul_f32_e32 v71, v72, v71
	v_and_b32_e32 v72, 0xffff0000, v137
	v_add_f32_e32 v73, v195, v143
	v_mul_f32_e32 v72, v73, v72
	v_cvt_pk_bf16_f32 v71, v71, v72
	global_store_dwordx2 v[130:131], v[70:71], off offset:64
	s_waitcnt vmcnt(31)
	v_lshlrev_b32_e32 v70, 16, v134
	v_add_f32_e32 v66, v195, v66
	v_mul_f32_e32 v66, v66, v70
	v_and_b32_e32 v70, 0xffff0000, v134
	v_add_f32_e32 v67, v195, v67
	v_mul_f32_e32 v67, v67, v70
	v_cvt_pk_bf16_f32 v158, v66, v67
	v_lshlrev_b32_e32 v66, 16, v135
	v_add_f32_e32 v67, v195, v68
	v_mul_f32_e32 v66, v67, v66
	v_and_b32_e32 v67, 0xffff0000, v135
	v_add_f32_e32 v68, v195, v69
	v_mul_f32_e32 v67, v68, v67
	v_cvt_pk_bf16_f32 v159, v66, v67
	ds_read_b128 v[66:69], v182 offset:1024
	ds_read_b128 v[70:73], v182 offset:1088
	s_waitcnt lgkmcnt(1)
	v_mfma_f32_16x16x32_bf16 v[66:69], v[66:69], v[62:65], 0
	ds_read_b128 v[74:77], v182 offset:1568
	ds_read_b128 v[78:81], v182 offset:1632
	ds_read_b128 v[134:137], v182 offset:2112
	ds_read_b128 v[138:141], v182 offset:2176
	ds_read_b128 v[142:145], v182 offset:2656
	ds_read_b128 v[196:199], v182 offset:2720
	s_waitcnt lgkmcnt(5)
	v_mfma_f32_16x16x32_bf16 v[74:77], v[74:77], v[62:65], 0
	global_store_dwordx2 v[130:131], v[158:159], off offset:96
	s_waitcnt lgkmcnt(3)
	v_mfma_f32_16x16x32_bf16 v[134:137], v[134:137], v[62:65], 0
	s_waitcnt lgkmcnt(1)
	v_mfma_f32_16x16x32_bf16 v[62:65], v[142:145], v[62:65], 0
	v_mfma_f32_16x16x32_bf16 v[66:69], v[70:73], v[58:61], v[66:69]
	v_mfma_f32_16x16x32_bf16 v[70:73], v[78:81], v[58:61], v[74:77]
	v_mfma_f32_16x16x32_bf16 v[74:77], v[138:141], v[58:61], v[134:137]
	s_waitcnt lgkmcnt(0)
	v_mfma_f32_16x16x32_bf16 v[58:61], v[196:199], v[58:61], v[62:65]
	s_waitcnt vmcnt(31)
	s_nop 1
	v_lshlrev_b32_e32 v62, 16, v132
	v_add_f32_e32 v63, v194, v66
	v_mul_f32_e32 v62, v63, v62
	v_and_b32_e32 v63, 0xffff0000, v132
	v_add_f32_e32 v64, v194, v67
	v_mul_f32_e32 v63, v64, v63
	v_cvt_pk_bf16_f32 v62, v62, v63
	v_lshlrev_b32_e32 v63, 16, v133
	v_add_f32_e32 v64, v194, v68
	v_mul_f32_e32 v63, v64, v63
	v_and_b32_e32 v64, 0xffff0000, v133
	v_add_f32_e32 v65, v194, v69
	v_mul_f32_e32 v64, v65, v64
	v_cvt_pk_bf16_f32 v63, v63, v64
	global_store_dwordx2 v[120:121], v[62:63], off
	s_waitcnt vmcnt(31)
	v_lshlrev_b32_e32 v62, 16, v128
	v_add_f32_e32 v63, v194, v70
	v_mul_f32_e32 v62, v63, v62
	v_and_b32_e32 v63, 0xffff0000, v128
	v_add_f32_e32 v64, v194, v71
	v_mul_f32_e32 v63, v64, v63
	v_cvt_pk_bf16_f32 v62, v62, v63
	v_lshlrev_b32_e32 v63, 16, v129
	v_add_f32_e32 v64, v194, v72
	v_mul_f32_e32 v63, v64, v63
	v_and_b32_e32 v64, 0xffff0000, v129
	v_add_f32_e32 v65, v194, v73
	v_mul_f32_e32 v64, v65, v64
	v_cvt_pk_bf16_f32 v63, v63, v64
	global_store_dwordx2 v[120:121], v[62:63], off offset:32
	s_waitcnt vmcnt(31)
	v_lshlrev_b32_e32 v62, 16, v126
	v_add_f32_e32 v63, v194, v74
	v_mul_f32_e32 v62, v63, v62
	v_and_b32_e32 v63, 0xffff0000, v126
	v_add_f32_e32 v64, v194, v75
	v_mul_f32_e32 v63, v64, v63
	v_cvt_pk_bf16_f32 v62, v62, v63
	v_lshlrev_b32_e32 v63, 16, v127
	v_add_f32_e32 v64, v194, v76
	v_mul_f32_e32 v63, v64, v63
	v_and_b32_e32 v64, 0xffff0000, v127
	v_add_f32_e32 v65, v194, v77
	v_mul_f32_e32 v64, v65, v64
	v_cvt_pk_bf16_f32 v63, v63, v64
	global_store_dwordx2 v[120:121], v[62:63], off offset:64
	s_waitcnt vmcnt(31)
	v_lshlrev_b32_e32 v62, 16, v124
	v_add_f32_e32 v58, v194, v58
	v_mul_f32_e32 v58, v58, v62
	v_and_b32_e32 v62, 0xffff0000, v124
	v_add_f32_e32 v59, v194, v59
	v_mul_f32_e32 v59, v59, v62
	v_cvt_pk_bf16_f32 v132, v58, v59
	v_lshlrev_b32_e32 v58, 16, v125
	v_add_f32_e32 v59, v194, v60
	v_mul_f32_e32 v58, v59, v58
	v_and_b32_e32 v59, 0xffff0000, v125
	v_add_f32_e32 v60, v194, v61
	v_mul_f32_e32 v59, v60, v59
	v_cvt_pk_bf16_f32 v133, v58, v59
	ds_read_b128 v[58:61], v182 offset:1024
	ds_read_b128 v[62:65], v182 offset:1088
	s_waitcnt lgkmcnt(1)
; __device__ __forceinline__ unsigned cvt_pk_bf16(float lo, float hi) { unsigned r; asm volatile("v_cvt_pk_bf16_f32 %0, %1, %2" : "=v"(r) : "v"(lo), "v"(hi)); return r; }
; __device__ __forceinline__ float bf_lo(unsigned w) { return __uint_as_float(w << 16); }
; __device__ __forceinline__ float bf_hi(unsigned w) { return __uint_as_float(w & 0xffff0000u); }
; #define LAS __attribute__((address_space(3)))
; __device__ __forceinline__ void sgu_unit(LAS unsigned char* lds, bf16* U, const bf16* VS, const float* SGS, const float* lnw, const float* lnb, const v4u* WF, const float* bsl, int unit, int tid) {
;     ...
;     {
;         int q = 0;
; #pragma unroll
;         for (int mt = 0; mt < 8; ++mt) {
;             const int t = 16 * mt + fr;
;             f32x4 acc[4];
; #pragma unroll
;             for (int nt = 0; nt < 4; ++nt) acc[nt] = (f32x4){0.f, 0.f, 0.f, 0.f};
; #pragma unroll
;             for (int ks = 0; ks <= (mt >> 1); ++ks) {
;                 const int sb = 32 * ks + 8 * fq; const bf16x8_t wf = __builtin_bit_cast(bf16x8_t, wfr[q++]);
; #pragma unroll
;                 for (int nt = 0; nt < 4; ++nt) { const bf16x8_t vf = *(const LAS bf16x8_t*)(vt + ((fr >> 3) + 8 * (fr & 7) + 2 * nt) * SGU_VP + sb * 2);
;                     acc[nt] = __builtin_amdgcn_mfma_f32_16x16x32_bf16(vf, wf, acc[nt], 0, 0, 0); }
;             }
;             const float bb = bbv[mt];
; #pragma unroll
;             for (int nt = 0; nt < 4; ++nt) { const v2u u2 = uu[mt][nt]; v2u w; w.x = cvt_pk_bf16(bf_lo(u2.x) * (acc[nt][0] + bb), bf_hi(u2.x) * (acc[nt][1] + bb)); w.y = cvt_pk_bf16(bf_lo(u2.y) * (acc[nt][2] + bb), bf_hi(u2.y) * (acc[nt][3] + bb));
;                 *(v2u*)(U + (size_t)(r0 + t) * 1024 + colbase + 16 * nt + 4 * fq) = w; }
;         }
	v_mfma_f32_16x16x32_bf16 v[58:61], v[58:61], v[50:53], 0
	ds_read_b128 v[66:69], v182 offset:1568
	ds_read_b128 v[70:73], v182 offset:1152
	ds_read_b128 v[74:77], v182 offset:2112
	ds_read_b128 v[78:81], v182 offset:2176
	ds_read_b128 v[124:127], v182 offset:2656
	ds_read_b128 v[128:131], v182 offset:2240
	s_waitcnt lgkmcnt(5)
	v_mfma_f32_16x16x32_bf16 v[66:69], v[66:69], v[50:53], 0
	s_waitcnt lgkmcnt(3)
	v_mfma_f32_16x16x32_bf16 v[74:77], v[74:77], v[50:53], 0
	s_waitcnt lgkmcnt(1)
	v_mfma_f32_16x16x32_bf16 v[50:53], v[124:127], v[50:53], 0
	v_mfma_f32_16x16x32_bf16 v[58:61], v[62:65], v[54:57], v[58:61]
	ds_read_b128 v[62:65], v182 offset:1632
	ds_read_b128 v[124:127], v182 offset:1696
	s_waitcnt lgkmcnt(1)
	v_mfma_f32_16x16x32_bf16 v[62:65], v[62:65], v[54:57], v[66:69]
	v_mfma_f32_16x16x32_bf16 v[66:69], v[78:81], v[54:57], v[74:77]
	s_nop 2
	ds_read_b128 v[74:77], v182 offset:2720
	ds_read_b128 v[78:81], v182 offset:2784
	global_store_dwordx2 v[120:121], v[132:133], off offset:96
	s_waitcnt lgkmcnt(1)
	v_mfma_f32_16x16x32_bf16 v[50:53], v[74:77], v[54:57], v[50:53]
	v_mfma_f32_16x16x32_bf16 v[54:57], v[70:73], v[46:49], v[58:61]
	v_mfma_f32_16x16x32_bf16 v[58:61], v[124:127], v[46:49], v[62:65]
	v_mfma_f32_16x16x32_bf16 v[62:65], v[128:131], v[46:49], v[66:69]
	s_waitcnt lgkmcnt(0)
	v_mfma_f32_16x16x32_bf16 v[46:49], v[78:81], v[46:49], v[50:53]
	s_waitcnt vmcnt(31)
	s_nop 1
	v_lshlrev_b32_e32 v50, 16, v122
	v_add_f32_e32 v51, v193, v54
	v_mul_f32_e32 v50, v51, v50
	v_and_b32_e32 v51, 0xffff0000, v122
	v_add_f32_e32 v52, v193, v55
	v_mul_f32_e32 v51, v52, v51
	v_cvt_pk_bf16_f32 v50, v50, v51
	v_lshlrev_b32_e32 v51, 16, v123
	v_add_f32_e32 v52, v193, v56
	v_mul_f32_e32 v51, v52, v51
	v_and_b32_e32 v52, 0xffff0000, v123
	v_add_f32_e32 v53, v193, v57
	v_mul_f32_e32 v52, v53, v52
	v_cvt_pk_bf16_f32 v51, v51, v52
	global_store_dwordx2 v[110:111], v[50:51], off
	s_waitcnt vmcnt(31)
	v_lshlrev_b32_e32 v50, 16, v118
	v_add_f32_e32 v51, v193, v58
	v_mul_f32_e32 v50, v51, v50
	v_and_b32_e32 v51, 0xffff0000, v118
	v_add_f32_e32 v52, v193, v59
	v_mul_f32_e32 v51, v52, v51
	v_cvt_pk_bf16_f32 v50, v50, v51
	v_lshlrev_b32_e32 v51, 16, v119
	v_add_f32_e32 v52, v193, v60
	v_mul_f32_e32 v51, v52, v51
	v_and_b32_e32 v52, 0xffff0000, v119
	v_add_f32_e32 v53, v193, v61
	v_mul_f32_e32 v52, v53, v52
	v_cvt_pk_bf16_f32 v51, v51, v52
	global_store_dwordx2 v[110:111], v[50:51], off offset:32
	s_waitcnt vmcnt(31)
	v_lshlrev_b32_e32 v50, 16, v116
	v_add_f32_e32 v51, v193, v62
	v_mul_f32_e32 v50, v51, v50
	v_and_b32_e32 v51, 0xffff0000, v116
	v_add_f32_e32 v52, v193, v63
	v_mul_f32_e32 v51, v52, v51
	v_cvt_pk_bf16_f32 v50, v50, v51
	v_lshlrev_b32_e32 v51, 16, v117
	v_add_f32_e32 v52, v193, v64
	v_mul_f32_e32 v51, v52, v51
	v_and_b32_e32 v52, 0xffff0000, v117
	v_add_f32_e32 v53, v193, v65
	v_mul_f32_e32 v52, v53, v52
	v_cvt_pk_bf16_f32 v51, v51, v52
	global_store_dwordx2 v[110:111], v[50:51], off offset:64
	s_waitcnt vmcnt(31)
	v_lshlrev_b32_e32 v50, 16, v114
	v_add_f32_e32 v46, v193, v46
	v_mul_f32_e32 v46, v46, v50
	v_and_b32_e32 v50, 0xffff0000, v114
	v_add_f32_e32 v47, v193, v47
	v_mul_f32_e32 v47, v47, v50
	v_cvt_pk_bf16_f32 v78, v46, v47
	v_lshlrev_b32_e32 v46, 16, v115
	v_add_f32_e32 v47, v193, v48
	v_mul_f32_e32 v46, v47, v46
	v_and_b32_e32 v47, 0xffff0000, v115
	v_add_f32_e32 v48, v193, v49
	v_mul_f32_e32 v47, v48, v47
	v_cvt_pk_bf16_f32 v79, v46, v47
	ds_read_b128 v[46:49], v182 offset:1024
	ds_read_b128 v[50:53], v182 offset:1088
	s_waitcnt lgkmcnt(1)
	v_mfma_f32_16x16x32_bf16 v[46:49], v[46:49], v[42:45], 0
	ds_read_b128 v[54:57], v182 offset:1568
	ds_read_b128 v[58:61], v182 offset:1152
	ds_read_b128 v[62:65], v182 offset:2112
	ds_read_b128 v[66:69], v182 offset:2176
	ds_read_b128 v[70:73], v182 offset:2656
	ds_read_b128 v[74:77], v182 offset:2240
	s_waitcnt lgkmcnt(5)
	v_mfma_f32_16x16x32_bf16 v[54:57], v[54:57], v[42:45], 0
	s_waitcnt lgkmcnt(3)
	v_mfma_f32_16x16x32_bf16 v[62:65], v[62:65], v[42:45], 0
	s_waitcnt lgkmcnt(1)
	v_mfma_f32_16x16x32_bf16 v[42:45], v[70:73], v[42:45], 0
	v_mfma_f32_16x16x32_bf16 v[46:49], v[50:53], v[34:37], v[46:49]
	ds_read_b128 v[50:53], v182 offset:1632
	ds_read_b128 v[70:73], v182 offset:1696
	s_waitcnt lgkmcnt(1)
	v_mfma_f32_16x16x32_bf16 v[50:53], v[50:53], v[34:37], v[54:57]
	v_mfma_f32_16x16x32_bf16 v[54:57], v[66:69], v[34:37], v[62:65]
	s_nop 2
	ds_read_b128 v[62:65], v182 offset:2720
	ds_read_b128 v[66:69], v182 offset:2784
	global_store_dwordx2 v[110:111], v[78:79], off offset:96
	s_waitcnt lgkmcnt(1)
	v_mfma_f32_16x16x32_bf16 v[34:37], v[62:65], v[34:37], v[42:45]
	v_mfma_f32_16x16x32_bf16 v[42:45], v[58:61], v[38:41], v[46:49]
	v_mfma_f32_16x16x32_bf16 v[46:49], v[70:73], v[38:41], v[50:53]
	v_mfma_f32_16x16x32_bf16 v[50:53], v[74:77], v[38:41], v[54:57]
	s_waitcnt lgkmcnt(0)
	v_mfma_f32_16x16x32_bf16 v[34:37], v[66:69], v[38:41], v[34:37]
	s_waitcnt vmcnt(31)
	v_lshlrev_b32_e32 v38, 16, v112
	s_nop 1
	v_add_f32_e32 v39, v192, v42
	v_mul_f32_e32 v38, v39, v38
	v_and_b32_e32 v39, 0xffff0000, v112
	v_add_f32_e32 v40, v192, v43
	v_mul_f32_e32 v39, v40, v39
	v_cvt_pk_bf16_f32 v38, v38, v39
	v_lshlrev_b32_e32 v39, 16, v113
	v_add_f32_e32 v40, v192, v44
	v_mul_f32_e32 v39, v40, v39
	v_and_b32_e32 v40, 0xffff0000, v113
	v_add_f32_e32 v41, v192, v45
	v_mul_f32_e32 v40, v41, v40
	v_cvt_pk_bf16_f32 v39, v39, v40
	global_store_dwordx2 v[100:101], v[38:39], off
	s_waitcnt vmcnt(31)
; __device__ __forceinline__ unsigned cvt_pk_bf16(float lo, float hi) { unsigned r; asm volatile("v_cvt_pk_bf16_f32 %0, %1, %2" : "=v"(r) : "v"(lo), "v"(hi)); return r; }
; __device__ __forceinline__ float bf_lo(unsigned w) { return __uint_as_float(w << 16); }
; __device__ __forceinline__ float bf_hi(unsigned w) { return __uint_as_float(w & 0xffff0000u); }
; #define LAS __attribute__((address_space(3)))
; __device__ __forceinline__ void sgu_unit(LAS unsigned char* lds, bf16* U, const bf16* VS, const float* SGS, const float* lnw, const float* lnb, const v4u* WF, const float* bsl, int unit, int tid) {
;     ...
;     {
;         int q = 0;
; #pragma unroll
;         for (int mt = 0; mt < 8; ++mt) {
;             const int t = 16 * mt + fr;
;             f32x4 acc[4];
; #pragma unroll
;             for (int nt = 0; nt < 4; ++nt) acc[nt] = (f32x4){0.f, 0.f, 0.f, 0.f};
; #pragma unroll
;             for (int ks = 0; ks <= (mt >> 1); ++ks) {
;                 const int sb = 32 * ks + 8 * fq; const bf16x8_t wf = __builtin_bit_cast(bf16x8_t, wfr[q++]);
; #pragma unroll
;                 for (int nt = 0; nt < 4; ++nt) { const bf16x8_t vf = *(const LAS bf16x8_t*)(vt + ((fr >> 3) + 8 * (fr & 7) + 2 * nt) * SGU_VP + sb * 2);
;                     acc[nt] = __builtin_amdgcn_mfma_f32_16x16x32_bf16(vf, wf, acc[nt], 0, 0, 0); }
;             }
;             const float bb = bbv[mt];
; #pragma unroll
;             for (int nt = 0; nt < 4; ++nt) { const v2u u2 = uu[mt][nt]; v2u w; w.x = cvt_pk_bf16(bf_lo(u2.x) * (acc[nt][0] + bb), bf_hi(u2.x) * (acc[nt][1] + bb)); w.y = cvt_pk_bf16(bf_lo(u2.y) * (acc[nt][2] + bb), bf_hi(u2.y) * (acc[nt][3] + bb));
;                 *(v2u*)(U + (size_t)(r0 + t) * 1024 + colbase + 16 * nt + 4 * fq) = w; }
;         }
	v_lshlrev_b32_e32 v38, 16, v108
	v_add_f32_e32 v39, v192, v46
	v_mul_f32_e32 v38, v39, v38
	v_and_b32_e32 v39, 0xffff0000, v108
	v_add_f32_e32 v40, v192, v47
	v_mul_f32_e32 v39, v40, v39
	v_cvt_pk_bf16_f32 v38, v38, v39
	v_lshlrev_b32_e32 v39, 16, v109
	v_add_f32_e32 v40, v192, v48
	v_mul_f32_e32 v39, v40, v39
	v_and_b32_e32 v40, 0xffff0000, v109
	v_add_f32_e32 v41, v192, v49
	v_mul_f32_e32 v40, v41, v40
	v_cvt_pk_bf16_f32 v39, v39, v40
	global_store_dwordx2 v[100:101], v[38:39], off offset:32
	s_waitcnt vmcnt(31)
	v_lshlrev_b32_e32 v38, 16, v106
	v_add_f32_e32 v39, v192, v50
	v_mul_f32_e32 v38, v39, v38
	v_and_b32_e32 v39, 0xffff0000, v106
	v_add_f32_e32 v40, v192, v51
	v_mul_f32_e32 v39, v40, v39
	v_cvt_pk_bf16_f32 v38, v38, v39
	v_lshlrev_b32_e32 v39, 16, v107
	v_add_f32_e32 v40, v192, v52
	v_mul_f32_e32 v39, v40, v39
	v_and_b32_e32 v40, 0xffff0000, v107
	v_add_f32_e32 v41, v192, v53
	v_mul_f32_e32 v40, v41, v40
	v_cvt_pk_bf16_f32 v39, v39, v40
	global_store_dwordx2 v[100:101], v[38:39], off offset:64
	s_waitcnt vmcnt(31)
	v_lshlrev_b32_e32 v38, 16, v104
	v_add_f32_e32 v34, v192, v34
	v_mul_f32_e32 v34, v34, v38
	v_and_b32_e32 v38, 0xffff0000, v104
	v_add_f32_e32 v35, v192, v35
	v_mul_f32_e32 v35, v35, v38
	v_cvt_pk_bf16_f32 v66, v34, v35
	v_lshlrev_b32_e32 v34, 16, v105
	v_add_f32_e32 v35, v192, v36
	v_mul_f32_e32 v34, v35, v34
	v_and_b32_e32 v35, 0xffff0000, v105
	v_add_f32_e32 v36, v192, v37
	v_mul_f32_e32 v35, v36, v35
	v_cvt_pk_bf16_f32 v67, v34, v35
	ds_read_b128 v[34:37], v182 offset:1024
	ds_read_b128 v[38:41], v182 offset:1088
	ds_read_b128 v[42:45], v182 offset:1568
	ds_read_b128 v[46:49], v182 offset:1632
	ds_read_b128 v[50:53], v182 offset:2112
	ds_read_b128 v[54:57], v182 offset:2176
	ds_read_b128 v[58:61], v182 offset:2656
	ds_read_b128 v[62:65], v182 offset:2720
	s_waitcnt lgkmcnt(7)
	v_mfma_f32_16x16x32_bf16 v[34:37], v[34:37], v[30:33], 0
	s_waitcnt lgkmcnt(5)
	v_mfma_f32_16x16x32_bf16 v[42:45], v[42:45], v[30:33], 0
	s_waitcnt lgkmcnt(3)
	v_mfma_f32_16x16x32_bf16 v[50:53], v[50:53], v[30:33], 0
	s_waitcnt lgkmcnt(1)
	v_mfma_f32_16x16x32_bf16 v[30:33], v[58:61], v[30:33], 0
	v_mfma_f32_16x16x32_bf16 v[34:37], v[38:41], v[26:29], v[34:37]
	v_mfma_f32_16x16x32_bf16 v[38:41], v[46:49], v[26:29], v[42:45]
	v_mfma_f32_16x16x32_bf16 v[42:45], v[54:57], v[26:29], v[50:53]
	s_waitcnt lgkmcnt(0)
	v_mfma_f32_16x16x32_bf16 v[26:29], v[62:65], v[26:29], v[30:33]
	s_nop 2
	ds_read_b128 v[30:33], v182 offset:1152
	ds_read_b128 v[46:49], v182 offset:1216
	s_waitcnt lgkmcnt(1)
	v_mfma_f32_16x16x32_bf16 v[30:33], v[30:33], v[22:25], v[34:37]
	s_nop 2
	ds_read_b128 v[34:37], v182 offset:1696
	ds_read_b128 v[50:53], v182 offset:1760
	s_waitcnt lgkmcnt(1)
	v_mfma_f32_16x16x32_bf16 v[34:37], v[34:37], v[22:25], v[38:41]
	s_nop 2
	ds_read_b128 v[38:41], v182 offset:2240
	ds_read_b128 v[54:57], v182 offset:2304
	s_waitcnt lgkmcnt(1)
	v_mfma_f32_16x16x32_bf16 v[38:41], v[38:41], v[22:25], v[42:45]
	s_nop 2
	ds_read_b128 v[42:45], v182 offset:2784
	ds_read_b128 v[58:61], v182 offset:2848
	global_store_dwordx2 v[100:101], v[66:67], off offset:96
	s_waitcnt lgkmcnt(1)
	v_mfma_f32_16x16x32_bf16 v[22:25], v[42:45], v[22:25], v[26:29]
	v_mfma_f32_16x16x32_bf16 v[26:29], v[46:49], v[18:21], v[30:33]
	v_mfma_f32_16x16x32_bf16 v[30:33], v[50:53], v[18:21], v[34:37]
	v_mfma_f32_16x16x32_bf16 v[34:37], v[54:57], v[18:21], v[38:41]
	s_waitcnt lgkmcnt(0)
	v_mfma_f32_16x16x32_bf16 v[18:21], v[58:61], v[18:21], v[22:25]
	s_waitcnt vmcnt(31)
	s_nop 1
	v_lshlrev_b32_e32 v22, 16, v102
	v_add_f32_e32 v23, v191, v26
	v_mul_f32_e32 v22, v23, v22
	v_and_b32_e32 v23, 0xffff0000, v102
	v_add_f32_e32 v24, v191, v27
	v_mul_f32_e32 v23, v24, v23
	v_cvt_pk_bf16_f32 v22, v22, v23
	v_lshlrev_b32_e32 v23, 16, v103
	v_add_f32_e32 v24, v191, v28
	v_mul_f32_e32 v23, v24, v23
	v_and_b32_e32 v24, 0xffff0000, v103
	v_add_f32_e32 v25, v191, v29
	v_mul_f32_e32 v24, v25, v24
	v_cvt_pk_bf16_f32 v23, v23, v24
	global_store_dwordx2 v[90:91], v[22:23], off
	s_waitcnt vmcnt(31)
	v_lshlrev_b32_e32 v22, 16, v98
	v_add_f32_e32 v23, v191, v30
	v_mul_f32_e32 v22, v23, v22
	v_and_b32_e32 v23, 0xffff0000, v98
	v_add_f32_e32 v24, v191, v31
	v_mul_f32_e32 v23, v24, v23
	v_cvt_pk_bf16_f32 v22, v22, v23
	v_lshlrev_b32_e32 v23, 16, v99
	v_add_f32_e32 v24, v191, v32
	v_mul_f32_e32 v23, v24, v23
	v_and_b32_e32 v24, 0xffff0000, v99
	v_add_f32_e32 v25, v191, v33
	v_mul_f32_e32 v24, v25, v24
	v_cvt_pk_bf16_f32 v23, v23, v24
	global_store_dwordx2 v[90:91], v[22:23], off offset:32
	s_waitcnt vmcnt(31)
; __device__ __forceinline__ unsigned cvt_pk_bf16(float lo, float hi) { unsigned r; asm volatile("v_cvt_pk_bf16_f32 %0, %1, %2" : "=v"(r) : "v"(lo), "v"(hi)); return r; }
; __device__ __forceinline__ float bf_lo(unsigned w) { return __uint_as_float(w << 16); }
; __device__ __forceinline__ float bf_hi(unsigned w) { return __uint_as_float(w & 0xffff0000u); }
; #define LAS __attribute__((address_space(3)))
; __device__ __forceinline__ void sgu_unit(LAS unsigned char* lds, bf16* U, const bf16* VS, const float* SGS, const float* lnw, const float* lnb, const v4u* WF, const float* bsl, int unit, int tid) {
;     ...
;     {
;         int q = 0;
; #pragma unroll
;         for (int mt = 0; mt < 8; ++mt) {
;             const int t = 16 * mt + fr;
;             f32x4 acc[4];
; #pragma unroll
;             for (int nt = 0; nt < 4; ++nt) acc[nt] = (f32x4){0.f, 0.f, 0.f, 0.f};
; #pragma unroll
;             for (int ks = 0; ks <= (mt >> 1); ++ks) {
;                 const int sb = 32 * ks + 8 * fq; const bf16x8_t wf = __builtin_bit_cast(bf16x8_t, wfr[q++]);
; #pragma unroll
;                 for (int nt = 0; nt < 4; ++nt) { const bf16x8_t vf = *(const LAS bf16x8_t*)(vt + ((fr >> 3) + 8 * (fr & 7) + 2 * nt) * SGU_VP + sb * 2);
;                     acc[nt] = __builtin_amdgcn_mfma_f32_16x16x32_bf16(vf, wf, acc[nt], 0, 0, 0); }
;             }
;             const float bb = bbv[mt];
; #pragma unroll
;             for (int nt = 0; nt < 4; ++nt) { const v2u u2 = uu[mt][nt]; v2u w; w.x = cvt_pk_bf16(bf_lo(u2.x) * (acc[nt][0] + bb), bf_hi(u2.x) * (acc[nt][1] + bb)); w.y = cvt_pk_bf16(bf_lo(u2.y) * (acc[nt][2] + bb), bf_hi(u2.y) * (acc[nt][3] + bb));
;                 *(v2u*)(U + (size_t)(r0 + t) * 1024 + colbase + 16 * nt + 4 * fq) = w; }
;         }
;     }
;     __syncthreads();
	v_lshlrev_b32_e32 v22, 16, v96
	v_add_f32_e32 v23, v191, v34
	v_mul_f32_e32 v22, v23, v22
	v_and_b32_e32 v23, 0xffff0000, v96
	v_add_f32_e32 v24, v191, v35
	v_mul_f32_e32 v23, v24, v23
	v_cvt_pk_bf16_f32 v22, v22, v23
	v_lshlrev_b32_e32 v23, 16, v97
	v_add_f32_e32 v24, v191, v36
	v_mul_f32_e32 v23, v24, v23
	v_and_b32_e32 v24, 0xffff0000, v97
	v_add_f32_e32 v25, v191, v37
	v_mul_f32_e32 v24, v25, v24
	v_cvt_pk_bf16_f32 v23, v23, v24
	global_store_dwordx2 v[90:91], v[22:23], off offset:64
	s_waitcnt vmcnt(31)
	v_lshlrev_b32_e32 v22, 16, v94
	v_add_f32_e32 v18, v191, v18
	v_mul_f32_e32 v18, v18, v22
	v_and_b32_e32 v22, 0xffff0000, v94
	v_add_f32_e32 v19, v191, v19
	v_mul_f32_e32 v19, v19, v22
	v_cvt_pk_bf16_f32 v50, v18, v19
	v_lshlrev_b32_e32 v18, 16, v95
	v_add_f32_e32 v19, v191, v20
	v_mul_f32_e32 v18, v19, v18
	v_and_b32_e32 v19, 0xffff0000, v95
	v_add_f32_e32 v20, v191, v21
	v_mul_f32_e32 v19, v20, v19
	v_cvt_pk_bf16_f32 v51, v18, v19
	ds_read_b128 v[18:21], v182 offset:1024
	ds_read_b128 v[22:25], v182 offset:1088
	ds_read_b128 v[26:29], v182 offset:1568
	ds_read_b128 v[30:33], v182 offset:1632
	ds_read_b128 v[34:37], v182 offset:2112
	ds_read_b128 v[38:41], v182 offset:2176
	ds_read_b128 v[42:45], v182 offset:2656
	ds_read_b128 v[46:49], v182 offset:2720
	s_waitcnt lgkmcnt(7)
	v_mfma_f32_16x16x32_bf16 v[18:21], v[18:21], v[14:17], 0
	s_waitcnt lgkmcnt(5)
	v_mfma_f32_16x16x32_bf16 v[26:29], v[26:29], v[14:17], 0
	s_waitcnt lgkmcnt(3)
	v_mfma_f32_16x16x32_bf16 v[34:37], v[34:37], v[14:17], 0
	s_waitcnt lgkmcnt(1)
	v_mfma_f32_16x16x32_bf16 v[14:17], v[42:45], v[14:17], 0
	v_mfma_f32_16x16x32_bf16 v[18:21], v[22:25], v[10:13], v[18:21]
	v_mfma_f32_16x16x32_bf16 v[22:25], v[30:33], v[10:13], v[26:29]
	v_mfma_f32_16x16x32_bf16 v[26:29], v[38:41], v[10:13], v[34:37]
	s_waitcnt lgkmcnt(0)
	v_mfma_f32_16x16x32_bf16 v[10:13], v[46:49], v[10:13], v[14:17]
	s_nop 2
	ds_read_b128 v[14:17], v182 offset:1152
	ds_read_b128 v[30:33], v182 offset:1216
	s_waitcnt lgkmcnt(1)
	v_mfma_f32_16x16x32_bf16 v[14:17], v[14:17], v[6:9], v[18:21]
	s_nop 2
	ds_read_b128 v[18:21], v182 offset:1696
	ds_read_b128 v[34:37], v182 offset:1760
	s_waitcnt lgkmcnt(1)
	v_mfma_f32_16x16x32_bf16 v[18:21], v[18:21], v[6:9], v[22:25]
	s_nop 2
	ds_read_b128 v[22:25], v182 offset:2240
	ds_read_b128 v[38:41], v182 offset:2304
	s_waitcnt lgkmcnt(1)
	v_mfma_f32_16x16x32_bf16 v[22:25], v[22:25], v[6:9], v[26:29]
	s_nop 2
	ds_read_b128 v[26:29], v182 offset:2784
	ds_read_b128 v[42:45], v182 offset:2848
	global_store_dwordx2 v[90:91], v[50:51], off offset:96
	s_waitcnt lgkmcnt(1)
	v_mfma_f32_16x16x32_bf16 v[6:9], v[26:29], v[6:9], v[10:13]
	v_mfma_f32_16x16x32_bf16 v[10:13], v[30:33], v[2:5], v[14:17]
	v_mfma_f32_16x16x32_bf16 v[14:17], v[34:37], v[2:5], v[18:21]
	v_mfma_f32_16x16x32_bf16 v[18:21], v[38:41], v[2:5], v[22:25]
	s_waitcnt lgkmcnt(0)
	v_mfma_f32_16x16x32_bf16 v[2:5], v[42:45], v[2:5], v[6:9]
	s_waitcnt vmcnt(31)
	s_nop 1
	v_lshlrev_b32_e32 v6, 16, v92
	v_add_f32_e32 v7, v157, v10
	v_mul_f32_e32 v6, v7, v6
	v_and_b32_e32 v7, 0xffff0000, v92
	v_add_f32_e32 v8, v157, v11
	v_mul_f32_e32 v7, v8, v7
	v_cvt_pk_bf16_f32 v6, v6, v7
	v_lshlrev_b32_e32 v7, 16, v93
	v_add_f32_e32 v8, v157, v12
	v_mul_f32_e32 v7, v8, v7
	v_and_b32_e32 v8, 0xffff0000, v93
	v_add_f32_e32 v9, v157, v13
	v_mul_f32_e32 v8, v9, v8
	v_cvt_pk_bf16_f32 v7, v7, v8
	global_store_dwordx2 v[82:83], v[6:7], off
	s_waitcnt vmcnt(31)
	v_lshlrev_b32_e32 v6, 16, v88
	v_add_f32_e32 v7, v157, v14
	v_mul_f32_e32 v6, v7, v6
	v_and_b32_e32 v7, 0xffff0000, v88
	v_add_f32_e32 v8, v157, v15
	v_mul_f32_e32 v7, v8, v7
	v_cvt_pk_bf16_f32 v6, v6, v7
	v_lshlrev_b32_e32 v7, 16, v89
	v_add_f32_e32 v8, v157, v16
	v_mul_f32_e32 v7, v8, v7
	v_and_b32_e32 v8, 0xffff0000, v89
	v_add_f32_e32 v9, v157, v17
	v_mul_f32_e32 v8, v9, v8
	v_cvt_pk_bf16_f32 v7, v7, v8
	global_store_dwordx2 v[82:83], v[6:7], off offset:32
	s_waitcnt vmcnt(31)
	v_lshlrev_b32_e32 v6, 16, v86
	v_add_f32_e32 v7, v157, v18
	v_mul_f32_e32 v6, v7, v6
	v_and_b32_e32 v7, 0xffff0000, v86
	v_add_f32_e32 v8, v157, v19
	v_mul_f32_e32 v7, v8, v7
	v_cvt_pk_bf16_f32 v6, v6, v7
	v_lshlrev_b32_e32 v7, 16, v87
	v_add_f32_e32 v8, v157, v20
	v_mul_f32_e32 v7, v8, v7
	v_and_b32_e32 v8, 0xffff0000, v87
	v_add_f32_e32 v9, v157, v21
	v_mul_f32_e32 v8, v9, v8
	v_cvt_pk_bf16_f32 v7, v7, v8
	global_store_dwordx2 v[82:83], v[6:7], off offset:64
	s_waitcnt vmcnt(31)
	v_lshlrev_b32_e32 v6, 16, v84
	v_add_f32_e32 v2, v157, v2
	v_mul_f32_e32 v2, v2, v6
	v_and_b32_e32 v6, 0xffff0000, v84
	v_add_f32_e32 v3, v157, v3
	v_mul_f32_e32 v3, v3, v6
	v_cvt_pk_bf16_f32 v2, v2, v3
	v_lshlrev_b32_e32 v3, 16, v85
	v_add_f32_e32 v4, v157, v4
	v_mul_f32_e32 v3, v4, v3
	v_and_b32_e32 v4, 0xffff0000, v85
	v_add_f32_e32 v5, v157, v5
	v_mul_f32_e32 v4, v5, v4
	v_cvt_pk_bf16_f32 v3, v3, v4
	global_store_dwordx2 v[82:83], v[2:3], off offset:96
	s_barrier

; __device__ __forceinline__ float sigm(float v) { return __builtin_amdgcn_rcpf(1.0f + __expf(-v)); }
;     __host__ __device__ bool next(int i, Unit& u) const { Unit b; if (!base.next(i >> 1, b)) return false; u.pm = b.pm; u.pn = b.pn + 4 * (i & 1); return true; }
; __device__ __forceinline__ unsigned f2bf(float f) { unsigned u = __builtin_bit_cast(unsigned, f); return (u + 0x7fffu + ((u >> 16) & 1u)) >> 16; }
; __global__ void __launch_bounds__(512, 2) fwd_mega(Args a) {
;     ...
;                 for (int i = 0; S.next(i, fu); ++i) {
;                     if ((fu.pm & 15) == 0) continue;
;                     for (int idx = threadIdx.x; idx < 2 * FF; idx += 512) {
;                         const int j = idx / FF, f = idx % FF; const size_t cur = (size_t)fu.pm * 2 * FF, prv = (size_t)(fu.pm - 1) * 2 * FF;
;                         const float a2 = RA[cur + j * FF + f], a1 = (j == 0) ? TA[prv + FF + f] : RA[cur + f], a0 = (j == 0) ? TA[prv + f] : TA[prv + FF + f];
;                         const float cv = cbp[f] + cw[f] * a0 + cw[FF + f] * a1 + cw[2 * FF + f] * a2;
;                         WSP(WS_ACT)[(size_t)(fu.pm * 256 + j) * FF + f] = (bf16)f2bf(cv * pg8::sigm(cv) * RU[cur + j * FF + f]);
;                     }
;                 }
.LBB0_1817:
	v_subrev_co_u32_e32 v6, vcc, 0xb00, v17
	s_nop 0
	v_mov_b32_e32 v41, v7
	v_cndmask_b32_e32 v40, v6, v17, vcc
	v_cmp_lt_u32_e64 s[6:7], s26, v17
	v_cndmask_b32_e32 v45, v11, v12, vcc
	v_cndmask_b32_e32 v44, v13, v14, vcc
	v_lshlrev_b64 v[46:47], 2, v[40:41]
	v_cndmask_b32_e32 v49, v12, v15, vcc
	v_cndmask_b32_e32 v48, v14, v16, vcc
	v_cndmask_b32_e64 v6, 0, v10, s[6:7]
	v_lshl_add_u64 v[44:45], v[44:45], 0, v[46:47]
	v_lshl_add_u64 v[48:49], v[48:49], 0, v[46:47]
	v_lshl_add_u64 v[50:51], s[10:11], 0, v[46:47]
	v_lshl_add_u64 v[46:47], s[8:9], 0, v[46:47]
	v_lshl_add_u64 v[42:43], v[6:7], 0, s[20:21]
	global_load_dword v52, v[44:45], off
	global_load_dword v57, v[48:49], off
	global_load_dword v55, v[50:51], off
	global_load_dword v56, v[46:47], off
	v_add_co_u32_e32 v44, vcc, s27, v46
	v_lshl_add_u64 v[42:43], v[42:43], 0, v[40:41]
	s_nop 0
	v_addc_co_u32_e32 v45, vcc, 0, v47, vcc
	v_lshlrev_b64 v[42:43], 2, v[42:43]
	v_add_co_u32_e32 v46, vcc, s28, v46
	v_lshl_add_u64 v[48:49], s[14:15], 0, v[42:43]
	s_nop 0
	v_addc_co_u32_e32 v47, vcc, 0, v47, vcc
	global_load_dword v50, v[44:45], off offset:3072
	global_load_dword v51, v[46:47], off offset:2048
	global_load_dword v53, v[48:49], off
	v_lshl_add_u64 v[42:43], s[18:19], 0, v[42:43]
	global_load_dword v44, v[42:43], off
	v_cndmask_b32_e64 v54, 0, 1, s[6:7]
	v_add_u32_e32 v17, 0x200, v17
	v_subrev_co_u32_e32 v6, vcc, 0xb00, v17
	s_nop 0
	v_mov_b32_e32 v59, v7
	v_cndmask_b32_e32 v58, v6, v17, vcc
	v_cmp_lt_u32_e64 s[6:7], s26, v17
	v_cndmask_b32_e32 v63, v11, v12, vcc
	v_cndmask_b32_e32 v62, v13, v14, vcc
	v_lshlrev_b64 v[64:65], 2, v[58:59]
	v_cndmask_b32_e32 v67, v12, v15, vcc
	v_cndmask_b32_e32 v66, v14, v16, vcc
	v_cndmask_b32_e64 v6, 0, v10, s[6:7]
	v_lshl_add_u64 v[62:63], v[62:63], 0, v[64:65]
	v_lshl_add_u64 v[66:67], v[66:67], 0, v[64:65]
	v_lshl_add_u64 v[68:69], s[10:11], 0, v[64:65]
	v_lshl_add_u64 v[64:65], s[8:9], 0, v[64:65]
	v_lshl_add_u64 v[60:61], v[6:7], 0, s[20:21]
	global_load_dword v70, v[62:63], off
	global_load_dword v75, v[66:67], off
	global_load_dword v73, v[68:69], off
	global_load_dword v74, v[64:65], off
	v_add_co_u32_e32 v62, vcc, s27, v64
	v_lshl_add_u64 v[60:61], v[60:61], 0, v[58:59]
	s_nop 0
	v_addc_co_u32_e32 v63, vcc, 0, v65, vcc
	v_lshlrev_b64 v[60:61], 2, v[60:61]
	v_add_co_u32_e32 v64, vcc, s28, v64
	v_lshl_add_u64 v[66:67], s[14:15], 0, v[60:61]
	s_nop 0
	v_addc_co_u32_e32 v65, vcc, 0, v65, vcc
	global_load_dword v68, v[62:63], off offset:3072
	global_load_dword v69, v[64:65], off offset:2048
	global_load_dword v71, v[66:67], off
	v_lshl_add_u64 v[60:61], s[18:19], 0, v[60:61]
	global_load_dword v62, v[60:61], off
	v_cndmask_b32_e64 v72, 0, 1, s[6:7]
	v_add_u32_e32 v17, 0x200, v17
	v_subrev_co_u32_e32 v6, vcc, 0xb00, v17
	s_nop 0
	v_mov_b32_e32 v77, v7
	v_cndmask_b32_e32 v76, v6, v17, vcc
	v_cmp_lt_u32_e64 s[6:7], s26, v17
	v_cndmask_b32_e32 v81, v11, v12, vcc
	v_cndmask_b32_e32 v80, v13, v14, vcc
	v_lshlrev_b64 v[82:83], 2, v[76:77]
	v_cndmask_b32_e32 v85, v12, v15, vcc
	v_cndmask_b32_e32 v84, v14, v16, vcc
	v_cndmask_b32_e64 v6, 0, v10, s[6:7]
	v_lshl_add_u64 v[80:81], v[80:81], 0, v[82:83]
	v_lshl_add_u64 v[84:85], v[84:85], 0, v[82:83]
	v_lshl_add_u64 v[86:87], s[10:11], 0, v[82:83]
	v_lshl_add_u64 v[82:83], s[8:9], 0, v[82:83]
	v_lshl_add_u64 v[78:79], v[6:7], 0, s[20:21]
	global_load_dword v88, v[80:81], off
	global_load_dword v93, v[84:85], off
	global_load_dword v91, v[86:87], off
	global_load_dword v92, v[82:83], off
	v_add_co_u32_e32 v80, vcc, s27, v82
	v_lshl_add_u64 v[78:79], v[78:79], 0, v[76:77]
	s_nop 0
	v_addc_co_u32_e32 v81, vcc, 0, v83, vcc
	v_lshlrev_b64 v[78:79], 2, v[78:79]
	v_add_co_u32_e32 v82, vcc, s28, v82
	v_lshl_add_u64 v[84:85], s[14:15], 0, v[78:79]
	s_nop 0
	v_addc_co_u32_e32 v83, vcc, 0, v83, vcc
	global_load_dword v86, v[80:81], off offset:3072
	global_load_dword v87, v[82:83], off offset:2048
	global_load_dword v89, v[84:85], off
	v_lshl_add_u64 v[78:79], s[18:19], 0, v[78:79]
	global_load_dword v80, v[78:79], off
	v_cndmask_b32_e64 v90, 0, 1, s[6:7]
	v_add_u32_e32 v17, 0x200, v17
	v_subrev_co_u32_e32 v6, vcc, 0xb00, v17
	s_nop 0
	v_mov_b32_e32 v95, v7
	v_cndmask_b32_e32 v94, v6, v17, vcc
	v_cmp_lt_u32_e64 s[6:7], s26, v17
	v_cndmask_b32_e32 v99, v11, v12, vcc
	v_cndmask_b32_e32 v98, v13, v14, vcc
	v_lshlrev_b64 v[100:101], 2, v[94:95]
	v_cndmask_b32_e32 v103, v12, v15, vcc
	v_cndmask_b32_e32 v102, v14, v16, vcc
	v_cndmask_b32_e64 v6, 0, v10, s[6:7]
	v_lshl_add_u64 v[98:99], v[98:99], 0, v[100:101]
	v_lshl_add_u64 v[102:103], v[102:103], 0, v[100:101]
	v_lshl_add_u64 v[104:105], s[10:11], 0, v[100:101]
	v_lshl_add_u64 v[100:101], s[8:9], 0, v[100:101]
	v_lshl_add_u64 v[96:97], v[6:7], 0, s[20:21]
	global_load_dword v106, v[98:99], off
	global_load_dword v111, v[102:103], off
	global_load_dword v109, v[104:105], off
	global_load_dword v110, v[100:101], off
	v_add_co_u32_e32 v98, vcc, s27, v100
	v_lshl_add_u64 v[96:97], v[96:97], 0, v[94:95]
	s_nop 0
	v_addc_co_u32_e32 v99, vcc, 0, v101, vcc
	v_lshlrev_b64 v[96:97], 2, v[96:97]
	v_add_co_u32_e32 v100, vcc, s28, v100
	v_lshl_add_u64 v[102:103], s[14:15], 0, v[96:97]
	s_nop 0
	v_addc_co_u32_e32 v101, vcc, 0, v101, vcc
	global_load_dword v104, v[98:99], off offset:3072
	global_load_dword v105, v[100:101], off offset:2048
	global_load_dword v107, v[102:103], off
	v_lshl_add_u64 v[96:97], s[18:19], 0, v[96:97]
	global_load_dword v98, v[96:97], off
	v_cndmask_b32_e64 v108, 0, 1, s[6:7]
	v_add_u32_e32 v17, 0x200, v17
	v_subrev_co_u32_e32 v6, vcc, 0xb00, v17
	s_nop 0
	v_mov_b32_e32 v113, v7
	v_cndmask_b32_e32 v112, v6, v17, vcc
	v_cmp_lt_u32_e64 s[6:7], s26, v17
; __device__ __forceinline__ float sigm(float v) { return __builtin_amdgcn_rcpf(1.0f + __expf(-v)); }
;     __host__ __device__ bool next(int i, Unit& u) const { Unit b; if (!base.next(i >> 1, b)) return false; u.pm = b.pm; u.pn = b.pn + 4 * (i & 1); return true; }
; __device__ __forceinline__ unsigned f2bf(float f) { unsigned u = __builtin_bit_cast(unsigned, f); return (u + 0x7fffu + ((u >> 16) & 1u)) >> 16; }
; __global__ void __launch_bounds__(512, 2) fwd_mega(Args a) {
;     ...
;                 for (int i = 0; S.next(i, fu); ++i) {
;                     if ((fu.pm & 15) == 0) continue;
;                     for (int idx = threadIdx.x; idx < 2 * FF; idx += 512) {
;                         const int j = idx / FF, f = idx % FF; const size_t cur = (size_t)fu.pm * 2 * FF, prv = (size_t)(fu.pm - 1) * 2 * FF;
;                         const float a2 = RA[cur + j * FF + f], a1 = (j == 0) ? TA[prv + FF + f] : RA[cur + f], a0 = (j == 0) ? TA[prv + f] : TA[prv + FF + f];
;                         const float cv = cbp[f] + cw[f] * a0 + cw[FF + f] * a1 + cw[2 * FF + f] * a2;
;                         WSP(WS_ACT)[(size_t)(fu.pm * 256 + j) * FF + f] = (bf16)f2bf(cv * pg8::sigm(cv) * RU[cur + j * FF + f]);
;                     }
;                 }
	v_cndmask_b32_e32 v117, v11, v12, vcc
	v_cndmask_b32_e32 v116, v13, v14, vcc
	v_lshlrev_b64 v[118:119], 2, v[112:113]
	v_cndmask_b32_e32 v121, v12, v15, vcc
	v_cndmask_b32_e32 v120, v14, v16, vcc
	v_cndmask_b32_e64 v6, 0, v10, s[6:7]
	v_lshl_add_u64 v[116:117], v[116:117], 0, v[118:119]
	v_lshl_add_u64 v[120:121], v[120:121], 0, v[118:119]
	v_lshl_add_u64 v[122:123], s[10:11], 0, v[118:119]
	v_lshl_add_u64 v[118:119], s[8:9], 0, v[118:119]
	v_lshl_add_u64 v[114:115], v[6:7], 0, s[20:21]
	global_load_dword v124, v[116:117], off
	global_load_dword v129, v[120:121], off
	global_load_dword v127, v[122:123], off
	global_load_dword v128, v[118:119], off
	v_add_co_u32_e32 v116, vcc, s27, v118
	v_lshl_add_u64 v[114:115], v[114:115], 0, v[112:113]
	s_nop 0
	v_addc_co_u32_e32 v117, vcc, 0, v119, vcc
	v_lshlrev_b64 v[114:115], 2, v[114:115]
	v_add_co_u32_e32 v118, vcc, s28, v118
	v_lshl_add_u64 v[120:121], s[14:15], 0, v[114:115]
	s_nop 0
	v_addc_co_u32_e32 v119, vcc, 0, v119, vcc
	global_load_dword v122, v[116:117], off offset:3072
	global_load_dword v123, v[118:119], off offset:2048
	global_load_dword v125, v[120:121], off
	v_lshl_add_u64 v[114:115], s[18:19], 0, v[114:115]
	global_load_dword v116, v[114:115], off
	v_cndmask_b32_e64 v126, 0, 1, s[6:7]
	v_add_u32_e32 v17, 0x200, v17
	v_subrev_co_u32_e32 v6, vcc, 0xb00, v17
	s_nop 0
	v_mov_b32_e32 v131, v7
	v_cndmask_b32_e32 v130, v6, v17, vcc
	v_cmp_lt_u32_e64 s[6:7], s26, v17
	v_cndmask_b32_e32 v135, v11, v12, vcc
	v_cndmask_b32_e32 v134, v13, v14, vcc
	v_lshlrev_b64 v[136:137], 2, v[130:131]
	v_cndmask_b32_e32 v139, v12, v15, vcc
	v_cndmask_b32_e32 v138, v14, v16, vcc
	v_cndmask_b32_e64 v6, 0, v10, s[6:7]
	v_lshl_add_u64 v[134:135], v[134:135], 0, v[136:137]
	v_lshl_add_u64 v[138:139], v[138:139], 0, v[136:137]
	v_lshl_add_u64 v[140:141], s[10:11], 0, v[136:137]
	v_lshl_add_u64 v[136:137], s[8:9], 0, v[136:137]
	v_lshl_add_u64 v[132:133], v[6:7], 0, s[20:21]
	global_load_dword v142, v[134:135], off
	global_load_dword v147, v[138:139], off
	global_load_dword v145, v[140:141], off
	global_load_dword v146, v[136:137], off
	v_add_co_u32_e32 v134, vcc, s27, v136
	v_lshl_add_u64 v[132:133], v[132:133], 0, v[130:131]
	s_nop 0
	v_addc_co_u32_e32 v135, vcc, 0, v137, vcc
	v_lshlrev_b64 v[132:133], 2, v[132:133]
	v_add_co_u32_e32 v136, vcc, s28, v136
	v_lshl_add_u64 v[138:139], s[14:15], 0, v[132:133]
	s_nop 0
	v_addc_co_u32_e32 v137, vcc, 0, v137, vcc
	global_load_dword v140, v[134:135], off offset:3072
	global_load_dword v141, v[136:137], off offset:2048
	global_load_dword v143, v[138:139], off
	v_lshl_add_u64 v[132:133], s[18:19], 0, v[132:133]
	global_load_dword v134, v[132:133], off
	v_cndmask_b32_e64 v144, 0, 1, s[6:7]
	v_add_u32_e32 v17, 0x200, v17
	s_waitcnt vmcnt(40)
	v_fmac_f32_e32 v55, v57, v56
	s_nop 0
	v_pk_mul_f32 v[42:43], v[52:53], v[50:51]
	s_nop 0
	v_add_f32_e32 v57, v55, v42
	v_add_f32_e32 v57, v57, v43
	v_mul_f32_e32 v42, 0xbfb8aa3b, v57
	v_exp_f32_e32 v42, v42
	v_or_b32_e32 v43, s33, v54
	v_add_f32_e32 v42, 1.0, v42
	v_rcp_f32_e32 v45, v42
	v_mad_i64_i32 v[42:43], s[6:7], v43, s25, v[8:9]
	v_lshl_add_u64 v[40:41], v[40:41], 1, v[42:43]
	v_mul_f32_e32 v57, v57, v45
	s_nop 0
	v_mul_f32_e32 v57, v44, v57
	v_bfe_u32 v42, v57, 16, 1
	v_add3_u32 v57, v57, v42, s29
	global_store_short_d16_hi v[40:41], v57, off
	s_waitcnt vmcnt(33)
	v_fmac_f32_e32 v73, v75, v74
	s_nop 0
	v_pk_mul_f32 v[60:61], v[70:71], v[68:69]
	s_nop 0
	v_add_f32_e32 v75, v73, v60
	v_add_f32_e32 v75, v75, v61
	v_mul_f32_e32 v60, 0xbfb8aa3b, v75
	v_exp_f32_e32 v60, v60
	v_or_b32_e32 v61, s33, v72
	v_add_f32_e32 v60, 1.0, v60
	v_rcp_f32_e32 v63, v60
	v_mad_i64_i32 v[60:61], s[6:7], v61, s25, v[8:9]
	v_lshl_add_u64 v[58:59], v[58:59], 1, v[60:61]
	v_mul_f32_e32 v75, v75, v63
	s_nop 0
	v_mul_f32_e32 v75, v62, v75
	v_bfe_u32 v60, v75, 16, 1
	v_add3_u32 v75, v75, v60, s29
	global_store_short_d16_hi v[58:59], v75, off
	s_waitcnt vmcnt(26)
	v_fmac_f32_e32 v91, v93, v92
	s_nop 0
	v_pk_mul_f32 v[78:79], v[88:89], v[86:87]
	s_nop 0
	v_add_f32_e32 v93, v91, v78
	v_add_f32_e32 v93, v93, v79
	v_mul_f32_e32 v78, 0xbfb8aa3b, v93
	v_exp_f32_e32 v78, v78
	v_or_b32_e32 v79, s33, v90
	v_add_f32_e32 v78, 1.0, v78
	v_rcp_f32_e32 v81, v78
	v_mad_i64_i32 v[78:79], s[6:7], v79, s25, v[8:9]
	v_lshl_add_u64 v[76:77], v[76:77], 1, v[78:79]
	v_mul_f32_e32 v93, v93, v81
	s_nop 0
	v_mul_f32_e32 v93, v80, v93
	v_bfe_u32 v78, v93, 16, 1
	v_add3_u32 v93, v93, v78, s29
	global_store_short_d16_hi v[76:77], v93, off
	s_waitcnt vmcnt(19)
	v_fmac_f32_e32 v109, v111, v110
	s_nop 0
	v_pk_mul_f32 v[96:97], v[106:107], v[104:105]
	s_nop 0
	v_add_f32_e32 v111, v109, v96
	v_add_f32_e32 v111, v111, v97
	v_mul_f32_e32 v96, 0xbfb8aa3b, v111
	v_exp_f32_e32 v96, v96
	v_or_b32_e32 v97, s33, v108
	v_add_f32_e32 v96, 1.0, v96
	v_rcp_f32_e32 v99, v96
	v_mad_i64_i32 v[96:97], s[6:7], v97, s25, v[8:9]
	v_lshl_add_u64 v[94:95], v[94:95], 1, v[96:97]
	v_mul_f32_e32 v111, v111, v99
	s_nop 0
	v_mul_f32_e32 v111, v98, v111
	v_bfe_u32 v96, v111, 16, 1
	v_add3_u32 v111, v111, v96, s29
	global_store_short_d16_hi v[94:95], v111, off
	s_waitcnt vmcnt(12)
	v_fmac_f32_e32 v127, v129, v128
	s_nop 0
	v_pk_mul_f32 v[114:115], v[124:125], v[122:123]
	s_nop 0
	v_add_f32_e32 v129, v127, v114
	v_add_f32_e32 v129, v129, v115
	v_mul_f32_e32 v114, 0xbfb8aa3b, v129
	v_exp_f32_e32 v114, v114
	v_or_b32_e32 v115, s33, v126
	v_add_f32_e32 v114, 1.0, v114
	v_rcp_f32_e32 v117, v114
	v_mad_i64_i32 v[114:115], s[6:7], v115, s25, v[8:9]
	v_lshl_add_u64 v[112:113], v[112:113], 1, v[114:115]
	v_mul_f32_e32 v129, v129, v117
	s_nop 0
	v_mul_f32_e32 v129, v116, v129
	v_bfe_u32 v114, v129, 16, 1
	v_add3_u32 v129, v129, v114, s29
	global_store_short_d16_hi v[112:113], v129, off
	s_waitcnt vmcnt(5)
; __device__ __forceinline__ float sigm(float v) { return __builtin_amdgcn_rcpf(1.0f + __expf(-v)); }
;     __host__ __device__ bool next(int i, Unit& u) const { Unit b; if (!base.next(i >> 1, b)) return false; u.pm = b.pm; u.pn = b.pn + 4 * (i & 1); return true; }
; __device__ __forceinline__ unsigned f2bf(float f) { unsigned u = __builtin_bit_cast(unsigned, f); return (u + 0x7fffu + ((u >> 16) & 1u)) >> 16; }
; __global__ void __launch_bounds__(512, 2) fwd_mega(Args a) {
;     ...
;                 for (int i = 0; S.next(i, fu); ++i) {
;                     if ((fu.pm & 15) == 0) continue;
;                     for (int idx = threadIdx.x; idx < 2 * FF; idx += 512) {
;                         const int j = idx / FF, f = idx % FF; const size_t cur = (size_t)fu.pm * 2 * FF, prv = (size_t)(fu.pm - 1) * 2 * FF;
;                         const float a2 = RA[cur + j * FF + f], a1 = (j == 0) ? TA[prv + FF + f] : RA[cur + f], a0 = (j == 0) ? TA[prv + f] : TA[prv + FF + f];
;                         const float cv = cbp[f] + cw[f] * a0 + cw[FF + f] * a1 + cw[2 * FF + f] * a2;
;                         WSP(WS_ACT)[(size_t)(fu.pm * 256 + j) * FF + f] = (bf16)f2bf(cv * pg8::sigm(cv) * RU[cur + j * FF + f]);
;                     }
;                 }
	v_fmac_f32_e32 v145, v147, v146
	s_nop 0
	v_pk_mul_f32 v[132:133], v[142:143], v[140:141]
	s_nop 0
	v_add_f32_e32 v147, v145, v132
	v_add_f32_e32 v147, v147, v133
	v_mul_f32_e32 v132, 0xbfb8aa3b, v147
	v_exp_f32_e32 v132, v132
	v_or_b32_e32 v133, s33, v144
	v_add_f32_e32 v132, 1.0, v132
	v_rcp_f32_e32 v135, v132
	v_mad_i64_i32 v[132:133], s[6:7], v133, s25, v[8:9]
	v_lshl_add_u64 v[130:131], v[130:131], 1, v[132:133]
	v_mul_f32_e32 v147, v147, v135
	s_nop 0
	v_mul_f32_e32 v147, v134, v147
	v_bfe_u32 v132, v147, 16, 1
	v_add3_u32 v147, v147, v132, s29
	global_store_short_d16_hi v[130:131], v147, off
	v_subrev_co_u32_e32 v6, vcc, 0xb00, v17
	s_nop 0
	v_mov_b32_e32 v41, v7
	v_cndmask_b32_e32 v40, v6, v17, vcc
	v_cmp_lt_u32_e64 s[6:7], s26, v17
	v_cndmask_b32_e32 v45, v11, v12, vcc
	v_cndmask_b32_e32 v44, v13, v14, vcc
	v_lshlrev_b64 v[46:47], 2, v[40:41]
	v_cndmask_b32_e32 v49, v12, v15, vcc
	v_cndmask_b32_e32 v48, v14, v16, vcc
	v_cndmask_b32_e64 v6, 0, v10, s[6:7]
	v_lshl_add_u64 v[44:45], v[44:45], 0, v[46:47]
	v_lshl_add_u64 v[48:49], v[48:49], 0, v[46:47]
	v_lshl_add_u64 v[50:51], s[10:11], 0, v[46:47]
	v_lshl_add_u64 v[46:47], s[8:9], 0, v[46:47]
	v_lshl_add_u64 v[42:43], v[6:7], 0, s[20:21]
	global_load_dword v52, v[44:45], off
	global_load_dword v57, v[48:49], off
	global_load_dword v55, v[50:51], off
	global_load_dword v56, v[46:47], off
	v_add_co_u32_e32 v44, vcc, s27, v46
	v_lshl_add_u64 v[42:43], v[42:43], 0, v[40:41]
	s_nop 0
	v_addc_co_u32_e32 v45, vcc, 0, v47, vcc
	v_lshlrev_b64 v[42:43], 2, v[42:43]
	v_add_co_u32_e32 v46, vcc, s28, v46
	v_lshl_add_u64 v[48:49], s[14:15], 0, v[42:43]
	s_nop 0
	v_addc_co_u32_e32 v47, vcc, 0, v47, vcc
	global_load_dword v50, v[44:45], off offset:3072
	global_load_dword v51, v[46:47], off offset:2048
	global_load_dword v53, v[48:49], off
	v_lshl_add_u64 v[42:43], s[18:19], 0, v[42:43]
	global_load_dword v44, v[42:43], off
	v_cndmask_b32_e64 v54, 0, 1, s[6:7]
	v_add_u32_e32 v17, 0x200, v17
	v_subrev_co_u32_e32 v6, vcc, 0xb00, v17
	s_nop 0
	v_mov_b32_e32 v59, v7
	v_cndmask_b32_e32 v58, v6, v17, vcc
	v_cmp_lt_u32_e64 s[6:7], s26, v17
	v_cndmask_b32_e32 v63, v11, v12, vcc
	v_cndmask_b32_e32 v62, v13, v14, vcc
	v_lshlrev_b64 v[64:65], 2, v[58:59]
	v_cndmask_b32_e32 v67, v12, v15, vcc
	v_cndmask_b32_e32 v66, v14, v16, vcc
	v_cndmask_b32_e64 v6, 0, v10, s[6:7]
	v_lshl_add_u64 v[62:63], v[62:63], 0, v[64:65]
	v_lshl_add_u64 v[66:67], v[66:67], 0, v[64:65]
	v_lshl_add_u64 v[68:69], s[10:11], 0, v[64:65]
	v_lshl_add_u64 v[64:65], s[8:9], 0, v[64:65]
	v_lshl_add_u64 v[60:61], v[6:7], 0, s[20:21]
	global_load_dword v70, v[62:63], off
	global_load_dword v75, v[66:67], off
	global_load_dword v73, v[68:69], off
	global_load_dword v74, v[64:65], off
	v_add_co_u32_e32 v62, vcc, s27, v64
	v_lshl_add_u64 v[60:61], v[60:61], 0, v[58:59]
	s_nop 0
	v_addc_co_u32_e32 v63, vcc, 0, v65, vcc
	v_lshlrev_b64 v[60:61], 2, v[60:61]
	v_add_co_u32_e32 v64, vcc, s28, v64
	v_lshl_add_u64 v[66:67], s[14:15], 0, v[60:61]
	s_nop 0
	v_addc_co_u32_e32 v65, vcc, 0, v65, vcc
	global_load_dword v68, v[62:63], off offset:3072
	global_load_dword v69, v[64:65], off offset:2048
	global_load_dword v71, v[66:67], off
	v_lshl_add_u64 v[60:61], s[18:19], 0, v[60:61]
	global_load_dword v62, v[60:61], off
	v_cndmask_b32_e64 v72, 0, 1, s[6:7]
	v_add_u32_e32 v17, 0x200, v17
	v_subrev_co_u32_e32 v6, vcc, 0xb00, v17
	s_nop 0
	v_mov_b32_e32 v77, v7
	v_cndmask_b32_e32 v76, v6, v17, vcc
	v_cmp_lt_u32_e64 s[6:7], s26, v17
	v_cndmask_b32_e32 v81, v11, v12, vcc
	v_cndmask_b32_e32 v80, v13, v14, vcc
	v_lshlrev_b64 v[82:83], 2, v[76:77]
	v_cndmask_b32_e32 v85, v12, v15, vcc
	v_cndmask_b32_e32 v84, v14, v16, vcc
	v_cndmask_b32_e64 v6, 0, v10, s[6:7]
	v_lshl_add_u64 v[80:81], v[80:81], 0, v[82:83]
	v_lshl_add_u64 v[84:85], v[84:85], 0, v[82:83]
	v_lshl_add_u64 v[86:87], s[10:11], 0, v[82:83]
	v_lshl_add_u64 v[82:83], s[8:9], 0, v[82:83]
	v_lshl_add_u64 v[78:79], v[6:7], 0, s[20:21]
	global_load_dword v88, v[80:81], off
	global_load_dword v93, v[84:85], off
	global_load_dword v91, v[86:87], off
	global_load_dword v92, v[82:83], off
	v_add_co_u32_e32 v80, vcc, s27, v82
	v_lshl_add_u64 v[78:79], v[78:79], 0, v[76:77]
	s_nop 0
	v_addc_co_u32_e32 v81, vcc, 0, v83, vcc
	v_lshlrev_b64 v[78:79], 2, v[78:79]
	v_add_co_u32_e32 v82, vcc, s28, v82
	v_lshl_add_u64 v[84:85], s[14:15], 0, v[78:79]
	s_nop 0
	v_addc_co_u32_e32 v83, vcc, 0, v83, vcc
	global_load_dword v86, v[80:81], off offset:3072
	global_load_dword v87, v[82:83], off offset:2048
	global_load_dword v89, v[84:85], off
	v_lshl_add_u64 v[78:79], s[18:19], 0, v[78:79]
	global_load_dword v80, v[78:79], off
	v_cndmask_b32_e64 v90, 0, 1, s[6:7]
	v_add_u32_e32 v17, 0x200, v17
	v_subrev_co_u32_e32 v6, vcc, 0xb00, v17
	s_nop 0
	v_mov_b32_e32 v95, v7
	v_cndmask_b32_e32 v94, v6, v17, vcc
	v_cmp_lt_u32_e64 s[6:7], s26, v17
	v_cndmask_b32_e32 v99, v11, v12, vcc
	v_cndmask_b32_e32 v98, v13, v14, vcc
	v_lshlrev_b64 v[100:101], 2, v[94:95]
	v_cndmask_b32_e32 v103, v12, v15, vcc
	v_cndmask_b32_e32 v102, v14, v16, vcc
	v_cndmask_b32_e64 v6, 0, v10, s[6:7]
	v_lshl_add_u64 v[98:99], v[98:99], 0, v[100:101]
	v_lshl_add_u64 v[102:103], v[102:103], 0, v[100:101]
	v_lshl_add_u64 v[104:105], s[10:11], 0, v[100:101]
	v_lshl_add_u64 v[100:101], s[8:9], 0, v[100:101]
; __device__ __forceinline__ float sigm(float v) { return __builtin_amdgcn_rcpf(1.0f + __expf(-v)); }
;     __host__ __device__ bool next(int i, Unit& u) const { Unit b; if (!base.next(i >> 1, b)) return false; u.pm = b.pm; u.pn = b.pn + 4 * (i & 1); return true; }
; __device__ __forceinline__ unsigned f2bf(float f) { unsigned u = __builtin_bit_cast(unsigned, f); return (u + 0x7fffu + ((u >> 16) & 1u)) >> 16; }
; __global__ void __launch_bounds__(512, 2) fwd_mega(Args a) {
;     ...
;                 for (int i = 0; S.next(i, fu); ++i) {
;                     if ((fu.pm & 15) == 0) continue;
;                     for (int idx = threadIdx.x; idx < 2 * FF; idx += 512) {
;                         const int j = idx / FF, f = idx % FF; const size_t cur = (size_t)fu.pm * 2 * FF, prv = (size_t)(fu.pm - 1) * 2 * FF;
;                         const float a2 = RA[cur + j * FF + f], a1 = (j == 0) ? TA[prv + FF + f] : RA[cur + f], a0 = (j == 0) ? TA[prv + f] : TA[prv + FF + f];
;                         const float cv = cbp[f] + cw[f] * a0 + cw[FF + f] * a1 + cw[2 * FF + f] * a2;
;                         WSP(WS_ACT)[(size_t)(fu.pm * 256 + j) * FF + f] = (bf16)f2bf(cv * pg8::sigm(cv) * RU[cur + j * FF + f]);
;                     }
;                 }
	v_lshl_add_u64 v[96:97], v[6:7], 0, s[20:21]
	global_load_dword v106, v[98:99], off
	global_load_dword v111, v[102:103], off
	global_load_dword v109, v[104:105], off
	global_load_dword v110, v[100:101], off
	v_add_co_u32_e32 v98, vcc, s27, v100
	v_lshl_add_u64 v[96:97], v[96:97], 0, v[94:95]
	s_nop 0
	v_addc_co_u32_e32 v99, vcc, 0, v101, vcc
	v_lshlrev_b64 v[96:97], 2, v[96:97]
	v_add_co_u32_e32 v100, vcc, s28, v100
	v_lshl_add_u64 v[102:103], s[14:15], 0, v[96:97]
	s_nop 0
	v_addc_co_u32_e32 v101, vcc, 0, v101, vcc
	global_load_dword v104, v[98:99], off offset:3072
	global_load_dword v105, v[100:101], off offset:2048
	global_load_dword v107, v[102:103], off
	v_lshl_add_u64 v[96:97], s[18:19], 0, v[96:97]
	global_load_dword v98, v[96:97], off
	v_cndmask_b32_e64 v108, 0, 1, s[6:7]
	v_add_u32_e32 v17, 0x200, v17
	v_subrev_co_u32_e32 v6, vcc, 0xb00, v17
	s_nop 0
	v_mov_b32_e32 v113, v7
	v_cndmask_b32_e32 v112, v6, v17, vcc
	v_cmp_lt_u32_e64 s[6:7], s26, v17
	v_cndmask_b32_e32 v117, v11, v12, vcc
	v_cndmask_b32_e32 v116, v13, v14, vcc
	v_lshlrev_b64 v[118:119], 2, v[112:113]
	v_cndmask_b32_e32 v121, v12, v15, vcc
	v_cndmask_b32_e32 v120, v14, v16, vcc
	v_cndmask_b32_e64 v6, 0, v10, s[6:7]
	v_lshl_add_u64 v[116:117], v[116:117], 0, v[118:119]
	v_lshl_add_u64 v[120:121], v[120:121], 0, v[118:119]
	v_lshl_add_u64 v[122:123], s[10:11], 0, v[118:119]
	v_lshl_add_u64 v[118:119], s[8:9], 0, v[118:119]
	v_lshl_add_u64 v[114:115], v[6:7], 0, s[20:21]
	global_load_dword v124, v[116:117], off
	global_load_dword v129, v[120:121], off
	global_load_dword v127, v[122:123], off
	global_load_dword v128, v[118:119], off
	v_add_co_u32_e32 v116, vcc, s27, v118
	v_lshl_add_u64 v[114:115], v[114:115], 0, v[112:113]
	s_nop 0
	v_addc_co_u32_e32 v117, vcc, 0, v119, vcc
	v_lshlrev_b64 v[114:115], 2, v[114:115]
	v_add_co_u32_e32 v118, vcc, s28, v118
	v_lshl_add_u64 v[120:121], s[14:15], 0, v[114:115]
	s_nop 0
	v_addc_co_u32_e32 v119, vcc, 0, v119, vcc
	global_load_dword v122, v[116:117], off offset:3072
	global_load_dword v123, v[118:119], off offset:2048
	global_load_dword v125, v[120:121], off
	v_lshl_add_u64 v[114:115], s[18:19], 0, v[114:115]
	global_load_dword v116, v[114:115], off
	v_cndmask_b32_e64 v126, 0, 1, s[6:7]
	v_add_u32_e32 v17, 0x200, v17
	s_waitcnt vmcnt(32)
	v_fmac_f32_e32 v55, v57, v56
	s_nop 0
	v_pk_mul_f32 v[42:43], v[52:53], v[50:51]
	s_nop 0
	v_add_f32_e32 v57, v55, v42
	v_add_f32_e32 v57, v57, v43
	v_mul_f32_e32 v42, 0xbfb8aa3b, v57
	v_exp_f32_e32 v42, v42
	v_or_b32_e32 v43, s33, v54
	v_add_f32_e32 v42, 1.0, v42
	v_rcp_f32_e32 v45, v42
	v_mad_i64_i32 v[42:43], s[6:7], v43, s25, v[8:9]
	v_lshl_add_u64 v[40:41], v[40:41], 1, v[42:43]
	v_mul_f32_e32 v57, v57, v45
	s_nop 0
	v_mul_f32_e32 v57, v44, v57
	v_bfe_u32 v42, v57, 16, 1
	v_add3_u32 v57, v57, v42, s29
	global_store_short_d16_hi v[40:41], v57, off
	s_waitcnt vmcnt(25)
	v_fmac_f32_e32 v73, v75, v74
	s_nop 0
	v_pk_mul_f32 v[60:61], v[70:71], v[68:69]
	s_nop 0
	v_add_f32_e32 v75, v73, v60
	v_add_f32_e32 v75, v75, v61
	v_mul_f32_e32 v60, 0xbfb8aa3b, v75
	v_exp_f32_e32 v60, v60
	v_or_b32_e32 v61, s33, v72
	v_add_f32_e32 v60, 1.0, v60
	v_rcp_f32_e32 v63, v60
	v_mad_i64_i32 v[60:61], s[6:7], v61, s25, v[8:9]
	v_lshl_add_u64 v[58:59], v[58:59], 1, v[60:61]
	v_mul_f32_e32 v75, v75, v63
	s_nop 0
	v_mul_f32_e32 v75, v62, v75
	v_bfe_u32 v60, v75, 16, 1
	v_add3_u32 v75, v75, v60, s29
	global_store_short_d16_hi v[58:59], v75, off
	s_waitcnt vmcnt(18)
	v_fmac_f32_e32 v91, v93, v92
	s_nop 0
	v_pk_mul_f32 v[78:79], v[88:89], v[86:87]
	s_nop 0
	v_add_f32_e32 v93, v91, v78
	v_add_f32_e32 v93, v93, v79
	v_mul_f32_e32 v78, 0xbfb8aa3b, v93
	v_exp_f32_e32 v78, v78
	v_or_b32_e32 v79, s33, v90
	v_add_f32_e32 v78, 1.0, v78
	v_rcp_f32_e32 v81, v78
	v_mad_i64_i32 v[78:79], s[6:7], v79, s25, v[8:9]
	v_lshl_add_u64 v[76:77], v[76:77], 1, v[78:79]
	v_mul_f32_e32 v93, v93, v81
	s_nop 0
	v_mul_f32_e32 v93, v80, v93
	v_bfe_u32 v78, v93, 16, 1
	v_add3_u32 v93, v93, v78, s29
	global_store_short_d16_hi v[76:77], v93, off
	s_waitcnt vmcnt(11)
	v_fmac_f32_e32 v109, v111, v110
	s_nop 0
	v_pk_mul_f32 v[96:97], v[106:107], v[104:105]
	s_nop 0
	v_add_f32_e32 v111, v109, v96
	v_add_f32_e32 v111, v111, v97
	v_mul_f32_e32 v96, 0xbfb8aa3b, v111
	v_exp_f32_e32 v96, v96
	v_or_b32_e32 v97, s33, v108
	v_add_f32_e32 v96, 1.0, v96
	v_rcp_f32_e32 v99, v96
	v_mad_i64_i32 v[96:97], s[6:7], v97, s25, v[8:9]
	v_lshl_add_u64 v[94:95], v[94:95], 1, v[96:97]
	v_mul_f32_e32 v111, v111, v99
	s_nop 0
	v_mul_f32_e32 v111, v98, v111
	v_bfe_u32 v96, v111, 16, 1
	v_add3_u32 v111, v111, v96, s29
	global_store_short_d16_hi v[94:95], v111, off
	s_waitcnt vmcnt(4)
	v_fmac_f32_e32 v127, v129, v128
	s_nop 0
	v_pk_mul_f32 v[114:115], v[124:125], v[122:123]
	s_nop 0
	v_add_f32_e32 v129, v127, v114
	v_add_f32_e32 v129, v129, v115
	v_mul_f32_e32 v114, 0xbfb8aa3b, v129
	v_exp_f32_e32 v114, v114
	v_or_b32_e32 v115, s33, v126
	v_add_f32_e32 v114, 1.0, v114
	v_rcp_f32_e32 v117, v114
	v_mad_i64_i32 v[114:115], s[6:7], v115, s25, v[8:9]
	v_lshl_add_u64 v[112:113], v[112:113], 1, v[114:115]
	v_mul_f32_e32 v129, v129, v117
	s_nop 0
	v_mul_f32_e32 v129, v116, v129
	v_bfe_u32 v114, v129, 16, 1
	v_add3_u32 v129, v129, v114, s29
	global_store_short_d16_hi v[112:113], v129, off
	s_or_b64 exec, exec, s[22:23]
	s_branch .LBB0_1806
